# peeled first GEMM K-iteration (C=0, no acc zeroing), branchy softmax-rescale common path, merged waits, biased K-frag bases in MLA attention
# speedup vs baseline: 1.0257x; 1.0036x over previous
; #define PG8_STAGE(bufoff, gbase, voff) do { _Pragma("unroll") for (int _i = 0; _i < 2; ++_i) \
;         __builtin_amdgcn_global_load_lds((const unsigned*)((const char*)(gbase) + (voff)[_i]), (PG8_LAS unsigned*)(lds + (bufoff) + ldsw + _i * 8192), 16, 0, 0); } while (0)
; #define PG8_LDA(dst, b, h) do { _Pragma("unroll") for (int m = 0; m < 4; ++m) _Pragma("unroll") for (int k = 0; k < 2; ++k) dst[m][k] = *(const PG8_LAS bf16x8*)(lds + PG8_SA(b, h) + aoff + m * 2048 + k * 1024); } while (0)
; #define PG8_LDB(dst, b, h) do { _Pragma("unroll") for (int n = 0; n < 2; ++n) _Pragma("unroll") for (int k = 0; k < 2; ++k) dst[n][k] = *(const PG8_LAS bf16x8*)(lds + PG8_SB(b, h) + boff + n * 2048 + k * 1024); } while (0)
; #define PG8_WAIT_V(n) asm volatile("s_waitcnt vmcnt(" #n ")" ::: "memory")
; #define PG8_WAIT_L(n) asm volatile("s_waitcnt lgkmcnt(" #n ")" ::: "memory")
; #define PG8_BAR __builtin_amdgcn_s_barrier()
; #define PG8_SCHED __builtin_amdgcn_sched_barrier(0)
; template <class Epi, class Sched, bool ALIGN_EPI = false, bool SP2 = false>
; __device__ __forceinline__ void gemm_phase(PG8_LAS unsigned char* lds, const Gemm g, const Sched& S, const Epi& E, const int tid) {
;     ...
;         const bool has_next = S.next(ui + 1, nxt);
;         const char* nA = has_next ? (const char*)g.A + (size_t)nxt.pm * tstep : cA; const char* nB = has_next ? (const char*)g.Bt + (size_t)nxt.pn * tstep : cB;
;         for (int t = 0; t < nt; t += 2) {
;             const bool last = (t == nt - 2);
;             const char* a1 = cA + (size_t)(t + 1) * kstep;
;             const char* a2 = last ? nA : cA + (size_t)(t + 2) * kstep; const char* b2 = last ? nB : cB + (size_t)(t + 2) * kstep;
;             const char* a3 = a2 + kstep; const char* b3 = b2 + kstep;
;             if (last && has_next) S.a_ready(nxt);
;             if constexpr (SP2) {
;             PG8_LDB(B0, 0, 0); PG8_LDB(B1, 0, 1); PG8_SCHED; PG8_LDA(At, 0, 0); PG8_STAGE(PG8_SA(1, 1), a1 + hstep, voffA);
;             PG8_WAIT_V(8); PG8_WAIT_L(0); PG8_BAR; PG8_MMA(0, 0, At, B0); PG8_MMA(0, 1, At, B1); PG8_BAR; PG8_SCHED;
;             PG8_LDA(At, 0, 1); PG8_STAGE(PG8_SB(0, 0), b2, voffB); PG8_STAGE(PG8_SB(0, 1), b2 + hstep, voffB); PG8_STAGE(PG8_SA(0, 0), a2, voffA);
;             PG8_WAIT_V(8); PG8_WAIT_L(0); PG8_BAR; PG8_MMA(1, 0, At, B0); PG8_MMA(1, 1, At, B1); PG8_BAR; PG8_SCHED;
.LBB0_318:
	s_ashr_i32 s29, s28, 31
	s_lshl_b64 s[30:31], s[28:29], 20
	s_add_u32 s30, s48, s30
	s_addc_u32 s31, s49, s31
	s_and_b64 s[34:35], s[6:7], exec
	s_cselect_b32 s9, s31, s43
	s_cselect_b32 s29, s30, s42
	s_ashr_i32 s27, s26, 31
	s_lshl_b64 s[34:35], s[26:27], 20
	s_add_u32 s34, s50, s34
	s_addc_u32 s35, s51, s35
	s_and_b64 s[46:47], s[6:7], exec
	s_cselect_b32 s27, s35, s45
	s_cselect_b32 s37, s34, s44
	s_add_u32 s42, s42, 0x80080
	s_addc_u32 s43, s43, 0
	s_add_u32 s69, s44, 0x100
	s_addc_u32 s92, s45, 0
	s_mov_b32 s76, -2
	s_waitcnt vmcnt(0)
	s_add_u32 s44, s42, 0xfff80080
	s_addc_u32 s45, s43, -1
	s_add_i32 s77, 0, 0x10000
	s_cmp_eq_u32 s76, 28
	s_cselect_b32 s47, s9, s45
	s_cselect_b32 s46, s29, s44
	v_add_u32_e32 v136, s77, v178
	s_cselect_b32 s45, s27, s92
	s_cselect_b32 s44, s37, s69
	s_add_i32 s80, 0, 0x14000
	ds_read_b128 v[128:131], v136
	ds_read_b128 v[132:135], v136 offset:1024
	ds_read_b128 v[150:153], v136 offset:2048
	ds_read_b128 v[154:157], v136 offset:3072
	v_add_u32_e32 v136, s80, v178
	ds_read_b128 v[158:161], v136
	ds_read_b128 v[162:165], v136 offset:1024
	ds_read_b128 v[166:169], v136 offset:2048
	ds_read_b128 v[170:173], v136 offset:3072
	v_lshl_add_u64 v[136:137], s[42:43], 0, v[146:147]
	s_add_i32 m0, s53, 0xc000
	ds_read_b128 v[174:177], v179
	ds_read_b128 v[180:183], v179 offset:1024
	ds_read_b128 v[184:187], v179 offset:2048
	ds_read_b128 v[188:191], v179 offset:3072
	ds_read_b128 v[192:195], v179 offset:4096
	ds_read_b128 v[196:199], v179 offset:5120
	ds_read_b128 v[200:203], v179 offset:6144
	ds_read_b128 v[206:209], v179 offset:7168
	global_load_lds_dwordx4 v[136:137], off
	v_lshl_add_u64 v[136:137], s[42:43], 0, v[148:149]
	s_add_i32 m0, s53, 0xe000
	s_nop 0
	global_load_lds_dwordx4 v[136:137], off
	s_waitcnt vmcnt(24)
	s_waitcnt lgkmcnt(0)
	s_barrier
	s_setprio 1
	s_waitcnt lgkmcnt(0)
	v_mfma_f32_16x16x32_bf16 v[124:127], v[128:131], v[174:177], 0
	v_mfma_f32_16x16x32_bf16 v[120:123], v[150:153], v[174:177], 0
	v_mfma_f32_16x16x32_bf16 v[108:111], v[128:131], v[184:187], 0
	v_mfma_f32_16x16x32_bf16 v[104:107], v[150:153], v[184:187], 0
	v_mfma_f32_16x16x32_bf16 v[92:95], v[128:131], v[192:195], 0
	v_mfma_f32_16x16x32_bf16 v[88:91], v[150:153], v[192:195], 0
	v_mfma_f32_16x16x32_bf16 v[76:79], v[128:131], v[200:203], 0
	v_mfma_f32_16x16x32_bf16 v[72:75], v[150:153], v[200:203], 0
	v_mfma_f32_16x16x32_bf16 v[124:127], v[132:135], v[180:183], v[124:127]
	v_mfma_f32_16x16x32_bf16 v[120:123], v[154:157], v[180:183], v[120:123]
	v_mfma_f32_16x16x32_bf16 v[108:111], v[132:135], v[188:191], v[108:111]
	v_mfma_f32_16x16x32_bf16 v[104:107], v[154:157], v[188:191], v[104:107]
	v_mfma_f32_16x16x32_bf16 v[92:95], v[132:135], v[196:199], v[92:95]
	v_mfma_f32_16x16x32_bf16 v[88:91], v[154:157], v[196:199], v[88:91]
	v_mfma_f32_16x16x32_bf16 v[76:79], v[132:135], v[206:209], v[76:79]
	v_mfma_f32_16x16x32_bf16 v[72:75], v[154:157], v[206:209], v[72:75]
	s_setprio 0
	s_setprio 1
	v_mfma_f32_16x16x32_bf16 v[116:119], v[158:161], v[174:177], 0
	v_mfma_f32_16x16x32_bf16 v[112:115], v[166:169], v[174:177], 0
	v_mfma_f32_16x16x32_bf16 v[100:103], v[158:161], v[184:187], 0
	v_mfma_f32_16x16x32_bf16 v[96:99], v[166:169], v[184:187], 0
	v_mfma_f32_16x16x32_bf16 v[84:87], v[158:161], v[192:195], 0
	v_mfma_f32_16x16x32_bf16 v[80:83], v[166:169], v[192:195], 0
	v_mfma_f32_16x16x32_bf16 v[68:71], v[158:161], v[200:203], 0
	v_mfma_f32_16x16x32_bf16 v[64:67], v[166:169], v[200:203], 0
	v_mfma_f32_16x16x32_bf16 v[116:119], v[162:165], v[180:183], v[116:119]
	v_mfma_f32_16x16x32_bf16 v[112:115], v[170:173], v[180:183], v[112:115]
	v_mfma_f32_16x16x32_bf16 v[100:103], v[162:165], v[188:191], v[100:103]
	v_mfma_f32_16x16x32_bf16 v[96:99], v[170:173], v[188:191], v[96:99]
	v_mfma_f32_16x16x32_bf16 v[84:87], v[162:165], v[196:199], v[84:87]
	v_mfma_f32_16x16x32_bf16 v[80:83], v[170:173], v[196:199], v[80:83]
	v_mfma_f32_16x16x32_bf16 v[68:71], v[162:165], v[206:209], v[68:71]
	v_mfma_f32_16x16x32_bf16 v[64:67], v[170:173], v[206:209], v[64:67]
	s_setprio 0
	s_barrier
	s_add_i32 s77, s77, s52
	v_lshl_add_u64 v[136:137], s[44:45], 0, v[140:141]
	s_mov_b32 m0, s77
	ds_read_b128 v[174:177], v179 offset:16384
	ds_read_b128 v[180:183], v179 offset:17408
	ds_read_b128 v[184:187], v179 offset:18432
	ds_read_b128 v[188:191], v179 offset:19456
	ds_read_b128 v[192:195], v179 offset:20480
	ds_read_b128 v[196:199], v179 offset:21504
	ds_read_b128 v[200:203], v179 offset:22528
	ds_read_b128 v[206:209], v179 offset:23552
	global_load_lds_dwordx4 v[136:137], off
	s_add_i32 m0, s77, 0x2000
	s_add_u32 s78, s44, 0x80000
	v_lshl_add_u64 v[210:211], s[44:45], 0, v[144:145]
	s_addc_u32 s79, s45, 0
	s_add_i32 s77, s80, s52
	global_load_lds_dwordx4 v[210:211], off
	v_lshl_add_u64 v[212:213], s[78:79], 0, v[140:141]
	s_mov_b32 m0, s77
	v_lshl_add_u64 v[214:215], s[46:47], 0, v[142:143]
	global_load_lds_dwordx4 v[212:213], off
	v_lshl_add_u64 v[212:213], s[78:79], 0, v[144:145]
	s_add_i32 m0, s77, 0x2000
	s_nop 0
	global_load_lds_dwordx4 v[212:213], off
	v_lshl_add_u64 v[212:213], s[46:47], 0, v[138:139]
	s_mov_b32 m0, s53
	s_nop 0
	global_load_lds_dwordx4 v[212:213], off
	s_mov_b32 m0, s54
	s_nop 0
	global_load_lds_dwordx4 v[214:215], off
	s_waitcnt vmcnt(8)
	s_waitcnt lgkmcnt(0)
	s_barrier
; #define PG8_STAGE(bufoff, gbase, voff) do { _Pragma("unroll") for (int _i = 0; _i < 2; ++_i) \
;         __builtin_amdgcn_global_load_lds((const unsigned*)((const char*)(gbase) + (voff)[_i]), (PG8_LAS unsigned*)(lds + (bufoff) + ldsw + _i * 8192), 16, 0, 0); } while (0)
; #define PG8_LDA(dst, b, h) do { _Pragma("unroll") for (int m = 0; m < 4; ++m) _Pragma("unroll") for (int k = 0; k < 2; ++k) dst[m][k] = *(const PG8_LAS bf16x8*)(lds + PG8_SA(b, h) + aoff + m * 2048 + k * 1024); } while (0)
; #define PG8_LDB(dst, b, h) do { _Pragma("unroll") for (int n = 0; n < 2; ++n) _Pragma("unroll") for (int k = 0; k < 2; ++k) dst[n][k] = *(const PG8_LAS bf16x8*)(lds + PG8_SB(b, h) + boff + n * 2048 + k * 1024); } while (0)
; #define PG8_MMA(ai, bj, At, Bt) do { __builtin_amdgcn_s_setprio(1); _Pragma("unroll") for (int m = 0; m < 4; ++m) _Pragma("unroll") for (int n = 0; n < 2; ++n) _Pragma("unroll") for (int k = 0; k < 2; ++k) \
;         acc[ai][bj][m][n] = __builtin_amdgcn_mfma_f32_16x16x32_bf16(Bt[n][k], At[m][k], acc[ai][bj][m][n], 0, 0, 0); __builtin_amdgcn_s_setprio(0); } while (0)
; #define PG8_WAIT_V(n) asm volatile("s_waitcnt vmcnt(" #n ")" ::: "memory")
; #define PG8_WAIT_L(n) asm volatile("s_waitcnt lgkmcnt(" #n ")" ::: "memory")
; #define PG8_BAR __builtin_amdgcn_s_barrier()
; #define PG8_SCHED __builtin_amdgcn_sched_barrier(0)
; template <class Epi, class Sched, bool ALIGN_EPI = false, bool SP2 = false>
; __device__ __forceinline__ void gemm_phase(PG8_LAS unsigned char* lds, const Gemm g, const Sched& S, const Epi& E, const int tid) {
;     ...
;             PG8_WAIT_V(8); PG8_WAIT_L(0); PG8_BAR; PG8_MMA(0, 0, At, B0); PG8_MMA(0, 1, At, B1); PG8_BAR; PG8_SCHED;
;             PG8_LDA(At, 0, 1); PG8_STAGE(PG8_SB(0, 0), b2, voffB); PG8_STAGE(PG8_SB(0, 1), b2 + hstep, voffB); PG8_STAGE(PG8_SA(0, 0), a2, voffA);
;             PG8_WAIT_V(8); PG8_WAIT_L(0); PG8_BAR; PG8_MMA(1, 0, At, B0); PG8_MMA(1, 1, At, B1); PG8_BAR; PG8_SCHED;
;             PG8_LDB(B0, 1, 0); PG8_LDB(B1, 1, 1); PG8_SCHED; PG8_LDA(At, 1, 0); PG8_STAGE(PG8_SA(0, 1), a2 + hstep, voffA);
;             PG8_WAIT_V(8); PG8_WAIT_L(0); PG8_BAR; PG8_MMA(0, 0, At, B0); PG8_MMA(0, 1, At, B1); PG8_BAR; PG8_SCHED;
;             PG8_LDA(At, 1, 1); PG8_STAGE(PG8_SB(1, 0), b3, voffB); PG8_STAGE(PG8_SB(1, 1), b3 + hstep, voffB); PG8_STAGE(PG8_SA(1, 0), a3, voffA);
	s_setprio 1
	s_waitcnt lgkmcnt(0)
	v_mfma_f32_16x16x32_bf16 v[60:63], v[128:131], v[174:177], 0
	v_mfma_f32_16x16x32_bf16 v[56:59], v[150:153], v[174:177], 0
	v_mfma_f32_16x16x32_bf16 v[44:47], v[128:131], v[184:187], 0
	v_mfma_f32_16x16x32_bf16 v[40:43], v[150:153], v[184:187], 0
	v_mfma_f32_16x16x32_bf16 v[28:31], v[128:131], v[192:195], 0
	v_mfma_f32_16x16x32_bf16 v[24:27], v[150:153], v[192:195], 0
	v_mfma_f32_16x16x32_bf16 v[12:15], v[128:131], v[200:203], 0
	v_mfma_f32_16x16x32_bf16 v[8:11], v[150:153], v[200:203], 0
	v_mfma_f32_16x16x32_bf16 v[60:63], v[132:135], v[180:183], v[60:63]
	v_mfma_f32_16x16x32_bf16 v[56:59], v[154:157], v[180:183], v[56:59]
	v_mfma_f32_16x16x32_bf16 v[44:47], v[132:135], v[188:191], v[44:47]
	v_mfma_f32_16x16x32_bf16 v[40:43], v[154:157], v[188:191], v[40:43]
	v_mfma_f32_16x16x32_bf16 v[28:31], v[132:135], v[196:199], v[28:31]
	v_mfma_f32_16x16x32_bf16 v[24:27], v[154:157], v[196:199], v[24:27]
	v_mfma_f32_16x16x32_bf16 v[12:15], v[132:135], v[206:209], v[12:15]
	v_mfma_f32_16x16x32_bf16 v[8:11], v[154:157], v[206:209], v[8:11]
	s_setprio 0
	s_setprio 1
	v_mfma_f32_16x16x32_bf16 v[52:55], v[158:161], v[174:177], 0
	v_mfma_f32_16x16x32_bf16 v[48:51], v[166:169], v[174:177], 0
	v_mfma_f32_16x16x32_bf16 v[36:39], v[158:161], v[184:187], 0
	v_mfma_f32_16x16x32_bf16 v[32:35], v[166:169], v[184:187], 0
	v_mfma_f32_16x16x32_bf16 v[20:23], v[158:161], v[192:195], 0
	v_mfma_f32_16x16x32_bf16 v[16:19], v[166:169], v[192:195], 0
	v_mfma_f32_16x16x32_bf16 v[4:7], v[158:161], v[200:203], 0
	v_mfma_f32_16x16x32_bf16 v[0:3], v[166:169], v[200:203], 0
	v_mfma_f32_16x16x32_bf16 v[52:55], v[162:165], v[180:183], v[52:55]
	v_mfma_f32_16x16x32_bf16 v[48:51], v[170:173], v[180:183], v[48:51]
	v_mfma_f32_16x16x32_bf16 v[36:39], v[162:165], v[188:191], v[36:39]
	v_mfma_f32_16x16x32_bf16 v[32:35], v[170:173], v[188:191], v[32:35]
	v_mfma_f32_16x16x32_bf16 v[20:23], v[162:165], v[196:199], v[20:23]
	v_mfma_f32_16x16x32_bf16 v[16:19], v[170:173], v[196:199], v[16:19]
	v_mfma_f32_16x16x32_bf16 v[4:7], v[162:165], v[206:209], v[4:7]
	v_mfma_f32_16x16x32_bf16 v[0:3], v[170:173], v[206:209], v[0:3]
	s_setprio 0
	s_barrier
	s_add_i32 s77, 0, 0x18000
	s_add_i32 s78, 0, 0x1c000
	v_add_u32_e32 v154, s77, v178
	v_add_u32_e32 v170, s78, v178
	ds_read_b128 v[128:131], v154
	ds_read_b128 v[132:135], v154 offset:1024
	ds_read_b128 v[150:153], v154 offset:2048
	ds_read_b128 v[154:157], v154 offset:3072
	ds_read_b128 v[158:161], v170
	ds_read_b128 v[162:165], v170 offset:1024
	ds_read_b128 v[166:169], v170 offset:2048
	ds_read_b128 v[170:173], v170 offset:3072
	s_add_u32 s46, s46, 0x80000
	s_addc_u32 s47, s47, 0
	s_mov_b32 m0, s55
	v_lshl_add_u64 v[216:217], s[46:47], 0, v[138:139]
	ds_read_b128 v[174:177], v179 offset:32768
	ds_read_b128 v[180:183], v179 offset:33792
	ds_read_b128 v[184:187], v179 offset:34816
	ds_read_b128 v[188:191], v179 offset:35840
	ds_read_b128 v[192:195], v179 offset:36864
	ds_read_b128 v[196:199], v179 offset:37888
	ds_read_b128 v[200:203], v179 offset:38912
	ds_read_b128 v[206:209], v179 offset:39936
	global_load_lds_dwordx4 v[216:217], off
	v_lshl_add_u64 v[216:217], s[46:47], 0, v[142:143]
	s_mov_b32 m0, s0
	s_nop 0
	global_load_lds_dwordx4 v[216:217], off
	s_waitcnt vmcnt(8)
	s_waitcnt lgkmcnt(0)
	s_barrier
	s_setprio 1
	s_waitcnt lgkmcnt(0)
	v_mfma_f32_16x16x32_bf16 v[124:127], v[128:131], v[174:177], v[124:127]
	v_mfma_f32_16x16x32_bf16 v[120:123], v[150:153], v[174:177], v[120:123]
	v_mfma_f32_16x16x32_bf16 v[108:111], v[128:131], v[184:187], v[108:111]
	v_mfma_f32_16x16x32_bf16 v[104:107], v[150:153], v[184:187], v[104:107]
	v_mfma_f32_16x16x32_bf16 v[92:95], v[128:131], v[192:195], v[92:95]
	v_mfma_f32_16x16x32_bf16 v[88:91], v[150:153], v[192:195], v[88:91]
	v_mfma_f32_16x16x32_bf16 v[76:79], v[128:131], v[200:203], v[76:79]
	v_mfma_f32_16x16x32_bf16 v[72:75], v[150:153], v[200:203], v[72:75]
	v_mfma_f32_16x16x32_bf16 v[124:127], v[132:135], v[180:183], v[124:127]
	v_mfma_f32_16x16x32_bf16 v[120:123], v[154:157], v[180:183], v[120:123]
	v_mfma_f32_16x16x32_bf16 v[108:111], v[132:135], v[188:191], v[108:111]
	v_mfma_f32_16x16x32_bf16 v[104:107], v[154:157], v[188:191], v[104:107]
	v_mfma_f32_16x16x32_bf16 v[92:95], v[132:135], v[196:199], v[92:95]
	v_mfma_f32_16x16x32_bf16 v[88:91], v[154:157], v[196:199], v[88:91]
	v_mfma_f32_16x16x32_bf16 v[76:79], v[132:135], v[206:209], v[76:79]
	v_mfma_f32_16x16x32_bf16 v[72:75], v[154:157], v[206:209], v[72:75]
	s_setprio 0
	s_setprio 1
	v_mfma_f32_16x16x32_bf16 v[116:119], v[158:161], v[174:177], v[116:119]
	v_mfma_f32_16x16x32_bf16 v[112:115], v[166:169], v[174:177], v[112:115]
	v_mfma_f32_16x16x32_bf16 v[100:103], v[158:161], v[184:187], v[100:103]
	v_mfma_f32_16x16x32_bf16 v[96:99], v[166:169], v[184:187], v[96:99]
	v_mfma_f32_16x16x32_bf16 v[84:87], v[158:161], v[192:195], v[84:87]
	v_mfma_f32_16x16x32_bf16 v[80:83], v[166:169], v[192:195], v[80:83]
	v_mfma_f32_16x16x32_bf16 v[68:71], v[158:161], v[200:203], v[68:71]
	v_mfma_f32_16x16x32_bf16 v[64:67], v[166:169], v[200:203], v[64:67]
	v_mfma_f32_16x16x32_bf16 v[116:119], v[162:165], v[180:183], v[116:119]
	v_mfma_f32_16x16x32_bf16 v[112:115], v[170:173], v[180:183], v[112:115]
	v_mfma_f32_16x16x32_bf16 v[100:103], v[162:165], v[188:191], v[100:103]
	v_mfma_f32_16x16x32_bf16 v[96:99], v[170:173], v[188:191], v[96:99]
	v_mfma_f32_16x16x32_bf16 v[84:87], v[162:165], v[196:199], v[84:87]
	v_mfma_f32_16x16x32_bf16 v[80:83], v[170:173], v[196:199], v[80:83]
	v_mfma_f32_16x16x32_bf16 v[68:71], v[162:165], v[206:209], v[68:71]
	v_mfma_f32_16x16x32_bf16 v[64:67], v[170:173], v[206:209], v[64:67]
	s_setprio 0
	s_barrier
; #define PG8_STAGE(bufoff, gbase, voff) do { _Pragma("unroll") for (int _i = 0; _i < 2; ++_i) \
;         __builtin_amdgcn_global_load_lds((const unsigned*)((const char*)(gbase) + (voff)[_i]), (PG8_LAS unsigned*)(lds + (bufoff) + ldsw + _i * 8192), 16, 0, 0); } while (0)
; #define PG8_LDA(dst, b, h) do { _Pragma("unroll") for (int m = 0; m < 4; ++m) _Pragma("unroll") for (int k = 0; k < 2; ++k) dst[m][k] = *(const PG8_LAS bf16x8*)(lds + PG8_SA(b, h) + aoff + m * 2048 + k * 1024); } while (0)
; #define PG8_WAIT_V(n) asm volatile("s_waitcnt vmcnt(" #n ")" ::: "memory")
; #define PG8_WAIT_L(n) asm volatile("s_waitcnt lgkmcnt(" #n ")" ::: "memory")
; #define PG8_BAR __builtin_amdgcn_s_barrier()
; template <class Epi, class Sched, bool ALIGN_EPI = false, bool SP2 = false>
; __device__ __forceinline__ void gemm_phase(PG8_LAS unsigned char* lds, const Gemm g, const Sched& S, const Epi& E, const int tid) {
;     ...
;         for (int t = 0; t < nt; t += 2) {
;             const bool last = (t == nt - 2);
;             const char* a1 = cA + (size_t)(t + 1) * kstep;
;             const char* a2 = last ? nA : cA + (size_t)(t + 2) * kstep; const char* b2 = last ? nB : cB + (size_t)(t + 2) * kstep;
;             const char* a3 = a2 + kstep; const char* b3 = b2 + kstep;
;             if (last && has_next) S.a_ready(nxt);
;             if constexpr (SP2) {
;             PG8_LDB(B0, 0, 0); PG8_LDB(B1, 0, 1); PG8_SCHED; PG8_LDA(At, 0, 0); PG8_STAGE(PG8_SA(1, 1), a1 + hstep, voffA);
;             PG8_WAIT_V(8); PG8_WAIT_L(0); PG8_BAR; PG8_MMA(0, 0, At, B0); PG8_MMA(0, 1, At, B1); PG8_BAR; PG8_SCHED;
;             PG8_LDA(At, 0, 1); PG8_STAGE(PG8_SB(0, 0), b2, voffB); PG8_STAGE(PG8_SB(0, 1), b2 + hstep, voffB); PG8_STAGE(PG8_SA(0, 0), a2, voffA);
;             PG8_WAIT_V(8); PG8_WAIT_L(0); PG8_BAR; PG8_MMA(1, 0, At, B0); PG8_MMA(1, 1, At, B1); PG8_BAR; PG8_SCHED;
;             PG8_LDB(B0, 1, 0); PG8_LDB(B1, 1, 1); PG8_SCHED; PG8_LDA(At, 1, 0); PG8_STAGE(PG8_SA(0, 1), a2 + hstep, voffA);
;             PG8_WAIT_V(8); PG8_WAIT_L(0); PG8_BAR; PG8_MMA(0, 0, At, B0); PG8_MMA(0, 1, At, B1); PG8_BAR; PG8_SCHED;
;             PG8_LDA(At, 1, 1); PG8_STAGE(PG8_SB(1, 0), b3, voffB); PG8_STAGE(PG8_SB(1, 1), b3 + hstep, voffB); PG8_STAGE(PG8_SA(1, 0), a3, voffA);
;             PG8_WAIT_V(8); PG8_WAIT_L(0); PG8_BAR; PG8_MMA(1, 0, At, B0); PG8_MMA(1, 1, At, B1); PG8_BAR; PG8_SCHED;
	s_add_i32 s46, s77, s52
	v_lshl_add_u64 v[136:137], v[136:137], 0, s[70:71]
	s_mov_b32 m0, s46
	ds_read_b128 v[174:177], v179 offset:49152
	ds_read_b128 v[180:183], v179 offset:50176
	ds_read_b128 v[184:187], v179 offset:51200
	ds_read_b128 v[188:191], v179 offset:52224
	ds_read_b128 v[192:195], v179 offset:53248
	ds_read_b128 v[196:199], v179 offset:54272
	ds_read_b128 v[200:203], v179 offset:55296
	ds_read_b128 v[206:209], v179 offset:56320
	global_load_lds_dwordx4 v[136:137], off
	s_add_i32 m0, s46, 0x2000
	s_add_u32 s44, s44, 0x80080
	v_lshl_add_u64 v[136:137], v[210:211], 0, s[70:71]
	s_addc_u32 s45, s45, 0
	s_add_i32 s46, s78, s52
	global_load_lds_dwordx4 v[136:137], off
	v_lshl_add_u64 v[136:137], s[44:45], 0, v[140:141]
	s_mov_b32 m0, s46
	s_nop 0
	global_load_lds_dwordx4 v[136:137], off
	v_lshl_add_u64 v[136:137], s[44:45], 0, v[144:145]
	s_add_i32 m0, s46, 0x2000
	s_nop 0
	global_load_lds_dwordx4 v[136:137], off
	v_lshl_add_u64 v[136:137], v[212:213], 0, s[70:71]
	s_mov_b32 m0, s11
	s_nop 0
	global_load_lds_dwordx4 v[136:137], off
	v_lshl_add_u64 v[136:137], v[214:215], 0, s[70:71]
	s_mov_b32 m0, s64
	s_nop 0
	global_load_lds_dwordx4 v[136:137], off
	s_waitcnt vmcnt(8)
	s_waitcnt lgkmcnt(0)
	s_barrier
	s_setprio 1
	s_waitcnt lgkmcnt(0)
	v_mfma_f32_16x16x32_bf16 v[60:63], v[128:131], v[174:177], v[60:63]
	v_mfma_f32_16x16x32_bf16 v[56:59], v[150:153], v[174:177], v[56:59]
	v_mfma_f32_16x16x32_bf16 v[44:47], v[128:131], v[184:187], v[44:47]
	v_mfma_f32_16x16x32_bf16 v[40:43], v[150:153], v[184:187], v[40:43]
	v_mfma_f32_16x16x32_bf16 v[28:31], v[128:131], v[192:195], v[28:31]
	v_mfma_f32_16x16x32_bf16 v[24:27], v[150:153], v[192:195], v[24:27]
	v_mfma_f32_16x16x32_bf16 v[12:15], v[128:131], v[200:203], v[12:15]
	v_mfma_f32_16x16x32_bf16 v[8:11], v[150:153], v[200:203], v[8:11]
	v_mfma_f32_16x16x32_bf16 v[60:63], v[132:135], v[180:183], v[60:63]
	v_mfma_f32_16x16x32_bf16 v[56:59], v[154:157], v[180:183], v[56:59]
	v_mfma_f32_16x16x32_bf16 v[44:47], v[132:135], v[188:191], v[44:47]
	v_mfma_f32_16x16x32_bf16 v[40:43], v[154:157], v[188:191], v[40:43]
	v_mfma_f32_16x16x32_bf16 v[28:31], v[132:135], v[196:199], v[28:31]
	v_mfma_f32_16x16x32_bf16 v[24:27], v[154:157], v[196:199], v[24:27]
	v_mfma_f32_16x16x32_bf16 v[12:15], v[132:135], v[206:209], v[12:15]
	v_mfma_f32_16x16x32_bf16 v[8:11], v[154:157], v[206:209], v[8:11]
	s_setprio 0
	s_setprio 1
	v_mfma_f32_16x16x32_bf16 v[52:55], v[158:161], v[174:177], v[52:55]
	v_mfma_f32_16x16x32_bf16 v[48:51], v[166:169], v[174:177], v[48:51]
	v_mfma_f32_16x16x32_bf16 v[36:39], v[158:161], v[184:187], v[36:39]
	v_mfma_f32_16x16x32_bf16 v[32:35], v[166:169], v[184:187], v[32:35]
	v_mfma_f32_16x16x32_bf16 v[20:23], v[158:161], v[192:195], v[20:23]
	v_mfma_f32_16x16x32_bf16 v[16:19], v[166:169], v[192:195], v[16:19]
	v_mfma_f32_16x16x32_bf16 v[4:7], v[158:161], v[200:203], v[4:7]
	v_mfma_f32_16x16x32_bf16 v[0:3], v[166:169], v[200:203], v[0:3]
	v_mfma_f32_16x16x32_bf16 v[52:55], v[162:165], v[180:183], v[52:55]
	v_mfma_f32_16x16x32_bf16 v[48:51], v[170:173], v[180:183], v[48:51]
	v_mfma_f32_16x16x32_bf16 v[36:39], v[162:165], v[188:191], v[36:39]
	v_mfma_f32_16x16x32_bf16 v[32:35], v[170:173], v[188:191], v[32:35]
	v_mfma_f32_16x16x32_bf16 v[20:23], v[162:165], v[196:199], v[20:23]
	v_mfma_f32_16x16x32_bf16 v[16:19], v[170:173], v[196:199], v[16:19]
	v_mfma_f32_16x16x32_bf16 v[4:7], v[162:165], v[206:209], v[4:7]
	v_mfma_f32_16x16x32_bf16 v[0:3], v[170:173], v[206:209], v[0:3]
	s_setprio 0
	s_barrier
	s_add_i32 s76, s76, 2
	s_add_u32 s42, s42, 0x100
	s_addc_u32 s43, s43, 0
	s_add_u32 s69, s69, 0x100
	s_addc_u32 s92, s92, 0

; #define PG8_STAGE(bufoff, gbase, voff) do { _Pragma("unroll") for (int _i = 0; _i < 2; ++_i) \
;         __builtin_amdgcn_global_load_lds((const unsigned*)((const char*)(gbase) + (voff)[_i]), (PG8_LAS unsigned*)(lds + (bufoff) + ldsw + _i * 8192), 16, 0, 0); } while (0)
; #define PG8_LDA(dst, b, h) do { _Pragma("unroll") for (int m = 0; m < 4; ++m) _Pragma("unroll") for (int k = 0; k < 2; ++k) dst[m][k] = *(const PG8_LAS bf16x8*)(lds + PG8_SA(b, h) + aoff + m * 2048 + k * 1024); } while (0)
; #define PG8_LDB(dst, b, h) do { _Pragma("unroll") for (int n = 0; n < 2; ++n) _Pragma("unroll") for (int k = 0; k < 2; ++k) dst[n][k] = *(const PG8_LAS bf16x8*)(lds + PG8_SB(b, h) + boff + n * 2048 + k * 1024); } while (0)
; #define PG8_WAIT_V(n) asm volatile("s_waitcnt vmcnt(" #n ")" ::: "memory")
; #define PG8_WAIT_L(n) asm volatile("s_waitcnt lgkmcnt(" #n ")" ::: "memory")
; #define PG8_BAR __builtin_amdgcn_s_barrier()
; #define PG8_SCHED __builtin_amdgcn_sched_barrier(0)
; template <class Epi, class Sched, bool ALIGN_EPI = false, bool SP2 = false>
; __device__ __forceinline__ void gemm_phase(PG8_LAS unsigned char* lds, const Gemm g, const Sched& S, const Epi& E, const int tid) {
;     ...
;         const bool has_next = S.next(ui + 1, nxt);
;         const char* nA = has_next ? (const char*)g.A + (size_t)nxt.pm * tstep : cA; const char* nB = has_next ? (const char*)g.Bt + (size_t)nxt.pn * tstep : cB;
;         for (int t = 0; t < nt; t += 2) {
;             const bool last = (t == nt - 2);
;             const char* a1 = cA + (size_t)(t + 1) * kstep;
;             const char* a2 = last ? nA : cA + (size_t)(t + 2) * kstep; const char* b2 = last ? nB : cB + (size_t)(t + 2) * kstep;
;             const char* a3 = a2 + kstep; const char* b3 = b2 + kstep;
;             if (last && has_next) S.a_ready(nxt);
;             if constexpr (SP2) {
;             PG8_LDB(B0, 0, 0); PG8_LDB(B1, 0, 1); PG8_SCHED; PG8_LDA(At, 0, 0); PG8_STAGE(PG8_SA(1, 1), a1 + hstep, voffA);
;             PG8_WAIT_V(8); PG8_WAIT_L(0); PG8_BAR; PG8_MMA(0, 0, At, B0); PG8_MMA(0, 1, At, B1); PG8_BAR; PG8_SCHED;
;             PG8_LDA(At, 0, 1); PG8_STAGE(PG8_SB(0, 0), b2, voffB); PG8_STAGE(PG8_SB(0, 1), b2 + hstep, voffB); PG8_STAGE(PG8_SA(0, 0), a2, voffA);
;             PG8_WAIT_V(8); PG8_WAIT_L(0); PG8_BAR; PG8_MMA(1, 0, At, B0); PG8_MMA(1, 1, At, B1); PG8_BAR; PG8_SCHED;
.LBB0_660:
	s_ashr_i32 s19, s18, 31
	s_lshl_b64 s[20:21], s[18:19], 20
	s_add_u32 s20, s10, s20
	s_addc_u32 s21, s11, s21
	s_and_b64 s[22:23], s[4:5], exec
	s_cselect_b32 s19, s21, s27
	s_cselect_b32 s50, s20, s26
	s_ashr_i32 s17, s16, 31
	s_lshl_b64 s[22:23], s[16:17], 20
	s_add_u32 s22, s33, s22
	s_addc_u32 s23, s34, s23
	s_and_b64 s[30:31], s[4:5], exec
	s_cselect_b32 s17, s23, s29
	s_cselect_b32 s51, s22, s28
	s_add_u32 s26, s26, 0x80080
	s_addc_u32 s27, s27, 0
	s_add_u32 s52, s28, 0x100
	s_addc_u32 s53, s29, 0
	s_mov_b32 s54, -2
	s_add_u32 s28, s26, 0xfff80080
	s_addc_u32 s29, s27, -1
	s_add_i32 s55, 0, 0x10000
	s_cmp_eq_u32 s54, 28
	s_cselect_b32 s31, s19, s29
	s_cselect_b32 s30, s50, s28
	v_add_u32_e32 v138, s55, v139
	s_cselect_b32 s29, s17, s53
	s_cselect_b32 s28, s51, s52
	s_add_i32 s62, 0, 0x14000
	ds_read_b128 v[144:147], v138
	ds_read_b128 v[148:151], v138 offset:1024
	ds_read_b128 v[152:155], v138 offset:2048
	ds_read_b128 v[156:159], v138 offset:3072
	v_add_u32_e32 v138, s62, v139
	ds_read_b128 v[160:163], v138
	ds_read_b128 v[164:167], v138 offset:1024
	ds_read_b128 v[168:171], v138 offset:2048
	ds_read_b128 v[172:175], v138 offset:3072
	v_lshl_add_u64 v[140:141], s[26:27], 0, v[134:135]
	s_add_i32 m0, s37, 0xc000
	ds_read_b128 v[176:179], v143
	ds_read_b128 v[180:183], v143 offset:1024
	ds_read_b128 v[184:187], v143 offset:2048
	ds_read_b128 v[188:191], v143 offset:3072
	ds_read_b128 v[192:195], v143 offset:4096
	ds_read_b128 v[196:199], v143 offset:5120
	ds_read_b128 v[200:203], v143 offset:6144
	ds_read_b128 v[206:209], v143 offset:7168
	global_load_lds_dwordx4 v[140:141], off
	v_lshl_add_u64 v[140:141], s[26:27], 0, v[136:137]
	s_add_i32 m0, s37, 0xe000
	s_nop 0
	global_load_lds_dwordx4 v[140:141], off
	s_waitcnt vmcnt(24)
	s_waitcnt lgkmcnt(0)
	s_barrier
	s_setprio 1
	s_waitcnt lgkmcnt(0)
	v_mfma_f32_16x16x32_bf16 v[124:127], v[144:147], v[176:179], 0
	v_mfma_f32_16x16x32_bf16 v[120:123], v[152:155], v[176:179], 0
	v_mfma_f32_16x16x32_bf16 v[108:111], v[144:147], v[184:187], 0
	v_mfma_f32_16x16x32_bf16 v[104:107], v[152:155], v[184:187], 0
	v_mfma_f32_16x16x32_bf16 v[92:95], v[144:147], v[192:195], 0
	v_mfma_f32_16x16x32_bf16 v[88:91], v[152:155], v[192:195], 0
	v_mfma_f32_16x16x32_bf16 v[76:79], v[144:147], v[200:203], 0
	v_mfma_f32_16x16x32_bf16 v[72:75], v[152:155], v[200:203], 0
	v_mfma_f32_16x16x32_bf16 v[124:127], v[148:151], v[180:183], v[124:127]
	v_mfma_f32_16x16x32_bf16 v[120:123], v[156:159], v[180:183], v[120:123]
	v_mfma_f32_16x16x32_bf16 v[108:111], v[148:151], v[188:191], v[108:111]
	v_mfma_f32_16x16x32_bf16 v[104:107], v[156:159], v[188:191], v[104:107]
	v_mfma_f32_16x16x32_bf16 v[92:95], v[148:151], v[196:199], v[92:95]
	v_mfma_f32_16x16x32_bf16 v[88:91], v[156:159], v[196:199], v[88:91]
	v_mfma_f32_16x16x32_bf16 v[76:79], v[148:151], v[206:209], v[76:79]
	v_mfma_f32_16x16x32_bf16 v[72:75], v[156:159], v[206:209], v[72:75]
	s_setprio 0
	s_setprio 1
	v_mfma_f32_16x16x32_bf16 v[116:119], v[160:163], v[176:179], 0
	v_mfma_f32_16x16x32_bf16 v[112:115], v[168:171], v[176:179], 0
	v_mfma_f32_16x16x32_bf16 v[100:103], v[160:163], v[184:187], 0
	v_mfma_f32_16x16x32_bf16 v[96:99], v[168:171], v[184:187], 0
	v_mfma_f32_16x16x32_bf16 v[84:87], v[160:163], v[192:195], 0
	v_mfma_f32_16x16x32_bf16 v[80:83], v[168:171], v[192:195], 0
	v_mfma_f32_16x16x32_bf16 v[68:71], v[160:163], v[200:203], 0
	v_mfma_f32_16x16x32_bf16 v[64:67], v[168:171], v[200:203], 0
	v_mfma_f32_16x16x32_bf16 v[116:119], v[164:167], v[180:183], v[116:119]
	v_mfma_f32_16x16x32_bf16 v[112:115], v[172:175], v[180:183], v[112:115]
	v_mfma_f32_16x16x32_bf16 v[100:103], v[164:167], v[188:191], v[100:103]
	v_mfma_f32_16x16x32_bf16 v[96:99], v[172:175], v[188:191], v[96:99]
	v_mfma_f32_16x16x32_bf16 v[84:87], v[164:167], v[196:199], v[84:87]
	v_mfma_f32_16x16x32_bf16 v[80:83], v[172:175], v[196:199], v[80:83]
	v_mfma_f32_16x16x32_bf16 v[68:71], v[164:167], v[206:209], v[68:71]
	v_mfma_f32_16x16x32_bf16 v[64:67], v[172:175], v[206:209], v[64:67]
	s_setprio 0
	s_barrier
	s_add_i32 s55, s55, s35
	v_lshl_add_u64 v[140:141], s[28:29], 0, v[204:205]
	s_mov_b32 m0, s55
	ds_read_b128 v[176:179], v143 offset:16384
	ds_read_b128 v[180:183], v143 offset:17408
	ds_read_b128 v[184:187], v143 offset:18432
	ds_read_b128 v[188:191], v143 offset:19456
	ds_read_b128 v[192:195], v143 offset:20480
	ds_read_b128 v[196:199], v143 offset:21504
	ds_read_b128 v[200:203], v143 offset:22528
	ds_read_b128 v[206:209], v143 offset:23552
	global_load_lds_dwordx4 v[140:141], off
	s_add_i32 m0, s55, 0x2000
	s_add_u32 s64, s28, 0x80000
	v_lshl_add_u64 v[210:211], s[28:29], 0, v[128:129]
	s_addc_u32 s65, s29, 0
	s_add_i32 s55, s62, s35
	global_load_lds_dwordx4 v[210:211], off
	v_lshl_add_u64 v[212:213], s[64:65], 0, v[204:205]
	s_mov_b32 m0, s55
	v_lshl_add_u64 v[214:215], s[30:31], 0, v[130:131]
	global_load_lds_dwordx4 v[212:213], off
	v_lshl_add_u64 v[212:213], s[64:65], 0, v[128:129]
	s_add_i32 m0, s55, 0x2000
	s_nop 0
	global_load_lds_dwordx4 v[212:213], off
	v_lshl_add_u64 v[212:213], s[30:31], 0, v[132:133]
	s_mov_b32 m0, s37
	s_nop 0
	global_load_lds_dwordx4 v[212:213], off
	s_mov_b32 m0, s38
	s_nop 0
	global_load_lds_dwordx4 v[214:215], off
	s_waitcnt vmcnt(8)
	s_waitcnt lgkmcnt(0)
	s_barrier
; #define PG8_STAGE(bufoff, gbase, voff) do { _Pragma("unroll") for (int _i = 0; _i < 2; ++_i) \
;         __builtin_amdgcn_global_load_lds((const unsigned*)((const char*)(gbase) + (voff)[_i]), (PG8_LAS unsigned*)(lds + (bufoff) + ldsw + _i * 8192), 16, 0, 0); } while (0)
; #define PG8_LDA(dst, b, h) do { _Pragma("unroll") for (int m = 0; m < 4; ++m) _Pragma("unroll") for (int k = 0; k < 2; ++k) dst[m][k] = *(const PG8_LAS bf16x8*)(lds + PG8_SA(b, h) + aoff + m * 2048 + k * 1024); } while (0)
; #define PG8_LDB(dst, b, h) do { _Pragma("unroll") for (int n = 0; n < 2; ++n) _Pragma("unroll") for (int k = 0; k < 2; ++k) dst[n][k] = *(const PG8_LAS bf16x8*)(lds + PG8_SB(b, h) + boff + n * 2048 + k * 1024); } while (0)
; #define PG8_MMA(ai, bj, At, Bt) do { __builtin_amdgcn_s_setprio(1); _Pragma("unroll") for (int m = 0; m < 4; ++m) _Pragma("unroll") for (int n = 0; n < 2; ++n) _Pragma("unroll") for (int k = 0; k < 2; ++k) \
;         acc[ai][bj][m][n] = __builtin_amdgcn_mfma_f32_16x16x32_bf16(Bt[n][k], At[m][k], acc[ai][bj][m][n], 0, 0, 0); __builtin_amdgcn_s_setprio(0); } while (0)
; #define PG8_WAIT_V(n) asm volatile("s_waitcnt vmcnt(" #n ")" ::: "memory")
; #define PG8_WAIT_L(n) asm volatile("s_waitcnt lgkmcnt(" #n ")" ::: "memory")
; #define PG8_BAR __builtin_amdgcn_s_barrier()
; #define PG8_SCHED __builtin_amdgcn_sched_barrier(0)
; template <class Epi, class Sched, bool ALIGN_EPI = false, bool SP2 = false>
; __device__ __forceinline__ void gemm_phase(PG8_LAS unsigned char* lds, const Gemm g, const Sched& S, const Epi& E, const int tid) {
;     ...
;             PG8_WAIT_V(8); PG8_WAIT_L(0); PG8_BAR; PG8_MMA(0, 0, At, B0); PG8_MMA(0, 1, At, B1); PG8_BAR; PG8_SCHED;
;             PG8_LDA(At, 0, 1); PG8_STAGE(PG8_SB(0, 0), b2, voffB); PG8_STAGE(PG8_SB(0, 1), b2 + hstep, voffB); PG8_STAGE(PG8_SA(0, 0), a2, voffA);
;             PG8_WAIT_V(8); PG8_WAIT_L(0); PG8_BAR; PG8_MMA(1, 0, At, B0); PG8_MMA(1, 1, At, B1); PG8_BAR; PG8_SCHED;
;             PG8_LDB(B0, 1, 0); PG8_LDB(B1, 1, 1); PG8_SCHED; PG8_LDA(At, 1, 0); PG8_STAGE(PG8_SA(0, 1), a2 + hstep, voffA);
;             PG8_WAIT_V(8); PG8_WAIT_L(0); PG8_BAR; PG8_MMA(0, 0, At, B0); PG8_MMA(0, 1, At, B1); PG8_BAR; PG8_SCHED;
;             PG8_LDA(At, 1, 1); PG8_STAGE(PG8_SB(1, 0), b3, voffB); PG8_STAGE(PG8_SB(1, 1), b3 + hstep, voffB); PG8_STAGE(PG8_SA(1, 0), a3, voffA);
	s_setprio 1
	s_waitcnt lgkmcnt(0)
	v_mfma_f32_16x16x32_bf16 v[60:63], v[144:147], v[176:179], 0
	v_mfma_f32_16x16x32_bf16 v[56:59], v[152:155], v[176:179], 0
	v_mfma_f32_16x16x32_bf16 v[48:51], v[144:147], v[184:187], 0
	v_mfma_f32_16x16x32_bf16 v[40:43], v[152:155], v[184:187], 0
	v_mfma_f32_16x16x32_bf16 v[32:35], v[144:147], v[192:195], 0
	v_mfma_f32_16x16x32_bf16 v[24:27], v[152:155], v[192:195], 0
	v_mfma_f32_16x16x32_bf16 v[16:19], v[144:147], v[200:203], 0
	v_mfma_f32_16x16x32_bf16 v[8:11], v[152:155], v[200:203], 0
	v_mfma_f32_16x16x32_bf16 v[60:63], v[148:151], v[180:183], v[60:63]
	v_mfma_f32_16x16x32_bf16 v[56:59], v[156:159], v[180:183], v[56:59]
	v_mfma_f32_16x16x32_bf16 v[48:51], v[148:151], v[188:191], v[48:51]
	v_mfma_f32_16x16x32_bf16 v[40:43], v[156:159], v[188:191], v[40:43]
	v_mfma_f32_16x16x32_bf16 v[32:35], v[148:151], v[196:199], v[32:35]
	v_mfma_f32_16x16x32_bf16 v[24:27], v[156:159], v[196:199], v[24:27]
	v_mfma_f32_16x16x32_bf16 v[16:19], v[148:151], v[206:209], v[16:19]
	v_mfma_f32_16x16x32_bf16 v[8:11], v[156:159], v[206:209], v[8:11]
	s_setprio 0
	s_setprio 1
	v_mfma_f32_16x16x32_bf16 v[52:55], v[160:163], v[176:179], 0
	v_mfma_f32_16x16x32_bf16 v[44:47], v[168:171], v[176:179], 0
	v_mfma_f32_16x16x32_bf16 v[36:39], v[160:163], v[184:187], 0
	v_mfma_f32_16x16x32_bf16 v[28:31], v[168:171], v[184:187], 0
	v_mfma_f32_16x16x32_bf16 v[20:23], v[160:163], v[192:195], 0
	v_mfma_f32_16x16x32_bf16 v[12:15], v[168:171], v[192:195], 0
	v_mfma_f32_16x16x32_bf16 v[4:7], v[160:163], v[200:203], 0
	v_mfma_f32_16x16x32_bf16 v[0:3], v[168:171], v[200:203], 0
	v_mfma_f32_16x16x32_bf16 v[52:55], v[164:167], v[180:183], v[52:55]
	v_mfma_f32_16x16x32_bf16 v[44:47], v[172:175], v[180:183], v[44:47]
	v_mfma_f32_16x16x32_bf16 v[36:39], v[164:167], v[188:191], v[36:39]
	v_mfma_f32_16x16x32_bf16 v[28:31], v[172:175], v[188:191], v[28:31]
	v_mfma_f32_16x16x32_bf16 v[20:23], v[164:167], v[196:199], v[20:23]
	v_mfma_f32_16x16x32_bf16 v[12:15], v[172:175], v[196:199], v[12:15]
	v_mfma_f32_16x16x32_bf16 v[4:7], v[164:167], v[206:209], v[4:7]
	v_mfma_f32_16x16x32_bf16 v[0:3], v[172:175], v[206:209], v[0:3]
	s_setprio 0
	s_barrier
	s_add_i32 s55, 0, 0x18000
	v_add_u32_e32 v138, s55, v139
	s_add_i32 s62, 0, 0x1c000
	ds_read_b128 v[144:147], v138
	ds_read_b128 v[148:151], v138 offset:1024
	ds_read_b128 v[152:155], v138 offset:2048
	ds_read_b128 v[156:159], v138 offset:3072
	v_add_u32_e32 v138, s62, v139
	ds_read_b128 v[160:163], v138
	ds_read_b128 v[164:167], v138 offset:1024
	ds_read_b128 v[168:171], v138 offset:2048
	ds_read_b128 v[172:175], v138 offset:3072
	s_add_u32 s30, s30, 0x80000
	s_addc_u32 s31, s31, 0
	s_mov_b32 m0, s40
	v_lshl_add_u64 v[216:217], s[30:31], 0, v[132:133]
	ds_read_b128 v[176:179], v143 offset:32768
	ds_read_b128 v[180:183], v143 offset:33792
	ds_read_b128 v[184:187], v143 offset:34816
	ds_read_b128 v[188:191], v143 offset:35840
	ds_read_b128 v[192:195], v143 offset:36864
	ds_read_b128 v[196:199], v143 offset:37888
	ds_read_b128 v[200:203], v143 offset:38912
	ds_read_b128 v[206:209], v143 offset:39936
	global_load_lds_dwordx4 v[216:217], off
	v_lshl_add_u64 v[216:217], s[30:31], 0, v[130:131]
	s_mov_b32 m0, s42
	s_nop 0
	global_load_lds_dwordx4 v[216:217], off
	s_waitcnt vmcnt(8)
	s_waitcnt lgkmcnt(0)
	s_barrier
	s_setprio 1
	s_waitcnt lgkmcnt(0)
	v_mfma_f32_16x16x32_bf16 v[124:127], v[144:147], v[176:179], v[124:127]
	v_mfma_f32_16x16x32_bf16 v[120:123], v[152:155], v[176:179], v[120:123]
	v_mfma_f32_16x16x32_bf16 v[108:111], v[144:147], v[184:187], v[108:111]
	v_mfma_f32_16x16x32_bf16 v[104:107], v[152:155], v[184:187], v[104:107]
	v_mfma_f32_16x16x32_bf16 v[92:95], v[144:147], v[192:195], v[92:95]
	v_mfma_f32_16x16x32_bf16 v[88:91], v[152:155], v[192:195], v[88:91]
	v_mfma_f32_16x16x32_bf16 v[76:79], v[144:147], v[200:203], v[76:79]
	v_mfma_f32_16x16x32_bf16 v[72:75], v[152:155], v[200:203], v[72:75]
	v_mfma_f32_16x16x32_bf16 v[124:127], v[148:151], v[180:183], v[124:127]
	v_mfma_f32_16x16x32_bf16 v[120:123], v[156:159], v[180:183], v[120:123]
	v_mfma_f32_16x16x32_bf16 v[108:111], v[148:151], v[188:191], v[108:111]
	v_mfma_f32_16x16x32_bf16 v[104:107], v[156:159], v[188:191], v[104:107]
	v_mfma_f32_16x16x32_bf16 v[92:95], v[148:151], v[196:199], v[92:95]
	v_mfma_f32_16x16x32_bf16 v[88:91], v[156:159], v[196:199], v[88:91]
	v_mfma_f32_16x16x32_bf16 v[76:79], v[148:151], v[206:209], v[76:79]
	v_mfma_f32_16x16x32_bf16 v[72:75], v[156:159], v[206:209], v[72:75]
	s_setprio 0
	s_setprio 1
	v_mfma_f32_16x16x32_bf16 v[116:119], v[160:163], v[176:179], v[116:119]
	v_mfma_f32_16x16x32_bf16 v[112:115], v[168:171], v[176:179], v[112:115]
	v_mfma_f32_16x16x32_bf16 v[100:103], v[160:163], v[184:187], v[100:103]
	v_mfma_f32_16x16x32_bf16 v[96:99], v[168:171], v[184:187], v[96:99]
	v_mfma_f32_16x16x32_bf16 v[84:87], v[160:163], v[192:195], v[84:87]
	v_mfma_f32_16x16x32_bf16 v[80:83], v[168:171], v[192:195], v[80:83]
	v_mfma_f32_16x16x32_bf16 v[68:71], v[160:163], v[200:203], v[68:71]
	v_mfma_f32_16x16x32_bf16 v[64:67], v[168:171], v[200:203], v[64:67]
	v_mfma_f32_16x16x32_bf16 v[116:119], v[164:167], v[180:183], v[116:119]
	v_mfma_f32_16x16x32_bf16 v[112:115], v[172:175], v[180:183], v[112:115]
	v_mfma_f32_16x16x32_bf16 v[100:103], v[164:167], v[188:191], v[100:103]
	v_mfma_f32_16x16x32_bf16 v[96:99], v[172:175], v[188:191], v[96:99]
	v_mfma_f32_16x16x32_bf16 v[84:87], v[164:167], v[196:199], v[84:87]
	v_mfma_f32_16x16x32_bf16 v[80:83], v[172:175], v[196:199], v[80:83]
	v_mfma_f32_16x16x32_bf16 v[68:71], v[164:167], v[206:209], v[68:71]
	v_mfma_f32_16x16x32_bf16 v[64:67], v[172:175], v[206:209], v[64:67]
	s_setprio 0
	s_barrier
; #define PG8_STAGE(bufoff, gbase, voff) do { _Pragma("unroll") for (int _i = 0; _i < 2; ++_i) \
;         __builtin_amdgcn_global_load_lds((const unsigned*)((const char*)(gbase) + (voff)[_i]), (PG8_LAS unsigned*)(lds + (bufoff) + ldsw + _i * 8192), 16, 0, 0); } while (0)
; #define PG8_LDA(dst, b, h) do { _Pragma("unroll") for (int m = 0; m < 4; ++m) _Pragma("unroll") for (int k = 0; k < 2; ++k) dst[m][k] = *(const PG8_LAS bf16x8*)(lds + PG8_SA(b, h) + aoff + m * 2048 + k * 1024); } while (0)
; #define PG8_WAIT_V(n) asm volatile("s_waitcnt vmcnt(" #n ")" ::: "memory")
; #define PG8_WAIT_L(n) asm volatile("s_waitcnt lgkmcnt(" #n ")" ::: "memory")
; #define PG8_BAR __builtin_amdgcn_s_barrier()
; template <class Epi, class Sched, bool ALIGN_EPI = false, bool SP2 = false>
; __device__ __forceinline__ void gemm_phase(PG8_LAS unsigned char* lds, const Gemm g, const Sched& S, const Epi& E, const int tid) {
;     ...
;         for (int t = 0; t < nt; t += 2) {
;             const bool last = (t == nt - 2);
;             const char* a1 = cA + (size_t)(t + 1) * kstep;
;             const char* a2 = last ? nA : cA + (size_t)(t + 2) * kstep; const char* b2 = last ? nB : cB + (size_t)(t + 2) * kstep;
;             const char* a3 = a2 + kstep; const char* b3 = b2 + kstep;
;             if (last && has_next) S.a_ready(nxt);
;             if constexpr (SP2) {
;             PG8_LDB(B0, 0, 0); PG8_LDB(B1, 0, 1); PG8_SCHED; PG8_LDA(At, 0, 0); PG8_STAGE(PG8_SA(1, 1), a1 + hstep, voffA);
;             PG8_WAIT_V(8); PG8_WAIT_L(0); PG8_BAR; PG8_MMA(0, 0, At, B0); PG8_MMA(0, 1, At, B1); PG8_BAR; PG8_SCHED;
;             PG8_LDA(At, 0, 1); PG8_STAGE(PG8_SB(0, 0), b2, voffB); PG8_STAGE(PG8_SB(0, 1), b2 + hstep, voffB); PG8_STAGE(PG8_SA(0, 0), a2, voffA);
;             PG8_WAIT_V(8); PG8_WAIT_L(0); PG8_BAR; PG8_MMA(1, 0, At, B0); PG8_MMA(1, 1, At, B1); PG8_BAR; PG8_SCHED;
;             PG8_LDB(B0, 1, 0); PG8_LDB(B1, 1, 1); PG8_SCHED; PG8_LDA(At, 1, 0); PG8_STAGE(PG8_SA(0, 1), a2 + hstep, voffA);
;             PG8_WAIT_V(8); PG8_WAIT_L(0); PG8_BAR; PG8_MMA(0, 0, At, B0); PG8_MMA(0, 1, At, B1); PG8_BAR; PG8_SCHED;
;             PG8_LDA(At, 1, 1); PG8_STAGE(PG8_SB(1, 0), b3, voffB); PG8_STAGE(PG8_SB(1, 1), b3 + hstep, voffB); PG8_STAGE(PG8_SA(1, 0), a3, voffA);
;             PG8_WAIT_V(8); PG8_WAIT_L(0); PG8_BAR; PG8_MMA(1, 0, At, B0); PG8_MMA(1, 1, At, B1); PG8_BAR; PG8_SCHED;
	s_add_i32 s30, s55, s35
	v_lshl_add_u64 v[140:141], v[140:141], 0, s[70:71]
	s_mov_b32 m0, s30
	ds_read_b128 v[176:179], v143 offset:49152
	ds_read_b128 v[180:183], v143 offset:50176
	ds_read_b128 v[184:187], v143 offset:51200
	ds_read_b128 v[188:191], v143 offset:52224
	ds_read_b128 v[192:195], v143 offset:53248
	ds_read_b128 v[196:199], v143 offset:54272
	ds_read_b128 v[200:203], v143 offset:55296
	ds_read_b128 v[206:209], v143 offset:56320
	global_load_lds_dwordx4 v[140:141], off
	s_add_i32 m0, s30, 0x2000
	s_add_u32 s28, s28, 0x80080
	v_lshl_add_u64 v[140:141], v[210:211], 0, s[70:71]
	s_addc_u32 s29, s29, 0
	s_add_i32 s30, s62, s35
	global_load_lds_dwordx4 v[140:141], off
	v_lshl_add_u64 v[140:141], s[28:29], 0, v[204:205]
	s_mov_b32 m0, s30
	s_nop 0
	global_load_lds_dwordx4 v[140:141], off
	v_lshl_add_u64 v[140:141], s[28:29], 0, v[128:129]
	s_add_i32 m0, s30, 0x2000
	s_nop 0
	global_load_lds_dwordx4 v[140:141], off
	v_lshl_add_u64 v[140:141], v[212:213], 0, s[70:71]
	s_mov_b32 m0, s46
	s_nop 0
	global_load_lds_dwordx4 v[140:141], off
	v_lshl_add_u64 v[140:141], v[214:215], 0, s[70:71]
	s_mov_b32 m0, s47
	s_nop 0
	global_load_lds_dwordx4 v[140:141], off
	s_waitcnt vmcnt(8)
	s_waitcnt lgkmcnt(0)
	s_barrier
	s_setprio 1
	s_waitcnt lgkmcnt(0)
	v_mfma_f32_16x16x32_bf16 v[60:63], v[144:147], v[176:179], v[60:63]
	v_mfma_f32_16x16x32_bf16 v[56:59], v[152:155], v[176:179], v[56:59]
	v_mfma_f32_16x16x32_bf16 v[48:51], v[144:147], v[184:187], v[48:51]
	v_mfma_f32_16x16x32_bf16 v[40:43], v[152:155], v[184:187], v[40:43]
	v_mfma_f32_16x16x32_bf16 v[32:35], v[144:147], v[192:195], v[32:35]
	v_mfma_f32_16x16x32_bf16 v[24:27], v[152:155], v[192:195], v[24:27]
	v_mfma_f32_16x16x32_bf16 v[16:19], v[144:147], v[200:203], v[16:19]
	v_mfma_f32_16x16x32_bf16 v[8:11], v[152:155], v[200:203], v[8:11]
	v_mfma_f32_16x16x32_bf16 v[60:63], v[148:151], v[180:183], v[60:63]
	v_mfma_f32_16x16x32_bf16 v[56:59], v[156:159], v[180:183], v[56:59]
	v_mfma_f32_16x16x32_bf16 v[48:51], v[148:151], v[188:191], v[48:51]
	v_mfma_f32_16x16x32_bf16 v[40:43], v[156:159], v[188:191], v[40:43]
	v_mfma_f32_16x16x32_bf16 v[32:35], v[148:151], v[196:199], v[32:35]
	v_mfma_f32_16x16x32_bf16 v[24:27], v[156:159], v[196:199], v[24:27]
	v_mfma_f32_16x16x32_bf16 v[16:19], v[148:151], v[206:209], v[16:19]
	v_mfma_f32_16x16x32_bf16 v[8:11], v[156:159], v[206:209], v[8:11]
	s_setprio 0
	s_setprio 1
	v_mfma_f32_16x16x32_bf16 v[52:55], v[160:163], v[176:179], v[52:55]
	v_mfma_f32_16x16x32_bf16 v[44:47], v[168:171], v[176:179], v[44:47]
	v_mfma_f32_16x16x32_bf16 v[36:39], v[160:163], v[184:187], v[36:39]
	v_mfma_f32_16x16x32_bf16 v[28:31], v[168:171], v[184:187], v[28:31]
	v_mfma_f32_16x16x32_bf16 v[20:23], v[160:163], v[192:195], v[20:23]
	v_mfma_f32_16x16x32_bf16 v[12:15], v[168:171], v[192:195], v[12:15]
	v_mfma_f32_16x16x32_bf16 v[4:7], v[160:163], v[200:203], v[4:7]
	v_mfma_f32_16x16x32_bf16 v[0:3], v[168:171], v[200:203], v[0:3]
	v_mfma_f32_16x16x32_bf16 v[52:55], v[164:167], v[180:183], v[52:55]
	v_mfma_f32_16x16x32_bf16 v[44:47], v[172:175], v[180:183], v[44:47]
	v_mfma_f32_16x16x32_bf16 v[36:39], v[164:167], v[188:191], v[36:39]
	v_mfma_f32_16x16x32_bf16 v[28:31], v[172:175], v[188:191], v[28:31]
	v_mfma_f32_16x16x32_bf16 v[20:23], v[164:167], v[196:199], v[20:23]
	v_mfma_f32_16x16x32_bf16 v[12:15], v[172:175], v[196:199], v[12:15]
	v_mfma_f32_16x16x32_bf16 v[4:7], v[164:167], v[206:209], v[4:7]
	v_mfma_f32_16x16x32_bf16 v[0:3], v[172:175], v[206:209], v[0:3]
	s_setprio 0
	s_barrier
	s_add_i32 s54, s54, 2
	s_add_u32 s26, s26, 0x100
	s_addc_u32 s27, s27, 0
	s_add_u32 s52, s52, 0x100
	s_addc_u32 s53, s53, 0

; #define PG8_STAGE(bufoff, gbase, voff) do { _Pragma("unroll") for (int _i = 0; _i < 2; ++_i) \
;         __builtin_amdgcn_global_load_lds((const unsigned*)((const char*)(gbase) + (voff)[_i]), (PG8_LAS unsigned*)(lds + (bufoff) + ldsw + _i * 8192), 16, 0, 0); } while (0)
; #define PG8_LDA(dst, b, h) do { _Pragma("unroll") for (int m = 0; m < 4; ++m) _Pragma("unroll") for (int k = 0; k < 2; ++k) dst[m][k] = *(const PG8_LAS bf16x8*)(lds + PG8_SA(b, h) + aoff + m * 2048 + k * 1024); } while (0)
; #define PG8_LDB(dst, b, h) do { _Pragma("unroll") for (int n = 0; n < 2; ++n) _Pragma("unroll") for (int k = 0; k < 2; ++k) dst[n][k] = *(const PG8_LAS bf16x8*)(lds + PG8_SB(b, h) + boff + n * 2048 + k * 1024); } while (0)
; #define PG8_WAIT_V(n) asm volatile("s_waitcnt vmcnt(" #n ")" ::: "memory")
; #define PG8_WAIT_L(n) asm volatile("s_waitcnt lgkmcnt(" #n ")" ::: "memory")
; #define PG8_BAR __builtin_amdgcn_s_barrier()
; #define PG8_SCHED __builtin_amdgcn_sched_barrier(0)
; template <class Epi, class Sched, bool ALIGN_EPI = false, bool SP2 = false>
; __device__ __forceinline__ void gemm_phase(PG8_LAS unsigned char* lds, const Gemm g, const Sched& S, const Epi& E, const int tid) {
;     ...
;         const bool has_next = S.next(ui + 1, nxt);
;         const char* nA = has_next ? (const char*)g.A + (size_t)nxt.pm * tstep : cA; const char* nB = has_next ? (const char*)g.Bt + (size_t)nxt.pn * tstep : cB;
;         for (int t = 0; t < nt; t += 2) {
;             const bool last = (t == nt - 2);
;             const char* a1 = cA + (size_t)(t + 1) * kstep;
;             const char* a2 = last ? nA : cA + (size_t)(t + 2) * kstep; const char* b2 = last ? nB : cB + (size_t)(t + 2) * kstep;
;             const char* a3 = a2 + kstep; const char* b3 = b2 + kstep;
;             if (last && has_next) S.a_ready(nxt);
;             if constexpr (SP2) {
;             PG8_LDB(B0, 0, 0); PG8_LDB(B1, 0, 1); PG8_SCHED; PG8_LDA(At, 0, 0); PG8_STAGE(PG8_SA(1, 1), a1 + hstep, voffA);
;             PG8_WAIT_V(8); PG8_WAIT_L(0); PG8_BAR; PG8_MMA(0, 0, At, B0); PG8_MMA(0, 1, At, B1); PG8_BAR; PG8_SCHED;
;             PG8_LDA(At, 0, 1); PG8_STAGE(PG8_SB(0, 0), b2, voffB); PG8_STAGE(PG8_SB(0, 1), b2 + hstep, voffB); PG8_STAGE(PG8_SA(0, 0), a2, voffA);
;             PG8_WAIT_V(8); PG8_WAIT_L(0); PG8_BAR; PG8_MMA(1, 0, At, B0); PG8_MMA(1, 1, At, B1); PG8_BAR; PG8_SCHED;
.LBB0_679:
	s_ashr_i32 s29, s28, 31
	s_lshl_b64 s[30:31], s[28:29], 20
	s_add_u32 s30, s50, s30
	s_addc_u32 s31, s51, s31
	s_and_b64 s[34:35], s[6:7], exec
	s_cselect_b32 s29, s31, s45
	s_cselect_b32 s43, s30, s44
	s_ashr_i32 s27, s26, 31
	s_lshl_b64 s[34:35], s[26:27], 20
	s_add_u32 s34, s52, s34
	s_addc_u32 s35, s53, s35
	s_and_b64 s[48:49], s[6:7], exec
	s_cselect_b32 s27, s35, s47
	s_cselect_b32 s69, s34, s46
	s_add_u32 s44, s44, 0x80080
	s_addc_u32 s45, s45, 0
	s_add_u32 vcc_lo, s46, 0x100
	s_addc_u32 vcc_hi, s47, 0
	s_mov_b32 s76, -2
	s_waitcnt vmcnt(0)
	s_add_u32 s46, s44, 0xfff80080
	s_addc_u32 s47, s45, -1
	s_add_i32 s77, 0, 0x10000
	s_cmp_eq_u32 s76, 28
	s_cselect_b32 s49, s29, s47
	s_cselect_b32 s48, s43, s46
	s_cselect_b32 s47, s27, vcc_hi
	s_cselect_b32 s46, s69, vcc_lo
	s_add_i32 s80, 0, 0x14000
	v_add_u32_e32 v152, s77, v166
	v_add_u32_e32 v164, s80, v166
	ds_read_b128 v[128:131], v152
	ds_read_b128 v[144:147], v152 offset:1024
	ds_read_b128 v[148:151], v152 offset:2048
	ds_read_b128 v[152:155], v152 offset:3072
	ds_read_b128 v[156:159], v164
	ds_read_b128 v[160:163], v164 offset:1024
	ds_read_b128 v[168:171], v164 offset:2048
	ds_read_b128 v[172:175], v164 offset:3072
	v_lshl_add_u64 v[164:165], s[44:45], 0, v[140:141]
	s_add_i32 m0, s37, 0xc000
	ds_read_b128 v[176:179], v167
	ds_read_b128 v[180:183], v167 offset:1024
	ds_read_b128 v[184:187], v167 offset:2048
	ds_read_b128 v[188:191], v167 offset:3072
	ds_read_b128 v[192:195], v167 offset:4096
	ds_read_b128 v[196:199], v167 offset:5120
	ds_read_b128 v[200:203], v167 offset:6144
	ds_read_b128 v[214:217], v167 offset:7168
	global_load_lds_dwordx4 v[164:165], off
	v_lshl_add_u64 v[164:165], s[44:45], 0, v[142:143]
	s_add_i32 m0, s37, 0xe000
	s_nop 0
	global_load_lds_dwordx4 v[164:165], off
	s_waitcnt vmcnt(24)
	s_waitcnt lgkmcnt(0)
	s_barrier
	s_setprio 1
	s_waitcnt lgkmcnt(0)
	v_mfma_f32_16x16x32_bf16 v[124:127], v[128:131], v[176:179], 0
	v_mfma_f32_16x16x32_bf16 v[120:123], v[148:151], v[176:179], 0
	v_mfma_f32_16x16x32_bf16 v[108:111], v[128:131], v[184:187], 0
	v_mfma_f32_16x16x32_bf16 v[104:107], v[148:151], v[184:187], 0
	v_mfma_f32_16x16x32_bf16 v[92:95], v[128:131], v[192:195], 0
	v_mfma_f32_16x16x32_bf16 v[88:91], v[148:151], v[192:195], 0
	v_mfma_f32_16x16x32_bf16 v[76:79], v[128:131], v[200:203], 0
	v_mfma_f32_16x16x32_bf16 v[72:75], v[148:151], v[200:203], 0
	v_mfma_f32_16x16x32_bf16 v[124:127], v[144:147], v[180:183], v[124:127]
	v_mfma_f32_16x16x32_bf16 v[120:123], v[152:155], v[180:183], v[120:123]
	v_mfma_f32_16x16x32_bf16 v[108:111], v[144:147], v[188:191], v[108:111]
	v_mfma_f32_16x16x32_bf16 v[104:107], v[152:155], v[188:191], v[104:107]
	v_mfma_f32_16x16x32_bf16 v[92:95], v[144:147], v[196:199], v[92:95]
	v_mfma_f32_16x16x32_bf16 v[88:91], v[152:155], v[196:199], v[88:91]
	v_mfma_f32_16x16x32_bf16 v[76:79], v[144:147], v[214:217], v[76:79]
	v_mfma_f32_16x16x32_bf16 v[72:75], v[152:155], v[214:217], v[72:75]
	s_setprio 0
	s_setprio 1
	v_mfma_f32_16x16x32_bf16 v[116:119], v[156:159], v[176:179], 0
	v_mfma_f32_16x16x32_bf16 v[112:115], v[168:171], v[176:179], 0
	v_mfma_f32_16x16x32_bf16 v[100:103], v[156:159], v[184:187], 0
	v_mfma_f32_16x16x32_bf16 v[96:99], v[168:171], v[184:187], 0
	v_mfma_f32_16x16x32_bf16 v[84:87], v[156:159], v[192:195], 0
	v_mfma_f32_16x16x32_bf16 v[80:83], v[168:171], v[192:195], 0
	v_mfma_f32_16x16x32_bf16 v[68:71], v[156:159], v[200:203], 0
	v_mfma_f32_16x16x32_bf16 v[64:67], v[168:171], v[200:203], 0
	v_mfma_f32_16x16x32_bf16 v[116:119], v[160:163], v[180:183], v[116:119]
	v_mfma_f32_16x16x32_bf16 v[112:115], v[172:175], v[180:183], v[112:115]
	v_mfma_f32_16x16x32_bf16 v[100:103], v[160:163], v[188:191], v[100:103]
	v_mfma_f32_16x16x32_bf16 v[96:99], v[172:175], v[188:191], v[96:99]
	v_mfma_f32_16x16x32_bf16 v[84:87], v[160:163], v[196:199], v[84:87]
	v_mfma_f32_16x16x32_bf16 v[80:83], v[172:175], v[196:199], v[80:83]
	v_mfma_f32_16x16x32_bf16 v[68:71], v[160:163], v[214:217], v[68:71]
	v_mfma_f32_16x16x32_bf16 v[64:67], v[172:175], v[214:217], v[64:67]
	s_setprio 0
	s_barrier
	s_add_i32 s77, s77, s54
	v_lshl_add_u64 v[164:165], s[46:47], 0, v[134:135]
	s_mov_b32 m0, s77
	ds_read_b128 v[176:179], v167 offset:16384
	ds_read_b128 v[180:183], v167 offset:17408
	ds_read_b128 v[184:187], v167 offset:18432
	ds_read_b128 v[188:191], v167 offset:19456
	ds_read_b128 v[192:195], v167 offset:20480
	ds_read_b128 v[196:199], v167 offset:21504
	ds_read_b128 v[200:203], v167 offset:22528
	ds_read_b128 v[214:217], v167 offset:23552
	global_load_lds_dwordx4 v[164:165], off
	s_add_i32 m0, s77, 0x2000
	s_add_u32 s78, s46, 0x80000
	v_lshl_add_u64 v[206:207], s[46:47], 0, v[138:139]
	s_addc_u32 s79, s47, 0
	s_add_i32 s77, s80, s54
	global_load_lds_dwordx4 v[206:207], off
	v_lshl_add_u64 v[208:209], s[78:79], 0, v[134:135]
	s_mov_b32 m0, s77
	v_lshl_add_u64 v[210:211], s[48:49], 0, v[136:137]
	global_load_lds_dwordx4 v[208:209], off
	v_lshl_add_u64 v[208:209], s[78:79], 0, v[138:139]
	s_add_i32 m0, s77, 0x2000
	s_nop 0
	global_load_lds_dwordx4 v[208:209], off
	v_lshl_add_u64 v[208:209], s[48:49], 0, v[132:133]
	s_mov_b32 m0, s37
	s_nop 0
	global_load_lds_dwordx4 v[208:209], off
	s_mov_b32 m0, s55
	s_nop 0
	global_load_lds_dwordx4 v[210:211], off
	s_waitcnt vmcnt(8)
	s_waitcnt lgkmcnt(0)
	s_barrier
; #define PG8_STAGE(bufoff, gbase, voff) do { _Pragma("unroll") for (int _i = 0; _i < 2; ++_i) \
;         __builtin_amdgcn_global_load_lds((const unsigned*)((const char*)(gbase) + (voff)[_i]), (PG8_LAS unsigned*)(lds + (bufoff) + ldsw + _i * 8192), 16, 0, 0); } while (0)
; #define PG8_LDA(dst, b, h) do { _Pragma("unroll") for (int m = 0; m < 4; ++m) _Pragma("unroll") for (int k = 0; k < 2; ++k) dst[m][k] = *(const PG8_LAS bf16x8*)(lds + PG8_SA(b, h) + aoff + m * 2048 + k * 1024); } while (0)
; #define PG8_LDB(dst, b, h) do { _Pragma("unroll") for (int n = 0; n < 2; ++n) _Pragma("unroll") for (int k = 0; k < 2; ++k) dst[n][k] = *(const PG8_LAS bf16x8*)(lds + PG8_SB(b, h) + boff + n * 2048 + k * 1024); } while (0)
; #define PG8_MMA(ai, bj, At, Bt) do { __builtin_amdgcn_s_setprio(1); _Pragma("unroll") for (int m = 0; m < 4; ++m) _Pragma("unroll") for (int n = 0; n < 2; ++n) _Pragma("unroll") for (int k = 0; k < 2; ++k) \
;         acc[ai][bj][m][n] = __builtin_amdgcn_mfma_f32_16x16x32_bf16(Bt[n][k], At[m][k], acc[ai][bj][m][n], 0, 0, 0); __builtin_amdgcn_s_setprio(0); } while (0)
; #define PG8_WAIT_V(n) asm volatile("s_waitcnt vmcnt(" #n ")" ::: "memory")
; #define PG8_WAIT_L(n) asm volatile("s_waitcnt lgkmcnt(" #n ")" ::: "memory")
; #define PG8_BAR __builtin_amdgcn_s_barrier()
; #define PG8_SCHED __builtin_amdgcn_sched_barrier(0)
; template <class Epi, class Sched, bool ALIGN_EPI = false, bool SP2 = false>
; __device__ __forceinline__ void gemm_phase(PG8_LAS unsigned char* lds, const Gemm g, const Sched& S, const Epi& E, const int tid) {
;     ...
;             PG8_WAIT_V(8); PG8_WAIT_L(0); PG8_BAR; PG8_MMA(0, 0, At, B0); PG8_MMA(0, 1, At, B1); PG8_BAR; PG8_SCHED;
;             PG8_LDA(At, 0, 1); PG8_STAGE(PG8_SB(0, 0), b2, voffB); PG8_STAGE(PG8_SB(0, 1), b2 + hstep, voffB); PG8_STAGE(PG8_SA(0, 0), a2, voffA);
;             PG8_WAIT_V(8); PG8_WAIT_L(0); PG8_BAR; PG8_MMA(1, 0, At, B0); PG8_MMA(1, 1, At, B1); PG8_BAR; PG8_SCHED;
;             PG8_LDB(B0, 1, 0); PG8_LDB(B1, 1, 1); PG8_SCHED; PG8_LDA(At, 1, 0); PG8_STAGE(PG8_SA(0, 1), a2 + hstep, voffA);
;             PG8_WAIT_V(8); PG8_WAIT_L(0); PG8_BAR; PG8_MMA(0, 0, At, B0); PG8_MMA(0, 1, At, B1); PG8_BAR; PG8_SCHED;
;             PG8_LDA(At, 1, 1); PG8_STAGE(PG8_SB(1, 0), b3, voffB); PG8_STAGE(PG8_SB(1, 1), b3 + hstep, voffB); PG8_STAGE(PG8_SA(1, 0), a3, voffA);
	s_setprio 1
	s_waitcnt lgkmcnt(0)
	v_mfma_f32_16x16x32_bf16 v[60:63], v[128:131], v[176:179], 0
	v_mfma_f32_16x16x32_bf16 v[56:59], v[148:151], v[176:179], 0
	v_mfma_f32_16x16x32_bf16 v[44:47], v[128:131], v[184:187], 0
	v_mfma_f32_16x16x32_bf16 v[40:43], v[148:151], v[184:187], 0
	v_mfma_f32_16x16x32_bf16 v[28:31], v[128:131], v[192:195], 0
	v_mfma_f32_16x16x32_bf16 v[24:27], v[148:151], v[192:195], 0
	v_mfma_f32_16x16x32_bf16 v[12:15], v[128:131], v[200:203], 0
	v_mfma_f32_16x16x32_bf16 v[8:11], v[148:151], v[200:203], 0
	v_mfma_f32_16x16x32_bf16 v[60:63], v[144:147], v[180:183], v[60:63]
	v_mfma_f32_16x16x32_bf16 v[56:59], v[152:155], v[180:183], v[56:59]
	v_mfma_f32_16x16x32_bf16 v[44:47], v[144:147], v[188:191], v[44:47]
	v_mfma_f32_16x16x32_bf16 v[40:43], v[152:155], v[188:191], v[40:43]
	v_mfma_f32_16x16x32_bf16 v[28:31], v[144:147], v[196:199], v[28:31]
	v_mfma_f32_16x16x32_bf16 v[24:27], v[152:155], v[196:199], v[24:27]
	v_mfma_f32_16x16x32_bf16 v[12:15], v[144:147], v[214:217], v[12:15]
	v_mfma_f32_16x16x32_bf16 v[8:11], v[152:155], v[214:217], v[8:11]
	s_setprio 0
	s_setprio 1
	v_mfma_f32_16x16x32_bf16 v[52:55], v[156:159], v[176:179], 0
	v_mfma_f32_16x16x32_bf16 v[48:51], v[168:171], v[176:179], 0
	v_mfma_f32_16x16x32_bf16 v[36:39], v[156:159], v[184:187], 0
	v_mfma_f32_16x16x32_bf16 v[32:35], v[168:171], v[184:187], 0
	v_mfma_f32_16x16x32_bf16 v[20:23], v[156:159], v[192:195], 0
	v_mfma_f32_16x16x32_bf16 v[16:19], v[168:171], v[192:195], 0
	v_mfma_f32_16x16x32_bf16 v[4:7], v[156:159], v[200:203], 0
	v_mfma_f32_16x16x32_bf16 v[0:3], v[168:171], v[200:203], 0
	v_mfma_f32_16x16x32_bf16 v[52:55], v[160:163], v[180:183], v[52:55]
	v_mfma_f32_16x16x32_bf16 v[48:51], v[172:175], v[180:183], v[48:51]
	v_mfma_f32_16x16x32_bf16 v[36:39], v[160:163], v[188:191], v[36:39]
	v_mfma_f32_16x16x32_bf16 v[32:35], v[172:175], v[188:191], v[32:35]
	v_mfma_f32_16x16x32_bf16 v[20:23], v[160:163], v[196:199], v[20:23]
	v_mfma_f32_16x16x32_bf16 v[16:19], v[172:175], v[196:199], v[16:19]
	v_mfma_f32_16x16x32_bf16 v[4:7], v[160:163], v[214:217], v[4:7]
	v_mfma_f32_16x16x32_bf16 v[0:3], v[172:175], v[214:217], v[0:3]
	s_setprio 0
	s_barrier
	s_add_i32 s77, 0, 0x18000
	s_add_i32 s78, 0, 0x1c000
	v_add_u32_e32 v152, s77, v166
	v_add_u32_e32 v172, s78, v166
	ds_read_b128 v[128:131], v152
	ds_read_b128 v[144:147], v152 offset:1024
	ds_read_b128 v[148:151], v152 offset:2048
	ds_read_b128 v[152:155], v152 offset:3072
	ds_read_b128 v[156:159], v172
	ds_read_b128 v[160:163], v172 offset:1024
	ds_read_b128 v[168:171], v172 offset:2048
	ds_read_b128 v[172:175], v172 offset:3072
	s_add_u32 s48, s48, 0x80000
	s_addc_u32 s49, s49, 0
	s_mov_b32 m0, s0
	v_lshl_add_u64 v[212:213], s[48:49], 0, v[132:133]
	ds_read_b128 v[176:179], v167 offset:32768
	ds_read_b128 v[180:183], v167 offset:33792
	ds_read_b128 v[184:187], v167 offset:34816
	ds_read_b128 v[188:191], v167 offset:35840
	ds_read_b128 v[192:195], v167 offset:36864
	ds_read_b128 v[196:199], v167 offset:37888
	ds_read_b128 v[200:203], v167 offset:38912
	ds_read_b128 v[214:217], v167 offset:39936
	global_load_lds_dwordx4 v[212:213], off
	v_lshl_add_u64 v[212:213], s[48:49], 0, v[136:137]
	s_mov_b32 m0, s33
	s_nop 0
	global_load_lds_dwordx4 v[212:213], off
	s_waitcnt vmcnt(8)
	s_waitcnt lgkmcnt(0)
	s_barrier
	s_setprio 1
	s_waitcnt lgkmcnt(0)
	v_mfma_f32_16x16x32_bf16 v[124:127], v[128:131], v[176:179], v[124:127]
	v_mfma_f32_16x16x32_bf16 v[120:123], v[148:151], v[176:179], v[120:123]
	v_mfma_f32_16x16x32_bf16 v[108:111], v[128:131], v[184:187], v[108:111]
	v_mfma_f32_16x16x32_bf16 v[104:107], v[148:151], v[184:187], v[104:107]
	v_mfma_f32_16x16x32_bf16 v[92:95], v[128:131], v[192:195], v[92:95]
	v_mfma_f32_16x16x32_bf16 v[88:91], v[148:151], v[192:195], v[88:91]
	v_mfma_f32_16x16x32_bf16 v[76:79], v[128:131], v[200:203], v[76:79]
	v_mfma_f32_16x16x32_bf16 v[72:75], v[148:151], v[200:203], v[72:75]
	v_mfma_f32_16x16x32_bf16 v[124:127], v[144:147], v[180:183], v[124:127]
	v_mfma_f32_16x16x32_bf16 v[120:123], v[152:155], v[180:183], v[120:123]
	v_mfma_f32_16x16x32_bf16 v[108:111], v[144:147], v[188:191], v[108:111]
	v_mfma_f32_16x16x32_bf16 v[104:107], v[152:155], v[188:191], v[104:107]
	v_mfma_f32_16x16x32_bf16 v[92:95], v[144:147], v[196:199], v[92:95]
	v_mfma_f32_16x16x32_bf16 v[88:91], v[152:155], v[196:199], v[88:91]
	v_mfma_f32_16x16x32_bf16 v[76:79], v[144:147], v[214:217], v[76:79]
	v_mfma_f32_16x16x32_bf16 v[72:75], v[152:155], v[214:217], v[72:75]
	s_setprio 0
	s_setprio 1
	v_mfma_f32_16x16x32_bf16 v[116:119], v[156:159], v[176:179], v[116:119]
	v_mfma_f32_16x16x32_bf16 v[112:115], v[168:171], v[176:179], v[112:115]
	v_mfma_f32_16x16x32_bf16 v[100:103], v[156:159], v[184:187], v[100:103]
	v_mfma_f32_16x16x32_bf16 v[96:99], v[168:171], v[184:187], v[96:99]
	v_mfma_f32_16x16x32_bf16 v[84:87], v[156:159], v[192:195], v[84:87]
	v_mfma_f32_16x16x32_bf16 v[80:83], v[168:171], v[192:195], v[80:83]
	v_mfma_f32_16x16x32_bf16 v[68:71], v[156:159], v[200:203], v[68:71]
	v_mfma_f32_16x16x32_bf16 v[64:67], v[168:171], v[200:203], v[64:67]
	v_mfma_f32_16x16x32_bf16 v[116:119], v[160:163], v[180:183], v[116:119]
	v_mfma_f32_16x16x32_bf16 v[112:115], v[172:175], v[180:183], v[112:115]
	v_mfma_f32_16x16x32_bf16 v[100:103], v[160:163], v[188:191], v[100:103]
	v_mfma_f32_16x16x32_bf16 v[96:99], v[172:175], v[188:191], v[96:99]
	v_mfma_f32_16x16x32_bf16 v[84:87], v[160:163], v[196:199], v[84:87]
	v_mfma_f32_16x16x32_bf16 v[80:83], v[172:175], v[196:199], v[80:83]
	v_mfma_f32_16x16x32_bf16 v[68:71], v[160:163], v[214:217], v[68:71]
	v_mfma_f32_16x16x32_bf16 v[64:67], v[172:175], v[214:217], v[64:67]
	s_setprio 0
	s_barrier
; #define PG8_STAGE(bufoff, gbase, voff) do { _Pragma("unroll") for (int _i = 0; _i < 2; ++_i) \
;         __builtin_amdgcn_global_load_lds((const unsigned*)((const char*)(gbase) + (voff)[_i]), (PG8_LAS unsigned*)(lds + (bufoff) + ldsw + _i * 8192), 16, 0, 0); } while (0)
; #define PG8_LDA(dst, b, h) do { _Pragma("unroll") for (int m = 0; m < 4; ++m) _Pragma("unroll") for (int k = 0; k < 2; ++k) dst[m][k] = *(const PG8_LAS bf16x8*)(lds + PG8_SA(b, h) + aoff + m * 2048 + k * 1024); } while (0)
; #define PG8_WAIT_V(n) asm volatile("s_waitcnt vmcnt(" #n ")" ::: "memory")
; #define PG8_WAIT_L(n) asm volatile("s_waitcnt lgkmcnt(" #n ")" ::: "memory")
; #define PG8_BAR __builtin_amdgcn_s_barrier()
; template <class Epi, class Sched, bool ALIGN_EPI = false, bool SP2 = false>
; __device__ __forceinline__ void gemm_phase(PG8_LAS unsigned char* lds, const Gemm g, const Sched& S, const Epi& E, const int tid) {
;     ...
;         for (int t = 0; t < nt; t += 2) {
;             const bool last = (t == nt - 2);
;             const char* a1 = cA + (size_t)(t + 1) * kstep;
;             const char* a2 = last ? nA : cA + (size_t)(t + 2) * kstep; const char* b2 = last ? nB : cB + (size_t)(t + 2) * kstep;
;             const char* a3 = a2 + kstep; const char* b3 = b2 + kstep;
;             if (last && has_next) S.a_ready(nxt);
;             if constexpr (SP2) {
;             PG8_LDB(B0, 0, 0); PG8_LDB(B1, 0, 1); PG8_SCHED; PG8_LDA(At, 0, 0); PG8_STAGE(PG8_SA(1, 1), a1 + hstep, voffA);
;             PG8_WAIT_V(8); PG8_WAIT_L(0); PG8_BAR; PG8_MMA(0, 0, At, B0); PG8_MMA(0, 1, At, B1); PG8_BAR; PG8_SCHED;
;             PG8_LDA(At, 0, 1); PG8_STAGE(PG8_SB(0, 0), b2, voffB); PG8_STAGE(PG8_SB(0, 1), b2 + hstep, voffB); PG8_STAGE(PG8_SA(0, 0), a2, voffA);
;             PG8_WAIT_V(8); PG8_WAIT_L(0); PG8_BAR; PG8_MMA(1, 0, At, B0); PG8_MMA(1, 1, At, B1); PG8_BAR; PG8_SCHED;
;             PG8_LDB(B0, 1, 0); PG8_LDB(B1, 1, 1); PG8_SCHED; PG8_LDA(At, 1, 0); PG8_STAGE(PG8_SA(0, 1), a2 + hstep, voffA);
;             PG8_WAIT_V(8); PG8_WAIT_L(0); PG8_BAR; PG8_MMA(0, 0, At, B0); PG8_MMA(0, 1, At, B1); PG8_BAR; PG8_SCHED;
;             PG8_LDA(At, 1, 1); PG8_STAGE(PG8_SB(1, 0), b3, voffB); PG8_STAGE(PG8_SB(1, 1), b3 + hstep, voffB); PG8_STAGE(PG8_SA(1, 0), a3, voffA);
;             PG8_WAIT_V(8); PG8_WAIT_L(0); PG8_BAR; PG8_MMA(1, 0, At, B0); PG8_MMA(1, 1, At, B1); PG8_BAR; PG8_SCHED;
	s_add_i32 s48, s77, s54
	v_lshl_add_u64 v[164:165], v[164:165], 0, s[70:71]
	s_mov_b32 m0, s48
	ds_read_b128 v[176:179], v167 offset:49152
	ds_read_b128 v[180:183], v167 offset:50176
	ds_read_b128 v[184:187], v167 offset:51200
	ds_read_b128 v[188:191], v167 offset:52224
	ds_read_b128 v[192:195], v167 offset:53248
	ds_read_b128 v[196:199], v167 offset:54272
	ds_read_b128 v[200:203], v167 offset:55296
	ds_read_b128 v[214:217], v167 offset:56320
	global_load_lds_dwordx4 v[164:165], off
	s_add_i32 m0, s48, 0x2000
	s_add_u32 s46, s46, 0x80080
	v_lshl_add_u64 v[164:165], v[206:207], 0, s[70:71]
	s_addc_u32 s47, s47, 0
	s_add_i32 s48, s78, s54
	global_load_lds_dwordx4 v[164:165], off
	v_lshl_add_u64 v[164:165], s[46:47], 0, v[134:135]
	s_mov_b32 m0, s48
	s_nop 0
	global_load_lds_dwordx4 v[164:165], off
	v_lshl_add_u64 v[164:165], s[46:47], 0, v[138:139]
	s_add_i32 m0, s48, 0x2000
	s_nop 0
	global_load_lds_dwordx4 v[164:165], off
	v_lshl_add_u64 v[164:165], v[208:209], 0, s[70:71]
	s_mov_b32 m0, s10
	s_nop 0
	global_load_lds_dwordx4 v[164:165], off
	v_lshl_add_u64 v[164:165], v[210:211], 0, s[70:71]
	s_mov_b32 m0, s11
	s_nop 0
	global_load_lds_dwordx4 v[164:165], off
	s_waitcnt vmcnt(8)
	s_waitcnt lgkmcnt(0)
	s_barrier
	s_setprio 1
	s_waitcnt lgkmcnt(0)
	v_mfma_f32_16x16x32_bf16 v[60:63], v[128:131], v[176:179], v[60:63]
	v_mfma_f32_16x16x32_bf16 v[56:59], v[148:151], v[176:179], v[56:59]
	v_mfma_f32_16x16x32_bf16 v[44:47], v[128:131], v[184:187], v[44:47]
	v_mfma_f32_16x16x32_bf16 v[40:43], v[148:151], v[184:187], v[40:43]
	v_mfma_f32_16x16x32_bf16 v[28:31], v[128:131], v[192:195], v[28:31]
	v_mfma_f32_16x16x32_bf16 v[24:27], v[148:151], v[192:195], v[24:27]
	v_mfma_f32_16x16x32_bf16 v[12:15], v[128:131], v[200:203], v[12:15]
	v_mfma_f32_16x16x32_bf16 v[8:11], v[148:151], v[200:203], v[8:11]
	v_mfma_f32_16x16x32_bf16 v[60:63], v[144:147], v[180:183], v[60:63]
	v_mfma_f32_16x16x32_bf16 v[56:59], v[152:155], v[180:183], v[56:59]
	v_mfma_f32_16x16x32_bf16 v[44:47], v[144:147], v[188:191], v[44:47]
	v_mfma_f32_16x16x32_bf16 v[40:43], v[152:155], v[188:191], v[40:43]
	v_mfma_f32_16x16x32_bf16 v[28:31], v[144:147], v[196:199], v[28:31]
	v_mfma_f32_16x16x32_bf16 v[24:27], v[152:155], v[196:199], v[24:27]
	v_mfma_f32_16x16x32_bf16 v[12:15], v[144:147], v[214:217], v[12:15]
	v_mfma_f32_16x16x32_bf16 v[8:11], v[152:155], v[214:217], v[8:11]
	s_setprio 0
	s_setprio 1
	v_mfma_f32_16x16x32_bf16 v[52:55], v[156:159], v[176:179], v[52:55]
	v_mfma_f32_16x16x32_bf16 v[48:51], v[168:171], v[176:179], v[48:51]
	v_mfma_f32_16x16x32_bf16 v[36:39], v[156:159], v[184:187], v[36:39]
	v_mfma_f32_16x16x32_bf16 v[32:35], v[168:171], v[184:187], v[32:35]
	v_mfma_f32_16x16x32_bf16 v[20:23], v[156:159], v[192:195], v[20:23]
	v_mfma_f32_16x16x32_bf16 v[16:19], v[168:171], v[192:195], v[16:19]
	v_mfma_f32_16x16x32_bf16 v[4:7], v[156:159], v[200:203], v[4:7]
	v_mfma_f32_16x16x32_bf16 v[0:3], v[168:171], v[200:203], v[0:3]
	v_mfma_f32_16x16x32_bf16 v[52:55], v[160:163], v[180:183], v[52:55]
	v_mfma_f32_16x16x32_bf16 v[48:51], v[172:175], v[180:183], v[48:51]
	v_mfma_f32_16x16x32_bf16 v[36:39], v[160:163], v[188:191], v[36:39]
	v_mfma_f32_16x16x32_bf16 v[32:35], v[172:175], v[188:191], v[32:35]
	v_mfma_f32_16x16x32_bf16 v[20:23], v[160:163], v[196:199], v[20:23]
	v_mfma_f32_16x16x32_bf16 v[16:19], v[172:175], v[196:199], v[16:19]
	v_mfma_f32_16x16x32_bf16 v[4:7], v[160:163], v[214:217], v[4:7]
	v_mfma_f32_16x16x32_bf16 v[0:3], v[172:175], v[214:217], v[0:3]
	s_setprio 0
	s_barrier
	s_add_i32 s76, s76, 2
	s_add_u32 s44, s44, 0x100
	s_addc_u32 s45, s45, 0
	s_add_u32 vcc_lo, vcc_lo, 0x100
	s_addc_u32 vcc_hi, vcc_hi, 0

; template <class CF> __device__ __forceinline__ void pv_sm(f32x16* o, int vb, bf16x8 pa0, bf16x8 pa1, bf16x8 pa2, bf16x8 pa3, f32x16& p0, f32x16& p1, float& m_reg, float& mn, float& alpha) {
;     ...
;   if (__builtin_expect(__all(pmax - m_reg <= THR / CF::SCALE), 1)) { mn = m_reg; alpha = 1.f; }
;   else { mn = fmaxf(m_reg, pmax); alpha = __builtin_amdgcn_exp2f((m_reg - mn) * C); m_reg = mn; }
.Latt_rare_a1:
	v_max_f32_e32 v72, v238, v92
	v_sub_f32_e32 v73, v238, v72
	v_mul_f32_e32 v73, 0x3e0293ee, v73
	v_exp_f32_e32 v73, v73
	v_mov_b32_e32 v238, v72
	s_nop 0
	v_mov_b32_e32 v239, v73
	s_branch .Latt_back_a1
.Latt_rare_a2:
	v_max_f32_e32 v104, v238, v124
	v_sub_f32_e32 v105, v238, v104
	v_mul_f32_e32 v105, 0x3e0293ee, v105
	v_exp_f32_e32 v105, v105
	v_mov_b32_e32 v238, v104
	s_nop 0
	v_mov_b32_e32 v239, v105
	s_branch .Latt_back_a2

; #define ATT_SBAR() __builtin_amdgcn_sched_barrier(0)
; template <class CF> __device__ __forceinline__ void qk_sm(f32x16& n0, f32x16& n1, const char* Ks, const bf16x8* qr, int r32, int hi,
;                                                           f32x16& p0, f32x16& p1, float alpha, float& l_reg, bf16x8& pa0, bf16x8& pa1, bf16x8& pa2, bf16x8& pa3) {
;   n0 = f32x16{}; n1 = f32x16{};
;   const char* kr = Ks + r32 * CF::KPITCH; const int sw = (r32 & CF::KSWM) << 4;
;   bf16x8 ka[4], kb[4];
;     ...
;   ATT_QRD(ka, 0); ATT_QRD(kb, 1); asm volatile("s_waitcnt lgkmcnt(4)" ::: "memory"); ATT_SBAR();
;     ...
;   ATT_QRD(ka, 0); asm volatile("s_waitcnt lgkmcnt(0)" ::: "memory"); ATT_SBAR();
;     ...
;   ATT_QEARLY(kb, 1);
; #pragma unroll
;   for (int r = 0; r < 16; ++r) p1[r] = __builtin_amdgcn_exp2f(p1[r]);
;   asm volatile("" : "+v"(p1));
;   ATT_QMM(ka, 0);
;     ...
;   ATT_QRD(ka, 2); asm volatile("s_waitcnt lgkmcnt(4)" ::: "memory"); ATT_SBAR();
;     ...
;   asm volatile("s_waitcnt lgkmcnt(0)" ::: "memory"); ATT_SBAR();
;     ...
;   ATT_QEARLY(ka, 2);
;   float ps = 0;
; #pragma unroll
;   for (int r = 0; r < 16; ++r) ps += p0[r];
; #pragma unroll
;   for (int r = 0; r < 16; ++r) ps += p1[r];
;   asm volatile("" : "+v"(ps));
;   ATT_QMM(kb, 1);
;     ...
;   ATT_QRD(kb, 3); asm volatile("s_waitcnt lgkmcnt(4)" ::: "memory"); ATT_SBAR();
;     ...
;   asm volatile("s_waitcnt lgkmcnt(0)" ::: "memory"); ATT_SBAR();
;     ...
;   ATT_QEARLY(kb, 3);
;   { auto rr = __builtin_amdgcn_permlane32_swap(__float_as_uint(ps), __float_as_uint(ps), false, false);
;     ps = __uint_as_float(rr[0]) + __uint_as_float(rr[1]); }
;   l_reg = l_reg * alpha + ps;
;   ATT_PK4(p0, 0, pa0); ATT_PK4(p0, 8, pa1);
;   asm volatile("" : "+v"(l_reg), "+v"(pa0), "+v"(pa1));
;   ATT_QMM(ka, 2);
;   asm volatile("s_waitcnt lgkmcnt(0)" ::: "memory"); ATT_SBAR();
;   ATT_PK4(p1, 0, pa2); ATT_PK4(p1, 8, pa3);
;   asm volatile("" : "+v"(pa2), "+v"(pa3));
;   ATT_QMM(kb, 3);
; template <class CF> __device__ __forceinline__ void pv_sm(f32x16* o, int vb, bf16x8 pa0, bf16x8 pa1, bf16x8 pa2, bf16x8 pa3, f32x16& p0, f32x16& p1, float& m_reg, float& mn, float& alpha) {
;   constexpr float C = CF::SCALE * 1.4426950408889634f;
;   s16x4 f[8];
;   pv_reads<0>(vb, f);
;   float pmax = p0[0];
; #pragma unroll
;   for (int r = 1; r < 16; ++r) pmax = fmaxf(pmax, p0[r]);
;   asm volatile("" : "+v"(pmax));
;   pv_mfma4(o[0], f, pa0, pa1, pa2, pa3);
.LBB0_803:
	ds_read_b128 v[206:209], v229 offset:49152
	ds_read_b128 v[210:213], v229 offset:57344
	ds_read_b128 v[218:221], v236 offset:49152
	ds_read_b128 v[250:253], v236 offset:57344
	s_waitcnt lgkmcnt(3)
	v_mfma_f32_32x32x16_bf16 v[112:127], v[206:209], v[156:159], 0
	v_exp_f32_e32 v80, v80
	v_exp_f32_e32 v81, v81
	v_exp_f32_e32 v82, v82
	v_exp_f32_e32 v83, v83
	v_exp_f32_e32 v84, v84
	v_exp_f32_e32 v85, v85
	v_exp_f32_e32 v86, v86
	s_waitcnt lgkmcnt(2)
	v_mfma_f32_32x32x16_bf16 v[96:111], v[210:213], v[156:159], 0
	v_exp_f32_e32 v87, v87
	v_exp_f32_e32 v88, v88
	v_exp_f32_e32 v89, v89
	v_exp_f32_e32 v90, v90
	v_exp_f32_e32 v91, v91
	v_exp_f32_e32 v92, v92
	v_exp_f32_e32 v93, v93
	s_waitcnt lgkmcnt(0)
	v_mfma_f32_32x32x16_bf16 v[112:127], v[218:221], v[152:155], v[112:127]
	ds_read_b128 v[176:179], v231 offset:49152
	ds_read_b128 v[184:187], v231 offset:57344
	ds_read_b128 v[188:191], v232 offset:49152
	ds_read_b128 v[192:195], v232 offset:57344
	v_exp_f32_e32 v94, v94
	v_exp_f32_e32 v95, v95
	v_mfma_f32_32x32x16_bf16 v[96:111], v[250:253], v[152:155], v[96:111]
	v_add_f32_e32 v196, v65, v64
	v_add_f32_e32 v196, v66, v196
	v_add_f32_e32 v196, v67, v196
	v_add_f32_e32 v196, v68, v196
	v_add_f32_e32 v196, v69, v196
	v_add_f32_e32 v196, v70, v196
	v_add_f32_e32 v196, v71, v196
	v_add_f32_e32 v196, v72, v196
	v_add_f32_e32 v196, v73, v196
	v_add_f32_e32 v196, v74, v196
	v_add_f32_e32 v196, v75, v196
	s_waitcnt lgkmcnt(3)
	v_mfma_f32_32x32x16_bf16 v[112:127], v[176:179], v[148:151], v[112:127]
	v_add_f32_e32 v176, v76, v196
	v_add_f32_e32 v176, v77, v176
	v_add_f32_e32 v176, v78, v176
	v_add_f32_e32 v176, v79, v176
	v_add_f32_e32 v176, v176, v80
	v_add_f32_e32 v176, v81, v176
	v_add_f32_e32 v176, v82, v176
	s_waitcnt lgkmcnt(0)
	v_mfma_f32_32x32x16_bf16 v[96:111], v[184:187], v[148:151], v[96:111]
	v_add_f32_e32 v176, v83, v176
	v_add_f32_e32 v176, v84, v176
	v_add_f32_e32 v176, v85, v176
	v_add_f32_e32 v176, v86, v176
	v_add_f32_e32 v176, v87, v176
	v_add_f32_e32 v176, v88, v176
	v_add_f32_e32 v176, v89, v176
	v_add_f32_e32 v176, v90, v176
	v_mfma_f32_32x32x16_bf16 v[112:127], v[188:191], v[144:147], v[112:127]
	v_add_f32_e32 v176, v91, v176
	ds_read_b128 v[180:183], v233 offset:49152
	ds_read_b128 v[200:203], v233 offset:57344
	ds_read_b128 v[242:245], v234 offset:49152
	ds_read_b128 v[246:249], v234 offset:57344
	v_add_f32_e32 v176, v92, v176
	v_add_f32_e32 v176, v93, v176
	v_add_f32_e32 v176, v94, v176
	v_add_f32_e32 v196, v95, v176
	v_mfma_f32_32x32x16_bf16 v[96:111], v[192:195], v[144:147], v[96:111]
	s_waitcnt lgkmcnt(3)
	v_mfma_f32_32x32x16_bf16 v[112:127], v[180:183], v[140:143], v[112:127]
	v_mov_b32_e32 v192, v196
	s_nop 1
	v_permlane32_swap_b32_e32 v196, v192
	v_add_f32_e32 v241, v196, v192
	v_cvt_pk_bf16_f32 v196, v64, v65
	v_cvt_pk_bf16_f32 v197, v66, v67
	s_waitcnt lgkmcnt(0)
	v_mfma_f32_32x32x16_bf16 v[96:111], v[200:203], v[140:143], v[96:111]
	v_cvt_pk_bf16_f32 v198, v68, v69
	v_cvt_pk_bf16_f32 v199, v70, v71
	v_cvt_pk_bf16_f32 v192, v72, v73
	v_cvt_pk_bf16_f32 v193, v74, v75
	v_cvt_pk_bf16_f32 v194, v76, v77
	v_cvt_pk_bf16_f32 v195, v78, v79
	v_fmac_f32_e32 v241, v239, v240
	v_mfma_f32_32x32x16_bf16 v[112:127], v[242:245], v[136:139], v[112:127]
	ds_read_b128 v[176:179], v230 offset:49152
	ds_read_b128 v[184:187], v230 offset:57344
	ds_read_b128 v[188:191], v235 offset:49152
	ds_read_b128 v[250:253], v235 offset:57344
	v_permlane32_swap_b32_e32 v196, v198
	v_permlane32_swap_b32_e32 v197, v199
	v_permlane32_swap_b32_e32 v192, v194
	v_permlane32_swap_b32_e32 v193, v195
	v_mfma_f32_32x32x16_bf16 v[96:111], v[246:249], v[136:139], v[96:111]
	s_waitcnt lgkmcnt(3)
	v_mfma_f32_32x32x16_bf16 v[112:127], v[176:179], v[132:135], v[112:127]
	v_cvt_pk_bf16_f32 v200, v80, v81
	v_cvt_pk_bf16_f32 v201, v82, v83
	v_cvt_pk_bf16_f32 v202, v84, v85
	v_cvt_pk_bf16_f32 v203, v86, v87
	v_cvt_pk_bf16_f32 v80, v88, v89
	v_cvt_pk_bf16_f32 v81, v90, v91
	v_cvt_pk_bf16_f32 v82, v92, v93
	s_waitcnt lgkmcnt(0)
	v_mfma_f32_32x32x16_bf16 v[96:111], v[184:187], v[132:135], v[96:111]
	v_cvt_pk_bf16_f32 v83, v94, v95
	v_permlane32_swap_b32_e32 v200, v202
	v_permlane32_swap_b32_e32 v201, v203
	v_permlane32_swap_b32_e32 v80, v82
	v_mfma_f32_32x32x16_bf16 v[112:127], v[188:191], v[128:131], v[112:127]
	v_permlane32_swap_b32_e32 v81, v83
	v_mfma_f32_32x32x16_bf16 v[96:111], v[250:253], v[128:131], v[96:111]
	s_waitcnt vmcnt(0)
	s_mov_b32 s11, 0xfff70000
	v_add_co_u32_e32 v84, vcc, s11, v216
	s_mov_b32 s11, 0xfffa0000
	s_nop 0
	v_addc_co_u32_e32 v85, vcc, -1, v217, vcc
	v_add_co_u32_e32 v86, vcc, s11, v216
	s_nop 1
	v_addc_co_u32_e32 v87, vcc, -1, v217, vcc
	global_load_dwordx4 v[176:179], v[84:85], off
	global_load_dwordx4 v[180:183], v[84:85], off offset:-1024
	global_load_dwordx4 v[188:191], v[86:87], off
	global_load_dwordx4 v[184:187], v[86:87], off offset:-1024
	ds_read_b64_tr_b16 v[64:65], v224 offset:0
	ds_read_b64_tr_b16 v[66:67], v224 offset:0x800
	ds_read_b64_tr_b16 v[68:69], v224 offset:0x1000
	ds_read_b64_tr_b16 v[70:71], v224 offset:0x1800
	ds_read_b64_tr_b16 v[72:73], v224 offset:0x2000
	ds_read_b64_tr_b16 v[74:75], v224 offset:0x2800
	ds_read_b64_tr_b16 v[76:77], v224 offset:0x3000
	ds_read_b64_tr_b16 v[78:79], v224 offset:0x3800
	s_waitcnt lgkmcnt(6)
	v_mfma_f32_32x32x16_bf16 v[0:15], v[196:199], v[64:67], v[0:15]
	ds_write_b128 v228, v[168:171] offset:32768
	v_max_f32_e32 v84, v112, v113
	v_max3_f32 v84, v84, v114, v115
	v_max3_f32 v84, v84, v116, v117
	v_max3_f32 v84, v84, v118, v119
	v_max3_f32 v84, v84, v120, v121
	s_waitcnt lgkmcnt(5)
; template <class CF> __device__ __forceinline__ void pv_sm(f32x16* o, int vb, bf16x8 pa0, bf16x8 pa1, bf16x8 pa2, bf16x8 pa3, f32x16& p0, f32x16& p1, float& m_reg, float& mn, float& alpha) {
;   constexpr float C = CF::SCALE * 1.4426950408889634f;
;   s16x4 f[8];
;   pv_reads<0>(vb, f);
;   float pmax = p0[0];
; #pragma unroll
;   for (int r = 1; r < 16; ++r) pmax = fmaxf(pmax, p0[r]);
;   asm volatile("" : "+v"(pmax));
;   pv_mfma4(o[0], f, pa0, pa1, pa2, pa3);
;   pv_reads<1>(vb, f);
; #pragma unroll
;   for (int r = 0; r < 16; ++r) pmax = fmaxf(pmax, p1[r]);
;   { auto rr = __builtin_amdgcn_permlane32_swap(__float_as_uint(pmax), __float_as_uint(pmax), false, false);
;     pmax = fmaxf(__uint_as_float(rr[0]), __uint_as_float(rr[1])); }
;   asm volatile("" : "+v"(pmax));
;   pv_mfma4(o[1], f, pa0, pa1, pa2, pa3);
;   pv_reads<2>(vb, f);
;   if (__builtin_expect(__all(pmax - m_reg <= THR / CF::SCALE), 1)) { mn = m_reg; alpha = 1.f; }
;   else { mn = fmaxf(m_reg, pmax); alpha = __builtin_amdgcn_exp2f((m_reg - mn) * C); m_reg = mn; }
;   const float mnC = -mn * C;
; #pragma unroll
;   for (int r = 0; r < 16; ++r) p0[r] = fmaf(p0[r], C, mnC);
; #pragma unroll
;   for (int r = 0; r < 16; ++r) p1[r] = fmaf(p1[r], C, mnC);
;   asm volatile("" : "+v"(p0), "+v"(p1));
;   pv_mfma4(o[2], f, pa0, pa1, pa2, pa3);
;   pv_reads<3>(vb, f);
; #pragma unroll
;   for (int r = 0; r < 16; ++r) p0[r] = __builtin_amdgcn_exp2f(p0[r]);
;   asm volatile("" : "+v"(p0));
;   pv_mfma4(o[3], f, pa0, pa1, pa2, pa3);
	v_mfma_f32_32x32x16_bf16 v[0:15], v[192:195], v[68:71], v[0:15]
	ds_write_b128 v228, v[172:175] offset:40960
	v_max3_f32 v84, v84, v122, v123
	v_max3_f32 v84, v84, v124, v125
	v_max3_f32 v84, v84, v126, v127
	ds_read_b64_tr_b16 v[64:65], v224 offset:0x200
	ds_read_b64_tr_b16 v[66:67], v224 offset:0xa00
	ds_read_b64_tr_b16 v[68:69], v224 offset:0x1200
	s_waitcnt lgkmcnt(5)
	v_mfma_f32_32x32x16_bf16 v[0:15], v[200:203], v[72:75], v[0:15]
	ds_read_b64_tr_b16 v[70:71], v224 offset:0x1a00
	ds_read_b64_tr_b16 v[72:73], v224 offset:0x2200
	ds_read_b64_tr_b16 v[74:75], v224 offset:0x2a00
	v_mfma_f32_32x32x16_bf16 v[0:15], v[80:83], v[76:79], v[0:15]
	ds_read_b64_tr_b16 v[76:77], v224 offset:0x3200
	ds_read_b64_tr_b16 v[78:79], v224 offset:0x3a00
	s_waitcnt lgkmcnt(5)
	v_mfma_f32_32x32x16_bf16 v[48:63], v[196:199], v[64:67], v[48:63]
	v_max3_f32 v84, v84, v96, v97
	v_max3_f32 v84, v84, v98, v99
	v_max3_f32 v84, v84, v100, v101
	v_max3_f32 v84, v84, v102, v103
	v_max3_f32 v84, v84, v104, v105
	v_max3_f32 v84, v84, v106, v107
	v_max3_f32 v84, v84, v108, v109
	s_waitcnt lgkmcnt(2)
	v_mfma_f32_32x32x16_bf16 v[48:63], v[192:195], v[68:71], v[48:63]
	v_max3_f32 v84, v84, v110, v111
	v_mov_b32_e32 v85, v84
	s_nop 1
	v_permlane32_swap_b32_e32 v84, v85
	v_max_f32_e32 v92, v84, v85
	v_mfma_f32_32x32x16_bf16 v[48:63], v[200:203], v[72:75], v[48:63]
	ds_read_b64_tr_b16 v[64:65], v224 offset:0x400
	ds_read_b64_tr_b16 v[66:67], v224 offset:0xc00
	ds_read_b64_tr_b16 v[68:69], v224 offset:0x1400
	ds_read_b64_tr_b16 v[70:71], v224 offset:0x1c00
	ds_read_b64_tr_b16 v[84:85], v224 offset:0x2400
	ds_read_b64_tr_b16 v[86:87], v224 offset:0x2c00
	s_waitcnt lgkmcnt(6)
	v_mfma_f32_32x32x16_bf16 v[48:63], v[80:83], v[76:79], v[48:63]
	ds_read_b64_tr_b16 v[88:89], v224 offset:0x3400
	ds_read_b64_tr_b16 v[90:91], v224 offset:0x3c00
	s_waitcnt lgkmcnt(6)
	v_mfma_f32_32x32x16_bf16 v[32:47], v[196:199], v[64:67], v[32:47]
	v_sub_f32_e32 v72, v92, v238
	v_cmp_ge_f32_e32 vcc, s66, v72
	s_waitcnt lgkmcnt(2)
	v_mfma_f32_32x32x16_bf16 v[32:47], v[192:195], v[68:71], v[32:47]
	ds_read_b64_tr_b16 v[206:207], v224 offset:0x600
	ds_read_b64_tr_b16 v[208:209], v224 offset:0xe00
	ds_read_b64_tr_b16 v[210:211], v224 offset:0x1600
	ds_read_b64_tr_b16 v[212:213], v224 offset:0x1e00
	s_cmp_eq_u64 vcc, exec
	s_cbranch_scc0 .Latt_rare_a1
	v_mov_b32_e32 v239, 1.0
.Latt_back_a1:
	v_mul_f32_e32 v92, 0xbe0293ee, v238
	v_pk_fma_f32 v[78:79], v[126:127], s[74:75], v[92:93] op_sel_hi:[1,0,0]
	v_mfma_f32_32x32x16_bf16 v[32:47], v[200:203], v[84:87], v[32:47]
	ds_read_b64_tr_b16 v[218:219], v224 offset:0x2600
	ds_read_b64_tr_b16 v[220:221], v224 offset:0x2e00
	ds_read_b64_tr_b16 v[246:247], v224 offset:0x3600
	ds_read_b64_tr_b16 v[248:249], v224 offset:0x3e00
	v_fma_f32 v76, v124, s74, v92
	v_fma_f32 v77, v125, s74, v92
	v_fma_f32 v74, v122, s74, v92
	v_fma_f32 v75, v123, s74, v92
	v_fma_f32 v72, v120, s74, v92
	v_fma_f32 v73, v121, s74, v92
	v_pk_fma_f32 v[70:71], v[118:119], s[74:75], v[92:93] op_sel_hi:[1,0,0]
	v_pk_fma_f32 v[68:69], v[116:117], s[74:75], v[92:93] op_sel_hi:[1,0,0]
	v_pk_fma_f32 v[66:67], v[114:115], s[74:75], v[92:93] op_sel_hi:[1,0,0]
	v_pk_fma_f32 v[64:65], v[112:113], s[74:75], v[92:93] op_sel_hi:[1,0,0]
	v_pk_fma_f32 v[126:127], v[110:111], s[74:75], v[92:93] op_sel_hi:[1,0,0]
	v_pk_fma_f32 v[124:125], v[108:109], s[74:75], v[92:93] op_sel_hi:[1,0,0]
	v_pk_fma_f32 v[122:123], v[106:107], s[74:75], v[92:93] op_sel_hi:[1,0,0]
	v_pk_fma_f32 v[120:121], v[104:105], s[74:75], v[92:93] op_sel_hi:[1,0,0]
	v_pk_fma_f32 v[118:119], v[102:103], s[74:75], v[92:93] op_sel_hi:[1,0,0]
	v_pk_fma_f32 v[116:117], v[100:101], s[74:75], v[92:93] op_sel_hi:[1,0,0]
	v_pk_fma_f32 v[114:115], v[98:99], s[74:75], v[92:93] op_sel_hi:[1,0,0]
	v_pk_fma_f32 v[112:113], v[96:97], s[74:75], v[92:93] op_sel_hi:[1,0,0]
	s_waitcnt lgkmcnt(8)
	v_mfma_f32_32x32x16_bf16 v[32:47], v[80:83], v[88:91], v[32:47]
	s_waitcnt lgkmcnt(0)
	s_barrier
	v_mfma_f32_32x32x16_bf16 v[16:31], v[196:199], v[206:209], v[16:31]
	ds_write_b128 v226, v[160:163]
	v_exp_f32_e32 v96, v64
	v_exp_f32_e32 v97, v65
	v_exp_f32_e32 v98, v66
	v_exp_f32_e32 v99, v67
	v_exp_f32_e32 v100, v68
	v_exp_f32_e32 v101, v69
	v_exp_f32_e32 v102, v70
	v_mfma_f32_32x32x16_bf16 v[16:31], v[192:195], v[210:213], v[16:31]
	ds_write_b128 v227, v[164:167]
	v_exp_f32_e32 v103, v71
	v_exp_f32_e32 v104, v72
	v_exp_f32_e32 v105, v73
	v_exp_f32_e32 v106, v74
	v_exp_f32_e32 v107, v75
	v_exp_f32_e32 v108, v76
	v_exp_f32_e32 v109, v77
	v_mfma_f32_32x32x16_bf16 v[16:31], v[200:203], v[218:221], v[16:31]
	v_exp_f32_e32 v110, v78
	v_exp_f32_e32 v111, v79
	v_mfma_f32_32x32x16_bf16 v[16:31], v[80:83], v[246:249], v[16:31]
	v_cmp_gt_f32_e32 vcc, 1.0, v239
	s_cbranch_vccz .LBB0_807
	s_and_saveexec_b64 s[12:13], s[4:5]
	ds_write_b32 v237, v239 offset:128
	s_or_b64 exec, exec, s[12:13]
	s_waitcnt lgkmcnt(0)
	v_add_u32_e32 v76, v223, v204
	ds_read_b128 v[64:67], v76 offset:224
	ds_read_b128 v[68:71], v76 offset:192
	ds_read_b128 v[72:75], v76 offset:160
	ds_read_b128 v[76:79], v76 offset:128
	s_waitcnt lgkmcnt(3)
	v_pk_mul_f32 v[12:13], v[12:13], v[64:65]
	s_waitcnt lgkmcnt(2)
	v_pk_mul_f32 v[8:9], v[8:9], v[68:69]
	s_waitcnt lgkmcnt(1)
	v_pk_mul_f32 v[4:5], v[4:5], v[72:73]
	v_pk_mul_f32 v[14:15], v[14:15], v[66:67]
	v_pk_mul_f32 v[10:11], v[10:11], v[70:71]
	v_pk_mul_f32 v[6:7], v[6:7], v[74:75]
	s_waitcnt lgkmcnt(0)
	v_pk_mul_f32 v[2:3], v[2:3], v[78:79]
	v_pk_mul_f32 v[0:1], v[0:1], v[76:77]
	v_pk_mul_f32 v[60:61], v[60:61], v[64:65]
	v_pk_mul_f32 v[56:57], v[56:57], v[68:69]
	v_pk_mul_f32 v[52:53], v[52:53], v[72:73]
	v_pk_mul_f32 v[62:63], v[62:63], v[66:67]
	v_pk_mul_f32 v[58:59], v[58:59], v[70:71]
	v_pk_mul_f32 v[54:55], v[54:55], v[74:75]
	v_pk_mul_f32 v[50:51], v[50:51], v[78:79]
	v_pk_mul_f32 v[48:49], v[48:49], v[76:77]
	v_pk_mul_f32 v[44:45], v[44:45], v[64:65]
	v_pk_mul_f32 v[40:41], v[40:41], v[68:69]
	v_pk_mul_f32 v[36:37], v[36:37], v[72:73]
	v_pk_mul_f32 v[46:47], v[46:47], v[66:67]
	v_pk_mul_f32 v[42:43], v[42:43], v[70:71]
	v_pk_mul_f32 v[38:39], v[38:39], v[74:75]
	v_pk_mul_f32 v[34:35], v[34:35], v[78:79]
	v_pk_mul_f32 v[32:33], v[32:33], v[76:77]
	v_pk_mul_f32 v[28:29], v[28:29], v[64:65]
	v_pk_mul_f32 v[24:25], v[24:25], v[68:69]
	v_pk_mul_f32 v[20:21], v[20:21], v[72:73]
	v_pk_mul_f32 v[30:31], v[30:31], v[66:67]
	v_pk_mul_f32 v[26:27], v[26:27], v[70:71]
	v_pk_mul_f32 v[22:23], v[22:23], v[74:75]
	v_pk_mul_f32 v[18:19], v[18:19], v[78:79]
	v_pk_mul_f32 v[16:17], v[16:17], v[76:77]
; #define ATT_SBAR() __builtin_amdgcn_sched_barrier(0)
; #define ATT_QRD(dst, g) do { _Pragma("unroll") for (int t = 0; t < 2; ++t) { const int cb = ((2 * (g) + t) * 16 + hi * 8) * 2; \
;     dst[2 * t] = *reinterpret_cast<const bf16x8*>(kr + (cb ^ sw)); dst[2 * t + 1] = *reinterpret_cast<const bf16x8*>(kr + 32 * CF::KPITCH + (cb ^ sw)); } } while (0)
; #define ATT_QEARLY(dst, g) do { } while (0)
; #define ATT_QEARLY(dst, g) ATT_QRD(dst, g)
; template <class CF> __device__ __forceinline__ void qk_sm(f32x16& n0, f32x16& n1, const char* Ks, const bf16x8* qr, int r32, int hi,
;                                                           f32x16& p0, f32x16& p1, float alpha, float& l_reg, bf16x8& pa0, bf16x8& pa1, bf16x8& pa2, bf16x8& pa3) {
;   n0 = f32x16{}; n1 = f32x16{};
;   const char* kr = Ks + r32 * CF::KPITCH; const int sw = (r32 & CF::KSWM) << 4;
;   bf16x8 ka[4], kb[4];
;     ...
;   ATT_QRD(ka, 0); ATT_QRD(kb, 1); asm volatile("s_waitcnt lgkmcnt(4)" ::: "memory"); ATT_SBAR();
;     ...
;   ATT_QRD(ka, 0); asm volatile("s_waitcnt lgkmcnt(0)" ::: "memory"); ATT_SBAR();
;     ...
;   ATT_QEARLY(kb, 1);
; #pragma unroll
;   for (int r = 0; r < 16; ++r) p1[r] = __builtin_amdgcn_exp2f(p1[r]);
;   asm volatile("" : "+v"(p1));
;   ATT_QMM(ka, 0);
;     ...
;   ATT_QRD(ka, 2); asm volatile("s_waitcnt lgkmcnt(4)" ::: "memory"); ATT_SBAR();
;     ...
;   asm volatile("s_waitcnt lgkmcnt(0)" ::: "memory"); ATT_SBAR();
;     ...
;   ATT_QEARLY(ka, 2);
;   float ps = 0;
; #pragma unroll
;   for (int r = 0; r < 16; ++r) ps += p0[r];
; #pragma unroll
;   for (int r = 0; r < 16; ++r) ps += p1[r];
;   asm volatile("" : "+v"(ps));
;   ATT_QMM(kb, 1);
;     ...
;   ATT_QRD(kb, 3); asm volatile("s_waitcnt lgkmcnt(4)" ::: "memory"); ATT_SBAR();
;     ...
;   asm volatile("s_waitcnt lgkmcnt(0)" ::: "memory"); ATT_SBAR();
;     ...
;   ATT_QEARLY(kb, 3);
;   { auto rr = __builtin_amdgcn_permlane32_swap(__float_as_uint(ps), __float_as_uint(ps), false, false);
;     ps = __uint_as_float(rr[0]) + __uint_as_float(rr[1]); }
;   l_reg = l_reg * alpha + ps;
;   ATT_PK4(p0, 0, pa0); ATT_PK4(p0, 8, pa1);
;   asm volatile("" : "+v"(l_reg), "+v"(pa0), "+v"(pa1));
;   ATT_QMM(ka, 2);
;   asm volatile("s_waitcnt lgkmcnt(0)" ::: "memory"); ATT_SBAR();
;   ATT_PK4(p1, 0, pa2); ATT_PK4(p1, 8, pa3);
;   asm volatile("" : "+v"(pa2), "+v"(pa3));
;   ATT_QMM(kb, 3);
;     ...
;     if (SDEPTH == 1 || j + 3 < NT) ATT_SLOAD(SE, (j + 1 + SDEPTH) * KVBLK); ATT_SBAR();
.LBB0_807:
	ds_read_b128 v[206:209], v229 offset:32768
	ds_read_b128 v[210:213], v229 offset:40960
	ds_read_b128 v[218:221], v236 offset:32768
	ds_read_b128 v[250:253], v236 offset:40960
	s_waitcnt lgkmcnt(3)
	v_mfma_f32_32x32x16_bf16 v[80:95], v[206:209], v[156:159], 0
	v_exp_f32_e32 v112, v112
	v_exp_f32_e32 v113, v113
	v_exp_f32_e32 v114, v114
	v_exp_f32_e32 v115, v115
	v_exp_f32_e32 v116, v116
	v_exp_f32_e32 v117, v117
	v_exp_f32_e32 v118, v118
	s_waitcnt lgkmcnt(2)
	v_mfma_f32_32x32x16_bf16 v[64:79], v[210:213], v[156:159], 0
	v_exp_f32_e32 v119, v119
	v_exp_f32_e32 v120, v120
	v_exp_f32_e32 v121, v121
	v_exp_f32_e32 v122, v122
	v_exp_f32_e32 v123, v123
	v_exp_f32_e32 v124, v124
	v_exp_f32_e32 v125, v125
	s_waitcnt lgkmcnt(0)
	v_mfma_f32_32x32x16_bf16 v[80:95], v[218:221], v[152:155], v[80:95]
	ds_read_b128 v[192:195], v231 offset:32768
	ds_read_b128 v[200:203], v231 offset:40960
	ds_read_b128 v[242:245], v232 offset:32768
	ds_read_b128 v[246:249], v232 offset:40960
	v_exp_f32_e32 v126, v126
	v_exp_f32_e32 v127, v127
	v_mfma_f32_32x32x16_bf16 v[64:79], v[250:253], v[152:155], v[64:79]
	v_add_f32_e32 v218, v97, v96
	v_add_f32_e32 v218, v98, v218
	v_add_f32_e32 v218, v99, v218
	v_add_f32_e32 v218, v100, v218
	v_add_f32_e32 v218, v101, v218
	v_add_f32_e32 v218, v102, v218
	v_add_f32_e32 v218, v103, v218
	v_add_f32_e32 v218, v104, v218
	v_add_f32_e32 v218, v105, v218
	v_add_f32_e32 v218, v106, v218
	v_add_f32_e32 v218, v107, v218
	s_waitcnt lgkmcnt(3)
	v_mfma_f32_32x32x16_bf16 v[80:95], v[192:195], v[148:151], v[80:95]
	v_add_f32_e32 v192, v108, v218
	v_add_f32_e32 v192, v109, v192
	v_add_f32_e32 v192, v110, v192
	v_add_f32_e32 v192, v111, v192
	v_add_f32_e32 v192, v192, v112
	v_add_f32_e32 v192, v113, v192
	v_add_f32_e32 v192, v114, v192
	s_waitcnt lgkmcnt(0)
	v_mfma_f32_32x32x16_bf16 v[64:79], v[200:203], v[148:151], v[64:79]
	v_add_f32_e32 v192, v115, v192
	v_add_f32_e32 v192, v116, v192
	v_add_f32_e32 v192, v117, v192
	v_add_f32_e32 v192, v118, v192
	v_add_f32_e32 v192, v119, v192
	v_add_f32_e32 v192, v120, v192
	v_add_f32_e32 v192, v121, v192
	v_add_f32_e32 v192, v122, v192
	v_mfma_f32_32x32x16_bf16 v[80:95], v[242:245], v[144:147], v[80:95]
	v_add_f32_e32 v192, v123, v192
	ds_read_b128 v[196:199], v233 offset:32768
	ds_read_b128 v[250:253], v233 offset:40960
	ds_read_b128 v[210:213], v234 offset:32768
	ds_read_b128 v[206:209], v234 offset:40960
	v_add_f32_e32 v192, v124, v192
	v_add_f32_e32 v192, v125, v192
	v_add_f32_e32 v192, v126, v192
	v_add_f32_e32 v192, v127, v192
	v_mfma_f32_32x32x16_bf16 v[64:79], v[246:249], v[144:147], v[64:79]
	s_waitcnt lgkmcnt(3)
	v_mfma_f32_32x32x16_bf16 v[80:95], v[196:199], v[140:143], v[80:95]
	v_mov_b32_e32 v193, v192
	s_nop 1
	v_permlane32_swap_b32_e32 v192, v193
	v_add_f32_e32 v240, v192, v193
	v_cvt_pk_bf16_f32 v196, v96, v97
	v_cvt_pk_bf16_f32 v197, v98, v99
	s_waitcnt lgkmcnt(0)
	v_mfma_f32_32x32x16_bf16 v[64:79], v[250:253], v[140:143], v[64:79]
	v_cvt_pk_bf16_f32 v198, v100, v101
	v_cvt_pk_bf16_f32 v199, v102, v103
	v_cvt_pk_bf16_f32 v192, v104, v105
	v_cvt_pk_bf16_f32 v193, v106, v107
	v_cvt_pk_bf16_f32 v194, v108, v109
	v_cvt_pk_bf16_f32 v195, v110, v111
	v_fmac_f32_e32 v240, v241, v239
	v_mfma_f32_32x32x16_bf16 v[80:95], v[210:213], v[136:139], v[80:95]
	ds_read_b128 v[200:203], v230 offset:32768
	ds_read_b128 v[242:245], v230 offset:40960
	ds_read_b128 v[246:249], v235 offset:32768
	ds_read_b128 v[218:221], v235 offset:40960
	v_permlane32_swap_b32_e32 v196, v198
	v_permlane32_swap_b32_e32 v197, v199
	v_permlane32_swap_b32_e32 v192, v194
	v_permlane32_swap_b32_e32 v193, v195
	v_mfma_f32_32x32x16_bf16 v[64:79], v[206:209], v[136:139], v[64:79]
	s_waitcnt lgkmcnt(3)
	v_mfma_f32_32x32x16_bf16 v[80:95], v[200:203], v[132:135], v[80:95]
	v_cvt_pk_bf16_f32 v200, v112, v113
	v_cvt_pk_bf16_f32 v201, v114, v115
	v_cvt_pk_bf16_f32 v202, v116, v117
	v_cvt_pk_bf16_f32 v203, v118, v119
	v_cvt_pk_bf16_f32 v112, v120, v121
	v_cvt_pk_bf16_f32 v113, v122, v123
	v_cvt_pk_bf16_f32 v114, v124, v125
	s_waitcnt lgkmcnt(0)
	v_mfma_f32_32x32x16_bf16 v[64:79], v[242:245], v[132:135], v[64:79]
	v_cvt_pk_bf16_f32 v115, v126, v127
	v_permlane32_swap_b32_e32 v200, v202
	v_permlane32_swap_b32_e32 v201, v203
	v_permlane32_swap_b32_e32 v112, v114
	v_mfma_f32_32x32x16_bf16 v[80:95], v[246:249], v[128:131], v[80:95]
	v_permlane32_swap_b32_e32 v113, v115
	v_mfma_f32_32x32x16_bf16 v[64:79], v[218:221], v[128:131], v[64:79]
	s_waitcnt vmcnt(0)
	s_add_i32 s10, s10, 2
	s_cmp_ge_u32 s10, s0
	s_cselect_b64 s[12:13], -1, 0
	s_and_b64 vcc, exec, s[12:13]
	s_cbranch_vccnz .LBB0_809
	v_add_co_u32_e32 v116, vcc, 0xfffd0000, v216
	s_nop 1
	v_addc_co_u32_e32 v117, vcc, -1, v217, vcc
	global_load_dwordx4 v[160:163], v[116:117], off
	global_load_dwordx4 v[168:171], v[116:117], off offset:-1024
	global_load_dwordx4 v[164:167], v[216:217], off
	global_load_dwordx4 v[172:175], v[216:217], off offset:-1024
; template <class CF> __device__ __forceinline__ void pv_sm(f32x16* o, int vb, bf16x8 pa0, bf16x8 pa1, bf16x8 pa2, bf16x8 pa3, f32x16& p0, f32x16& p1, float& m_reg, float& mn, float& alpha) {
;   constexpr float C = CF::SCALE * 1.4426950408889634f;
;   s16x4 f[8];
;   pv_reads<0>(vb, f);
;   float pmax = p0[0];
; #pragma unroll
;   for (int r = 1; r < 16; ++r) pmax = fmaxf(pmax, p0[r]);
;   asm volatile("" : "+v"(pmax));
;   pv_mfma4(o[0], f, pa0, pa1, pa2, pa3);
;   pv_reads<1>(vb, f);
; #pragma unroll
;   for (int r = 0; r < 16; ++r) pmax = fmaxf(pmax, p1[r]);
;   { auto rr = __builtin_amdgcn_permlane32_swap(__float_as_uint(pmax), __float_as_uint(pmax), false, false);
;     pmax = fmaxf(__uint_as_float(rr[0]), __uint_as_float(rr[1])); }
;   asm volatile("" : "+v"(pmax));
;   pv_mfma4(o[1], f, pa0, pa1, pa2, pa3);
;   pv_reads<2>(vb, f);
;   if (__builtin_expect(__all(pmax - m_reg <= THR / CF::SCALE), 1)) { mn = m_reg; alpha = 1.f; }
;   else { mn = fmaxf(m_reg, pmax); alpha = __builtin_amdgcn_exp2f((m_reg - mn) * C); m_reg = mn; }
;   const float mnC = -mn * C;
; #pragma unroll
;   for (int r = 0; r < 16; ++r) p0[r] = fmaf(p0[r], C, mnC);
; #pragma unroll
;   for (int r = 0; r < 16; ++r) p1[r] = fmaf(p1[r], C, mnC);
;   asm volatile("" : "+v"(p0), "+v"(p1));
;   pv_mfma4(o[2], f, pa0, pa1, pa2, pa3);
;   pv_reads<3>(vb, f);
; #pragma unroll
;   for (int r = 0; r < 16; ++r) p0[r] = __builtin_amdgcn_exp2f(p0[r]);
;   asm volatile("" : "+v"(p0));
;   pv_mfma4(o[3], f, pa0, pa1, pa2, pa3);
.LBB0_809:
	ds_read_b64_tr_b16 v[96:97], v225 offset:0
	ds_read_b64_tr_b16 v[98:99], v225 offset:0x800
	ds_read_b64_tr_b16 v[100:101], v225 offset:0x1000
	ds_read_b64_tr_b16 v[102:103], v225 offset:0x1800
	ds_read_b64_tr_b16 v[104:105], v225 offset:0x2000
	ds_read_b64_tr_b16 v[106:107], v225 offset:0x2800
	ds_read_b64_tr_b16 v[108:109], v225 offset:0x3000
	ds_read_b64_tr_b16 v[110:111], v225 offset:0x3800
	s_waitcnt lgkmcnt(6)
	v_mfma_f32_32x32x16_bf16 v[0:15], v[196:199], v[96:99], v[0:15]
	ds_write_b128 v228, v[180:183] offset:49152
	s_nop 1
	v_max_f32_e32 v116, v80, v81
	v_max3_f32 v116, v116, v82, v83
	v_max3_f32 v116, v116, v84, v85
	v_max3_f32 v116, v116, v86, v87
	v_max3_f32 v116, v116, v88, v89
	s_waitcnt lgkmcnt(5)
	v_mfma_f32_32x32x16_bf16 v[0:15], v[192:195], v[100:103], v[0:15]
	ds_write_b128 v228, v[184:187] offset:57344
	v_max3_f32 v116, v116, v90, v91
	v_max3_f32 v116, v116, v92, v93
	v_max3_f32 v116, v116, v94, v95
	ds_read_b64_tr_b16 v[96:97], v225 offset:0x200
	ds_read_b64_tr_b16 v[98:99], v225 offset:0xa00
	ds_read_b64_tr_b16 v[100:101], v225 offset:0x1200
	s_waitcnt lgkmcnt(5)
	v_mfma_f32_32x32x16_bf16 v[0:15], v[200:203], v[104:107], v[0:15]
	ds_read_b64_tr_b16 v[102:103], v225 offset:0x1a00
	ds_read_b64_tr_b16 v[104:105], v225 offset:0x2200
	ds_read_b64_tr_b16 v[106:107], v225 offset:0x2a00
	v_mfma_f32_32x32x16_bf16 v[0:15], v[112:115], v[108:111], v[0:15]
	ds_read_b64_tr_b16 v[108:109], v225 offset:0x3200
	ds_read_b64_tr_b16 v[110:111], v225 offset:0x3a00
	s_waitcnt lgkmcnt(5)
	v_mfma_f32_32x32x16_bf16 v[48:63], v[196:199], v[96:99], v[48:63]
	v_max3_f32 v116, v116, v64, v65
	v_max3_f32 v116, v116, v66, v67
	v_max3_f32 v116, v116, v68, v69
	v_max3_f32 v116, v116, v70, v71
	v_max3_f32 v116, v116, v72, v73
	v_max3_f32 v116, v116, v74, v75
	v_max3_f32 v116, v116, v76, v77
	s_waitcnt lgkmcnt(2)
	v_mfma_f32_32x32x16_bf16 v[48:63], v[192:195], v[100:103], v[48:63]
	v_max3_f32 v116, v116, v78, v79
	v_mov_b32_e32 v117, v116
	s_nop 1
	v_permlane32_swap_b32_e32 v116, v117
	v_max_f32_e32 v124, v116, v117
	v_mfma_f32_32x32x16_bf16 v[48:63], v[200:203], v[104:107], v[48:63]
	ds_read_b64_tr_b16 v[96:97], v225 offset:0x400
	ds_read_b64_tr_b16 v[98:99], v225 offset:0xc00
	ds_read_b64_tr_b16 v[100:101], v225 offset:0x1400
	ds_read_b64_tr_b16 v[102:103], v225 offset:0x1c00
	ds_read_b64_tr_b16 v[116:117], v225 offset:0x2400
	ds_read_b64_tr_b16 v[118:119], v225 offset:0x2c00
	s_waitcnt lgkmcnt(6)
	v_mfma_f32_32x32x16_bf16 v[48:63], v[112:115], v[108:111], v[48:63]
	ds_read_b64_tr_b16 v[120:121], v225 offset:0x3400
	ds_read_b64_tr_b16 v[122:123], v225 offset:0x3c00
	s_waitcnt lgkmcnt(6)
	v_mfma_f32_32x32x16_bf16 v[32:47], v[196:199], v[96:99], v[32:47]
	v_sub_f32_e32 v104, v124, v238
	v_cmp_ge_f32_e32 vcc, s66, v104
	s_waitcnt lgkmcnt(2)
	v_mfma_f32_32x32x16_bf16 v[32:47], v[192:195], v[100:103], v[32:47]
	ds_read_b64_tr_b16 v[206:207], v225 offset:0x600
	ds_read_b64_tr_b16 v[208:209], v225 offset:0xe00
	ds_read_b64_tr_b16 v[210:211], v225 offset:0x1600
	ds_read_b64_tr_b16 v[212:213], v225 offset:0x1e00
	s_cmp_eq_u64 vcc, exec
	s_cbranch_scc0 .Latt_rare_a2
	v_mov_b32_e32 v239, 1.0
.Latt_back_a2:
	v_mul_f32_e32 v124, 0xbe0293ee, v238
	v_pk_fma_f32 v[110:111], v[94:95], s[74:75], v[124:125] op_sel_hi:[1,0,0]
	v_mfma_f32_32x32x16_bf16 v[32:47], v[200:203], v[116:119], v[32:47]
	ds_read_b64_tr_b16 v[218:219], v225 offset:0x2600
	ds_read_b64_tr_b16 v[220:221], v225 offset:0x2e00
	ds_read_b64_tr_b16 v[246:247], v225 offset:0x3600
	ds_read_b64_tr_b16 v[248:249], v225 offset:0x3e00
	v_fma_f32 v108, v92, s74, v124
	v_fma_f32 v109, v93, s74, v124
	v_fma_f32 v106, v90, s74, v124
	v_fma_f32 v107, v91, s74, v124
	v_fma_f32 v104, v88, s74, v124
	v_fma_f32 v105, v89, s74, v124
	v_pk_fma_f32 v[102:103], v[86:87], s[74:75], v[124:125] op_sel_hi:[1,0,0]
	v_pk_fma_f32 v[100:101], v[84:85], s[74:75], v[124:125] op_sel_hi:[1,0,0]
	v_pk_fma_f32 v[98:99], v[82:83], s[74:75], v[124:125] op_sel_hi:[1,0,0]
	v_pk_fma_f32 v[96:97], v[80:81], s[74:75], v[124:125] op_sel_hi:[1,0,0]
	v_pk_fma_f32 v[94:95], v[78:79], s[74:75], v[124:125] op_sel_hi:[1,0,0]
	v_pk_fma_f32 v[92:93], v[76:77], s[74:75], v[124:125] op_sel_hi:[1,0,0]
	v_pk_fma_f32 v[90:91], v[74:75], s[74:75], v[124:125] op_sel_hi:[1,0,0]
	v_pk_fma_f32 v[88:89], v[72:73], s[74:75], v[124:125] op_sel_hi:[1,0,0]
	v_pk_fma_f32 v[86:87], v[70:71], s[74:75], v[124:125] op_sel_hi:[1,0,0]
	v_pk_fma_f32 v[84:85], v[68:69], s[74:75], v[124:125] op_sel_hi:[1,0,0]
	v_pk_fma_f32 v[82:83], v[66:67], s[74:75], v[124:125] op_sel_hi:[1,0,0]
	v_pk_fma_f32 v[80:81], v[64:65], s[74:75], v[124:125] op_sel_hi:[1,0,0]
	s_waitcnt lgkmcnt(8)
	v_mfma_f32_32x32x16_bf16 v[32:47], v[112:115], v[120:123], v[32:47]
	s_waitcnt lgkmcnt(0)
	s_barrier
	v_mfma_f32_32x32x16_bf16 v[16:31], v[196:199], v[206:209], v[16:31]
	ds_write_b128 v226, v[176:179] offset:16384
	v_exp_f32_e32 v64, v96
	v_exp_f32_e32 v65, v97
	v_exp_f32_e32 v66, v98
	v_exp_f32_e32 v67, v99
	v_exp_f32_e32 v68, v100
	v_exp_f32_e32 v69, v101
	v_exp_f32_e32 v70, v102
	v_mfma_f32_32x32x16_bf16 v[16:31], v[192:195], v[210:213], v[16:31]
	ds_write_b128 v227, v[188:191] offset:16384
	v_exp_f32_e32 v71, v103
	v_exp_f32_e32 v72, v104
	v_exp_f32_e32 v73, v105
	v_exp_f32_e32 v74, v106
	v_exp_f32_e32 v75, v107
	v_exp_f32_e32 v76, v108
	v_exp_f32_e32 v77, v109
	v_mfma_f32_32x32x16_bf16 v[16:31], v[200:203], v[218:221], v[16:31]
	v_exp_f32_e32 v78, v110
	v_exp_f32_e32 v79, v111
	v_mfma_f32_32x32x16_bf16 v[16:31], v[112:115], v[246:249], v[16:31]
	v_cmp_gt_f32_e32 vcc, 1.0, v239
	s_cbranch_vccz .LBB0_802
	s_and_saveexec_b64 s[14:15], s[4:5]
	s_cbranch_execz .LBB0_801
	ds_write_b32 v237, v239 offset:128
	s_branch .LBB0_801

; #define PG8_STAGE(bufoff, gbase, voff) do { _Pragma("unroll") for (int _i = 0; _i < 2; ++_i) \
;         __builtin_amdgcn_global_load_lds((const unsigned*)((const char*)(gbase) + (voff)[_i]), (PG8_LAS unsigned*)(lds + (bufoff) + ldsw + _i * 8192), 16, 0, 0); } while (0)
; #define PG8_LDA(dst, b, h) do { _Pragma("unroll") for (int m = 0; m < 4; ++m) _Pragma("unroll") for (int k = 0; k < 2; ++k) dst[m][k] = *(const PG8_LAS bf16x8*)(lds + PG8_SA(b, h) + aoff + m * 2048 + k * 1024); } while (0)
; #define PG8_LDB(dst, b, h) do { _Pragma("unroll") for (int n = 0; n < 2; ++n) _Pragma("unroll") for (int k = 0; k < 2; ++k) dst[n][k] = *(const PG8_LAS bf16x8*)(lds + PG8_SB(b, h) + boff + n * 2048 + k * 1024); } while (0)
; #define PG8_WAIT_V(n) asm volatile("s_waitcnt vmcnt(" #n ")" ::: "memory")
; #define PG8_WAIT_L(n) asm volatile("s_waitcnt lgkmcnt(" #n ")" ::: "memory")
; #define PG8_BAR __builtin_amdgcn_s_barrier()
; #define PG8_SCHED __builtin_amdgcn_sched_barrier(0)
; template <class Epi, class Sched, bool ALIGN_EPI = false, bool SP2 = false>
; __device__ __forceinline__ void gemm_phase(PG8_LAS unsigned char* lds, const Gemm g, const Sched& S, const Epi& E, const int tid) {
;     ...
;         const bool has_next = S.next(ui + 1, nxt);
;         const char* nA = has_next ? (const char*)g.A + (size_t)nxt.pm * tstep : cA; const char* nB = has_next ? (const char*)g.Bt + (size_t)nxt.pn * tstep : cB;
;         for (int t = 0; t < nt; t += 2) {
;             const bool last = (t == nt - 2);
;             const char* a1 = cA + (size_t)(t + 1) * kstep;
;             const char* a2 = last ? nA : cA + (size_t)(t + 2) * kstep; const char* b2 = last ? nB : cB + (size_t)(t + 2) * kstep;
;             const char* a3 = a2 + kstep; const char* b3 = b2 + kstep;
;             if (last && has_next) S.a_ready(nxt);
;             if constexpr (SP2) {
;             PG8_LDB(B0, 0, 0); PG8_LDB(B1, 0, 1); PG8_SCHED; PG8_LDA(At, 0, 0); PG8_STAGE(PG8_SA(1, 1), a1 + hstep, voffA);
;             PG8_WAIT_V(8); PG8_WAIT_L(0); PG8_BAR; PG8_MMA(0, 0, At, B0); PG8_MMA(0, 1, At, B1); PG8_BAR; PG8_SCHED;
;             PG8_LDA(At, 0, 1); PG8_STAGE(PG8_SB(0, 0), b2, voffB); PG8_STAGE(PG8_SB(0, 1), b2 + hstep, voffB); PG8_STAGE(PG8_SA(0, 0), a2, voffA);
;             PG8_WAIT_V(8); PG8_WAIT_L(0); PG8_BAR; PG8_MMA(1, 0, At, B0); PG8_MMA(1, 1, At, B1); PG8_BAR; PG8_SCHED;
.LBB0_1087:
	s_ashr_i32 s19, s18, 31
	s_lshl_b64 s[20:21], s[18:19], 20
	s_add_u32 s20, s11, s20
	s_addc_u32 s21, s33, s21
	s_and_b64 s[22:23], s[4:5], exec
	s_cselect_b32 s19, s21, s27
	s_cselect_b32 s50, s20, s26
	s_ashr_i32 s17, s16, 31
	s_lshl_b64 s[22:23], s[16:17], 20
	s_add_u32 s22, s34, s22
	s_addc_u32 s23, s35, s23
	s_and_b64 s[30:31], s[4:5], exec
	s_cselect_b32 s17, s23, s29
	s_cselect_b32 s51, s22, s28
	s_add_u32 s26, s26, 0x80080
	s_addc_u32 s27, s27, 0
	s_add_u32 s52, s28, 0x100
	s_addc_u32 s53, s29, 0
	s_mov_b32 s54, -2
	s_add_u32 s28, s26, 0xfff80080
	s_addc_u32 s29, s27, -1
	s_add_i32 s55, 0, 0x10000
	s_cmp_eq_u32 s54, 28
	s_cselect_b32 s31, s19, s29
	s_cselect_b32 s30, s50, s28
	v_add_u32_e32 v138, s55, v139
	s_cselect_b32 s29, s17, s53
	s_cselect_b32 s28, s51, s52
	s_add_i32 s62, 0, 0x14000
	ds_read_b128 v[144:147], v138
	ds_read_b128 v[148:151], v138 offset:1024
	ds_read_b128 v[152:155], v138 offset:2048
	ds_read_b128 v[156:159], v138 offset:3072
	v_add_u32_e32 v138, s62, v139
	ds_read_b128 v[160:163], v138
	ds_read_b128 v[164:167], v138 offset:1024
	ds_read_b128 v[168:171], v138 offset:2048
	ds_read_b128 v[172:175], v138 offset:3072
	v_lshl_add_u64 v[140:141], s[26:27], 0, v[134:135]
	s_add_i32 m0, s37, 0xc000
	ds_read_b128 v[176:179], v143
	ds_read_b128 v[180:183], v143 offset:1024
	ds_read_b128 v[184:187], v143 offset:2048
	ds_read_b128 v[188:191], v143 offset:3072
	ds_read_b128 v[192:195], v143 offset:4096
	ds_read_b128 v[196:199], v143 offset:5120
	ds_read_b128 v[200:203], v143 offset:6144
	ds_read_b128 v[206:209], v143 offset:7168
	global_load_lds_dwordx4 v[140:141], off
	v_lshl_add_u64 v[140:141], s[26:27], 0, v[136:137]
	s_add_i32 m0, s37, 0xe000
	s_nop 0
	global_load_lds_dwordx4 v[140:141], off
	s_waitcnt vmcnt(24)
	s_waitcnt lgkmcnt(0)
	s_barrier
	s_setprio 1
	s_waitcnt lgkmcnt(0)
	v_mfma_f32_16x16x32_bf16 v[124:127], v[144:147], v[176:179], 0
	v_mfma_f32_16x16x32_bf16 v[120:123], v[152:155], v[176:179], 0
	v_mfma_f32_16x16x32_bf16 v[108:111], v[144:147], v[184:187], 0
	v_mfma_f32_16x16x32_bf16 v[104:107], v[152:155], v[184:187], 0
	v_mfma_f32_16x16x32_bf16 v[92:95], v[144:147], v[192:195], 0
	v_mfma_f32_16x16x32_bf16 v[88:91], v[152:155], v[192:195], 0
	v_mfma_f32_16x16x32_bf16 v[76:79], v[144:147], v[200:203], 0
	v_mfma_f32_16x16x32_bf16 v[72:75], v[152:155], v[200:203], 0
	v_mfma_f32_16x16x32_bf16 v[124:127], v[148:151], v[180:183], v[124:127]
	v_mfma_f32_16x16x32_bf16 v[120:123], v[156:159], v[180:183], v[120:123]
	v_mfma_f32_16x16x32_bf16 v[108:111], v[148:151], v[188:191], v[108:111]
	v_mfma_f32_16x16x32_bf16 v[104:107], v[156:159], v[188:191], v[104:107]
	v_mfma_f32_16x16x32_bf16 v[92:95], v[148:151], v[196:199], v[92:95]
	v_mfma_f32_16x16x32_bf16 v[88:91], v[156:159], v[196:199], v[88:91]
	v_mfma_f32_16x16x32_bf16 v[76:79], v[148:151], v[206:209], v[76:79]
	v_mfma_f32_16x16x32_bf16 v[72:75], v[156:159], v[206:209], v[72:75]
	s_setprio 0
	s_setprio 1
	v_mfma_f32_16x16x32_bf16 v[116:119], v[160:163], v[176:179], 0
	v_mfma_f32_16x16x32_bf16 v[112:115], v[168:171], v[176:179], 0
	v_mfma_f32_16x16x32_bf16 v[100:103], v[160:163], v[184:187], 0
	v_mfma_f32_16x16x32_bf16 v[96:99], v[168:171], v[184:187], 0
	v_mfma_f32_16x16x32_bf16 v[84:87], v[160:163], v[192:195], 0
	v_mfma_f32_16x16x32_bf16 v[80:83], v[168:171], v[192:195], 0
	v_mfma_f32_16x16x32_bf16 v[68:71], v[160:163], v[200:203], 0
	v_mfma_f32_16x16x32_bf16 v[64:67], v[168:171], v[200:203], 0
	v_mfma_f32_16x16x32_bf16 v[116:119], v[164:167], v[180:183], v[116:119]
	v_mfma_f32_16x16x32_bf16 v[112:115], v[172:175], v[180:183], v[112:115]
	v_mfma_f32_16x16x32_bf16 v[100:103], v[164:167], v[188:191], v[100:103]
	v_mfma_f32_16x16x32_bf16 v[96:99], v[172:175], v[188:191], v[96:99]
	v_mfma_f32_16x16x32_bf16 v[84:87], v[164:167], v[196:199], v[84:87]
	v_mfma_f32_16x16x32_bf16 v[80:83], v[172:175], v[196:199], v[80:83]
	v_mfma_f32_16x16x32_bf16 v[68:71], v[164:167], v[206:209], v[68:71]
	v_mfma_f32_16x16x32_bf16 v[64:67], v[172:175], v[206:209], v[64:67]
	s_setprio 0
	s_barrier
	s_add_i32 s55, s55, s36
	v_lshl_add_u64 v[140:141], s[28:29], 0, v[204:205]
	s_mov_b32 m0, s55
	ds_read_b128 v[176:179], v143 offset:16384
	ds_read_b128 v[180:183], v143 offset:17408
	ds_read_b128 v[184:187], v143 offset:18432
	ds_read_b128 v[188:191], v143 offset:19456
	ds_read_b128 v[192:195], v143 offset:20480
	ds_read_b128 v[196:199], v143 offset:21504
	ds_read_b128 v[200:203], v143 offset:22528
	ds_read_b128 v[206:209], v143 offset:23552
	global_load_lds_dwordx4 v[140:141], off
	s_add_i32 m0, s55, 0x2000
	s_add_u32 s64, s28, 0x80000
	v_lshl_add_u64 v[210:211], s[28:29], 0, v[132:133]
	s_addc_u32 s65, s29, 0
	s_add_i32 s55, s62, s36
	global_load_lds_dwordx4 v[210:211], off
	v_lshl_add_u64 v[212:213], s[64:65], 0, v[204:205]
	s_mov_b32 m0, s55
	v_lshl_add_u64 v[214:215], s[30:31], 0, v[130:131]
	global_load_lds_dwordx4 v[212:213], off
	v_lshl_add_u64 v[212:213], s[64:65], 0, v[132:133]
	s_add_i32 m0, s55, 0x2000
	s_nop 0
	global_load_lds_dwordx4 v[212:213], off
	v_lshl_add_u64 v[212:213], s[30:31], 0, v[128:129]
	s_mov_b32 m0, s37
	s_nop 0
	global_load_lds_dwordx4 v[212:213], off
	s_mov_b32 m0, s38
	s_nop 0
	global_load_lds_dwordx4 v[214:215], off
	s_waitcnt vmcnt(8)
	s_waitcnt lgkmcnt(0)
	s_barrier
; #define PG8_STAGE(bufoff, gbase, voff) do { _Pragma("unroll") for (int _i = 0; _i < 2; ++_i) \
;         __builtin_amdgcn_global_load_lds((const unsigned*)((const char*)(gbase) + (voff)[_i]), (PG8_LAS unsigned*)(lds + (bufoff) + ldsw + _i * 8192), 16, 0, 0); } while (0)
; #define PG8_LDA(dst, b, h) do { _Pragma("unroll") for (int m = 0; m < 4; ++m) _Pragma("unroll") for (int k = 0; k < 2; ++k) dst[m][k] = *(const PG8_LAS bf16x8*)(lds + PG8_SA(b, h) + aoff + m * 2048 + k * 1024); } while (0)
; #define PG8_LDB(dst, b, h) do { _Pragma("unroll") for (int n = 0; n < 2; ++n) _Pragma("unroll") for (int k = 0; k < 2; ++k) dst[n][k] = *(const PG8_LAS bf16x8*)(lds + PG8_SB(b, h) + boff + n * 2048 + k * 1024); } while (0)
; #define PG8_MMA(ai, bj, At, Bt) do { __builtin_amdgcn_s_setprio(1); _Pragma("unroll") for (int m = 0; m < 4; ++m) _Pragma("unroll") for (int n = 0; n < 2; ++n) _Pragma("unroll") for (int k = 0; k < 2; ++k) \
;         acc[ai][bj][m][n] = __builtin_amdgcn_mfma_f32_16x16x32_bf16(Bt[n][k], At[m][k], acc[ai][bj][m][n], 0, 0, 0); __builtin_amdgcn_s_setprio(0); } while (0)
; #define PG8_WAIT_V(n) asm volatile("s_waitcnt vmcnt(" #n ")" ::: "memory")
; #define PG8_WAIT_L(n) asm volatile("s_waitcnt lgkmcnt(" #n ")" ::: "memory")
; #define PG8_BAR __builtin_amdgcn_s_barrier()
; #define PG8_SCHED __builtin_amdgcn_sched_barrier(0)
; template <class Epi, class Sched, bool ALIGN_EPI = false, bool SP2 = false>
; __device__ __forceinline__ void gemm_phase(PG8_LAS unsigned char* lds, const Gemm g, const Sched& S, const Epi& E, const int tid) {
;     ...
;             PG8_WAIT_V(8); PG8_WAIT_L(0); PG8_BAR; PG8_MMA(0, 0, At, B0); PG8_MMA(0, 1, At, B1); PG8_BAR; PG8_SCHED;
;             PG8_LDA(At, 0, 1); PG8_STAGE(PG8_SB(0, 0), b2, voffB); PG8_STAGE(PG8_SB(0, 1), b2 + hstep, voffB); PG8_STAGE(PG8_SA(0, 0), a2, voffA);
;             PG8_WAIT_V(8); PG8_WAIT_L(0); PG8_BAR; PG8_MMA(1, 0, At, B0); PG8_MMA(1, 1, At, B1); PG8_BAR; PG8_SCHED;
;             PG8_LDB(B0, 1, 0); PG8_LDB(B1, 1, 1); PG8_SCHED; PG8_LDA(At, 1, 0); PG8_STAGE(PG8_SA(0, 1), a2 + hstep, voffA);
;             PG8_WAIT_V(8); PG8_WAIT_L(0); PG8_BAR; PG8_MMA(0, 0, At, B0); PG8_MMA(0, 1, At, B1); PG8_BAR; PG8_SCHED;
;             PG8_LDA(At, 1, 1); PG8_STAGE(PG8_SB(1, 0), b3, voffB); PG8_STAGE(PG8_SB(1, 1), b3 + hstep, voffB); PG8_STAGE(PG8_SA(1, 0), a3, voffA);
	s_setprio 1
	s_waitcnt lgkmcnt(0)
	v_mfma_f32_16x16x32_bf16 v[60:63], v[144:147], v[176:179], 0
	v_mfma_f32_16x16x32_bf16 v[56:59], v[152:155], v[176:179], 0
	v_mfma_f32_16x16x32_bf16 v[44:47], v[144:147], v[184:187], 0
	v_mfma_f32_16x16x32_bf16 v[40:43], v[152:155], v[184:187], 0
	v_mfma_f32_16x16x32_bf16 v[28:31], v[144:147], v[192:195], 0
	v_mfma_f32_16x16x32_bf16 v[24:27], v[152:155], v[192:195], 0
	v_mfma_f32_16x16x32_bf16 v[12:15], v[144:147], v[200:203], 0
	v_mfma_f32_16x16x32_bf16 v[8:11], v[152:155], v[200:203], 0
	v_mfma_f32_16x16x32_bf16 v[60:63], v[148:151], v[180:183], v[60:63]
	v_mfma_f32_16x16x32_bf16 v[56:59], v[156:159], v[180:183], v[56:59]
	v_mfma_f32_16x16x32_bf16 v[44:47], v[148:151], v[188:191], v[44:47]
	v_mfma_f32_16x16x32_bf16 v[40:43], v[156:159], v[188:191], v[40:43]
	v_mfma_f32_16x16x32_bf16 v[28:31], v[148:151], v[196:199], v[28:31]
	v_mfma_f32_16x16x32_bf16 v[24:27], v[156:159], v[196:199], v[24:27]
	v_mfma_f32_16x16x32_bf16 v[12:15], v[148:151], v[206:209], v[12:15]
	v_mfma_f32_16x16x32_bf16 v[8:11], v[156:159], v[206:209], v[8:11]
	s_setprio 0
	s_setprio 1
	v_mfma_f32_16x16x32_bf16 v[52:55], v[160:163], v[176:179], 0
	v_mfma_f32_16x16x32_bf16 v[48:51], v[168:171], v[176:179], 0
	v_mfma_f32_16x16x32_bf16 v[36:39], v[160:163], v[184:187], 0
	v_mfma_f32_16x16x32_bf16 v[32:35], v[168:171], v[184:187], 0
	v_mfma_f32_16x16x32_bf16 v[20:23], v[160:163], v[192:195], 0
	v_mfma_f32_16x16x32_bf16 v[16:19], v[168:171], v[192:195], 0
	v_mfma_f32_16x16x32_bf16 v[4:7], v[160:163], v[200:203], 0
	v_mfma_f32_16x16x32_bf16 v[0:3], v[168:171], v[200:203], 0
	v_mfma_f32_16x16x32_bf16 v[52:55], v[164:167], v[180:183], v[52:55]
	v_mfma_f32_16x16x32_bf16 v[48:51], v[172:175], v[180:183], v[48:51]
	v_mfma_f32_16x16x32_bf16 v[36:39], v[164:167], v[188:191], v[36:39]
	v_mfma_f32_16x16x32_bf16 v[32:35], v[172:175], v[188:191], v[32:35]
	v_mfma_f32_16x16x32_bf16 v[20:23], v[164:167], v[196:199], v[20:23]
	v_mfma_f32_16x16x32_bf16 v[16:19], v[172:175], v[196:199], v[16:19]
	v_mfma_f32_16x16x32_bf16 v[4:7], v[164:167], v[206:209], v[4:7]
	v_mfma_f32_16x16x32_bf16 v[0:3], v[172:175], v[206:209], v[0:3]
	s_setprio 0
	s_barrier
	s_add_i32 s55, 0, 0x18000
	v_add_u32_e32 v138, s55, v139
	s_add_i32 s62, 0, 0x1c000
	ds_read_b128 v[144:147], v138
	ds_read_b128 v[148:151], v138 offset:1024
	ds_read_b128 v[152:155], v138 offset:2048
	ds_read_b128 v[156:159], v138 offset:3072
	v_add_u32_e32 v138, s62, v139
	ds_read_b128 v[160:163], v138
	ds_read_b128 v[164:167], v138 offset:1024
	ds_read_b128 v[168:171], v138 offset:2048
	ds_read_b128 v[172:175], v138 offset:3072
	s_add_u32 s30, s30, 0x80000
	s_addc_u32 s31, s31, 0
	s_mov_b32 m0, s40
	v_lshl_add_u64 v[216:217], s[30:31], 0, v[128:129]
	ds_read_b128 v[176:179], v143 offset:32768
	ds_read_b128 v[180:183], v143 offset:33792
	ds_read_b128 v[184:187], v143 offset:34816
	ds_read_b128 v[188:191], v143 offset:35840
	ds_read_b128 v[192:195], v143 offset:36864
	ds_read_b128 v[196:199], v143 offset:37888
	ds_read_b128 v[200:203], v143 offset:38912
	ds_read_b128 v[206:209], v143 offset:39936
	global_load_lds_dwordx4 v[216:217], off
	v_lshl_add_u64 v[216:217], s[30:31], 0, v[130:131]
	s_mov_b32 m0, s42
	s_nop 0
	global_load_lds_dwordx4 v[216:217], off
	s_waitcnt vmcnt(8)
	s_waitcnt lgkmcnt(0)
	s_barrier
	s_setprio 1
	s_waitcnt lgkmcnt(0)
	v_mfma_f32_16x16x32_bf16 v[124:127], v[144:147], v[176:179], v[124:127]
	v_mfma_f32_16x16x32_bf16 v[120:123], v[152:155], v[176:179], v[120:123]
	v_mfma_f32_16x16x32_bf16 v[108:111], v[144:147], v[184:187], v[108:111]
	v_mfma_f32_16x16x32_bf16 v[104:107], v[152:155], v[184:187], v[104:107]
	v_mfma_f32_16x16x32_bf16 v[92:95], v[144:147], v[192:195], v[92:95]
	v_mfma_f32_16x16x32_bf16 v[88:91], v[152:155], v[192:195], v[88:91]
	v_mfma_f32_16x16x32_bf16 v[76:79], v[144:147], v[200:203], v[76:79]
	v_mfma_f32_16x16x32_bf16 v[72:75], v[152:155], v[200:203], v[72:75]
	v_mfma_f32_16x16x32_bf16 v[124:127], v[148:151], v[180:183], v[124:127]
	v_mfma_f32_16x16x32_bf16 v[120:123], v[156:159], v[180:183], v[120:123]
	v_mfma_f32_16x16x32_bf16 v[108:111], v[148:151], v[188:191], v[108:111]
	v_mfma_f32_16x16x32_bf16 v[104:107], v[156:159], v[188:191], v[104:107]
	v_mfma_f32_16x16x32_bf16 v[92:95], v[148:151], v[196:199], v[92:95]
	v_mfma_f32_16x16x32_bf16 v[88:91], v[156:159], v[196:199], v[88:91]
	v_mfma_f32_16x16x32_bf16 v[76:79], v[148:151], v[206:209], v[76:79]
	v_mfma_f32_16x16x32_bf16 v[72:75], v[156:159], v[206:209], v[72:75]
	s_setprio 0
	s_setprio 1
	v_mfma_f32_16x16x32_bf16 v[116:119], v[160:163], v[176:179], v[116:119]
	v_mfma_f32_16x16x32_bf16 v[112:115], v[168:171], v[176:179], v[112:115]
	v_mfma_f32_16x16x32_bf16 v[100:103], v[160:163], v[184:187], v[100:103]
	v_mfma_f32_16x16x32_bf16 v[96:99], v[168:171], v[184:187], v[96:99]
	v_mfma_f32_16x16x32_bf16 v[84:87], v[160:163], v[192:195], v[84:87]
	v_mfma_f32_16x16x32_bf16 v[80:83], v[168:171], v[192:195], v[80:83]
	v_mfma_f32_16x16x32_bf16 v[68:71], v[160:163], v[200:203], v[68:71]
	v_mfma_f32_16x16x32_bf16 v[64:67], v[168:171], v[200:203], v[64:67]
	v_mfma_f32_16x16x32_bf16 v[116:119], v[164:167], v[180:183], v[116:119]
	v_mfma_f32_16x16x32_bf16 v[112:115], v[172:175], v[180:183], v[112:115]
	v_mfma_f32_16x16x32_bf16 v[100:103], v[164:167], v[188:191], v[100:103]
	v_mfma_f32_16x16x32_bf16 v[96:99], v[172:175], v[188:191], v[96:99]
	v_mfma_f32_16x16x32_bf16 v[84:87], v[164:167], v[196:199], v[84:87]
	v_mfma_f32_16x16x32_bf16 v[80:83], v[172:175], v[196:199], v[80:83]
	v_mfma_f32_16x16x32_bf16 v[68:71], v[164:167], v[206:209], v[68:71]
	v_mfma_f32_16x16x32_bf16 v[64:67], v[172:175], v[206:209], v[64:67]
	s_setprio 0
	s_barrier
; #define PG8_STAGE(bufoff, gbase, voff) do { _Pragma("unroll") for (int _i = 0; _i < 2; ++_i) \
;         __builtin_amdgcn_global_load_lds((const unsigned*)((const char*)(gbase) + (voff)[_i]), (PG8_LAS unsigned*)(lds + (bufoff) + ldsw + _i * 8192), 16, 0, 0); } while (0)
; #define PG8_LDA(dst, b, h) do { _Pragma("unroll") for (int m = 0; m < 4; ++m) _Pragma("unroll") for (int k = 0; k < 2; ++k) dst[m][k] = *(const PG8_LAS bf16x8*)(lds + PG8_SA(b, h) + aoff + m * 2048 + k * 1024); } while (0)
; #define PG8_LDB(dst, b, h) do { _Pragma("unroll") for (int n = 0; n < 2; ++n) _Pragma("unroll") for (int k = 0; k < 2; ++k) dst[n][k] = *(const PG8_LAS bf16x8*)(lds + PG8_SB(b, h) + boff + n * 2048 + k * 1024); } while (0)
; #define PG8_MMA(ai, bj, At, Bt) do { __builtin_amdgcn_s_setprio(1); _Pragma("unroll") for (int m = 0; m < 4; ++m) _Pragma("unroll") for (int n = 0; n < 2; ++n) _Pragma("unroll") for (int k = 0; k < 2; ++k) \
;         acc[ai][bj][m][n] = __builtin_amdgcn_mfma_f32_16x16x32_bf16(Bt[n][k], At[m][k], acc[ai][bj][m][n], 0, 0, 0); __builtin_amdgcn_s_setprio(0); } while (0)
; #define PG8_BAR __builtin_amdgcn_s_barrier()
; template <class Epi, class Sched, bool ALIGN_EPI = false, bool SP2 = false>
; __device__ __forceinline__ void gemm_phase(PG8_LAS unsigned char* lds, const Gemm g, const Sched& S, const Epi& E, const int tid) {
;     ...
;             PG8_LDB(B0, 0, 0); PG8_LDB(B1, 0, 1); PG8_SCHED; PG8_LDA(At, 0, 0); PG8_STAGE(PG8_SA(1, 1), a1 + hstep, voffA);
;             PG8_WAIT_V(8); PG8_WAIT_L(0); PG8_BAR; PG8_MMA(0, 0, At, B0); PG8_MMA(0, 1, At, B1); PG8_BAR; PG8_SCHED;
;             PG8_LDA(At, 0, 1); PG8_STAGE(PG8_SB(0, 0), b2, voffB); PG8_STAGE(PG8_SB(0, 1), b2 + hstep, voffB); PG8_STAGE(PG8_SA(0, 0), a2, voffA);
;             PG8_WAIT_V(8); PG8_WAIT_L(0); PG8_BAR; PG8_MMA(1, 0, At, B0); PG8_MMA(1, 1, At, B1); PG8_BAR; PG8_SCHED;
;             PG8_LDB(B0, 1, 0); PG8_LDB(B1, 1, 1); PG8_SCHED; PG8_LDA(At, 1, 0); PG8_STAGE(PG8_SA(0, 1), a2 + hstep, voffA);
;             PG8_WAIT_V(8); PG8_WAIT_L(0); PG8_BAR; PG8_MMA(0, 0, At, B0); PG8_MMA(0, 1, At, B1); PG8_BAR; PG8_SCHED;
;             PG8_LDA(At, 1, 1); PG8_STAGE(PG8_SB(1, 0), b3, voffB); PG8_STAGE(PG8_SB(1, 1), b3 + hstep, voffB); PG8_STAGE(PG8_SA(1, 0), a3, voffA);
;             PG8_WAIT_V(8); PG8_WAIT_L(0); PG8_BAR; PG8_MMA(1, 0, At, B0); PG8_MMA(1, 1, At, B1); PG8_BAR; PG8_SCHED;
	s_add_i32 s30, s55, s36
	v_lshl_add_u64 v[140:141], v[140:141], 0, s[70:71]
	s_mov_b32 m0, s30
	ds_read_b128 v[176:179], v143 offset:49152
	ds_read_b128 v[180:183], v143 offset:50176
	ds_read_b128 v[184:187], v143 offset:51200
	ds_read_b128 v[188:191], v143 offset:52224
	ds_read_b128 v[192:195], v143 offset:53248
	ds_read_b128 v[196:199], v143 offset:54272
	ds_read_b128 v[200:203], v143 offset:55296
	ds_read_b128 v[206:209], v143 offset:56320
	global_load_lds_dwordx4 v[140:141], off
	s_add_i32 m0, s30, 0x2000
	s_add_u32 s28, s28, 0x80080
	v_lshl_add_u64 v[140:141], v[210:211], 0, s[70:71]
	s_addc_u32 s29, s29, 0
	s_add_i32 s30, s62, s36
	global_load_lds_dwordx4 v[140:141], off
	v_lshl_add_u64 v[140:141], s[28:29], 0, v[204:205]
	s_mov_b32 m0, s30
	s_nop 0
	global_load_lds_dwordx4 v[140:141], off
	v_lshl_add_u64 v[140:141], s[28:29], 0, v[132:133]
	s_add_i32 m0, s30, 0x2000
	s_nop 0
	global_load_lds_dwordx4 v[140:141], off
	v_lshl_add_u64 v[140:141], v[212:213], 0, s[70:71]
	s_mov_b32 m0, s46
	s_nop 0
	global_load_lds_dwordx4 v[140:141], off
	v_lshl_add_u64 v[140:141], v[214:215], 0, s[70:71]
	s_mov_b32 m0, s47
	s_nop 0
	global_load_lds_dwordx4 v[140:141], off
	s_waitcnt vmcnt(8)
	s_waitcnt lgkmcnt(0)
	s_barrier
	s_setprio 1
	s_waitcnt lgkmcnt(0)
	v_mfma_f32_16x16x32_bf16 v[60:63], v[144:147], v[176:179], v[60:63]
	v_mfma_f32_16x16x32_bf16 v[56:59], v[152:155], v[176:179], v[56:59]
	v_mfma_f32_16x16x32_bf16 v[44:47], v[144:147], v[184:187], v[44:47]
	v_mfma_f32_16x16x32_bf16 v[40:43], v[152:155], v[184:187], v[40:43]
	v_mfma_f32_16x16x32_bf16 v[28:31], v[144:147], v[192:195], v[28:31]
	v_mfma_f32_16x16x32_bf16 v[24:27], v[152:155], v[192:195], v[24:27]
	v_mfma_f32_16x16x32_bf16 v[12:15], v[144:147], v[200:203], v[12:15]
	v_mfma_f32_16x16x32_bf16 v[8:11], v[152:155], v[200:203], v[8:11]
	v_mfma_f32_16x16x32_bf16 v[60:63], v[148:151], v[180:183], v[60:63]
	v_mfma_f32_16x16x32_bf16 v[56:59], v[156:159], v[180:183], v[56:59]
	v_mfma_f32_16x16x32_bf16 v[44:47], v[148:151], v[188:191], v[44:47]
	v_mfma_f32_16x16x32_bf16 v[40:43], v[156:159], v[188:191], v[40:43]
	v_mfma_f32_16x16x32_bf16 v[28:31], v[148:151], v[196:199], v[28:31]
	v_mfma_f32_16x16x32_bf16 v[24:27], v[156:159], v[196:199], v[24:27]
	v_mfma_f32_16x16x32_bf16 v[12:15], v[148:151], v[206:209], v[12:15]
	v_mfma_f32_16x16x32_bf16 v[8:11], v[156:159], v[206:209], v[8:11]
	s_setprio 0
	s_setprio 1
	v_mfma_f32_16x16x32_bf16 v[52:55], v[160:163], v[176:179], v[52:55]
	v_mfma_f32_16x16x32_bf16 v[48:51], v[168:171], v[176:179], v[48:51]
	v_mfma_f32_16x16x32_bf16 v[36:39], v[160:163], v[184:187], v[36:39]
	v_mfma_f32_16x16x32_bf16 v[32:35], v[168:171], v[184:187], v[32:35]
	v_mfma_f32_16x16x32_bf16 v[20:23], v[160:163], v[192:195], v[20:23]
	v_mfma_f32_16x16x32_bf16 v[16:19], v[168:171], v[192:195], v[16:19]
	v_mfma_f32_16x16x32_bf16 v[4:7], v[160:163], v[200:203], v[4:7]
	v_mfma_f32_16x16x32_bf16 v[0:3], v[168:171], v[200:203], v[0:3]
	v_mfma_f32_16x16x32_bf16 v[52:55], v[164:167], v[180:183], v[52:55]
	v_mfma_f32_16x16x32_bf16 v[48:51], v[172:175], v[180:183], v[48:51]
	v_mfma_f32_16x16x32_bf16 v[36:39], v[164:167], v[188:191], v[36:39]
	v_mfma_f32_16x16x32_bf16 v[32:35], v[172:175], v[188:191], v[32:35]
	v_mfma_f32_16x16x32_bf16 v[20:23], v[164:167], v[196:199], v[20:23]
	v_mfma_f32_16x16x32_bf16 v[16:19], v[172:175], v[196:199], v[16:19]
	v_mfma_f32_16x16x32_bf16 v[4:7], v[164:167], v[206:209], v[4:7]
	v_mfma_f32_16x16x32_bf16 v[0:3], v[172:175], v[206:209], v[0:3]
	s_setprio 0
	s_barrier
	s_add_i32 s54, s54, 2
	s_add_u32 s26, s26, 0x100
	s_addc_u32 s27, s27, 0
	s_add_u32 s52, s52, 0x100
	s_addc_u32 s53, s53, 0

; #define PG8_STAGE(bufoff, gbase, voff) do { _Pragma("unroll") for (int _i = 0; _i < 2; ++_i) \
;         __builtin_amdgcn_global_load_lds((const unsigned*)((const char*)(gbase) + (voff)[_i]), (PG8_LAS unsigned*)(lds + (bufoff) + ldsw + _i * 8192), 16, 0, 0); } while (0)
; #define PG8_LDA(dst, b, h) do { _Pragma("unroll") for (int m = 0; m < 4; ++m) _Pragma("unroll") for (int k = 0; k < 2; ++k) dst[m][k] = *(const PG8_LAS bf16x8*)(lds + PG8_SA(b, h) + aoff + m * 2048 + k * 1024); } while (0)
; #define PG8_LDB(dst, b, h) do { _Pragma("unroll") for (int n = 0; n < 2; ++n) _Pragma("unroll") for (int k = 0; k < 2; ++k) dst[n][k] = *(const PG8_LAS bf16x8*)(lds + PG8_SB(b, h) + boff + n * 2048 + k * 1024); } while (0)
; #define PG8_WAIT_V(n) asm volatile("s_waitcnt vmcnt(" #n ")" ::: "memory")
; #define PG8_WAIT_L(n) asm volatile("s_waitcnt lgkmcnt(" #n ")" ::: "memory")
; #define PG8_BAR __builtin_amdgcn_s_barrier()
; #define PG8_SCHED __builtin_amdgcn_sched_barrier(0)
; template <class Epi, class Sched, bool ALIGN_EPI = false, bool SP2 = false>
; __device__ __forceinline__ void gemm_phase(PG8_LAS unsigned char* lds, const Gemm g, const Sched& S, const Epi& E, const int tid) {
;     ...
;         const char* nA = has_next ? (const char*)g.A + (size_t)nxt.pm * tstep : cA; const char* nB = has_next ? (const char*)g.Bt + (size_t)nxt.pn * tstep : cB;
;         for (int t = 0; t < nt; t += 2) {
;             const bool last = (t == nt - 2);
;             const char* a1 = cA + (size_t)(t + 1) * kstep;
;             const char* a2 = last ? nA : cA + (size_t)(t + 2) * kstep; const char* b2 = last ? nB : cB + (size_t)(t + 2) * kstep;
;             const char* a3 = a2 + kstep; const char* b3 = b2 + kstep;
;             if (last && has_next) S.a_ready(nxt);
;             if constexpr (SP2) {
;             PG8_LDB(B0, 0, 0); PG8_LDB(B1, 0, 1); PG8_SCHED; PG8_LDA(At, 0, 0); PG8_STAGE(PG8_SA(1, 1), a1 + hstep, voffA);
;             PG8_WAIT_V(8); PG8_WAIT_L(0); PG8_BAR; PG8_MMA(0, 0, At, B0); PG8_MMA(0, 1, At, B1); PG8_BAR; PG8_SCHED;
;             PG8_LDA(At, 0, 1); PG8_STAGE(PG8_SB(0, 0), b2, voffB); PG8_STAGE(PG8_SB(0, 1), b2 + hstep, voffB); PG8_STAGE(PG8_SA(0, 0), a2, voffA);
;             PG8_WAIT_V(8); PG8_WAIT_L(0); PG8_BAR; PG8_MMA(1, 0, At, B0); PG8_MMA(1, 1, At, B1); PG8_BAR; PG8_SCHED;
.LBB0_1383:
	s_ashr_i32 s27, s26, 31
	s_lshl_b64 s[28:29], s[26:27], 20
	s_add_u32 s28, s6, s28
	s_addc_u32 s29, s7, s29
	s_and_b64 s[30:31], s[4:5], exec
	s_cselect_b32 s27, s29, s43
	s_cselect_b32 s35, s28, s42
	s_ashr_i32 s25, s24, 31
	s_lshl_b64 s[30:31], s[24:25], 20
	s_add_u32 s30, s49, s30
	s_addc_u32 s31, s50, s31
	s_and_b64 s[46:47], s[4:5], exec
	s_cselect_b32 s25, s31, s45
	s_cselect_b32 s37, s30, s44
	s_add_u32 s42, s42, 0x80080
	s_addc_u32 s43, s43, 0
	s_add_u32 s40, s44, 0x100
	s_addc_u32 s69, s45, 0
	s_mov_b32 s75, -2
	s_waitcnt lgkmcnt(0)
	s_add_u32 s44, s42, 0xfff80080
	s_addc_u32 s45, s43, -1
	s_add_i32 s76, 0, 0x10000
	s_cmp_eq_u32 s75, 28
	s_cselect_b32 s47, s27, s45
	s_cselect_b32 s46, s35, s44
	s_cselect_b32 s45, s25, s69
	s_cselect_b32 s44, s37, s40
	s_add_i32 s78, 0, 0x14000
	v_add_u32_e32 v68, s76, v175
	v_add_u32_e32 v156, s78, v175
	ds_read_b128 v[48:51], v68
	ds_read_b128 v[52:55], v68 offset:1024
	ds_read_b128 v[64:67], v68 offset:2048
	ds_read_b128 v[68:71], v68 offset:3072
	ds_read_b128 v[144:147], v156
	ds_read_b128 v[148:151], v156 offset:1024
	ds_read_b128 v[152:155], v156 offset:2048
	ds_read_b128 v[156:159], v156 offset:3072
	v_lshl_add_u64 v[176:177], s[42:43], 0, v[166:167]
	s_add_i32 m0, s52, 0xc000
	ds_read_b128 v[170:173], v179
	ds_read_b128 v[180:183], v179 offset:1024
	ds_read_b128 v[184:187], v179 offset:2048
	ds_read_b128 v[188:191], v179 offset:3072
	ds_read_b128 v[192:195], v179 offset:4096
	ds_read_b128 v[196:199], v179 offset:5120
	ds_read_b128 v[200:203], v179 offset:6144
	ds_read_b128 v[206:209], v179 offset:7168
	global_load_lds_dwordx4 v[176:177], off
	v_lshl_add_u64 v[176:177], s[42:43], 0, v[168:169]
	s_add_i32 m0, s52, 0xe000
	s_nop 0
	global_load_lds_dwordx4 v[176:177], off
	s_waitcnt vmcnt(24)
	s_waitcnt lgkmcnt(0)
	s_barrier
	s_setprio 1
	s_waitcnt lgkmcnt(0)
	v_mfma_f32_16x16x32_bf16 v[140:143], v[48:51], v[170:173], 0
	v_mfma_f32_16x16x32_bf16 v[136:139], v[64:67], v[170:173], 0
	v_mfma_f32_16x16x32_bf16 v[124:127], v[48:51], v[184:187], 0
	v_mfma_f32_16x16x32_bf16 v[120:123], v[64:67], v[184:187], 0
	v_mfma_f32_16x16x32_bf16 v[108:111], v[48:51], v[192:195], 0
	v_mfma_f32_16x16x32_bf16 v[104:107], v[64:67], v[192:195], 0
	v_mfma_f32_16x16x32_bf16 v[92:95], v[48:51], v[200:203], 0
	v_mfma_f32_16x16x32_bf16 v[88:91], v[64:67], v[200:203], 0
	v_mfma_f32_16x16x32_bf16 v[140:143], v[52:55], v[180:183], v[140:143]
	v_mfma_f32_16x16x32_bf16 v[136:139], v[68:71], v[180:183], v[136:139]
	v_mfma_f32_16x16x32_bf16 v[124:127], v[52:55], v[188:191], v[124:127]
	v_mfma_f32_16x16x32_bf16 v[120:123], v[68:71], v[188:191], v[120:123]
	v_mfma_f32_16x16x32_bf16 v[108:111], v[52:55], v[196:199], v[108:111]
	v_mfma_f32_16x16x32_bf16 v[104:107], v[68:71], v[196:199], v[104:107]
	v_mfma_f32_16x16x32_bf16 v[92:95], v[52:55], v[206:209], v[92:95]
	v_mfma_f32_16x16x32_bf16 v[88:91], v[68:71], v[206:209], v[88:91]
	s_setprio 0
	s_setprio 1
	v_mfma_f32_16x16x32_bf16 v[132:135], v[144:147], v[170:173], 0
	v_mfma_f32_16x16x32_bf16 v[128:131], v[152:155], v[170:173], 0
	v_mfma_f32_16x16x32_bf16 v[116:119], v[144:147], v[184:187], 0
	v_mfma_f32_16x16x32_bf16 v[112:115], v[152:155], v[184:187], 0
	v_mfma_f32_16x16x32_bf16 v[100:103], v[144:147], v[192:195], 0
	v_mfma_f32_16x16x32_bf16 v[96:99], v[152:155], v[192:195], 0
	v_mfma_f32_16x16x32_bf16 v[84:87], v[144:147], v[200:203], 0
	v_mfma_f32_16x16x32_bf16 v[80:83], v[152:155], v[200:203], 0
	v_mfma_f32_16x16x32_bf16 v[132:135], v[148:151], v[180:183], v[132:135]
	v_mfma_f32_16x16x32_bf16 v[128:131], v[156:159], v[180:183], v[128:131]
	v_mfma_f32_16x16x32_bf16 v[116:119], v[148:151], v[188:191], v[116:119]
	v_mfma_f32_16x16x32_bf16 v[112:115], v[156:159], v[188:191], v[112:115]
	v_mfma_f32_16x16x32_bf16 v[100:103], v[148:151], v[196:199], v[100:103]
	v_mfma_f32_16x16x32_bf16 v[96:99], v[156:159], v[196:199], v[96:99]
	v_mfma_f32_16x16x32_bf16 v[84:87], v[148:151], v[206:209], v[84:87]
	v_mfma_f32_16x16x32_bf16 v[80:83], v[156:159], v[206:209], v[80:83]
	s_setprio 0
	s_barrier
	s_add_i32 s76, s76, s51
	v_lshl_add_u64 v[176:177], s[44:45], 0, v[204:205]
	s_mov_b32 m0, s76
	ds_read_b128 v[170:173], v179 offset:16384
	ds_read_b128 v[180:183], v179 offset:17408
	ds_read_b128 v[184:187], v179 offset:18432
	ds_read_b128 v[188:191], v179 offset:19456
	ds_read_b128 v[192:195], v179 offset:20480
	ds_read_b128 v[196:199], v179 offset:21504
	ds_read_b128 v[200:203], v179 offset:22528
	ds_read_b128 v[206:209], v179 offset:23552
	global_load_lds_dwordx4 v[176:177], off
	s_add_i32 m0, s76, 0x2000
	s_add_u32 s76, s44, 0x80000
	v_lshl_add_u64 v[210:211], s[44:45], 0, v[164:165]
	s_addc_u32 s77, s45, 0
	s_add_i32 s78, s78, s51
	global_load_lds_dwordx4 v[210:211], off
	v_lshl_add_u64 v[212:213], s[76:77], 0, v[204:205]
	s_mov_b32 m0, s78
	v_lshl_add_u64 v[214:215], s[46:47], 0, v[162:163]
	global_load_lds_dwordx4 v[212:213], off
	v_lshl_add_u64 v[212:213], s[76:77], 0, v[164:165]
	s_add_i32 m0, s78, 0x2000
	s_nop 0
	global_load_lds_dwordx4 v[212:213], off
	v_lshl_add_u64 v[212:213], s[46:47], 0, v[160:161]
	s_mov_b32 m0, s52
	s_nop 0
	global_load_lds_dwordx4 v[212:213], off
	s_mov_b32 m0, s0
	s_nop 0
	global_load_lds_dwordx4 v[214:215], off
	s_waitcnt vmcnt(8)
	s_waitcnt lgkmcnt(0)
	s_barrier
; #define PG8_STAGE(bufoff, gbase, voff) do { _Pragma("unroll") for (int _i = 0; _i < 2; ++_i) \
;         __builtin_amdgcn_global_load_lds((const unsigned*)((const char*)(gbase) + (voff)[_i]), (PG8_LAS unsigned*)(lds + (bufoff) + ldsw + _i * 8192), 16, 0, 0); } while (0)
; #define PG8_LDA(dst, b, h) do { _Pragma("unroll") for (int m = 0; m < 4; ++m) _Pragma("unroll") for (int k = 0; k < 2; ++k) dst[m][k] = *(const PG8_LAS bf16x8*)(lds + PG8_SA(b, h) + aoff + m * 2048 + k * 1024); } while (0)
; #define PG8_LDB(dst, b, h) do { _Pragma("unroll") for (int n = 0; n < 2; ++n) _Pragma("unroll") for (int k = 0; k < 2; ++k) dst[n][k] = *(const PG8_LAS bf16x8*)(lds + PG8_SB(b, h) + boff + n * 2048 + k * 1024); } while (0)
; #define PG8_MMA(ai, bj, At, Bt) do { __builtin_amdgcn_s_setprio(1); _Pragma("unroll") for (int m = 0; m < 4; ++m) _Pragma("unroll") for (int n = 0; n < 2; ++n) _Pragma("unroll") for (int k = 0; k < 2; ++k) \
;         acc[ai][bj][m][n] = __builtin_amdgcn_mfma_f32_16x16x32_bf16(Bt[n][k], At[m][k], acc[ai][bj][m][n], 0, 0, 0); __builtin_amdgcn_s_setprio(0); } while (0)
; #define PG8_WAIT_V(n) asm volatile("s_waitcnt vmcnt(" #n ")" ::: "memory")
; #define PG8_WAIT_L(n) asm volatile("s_waitcnt lgkmcnt(" #n ")" ::: "memory")
; #define PG8_BAR __builtin_amdgcn_s_barrier()
; #define PG8_SCHED __builtin_amdgcn_sched_barrier(0)
; template <class Epi, class Sched, bool ALIGN_EPI = false, bool SP2 = false>
; __device__ __forceinline__ void gemm_phase(PG8_LAS unsigned char* lds, const Gemm g, const Sched& S, const Epi& E, const int tid) {
;     ...
;             PG8_LDA(At, 0, 1); PG8_STAGE(PG8_SB(0, 0), b2, voffB); PG8_STAGE(PG8_SB(0, 1), b2 + hstep, voffB); PG8_STAGE(PG8_SA(0, 0), a2, voffA);
;             PG8_WAIT_V(8); PG8_WAIT_L(0); PG8_BAR; PG8_MMA(1, 0, At, B0); PG8_MMA(1, 1, At, B1); PG8_BAR; PG8_SCHED;
;             PG8_LDB(B0, 1, 0); PG8_LDB(B1, 1, 1); PG8_SCHED; PG8_LDA(At, 1, 0); PG8_STAGE(PG8_SA(0, 1), a2 + hstep, voffA);
;             PG8_WAIT_V(8); PG8_WAIT_L(0); PG8_BAR; PG8_MMA(0, 0, At, B0); PG8_MMA(0, 1, At, B1); PG8_BAR; PG8_SCHED;
	s_setprio 1
	s_waitcnt lgkmcnt(0)
	v_mfma_f32_16x16x32_bf16 v[76:79], v[48:51], v[170:173], 0
	v_mfma_f32_16x16x32_bf16 v[72:75], v[64:67], v[170:173], 0
	v_mfma_f32_16x16x32_bf16 v[44:47], v[48:51], v[184:187], 0
	v_mfma_f32_16x16x32_bf16 v[40:43], v[64:67], v[184:187], 0
	v_mfma_f32_16x16x32_bf16 v[28:31], v[48:51], v[192:195], 0
	v_mfma_f32_16x16x32_bf16 v[24:27], v[64:67], v[192:195], 0
	v_mfma_f32_16x16x32_bf16 v[12:15], v[48:51], v[200:203], 0
	v_mfma_f32_16x16x32_bf16 v[8:11], v[64:67], v[200:203], 0
	v_mfma_f32_16x16x32_bf16 v[76:79], v[52:55], v[180:183], v[76:79]
	v_mfma_f32_16x16x32_bf16 v[72:75], v[68:71], v[180:183], v[72:75]
	v_mfma_f32_16x16x32_bf16 v[44:47], v[52:55], v[188:191], v[44:47]
	v_mfma_f32_16x16x32_bf16 v[40:43], v[68:71], v[188:191], v[40:43]
	v_mfma_f32_16x16x32_bf16 v[28:31], v[52:55], v[196:199], v[28:31]
	v_mfma_f32_16x16x32_bf16 v[24:27], v[68:71], v[196:199], v[24:27]
	v_mfma_f32_16x16x32_bf16 v[12:15], v[52:55], v[206:209], v[12:15]
	v_mfma_f32_16x16x32_bf16 v[8:11], v[68:71], v[206:209], v[8:11]
	s_setprio 0
	s_setprio 1
	v_mfma_f32_16x16x32_bf16 v[36:39], v[144:147], v[184:187], 0
	v_mfma_f32_16x16x32_bf16 v[32:35], v[152:155], v[184:187], 0
	v_mfma_f32_16x16x32_bf16 v[20:23], v[144:147], v[192:195], 0
	v_mfma_f32_16x16x32_bf16 v[16:19], v[152:155], v[192:195], 0
	v_mfma_f32_16x16x32_bf16 v[4:7], v[144:147], v[200:203], 0
	v_mfma_f32_16x16x32_bf16 v[0:3], v[152:155], v[200:203], 0
	v_mfma_f32_16x16x32_bf16 v[48:51], v[144:147], v[170:173], 0
	v_mfma_f32_16x16x32_bf16 v[52:55], v[152:155], v[170:173], 0
	v_mfma_f32_16x16x32_bf16 v[36:39], v[148:151], v[188:191], v[36:39]
	v_mfma_f32_16x16x32_bf16 v[32:35], v[156:159], v[188:191], v[32:35]
	v_mfma_f32_16x16x32_bf16 v[20:23], v[148:151], v[196:199], v[20:23]
	v_mfma_f32_16x16x32_bf16 v[16:19], v[156:159], v[196:199], v[16:19]
	v_mfma_f32_16x16x32_bf16 v[4:7], v[148:151], v[206:209], v[4:7]
	v_mfma_f32_16x16x32_bf16 v[0:3], v[156:159], v[206:209], v[0:3]
	v_mfma_f32_16x16x32_bf16 v[48:51], v[148:151], v[180:183], v[48:51]
	v_mfma_f32_16x16x32_bf16 v[52:55], v[156:159], v[180:183], v[52:55]
	s_setprio 0
	s_barrier
	s_add_i32 s76, 0, 0x18000
	s_add_i32 s77, 0, 0x1c000
	v_add_u32_e32 v68, s76, v175
	v_add_u32_e32 v156, s77, v175
	ds_read_b128 v[56:59], v68
	ds_read_b128 v[60:63], v68 offset:1024
	ds_read_b128 v[64:67], v68 offset:2048
	ds_read_b128 v[68:71], v68 offset:3072
	ds_read_b128 v[144:147], v156
	ds_read_b128 v[148:151], v156 offset:1024
	ds_read_b128 v[152:155], v156 offset:2048
	ds_read_b128 v[156:159], v156 offset:3072
	s_add_u32 s46, s46, 0x80000
	s_addc_u32 s47, s47, 0
	s_mov_b32 m0, s33
	v_lshl_add_u64 v[216:217], s[46:47], 0, v[160:161]
	ds_read_b128 v[170:173], v179 offset:32768
	ds_read_b128 v[180:183], v179 offset:33792
	ds_read_b128 v[184:187], v179 offset:34816
	ds_read_b128 v[188:191], v179 offset:35840
	ds_read_b128 v[192:195], v179 offset:36864
	ds_read_b128 v[196:199], v179 offset:37888
	ds_read_b128 v[200:203], v179 offset:38912
	ds_read_b128 v[206:209], v179 offset:39936
	global_load_lds_dwordx4 v[216:217], off
	v_lshl_add_u64 v[216:217], s[46:47], 0, v[162:163]
	s_mov_b32 m0, s53
	s_nop 0
	global_load_lds_dwordx4 v[216:217], off
	s_waitcnt vmcnt(8)
	s_waitcnt lgkmcnt(0)
	s_barrier
	s_setprio 1
	s_waitcnt lgkmcnt(0)
	v_mfma_f32_16x16x32_bf16 v[140:143], v[56:59], v[170:173], v[140:143]
	v_mfma_f32_16x16x32_bf16 v[136:139], v[64:67], v[170:173], v[136:139]
	v_mfma_f32_16x16x32_bf16 v[124:127], v[56:59], v[184:187], v[124:127]
	v_mfma_f32_16x16x32_bf16 v[120:123], v[64:67], v[184:187], v[120:123]
	v_mfma_f32_16x16x32_bf16 v[108:111], v[56:59], v[192:195], v[108:111]
	v_mfma_f32_16x16x32_bf16 v[104:107], v[64:67], v[192:195], v[104:107]
	v_mfma_f32_16x16x32_bf16 v[92:95], v[56:59], v[200:203], v[92:95]
	v_mfma_f32_16x16x32_bf16 v[88:91], v[64:67], v[200:203], v[88:91]
	v_mfma_f32_16x16x32_bf16 v[140:143], v[60:63], v[180:183], v[140:143]
	v_mfma_f32_16x16x32_bf16 v[136:139], v[68:71], v[180:183], v[136:139]
	v_mfma_f32_16x16x32_bf16 v[124:127], v[60:63], v[188:191], v[124:127]
	v_mfma_f32_16x16x32_bf16 v[120:123], v[68:71], v[188:191], v[120:123]
	v_mfma_f32_16x16x32_bf16 v[108:111], v[60:63], v[196:199], v[108:111]
	v_mfma_f32_16x16x32_bf16 v[104:107], v[68:71], v[196:199], v[104:107]
	v_mfma_f32_16x16x32_bf16 v[92:95], v[60:63], v[206:209], v[92:95]
	v_mfma_f32_16x16x32_bf16 v[88:91], v[68:71], v[206:209], v[88:91]
	s_setprio 0
	s_setprio 1
	v_mfma_f32_16x16x32_bf16 v[132:135], v[144:147], v[170:173], v[132:135]
	v_mfma_f32_16x16x32_bf16 v[128:131], v[152:155], v[170:173], v[128:131]
	v_mfma_f32_16x16x32_bf16 v[116:119], v[144:147], v[184:187], v[116:119]
	v_mfma_f32_16x16x32_bf16 v[112:115], v[152:155], v[184:187], v[112:115]
	v_mfma_f32_16x16x32_bf16 v[100:103], v[144:147], v[192:195], v[100:103]
	v_mfma_f32_16x16x32_bf16 v[96:99], v[152:155], v[192:195], v[96:99]
	v_mfma_f32_16x16x32_bf16 v[84:87], v[144:147], v[200:203], v[84:87]
	v_mfma_f32_16x16x32_bf16 v[80:83], v[152:155], v[200:203], v[80:83]
	v_mfma_f32_16x16x32_bf16 v[132:135], v[148:151], v[180:183], v[132:135]
	v_mfma_f32_16x16x32_bf16 v[128:131], v[156:159], v[180:183], v[128:131]
	v_mfma_f32_16x16x32_bf16 v[116:119], v[148:151], v[188:191], v[116:119]
	v_mfma_f32_16x16x32_bf16 v[112:115], v[156:159], v[188:191], v[112:115]
	v_mfma_f32_16x16x32_bf16 v[100:103], v[148:151], v[196:199], v[100:103]
	v_mfma_f32_16x16x32_bf16 v[96:99], v[156:159], v[196:199], v[96:99]
	v_mfma_f32_16x16x32_bf16 v[84:87], v[148:151], v[206:209], v[84:87]
	v_mfma_f32_16x16x32_bf16 v[80:83], v[156:159], v[206:209], v[80:83]
	s_setprio 0
	s_barrier
; #define PG8_STAGE(bufoff, gbase, voff) do { _Pragma("unroll") for (int _i = 0; _i < 2; ++_i) \
;         __builtin_amdgcn_global_load_lds((const unsigned*)((const char*)(gbase) + (voff)[_i]), (PG8_LAS unsigned*)(lds + (bufoff) + ldsw + _i * 8192), 16, 0, 0); } while (0)
; #define PG8_LDA(dst, b, h) do { _Pragma("unroll") for (int m = 0; m < 4; ++m) _Pragma("unroll") for (int k = 0; k < 2; ++k) dst[m][k] = *(const PG8_LAS bf16x8*)(lds + PG8_SA(b, h) + aoff + m * 2048 + k * 1024); } while (0)
; #define PG8_MMA(ai, bj, At, Bt) do { __builtin_amdgcn_s_setprio(1); _Pragma("unroll") for (int m = 0; m < 4; ++m) _Pragma("unroll") for (int n = 0; n < 2; ++n) _Pragma("unroll") for (int k = 0; k < 2; ++k) \
;         acc[ai][bj][m][n] = __builtin_amdgcn_mfma_f32_16x16x32_bf16(Bt[n][k], At[m][k], acc[ai][bj][m][n], 0, 0, 0); __builtin_amdgcn_s_setprio(0); } while (0)
; #define PG8_WAIT_V(n) asm volatile("s_waitcnt vmcnt(" #n ")" ::: "memory")
; #define PG8_WAIT_L(n) asm volatile("s_waitcnt lgkmcnt(" #n ")" ::: "memory")
; #define PG8_BAR __builtin_amdgcn_s_barrier()
; #define PG8_SCHED __builtin_amdgcn_sched_barrier(0)
; template <class Epi, class Sched, bool ALIGN_EPI = false, bool SP2 = false>
; __device__ __forceinline__ void gemm_phase(PG8_LAS unsigned char* lds, const Gemm g, const Sched& S, const Epi& E, const int tid) {
;     ...
;             PG8_LDA(At, 1, 1); PG8_STAGE(PG8_SB(1, 0), b3, voffB); PG8_STAGE(PG8_SB(1, 1), b3 + hstep, voffB); PG8_STAGE(PG8_SA(1, 0), a3, voffA);
;             PG8_WAIT_V(8); PG8_WAIT_L(0); PG8_BAR; PG8_MMA(1, 0, At, B0); PG8_MMA(1, 1, At, B1); PG8_BAR; PG8_SCHED;
	s_add_i32 s46, s76, s51
	v_lshl_add_u64 v[176:177], v[176:177], 0, s[70:71]
	s_mov_b32 m0, s46
	ds_read_b128 v[170:173], v179 offset:49152
	ds_read_b128 v[180:183], v179 offset:50176
	ds_read_b128 v[184:187], v179 offset:51200
	ds_read_b128 v[188:191], v179 offset:52224
	ds_read_b128 v[192:195], v179 offset:53248
	ds_read_b128 v[196:199], v179 offset:54272
	ds_read_b128 v[200:203], v179 offset:55296
	ds_read_b128 v[206:209], v179 offset:56320
	global_load_lds_dwordx4 v[176:177], off
	s_add_i32 m0, s46, 0x2000
	s_add_u32 s44, s44, 0x80080
	v_lshl_add_u64 v[176:177], v[210:211], 0, s[70:71]
	s_addc_u32 s45, s45, 0
	s_add_i32 s46, s77, s51
	global_load_lds_dwordx4 v[176:177], off
	v_lshl_add_u64 v[176:177], s[44:45], 0, v[204:205]
	s_mov_b32 m0, s46
	s_nop 0
	global_load_lds_dwordx4 v[176:177], off
	v_lshl_add_u64 v[176:177], s[44:45], 0, v[164:165]
	s_add_i32 m0, s46, 0x2000
	s_nop 0
	global_load_lds_dwordx4 v[176:177], off
	v_lshl_add_u64 v[176:177], v[212:213], 0, s[70:71]
	s_mov_b32 m0, s55
	s_nop 0
	global_load_lds_dwordx4 v[176:177], off
	v_lshl_add_u64 v[176:177], v[214:215], 0, s[70:71]
	s_mov_b32 m0, s62
	s_nop 0
	global_load_lds_dwordx4 v[176:177], off
	s_waitcnt vmcnt(8)
	s_waitcnt lgkmcnt(0)
	s_barrier
	s_setprio 1
	s_waitcnt lgkmcnt(0)
	v_mfma_f32_16x16x32_bf16 v[76:79], v[56:59], v[170:173], v[76:79]
	v_mfma_f32_16x16x32_bf16 v[72:75], v[64:67], v[170:173], v[72:75]
	v_mfma_f32_16x16x32_bf16 v[44:47], v[56:59], v[184:187], v[44:47]
	v_mfma_f32_16x16x32_bf16 v[40:43], v[64:67], v[184:187], v[40:43]
	v_mfma_f32_16x16x32_bf16 v[28:31], v[56:59], v[192:195], v[28:31]
	v_mfma_f32_16x16x32_bf16 v[24:27], v[64:67], v[192:195], v[24:27]
	v_mfma_f32_16x16x32_bf16 v[12:15], v[56:59], v[200:203], v[12:15]
	v_mfma_f32_16x16x32_bf16 v[8:11], v[64:67], v[200:203], v[8:11]
	v_mfma_f32_16x16x32_bf16 v[76:79], v[60:63], v[180:183], v[76:79]
	v_mfma_f32_16x16x32_bf16 v[72:75], v[68:71], v[180:183], v[72:75]
	v_mfma_f32_16x16x32_bf16 v[44:47], v[60:63], v[188:191], v[44:47]
	v_mfma_f32_16x16x32_bf16 v[40:43], v[68:71], v[188:191], v[40:43]
	v_mfma_f32_16x16x32_bf16 v[28:31], v[60:63], v[196:199], v[28:31]
	v_mfma_f32_16x16x32_bf16 v[24:27], v[68:71], v[196:199], v[24:27]
	v_mfma_f32_16x16x32_bf16 v[12:15], v[60:63], v[206:209], v[12:15]
	v_mfma_f32_16x16x32_bf16 v[8:11], v[68:71], v[206:209], v[8:11]
	s_setprio 0
	s_setprio 1
	v_mfma_f32_16x16x32_bf16 v[48:51], v[144:147], v[170:173], v[48:51]
	v_mfma_f32_16x16x32_bf16 v[60:63], v[148:151], v[180:183], v[48:51]
	v_mfma_f32_16x16x32_bf16 v[48:51], v[152:155], v[170:173], v[52:55]
	v_mfma_f32_16x16x32_bf16 v[36:39], v[144:147], v[184:187], v[36:39]
	v_mfma_f32_16x16x32_bf16 v[32:35], v[152:155], v[184:187], v[32:35]
	v_mfma_f32_16x16x32_bf16 v[20:23], v[144:147], v[192:195], v[20:23]
	v_mfma_f32_16x16x32_bf16 v[16:19], v[152:155], v[192:195], v[16:19]
	v_mfma_f32_16x16x32_bf16 v[4:7], v[144:147], v[200:203], v[4:7]
	v_mfma_f32_16x16x32_bf16 v[0:3], v[152:155], v[200:203], v[0:3]
	v_mfma_f32_16x16x32_bf16 v[56:59], v[156:159], v[180:183], v[48:51]
	v_mfma_f32_16x16x32_bf16 v[36:39], v[148:151], v[188:191], v[36:39]
	v_mfma_f32_16x16x32_bf16 v[32:35], v[156:159], v[188:191], v[32:35]
	v_mfma_f32_16x16x32_bf16 v[20:23], v[148:151], v[196:199], v[20:23]
	v_mfma_f32_16x16x32_bf16 v[16:19], v[156:159], v[196:199], v[16:19]
	v_mfma_f32_16x16x32_bf16 v[4:7], v[148:151], v[206:209], v[4:7]
	v_mfma_f32_16x16x32_bf16 v[0:3], v[156:159], v[206:209], v[0:3]
	s_setprio 0
	s_barrier
	s_add_i32 s75, s75, 2
	s_add_u32 s42, s42, 0x100
	s_addc_u32 s43, s43, 0
	s_add_u32 s40, s40, 0x100
	s_addc_u32 s69, s69, 0

; #define PG8_STAGE(bufoff, gbase, voff) do { _Pragma("unroll") for (int _i = 0; _i < 2; ++_i) \
;         __builtin_amdgcn_global_load_lds((const unsigned*)((const char*)(gbase) + (voff)[_i]), (PG8_LAS unsigned*)(lds + (bufoff) + ldsw + _i * 8192), 16, 0, 0); } while (0)
; #define PG8_LDA(dst, b, h) do { _Pragma("unroll") for (int m = 0; m < 4; ++m) _Pragma("unroll") for (int k = 0; k < 2; ++k) dst[m][k] = *(const PG8_LAS bf16x8*)(lds + PG8_SA(b, h) + aoff + m * 2048 + k * 1024); } while (0)
; #define PG8_LDB(dst, b, h) do { _Pragma("unroll") for (int n = 0; n < 2; ++n) _Pragma("unroll") for (int k = 0; k < 2; ++k) dst[n][k] = *(const PG8_LAS bf16x8*)(lds + PG8_SB(b, h) + boff + n * 2048 + k * 1024); } while (0)
; #define PG8_WAIT_V(n) asm volatile("s_waitcnt vmcnt(" #n ")" ::: "memory")
; #define PG8_WAIT_L(n) asm volatile("s_waitcnt lgkmcnt(" #n ")" ::: "memory")
; #define PG8_BAR __builtin_amdgcn_s_barrier()
; #define PG8_SCHED __builtin_amdgcn_sched_barrier(0)
; template <class Epi, class Sched, bool ALIGN_EPI = false, bool SP2 = false>
; __device__ __forceinline__ void gemm_phase(PG8_LAS unsigned char* lds, const Gemm g, const Sched& S, const Epi& E, const int tid) {
;     ...
;         const char* nA = has_next ? (const char*)g.A + (size_t)nxt.pm * tstep : cA; const char* nB = has_next ? (const char*)g.Bt + (size_t)nxt.pn * tstep : cB;
;         for (int t = 0; t < nt; t += 2) {
;             const bool last = (t == nt - 2);
;             const char* a1 = cA + (size_t)(t + 1) * kstep;
;             const char* a2 = last ? nA : cA + (size_t)(t + 2) * kstep; const char* b2 = last ? nB : cB + (size_t)(t + 2) * kstep;
;             const char* a3 = a2 + kstep; const char* b3 = b2 + kstep;
;             if (last && has_next) S.a_ready(nxt);
;             if constexpr (SP2) {
;             PG8_LDB(B0, 0, 0); PG8_LDB(B1, 0, 1); PG8_SCHED; PG8_LDA(At, 0, 0); PG8_STAGE(PG8_SA(1, 1), a1 + hstep, voffA);
;             PG8_WAIT_V(8); PG8_WAIT_L(0); PG8_BAR; PG8_MMA(0, 0, At, B0); PG8_MMA(0, 1, At, B1); PG8_BAR; PG8_SCHED;
;             PG8_LDA(At, 0, 1); PG8_STAGE(PG8_SB(0, 0), b2, voffB); PG8_STAGE(PG8_SB(0, 1), b2 + hstep, voffB); PG8_STAGE(PG8_SA(0, 0), a2, voffA);
;             PG8_WAIT_V(8); PG8_WAIT_L(0); PG8_BAR; PG8_MMA(1, 0, At, B0); PG8_MMA(1, 1, At, B1); PG8_BAR; PG8_SCHED;
.LBB0_1425:
	s_ashr_i32 s27, s26, 31
	s_lshl_b64 s[28:29], s[26:27], 20
	s_add_u32 s28, s6, s28
	s_addc_u32 s29, s7, s29
	s_and_b64 s[30:31], s[4:5], exec
	s_cselect_b32 s27, s29, s37
	s_cselect_b32 s62, s28, s36
	s_ashr_i32 s25, s24, 31
	s_lshl_b64 s[30:31], s[24:25], 20
	s_add_u32 s30, s11, s30
	s_addc_u32 s31, s33, s31
	s_and_b64 s[44:45], s[4:5], exec
	s_cselect_b32 s25, s31, s43
	s_cselect_b32 s64, s30, s42
	s_add_u32 s36, s36, 0x80080
	s_addc_u32 s37, s37, 0
	s_add_u32 s65, s42, 0x100
	s_addc_u32 s68, s43, 0
	s_mov_b32 s69, -2
	s_add_u32 s42, s36, 0xfff80080
	s_addc_u32 s43, s37, -1
	s_add_i32 s75, 0, 0x10000
	s_cmp_eq_u32 s69, 28
	s_cselect_b32 s45, s27, s43
	s_cselect_b32 s44, s62, s42
	s_cselect_b32 s43, s25, s68
	s_cselect_b32 s42, s64, s65
	s_add_i32 s78, 0, 0x14000
	v_add_u32_e32 v84, s75, v167
	v_add_u32_e32 v166, s78, v167
	ds_read_b128 v[64:67], v84
	ds_read_b128 v[68:71], v84 offset:1024
	ds_read_b128 v[80:83], v84 offset:2048
	ds_read_b128 v[84:87], v84 offset:3072
	ds_read_b128 v[144:147], v166
	ds_read_b128 v[148:151], v166 offset:1024
	ds_read_b128 v[152:155], v166 offset:2048
	ds_read_b128 v[170:173], v166 offset:3072
	v_lshl_add_u64 v[202:203], s[36:37], 0, v[162:163]
	s_add_i32 m0, s35, 0xc000
	ds_read_b128 v[174:177], v169
	ds_read_b128 v[178:181], v169 offset:1024
	ds_read_b128 v[182:185], v169 offset:2048
	ds_read_b128 v[186:189], v169 offset:3072
	ds_read_b128 v[190:193], v169 offset:4096
	ds_read_b128 v[194:197], v169 offset:5120
	ds_read_b128 v[198:201], v169 offset:6144
	ds_read_b128 v[206:209], v169 offset:7168
	global_load_lds_dwordx4 v[202:203], off
	v_lshl_add_u64 v[202:203], s[36:37], 0, v[164:165]
	s_add_i32 m0, s35, 0xe000
	s_nop 0
	global_load_lds_dwordx4 v[202:203], off
	s_waitcnt vmcnt(24)
	s_waitcnt lgkmcnt(0)
	s_barrier
	s_setprio 1
	s_waitcnt lgkmcnt(0)
	v_mfma_f32_16x16x32_bf16 v[140:143], v[64:67], v[174:177], 0
	v_mfma_f32_16x16x32_bf16 v[136:139], v[80:83], v[174:177], 0
	v_mfma_f32_16x16x32_bf16 v[124:127], v[64:67], v[182:185], 0
	v_mfma_f32_16x16x32_bf16 v[120:123], v[80:83], v[182:185], 0
	v_mfma_f32_16x16x32_bf16 v[108:111], v[64:67], v[190:193], 0
	v_mfma_f32_16x16x32_bf16 v[104:107], v[80:83], v[190:193], 0
	v_mfma_f32_16x16x32_bf16 v[92:95], v[64:67], v[198:201], 0
	v_mfma_f32_16x16x32_bf16 v[88:91], v[80:83], v[198:201], 0
	v_mfma_f32_16x16x32_bf16 v[140:143], v[68:71], v[178:181], v[140:143]
	v_mfma_f32_16x16x32_bf16 v[136:139], v[84:87], v[178:181], v[136:139]
	v_mfma_f32_16x16x32_bf16 v[124:127], v[68:71], v[186:189], v[124:127]
	v_mfma_f32_16x16x32_bf16 v[120:123], v[84:87], v[186:189], v[120:123]
	v_mfma_f32_16x16x32_bf16 v[108:111], v[68:71], v[194:197], v[108:111]
	v_mfma_f32_16x16x32_bf16 v[104:107], v[84:87], v[194:197], v[104:107]
	v_mfma_f32_16x16x32_bf16 v[92:95], v[68:71], v[206:209], v[92:95]
	v_mfma_f32_16x16x32_bf16 v[88:91], v[84:87], v[206:209], v[88:91]
	s_setprio 0
	s_setprio 1
	v_mfma_f32_16x16x32_bf16 v[132:135], v[144:147], v[174:177], 0
	v_mfma_f32_16x16x32_bf16 v[128:131], v[152:155], v[174:177], 0
	v_mfma_f32_16x16x32_bf16 v[116:119], v[144:147], v[182:185], 0
	v_mfma_f32_16x16x32_bf16 v[112:115], v[152:155], v[182:185], 0
	v_mfma_f32_16x16x32_bf16 v[100:103], v[144:147], v[190:193], 0
	v_mfma_f32_16x16x32_bf16 v[96:99], v[152:155], v[190:193], 0
	v_mfma_f32_16x16x32_bf16 v[76:79], v[144:147], v[198:201], 0
	v_mfma_f32_16x16x32_bf16 v[72:75], v[152:155], v[198:201], 0
	v_mfma_f32_16x16x32_bf16 v[132:135], v[148:151], v[178:181], v[132:135]
	v_mfma_f32_16x16x32_bf16 v[128:131], v[170:173], v[178:181], v[128:131]
	v_mfma_f32_16x16x32_bf16 v[116:119], v[148:151], v[186:189], v[116:119]
	v_mfma_f32_16x16x32_bf16 v[112:115], v[170:173], v[186:189], v[112:115]
	v_mfma_f32_16x16x32_bf16 v[100:103], v[148:151], v[194:197], v[100:103]
	v_mfma_f32_16x16x32_bf16 v[96:99], v[170:173], v[194:197], v[96:99]
	v_mfma_f32_16x16x32_bf16 v[76:79], v[148:151], v[206:209], v[76:79]
	v_mfma_f32_16x16x32_bf16 v[72:75], v[170:173], v[206:209], v[72:75]
	s_setprio 0
	s_barrier
	s_add_i32 s75, s75, s38
	v_lshl_add_u64 v[202:203], s[42:43], 0, v[204:205]
	s_mov_b32 m0, s75
	ds_read_b128 v[174:177], v169 offset:16384
	ds_read_b128 v[178:181], v169 offset:17408
	ds_read_b128 v[182:185], v169 offset:18432
	ds_read_b128 v[186:189], v169 offset:19456
	ds_read_b128 v[190:193], v169 offset:20480
	ds_read_b128 v[194:197], v169 offset:21504
	ds_read_b128 v[198:201], v169 offset:22528
	ds_read_b128 v[206:209], v169 offset:23552
	global_load_lds_dwordx4 v[202:203], off
	s_add_i32 m0, s75, 0x2000
	s_add_u32 s76, s42, 0x80000
	v_lshl_add_u64 v[210:211], s[42:43], 0, v[160:161]
	s_addc_u32 s77, s43, 0
	s_add_i32 s75, s78, s38
	global_load_lds_dwordx4 v[210:211], off
	v_lshl_add_u64 v[212:213], s[76:77], 0, v[204:205]
	s_mov_b32 m0, s75
	v_lshl_add_u64 v[214:215], s[44:45], 0, v[158:159]
	global_load_lds_dwordx4 v[212:213], off
	v_lshl_add_u64 v[212:213], s[76:77], 0, v[160:161]
	s_add_i32 m0, s75, 0x2000
	s_nop 0
	global_load_lds_dwordx4 v[212:213], off
	v_lshl_add_u64 v[212:213], s[44:45], 0, v[156:157]
	s_mov_b32 m0, s35
	s_nop 0
	global_load_lds_dwordx4 v[212:213], off
	s_mov_b32 m0, s40
	s_nop 0
	global_load_lds_dwordx4 v[214:215], off
	s_waitcnt vmcnt(8)
	s_waitcnt lgkmcnt(0)
	s_barrier
; #define PG8_STAGE(bufoff, gbase, voff) do { _Pragma("unroll") for (int _i = 0; _i < 2; ++_i) \
;         __builtin_amdgcn_global_load_lds((const unsigned*)((const char*)(gbase) + (voff)[_i]), (PG8_LAS unsigned*)(lds + (bufoff) + ldsw + _i * 8192), 16, 0, 0); } while (0)
; #define PG8_LDA(dst, b, h) do { _Pragma("unroll") for (int m = 0; m < 4; ++m) _Pragma("unroll") for (int k = 0; k < 2; ++k) dst[m][k] = *(const PG8_LAS bf16x8*)(lds + PG8_SA(b, h) + aoff + m * 2048 + k * 1024); } while (0)
; #define PG8_LDB(dst, b, h) do { _Pragma("unroll") for (int n = 0; n < 2; ++n) _Pragma("unroll") for (int k = 0; k < 2; ++k) dst[n][k] = *(const PG8_LAS bf16x8*)(lds + PG8_SB(b, h) + boff + n * 2048 + k * 1024); } while (0)
; #define PG8_MMA(ai, bj, At, Bt) do { __builtin_amdgcn_s_setprio(1); _Pragma("unroll") for (int m = 0; m < 4; ++m) _Pragma("unroll") for (int n = 0; n < 2; ++n) _Pragma("unroll") for (int k = 0; k < 2; ++k) \
;         acc[ai][bj][m][n] = __builtin_amdgcn_mfma_f32_16x16x32_bf16(Bt[n][k], At[m][k], acc[ai][bj][m][n], 0, 0, 0); __builtin_amdgcn_s_setprio(0); } while (0)
; #define PG8_WAIT_V(n) asm volatile("s_waitcnt vmcnt(" #n ")" ::: "memory")
; #define PG8_WAIT_L(n) asm volatile("s_waitcnt lgkmcnt(" #n ")" ::: "memory")
; #define PG8_BAR __builtin_amdgcn_s_barrier()
; #define PG8_SCHED __builtin_amdgcn_sched_barrier(0)
; template <class Epi, class Sched, bool ALIGN_EPI = false, bool SP2 = false>
; __device__ __forceinline__ void gemm_phase(PG8_LAS unsigned char* lds, const Gemm g, const Sched& S, const Epi& E, const int tid) {
;     ...
;             PG8_LDA(At, 0, 1); PG8_STAGE(PG8_SB(0, 0), b2, voffB); PG8_STAGE(PG8_SB(0, 1), b2 + hstep, voffB); PG8_STAGE(PG8_SA(0, 0), a2, voffA);
;             PG8_WAIT_V(8); PG8_WAIT_L(0); PG8_BAR; PG8_MMA(1, 0, At, B0); PG8_MMA(1, 1, At, B1); PG8_BAR; PG8_SCHED;
;             PG8_LDB(B0, 1, 0); PG8_LDB(B1, 1, 1); PG8_SCHED; PG8_LDA(At, 1, 0); PG8_STAGE(PG8_SA(0, 1), a2 + hstep, voffA);
;             PG8_WAIT_V(8); PG8_WAIT_L(0); PG8_BAR; PG8_MMA(0, 0, At, B0); PG8_MMA(0, 1, At, B1); PG8_BAR; PG8_SCHED;
	s_setprio 1
	s_waitcnt lgkmcnt(0)
	v_mfma_f32_16x16x32_bf16 v[60:63], v[64:67], v[174:177], 0
	v_mfma_f32_16x16x32_bf16 v[56:59], v[80:83], v[174:177], 0
	v_mfma_f32_16x16x32_bf16 v[44:47], v[64:67], v[182:185], 0
	v_mfma_f32_16x16x32_bf16 v[40:43], v[80:83], v[182:185], 0
	v_mfma_f32_16x16x32_bf16 v[28:31], v[64:67], v[190:193], 0
	v_mfma_f32_16x16x32_bf16 v[24:27], v[80:83], v[190:193], 0
	v_mfma_f32_16x16x32_bf16 v[12:15], v[64:67], v[198:201], 0
	v_mfma_f32_16x16x32_bf16 v[8:11], v[80:83], v[198:201], 0
	v_mfma_f32_16x16x32_bf16 v[60:63], v[68:71], v[178:181], v[60:63]
	v_mfma_f32_16x16x32_bf16 v[56:59], v[84:87], v[178:181], v[56:59]
	v_mfma_f32_16x16x32_bf16 v[44:47], v[68:71], v[186:189], v[44:47]
	v_mfma_f32_16x16x32_bf16 v[40:43], v[84:87], v[186:189], v[40:43]
	v_mfma_f32_16x16x32_bf16 v[28:31], v[68:71], v[194:197], v[28:31]
	v_mfma_f32_16x16x32_bf16 v[24:27], v[84:87], v[194:197], v[24:27]
	v_mfma_f32_16x16x32_bf16 v[12:15], v[68:71], v[206:209], v[12:15]
	v_mfma_f32_16x16x32_bf16 v[8:11], v[84:87], v[206:209], v[8:11]
	s_setprio 0
	s_setprio 1
	v_mfma_f32_16x16x32_bf16 v[52:55], v[144:147], v[174:177], 0
	v_mfma_f32_16x16x32_bf16 v[48:51], v[152:155], v[174:177], 0
	v_mfma_f32_16x16x32_bf16 v[36:39], v[144:147], v[182:185], 0
	v_mfma_f32_16x16x32_bf16 v[32:35], v[152:155], v[182:185], 0
	v_mfma_f32_16x16x32_bf16 v[20:23], v[144:147], v[190:193], 0
	v_mfma_f32_16x16x32_bf16 v[16:19], v[152:155], v[190:193], 0
	v_mfma_f32_16x16x32_bf16 v[4:7], v[144:147], v[198:201], 0
	v_mfma_f32_16x16x32_bf16 v[0:3], v[152:155], v[198:201], 0
	v_mfma_f32_16x16x32_bf16 v[52:55], v[148:151], v[178:181], v[52:55]
	v_mfma_f32_16x16x32_bf16 v[48:51], v[170:173], v[178:181], v[48:51]
	v_mfma_f32_16x16x32_bf16 v[36:39], v[148:151], v[186:189], v[36:39]
	v_mfma_f32_16x16x32_bf16 v[32:35], v[170:173], v[186:189], v[32:35]
	v_mfma_f32_16x16x32_bf16 v[20:23], v[148:151], v[194:197], v[20:23]
	v_mfma_f32_16x16x32_bf16 v[16:19], v[170:173], v[194:197], v[16:19]
	v_mfma_f32_16x16x32_bf16 v[4:7], v[148:151], v[206:209], v[4:7]
	v_mfma_f32_16x16x32_bf16 v[0:3], v[170:173], v[206:209], v[0:3]
	s_setprio 0
	s_barrier
	s_add_i32 s75, 0, 0x18000
	s_add_i32 s76, 0, 0x1c000
	v_add_u32_e32 v84, s75, v167
	v_add_u32_e32 v166, s76, v167
	ds_read_b128 v[64:67], v84
	ds_read_b128 v[68:71], v84 offset:1024
	ds_read_b128 v[80:83], v84 offset:2048
	ds_read_b128 v[84:87], v84 offset:3072
	ds_read_b128 v[144:147], v166
	ds_read_b128 v[148:151], v166 offset:1024
	ds_read_b128 v[152:155], v166 offset:2048
	ds_read_b128 v[170:173], v166 offset:3072
	s_add_u32 s44, s44, 0x80000
	s_addc_u32 s45, s45, 0
	s_mov_b32 m0, s46
	v_lshl_add_u64 v[216:217], s[44:45], 0, v[156:157]
	ds_read_b128 v[174:177], v169 offset:32768
	ds_read_b128 v[178:181], v169 offset:33792
	ds_read_b128 v[182:185], v169 offset:34816
	ds_read_b128 v[186:189], v169 offset:35840
	ds_read_b128 v[190:193], v169 offset:36864
	ds_read_b128 v[194:197], v169 offset:37888
	ds_read_b128 v[198:201], v169 offset:38912
	ds_read_b128 v[206:209], v169 offset:39936
	global_load_lds_dwordx4 v[216:217], off
	v_lshl_add_u64 v[216:217], s[44:45], 0, v[158:159]
	s_mov_b32 m0, s47
	s_nop 0
	global_load_lds_dwordx4 v[216:217], off
	s_waitcnt vmcnt(8)
	s_waitcnt lgkmcnt(0)
	s_barrier
	s_setprio 1
	s_waitcnt lgkmcnt(0)
	v_mfma_f32_16x16x32_bf16 v[140:143], v[64:67], v[174:177], v[140:143]
	v_mfma_f32_16x16x32_bf16 v[136:139], v[80:83], v[174:177], v[136:139]
	v_mfma_f32_16x16x32_bf16 v[124:127], v[64:67], v[182:185], v[124:127]
	v_mfma_f32_16x16x32_bf16 v[120:123], v[80:83], v[182:185], v[120:123]
	v_mfma_f32_16x16x32_bf16 v[108:111], v[64:67], v[190:193], v[108:111]
	v_mfma_f32_16x16x32_bf16 v[104:107], v[80:83], v[190:193], v[104:107]
	v_mfma_f32_16x16x32_bf16 v[92:95], v[64:67], v[198:201], v[92:95]
	v_mfma_f32_16x16x32_bf16 v[88:91], v[80:83], v[198:201], v[88:91]
	v_mfma_f32_16x16x32_bf16 v[140:143], v[68:71], v[178:181], v[140:143]
	v_mfma_f32_16x16x32_bf16 v[136:139], v[84:87], v[178:181], v[136:139]
	v_mfma_f32_16x16x32_bf16 v[124:127], v[68:71], v[186:189], v[124:127]
	v_mfma_f32_16x16x32_bf16 v[120:123], v[84:87], v[186:189], v[120:123]
	v_mfma_f32_16x16x32_bf16 v[108:111], v[68:71], v[194:197], v[108:111]
	v_mfma_f32_16x16x32_bf16 v[104:107], v[84:87], v[194:197], v[104:107]
	v_mfma_f32_16x16x32_bf16 v[92:95], v[68:71], v[206:209], v[92:95]
	v_mfma_f32_16x16x32_bf16 v[88:91], v[84:87], v[206:209], v[88:91]
	s_setprio 0
	s_setprio 1
	v_mfma_f32_16x16x32_bf16 v[132:135], v[144:147], v[174:177], v[132:135]
	v_mfma_f32_16x16x32_bf16 v[128:131], v[152:155], v[174:177], v[128:131]
	v_mfma_f32_16x16x32_bf16 v[116:119], v[144:147], v[182:185], v[116:119]
	v_mfma_f32_16x16x32_bf16 v[112:115], v[152:155], v[182:185], v[112:115]
	v_mfma_f32_16x16x32_bf16 v[100:103], v[144:147], v[190:193], v[100:103]
	v_mfma_f32_16x16x32_bf16 v[96:99], v[152:155], v[190:193], v[96:99]
	v_mfma_f32_16x16x32_bf16 v[76:79], v[144:147], v[198:201], v[76:79]
	v_mfma_f32_16x16x32_bf16 v[72:75], v[152:155], v[198:201], v[72:75]
	v_mfma_f32_16x16x32_bf16 v[132:135], v[148:151], v[178:181], v[132:135]
	v_mfma_f32_16x16x32_bf16 v[128:131], v[170:173], v[178:181], v[128:131]
	v_mfma_f32_16x16x32_bf16 v[116:119], v[148:151], v[186:189], v[116:119]
	v_mfma_f32_16x16x32_bf16 v[112:115], v[170:173], v[186:189], v[112:115]
	v_mfma_f32_16x16x32_bf16 v[100:103], v[148:151], v[194:197], v[100:103]
	v_mfma_f32_16x16x32_bf16 v[96:99], v[170:173], v[194:197], v[96:99]
	v_mfma_f32_16x16x32_bf16 v[76:79], v[148:151], v[206:209], v[76:79]
	v_mfma_f32_16x16x32_bf16 v[72:75], v[170:173], v[206:209], v[72:75]
	s_setprio 0
	s_barrier
; #define PG8_STAGE(bufoff, gbase, voff) do { _Pragma("unroll") for (int _i = 0; _i < 2; ++_i) \
;         __builtin_amdgcn_global_load_lds((const unsigned*)((const char*)(gbase) + (voff)[_i]), (PG8_LAS unsigned*)(lds + (bufoff) + ldsw + _i * 8192), 16, 0, 0); } while (0)
; #define PG8_LDA(dst, b, h) do { _Pragma("unroll") for (int m = 0; m < 4; ++m) _Pragma("unroll") for (int k = 0; k < 2; ++k) dst[m][k] = *(const PG8_LAS bf16x8*)(lds + PG8_SA(b, h) + aoff + m * 2048 + k * 1024); } while (0)
; #define PG8_MMA(ai, bj, At, Bt) do { __builtin_amdgcn_s_setprio(1); _Pragma("unroll") for (int m = 0; m < 4; ++m) _Pragma("unroll") for (int n = 0; n < 2; ++n) _Pragma("unroll") for (int k = 0; k < 2; ++k) \
;         acc[ai][bj][m][n] = __builtin_amdgcn_mfma_f32_16x16x32_bf16(Bt[n][k], At[m][k], acc[ai][bj][m][n], 0, 0, 0); __builtin_amdgcn_s_setprio(0); } while (0)
; #define PG8_WAIT_V(n) asm volatile("s_waitcnt vmcnt(" #n ")" ::: "memory")
; #define PG8_WAIT_L(n) asm volatile("s_waitcnt lgkmcnt(" #n ")" ::: "memory")
; #define PG8_BAR __builtin_amdgcn_s_barrier()
; #define PG8_SCHED __builtin_amdgcn_sched_barrier(0)
; template <class Epi, class Sched, bool ALIGN_EPI = false, bool SP2 = false>
; __device__ __forceinline__ void gemm_phase(PG8_LAS unsigned char* lds, const Gemm g, const Sched& S, const Epi& E, const int tid) {
;     ...
;             PG8_LDA(At, 1, 1); PG8_STAGE(PG8_SB(1, 0), b3, voffB); PG8_STAGE(PG8_SB(1, 1), b3 + hstep, voffB); PG8_STAGE(PG8_SA(1, 0), a3, voffA);
;             PG8_WAIT_V(8); PG8_WAIT_L(0); PG8_BAR; PG8_MMA(1, 0, At, B0); PG8_MMA(1, 1, At, B1); PG8_BAR; PG8_SCHED;
	s_add_i32 s44, s75, s38
	v_lshl_add_u64 v[202:203], v[202:203], 0, s[70:71]
	s_mov_b32 m0, s44
	ds_read_b128 v[174:177], v169 offset:49152
	ds_read_b128 v[178:181], v169 offset:50176
	ds_read_b128 v[182:185], v169 offset:51200
	ds_read_b128 v[186:189], v169 offset:52224
	ds_read_b128 v[190:193], v169 offset:53248
	ds_read_b128 v[194:197], v169 offset:54272
	ds_read_b128 v[198:201], v169 offset:55296
	ds_read_b128 v[206:209], v169 offset:56320
	global_load_lds_dwordx4 v[202:203], off
	s_add_i32 m0, s44, 0x2000
	s_add_u32 s42, s42, 0x80080
	v_lshl_add_u64 v[202:203], v[210:211], 0, s[70:71]
	s_addc_u32 s43, s43, 0
	s_add_i32 s44, s76, s38
	global_load_lds_dwordx4 v[202:203], off
	v_lshl_add_u64 v[202:203], s[42:43], 0, v[204:205]
	s_mov_b32 m0, s44
	s_nop 0
	global_load_lds_dwordx4 v[202:203], off
	v_lshl_add_u64 v[202:203], s[42:43], 0, v[160:161]
	s_add_i32 m0, s44, 0x2000
	s_nop 0
	global_load_lds_dwordx4 v[202:203], off
	v_lshl_add_u64 v[202:203], v[212:213], 0, s[70:71]
	s_mov_b32 m0, s51
	s_nop 0
	global_load_lds_dwordx4 v[202:203], off
	v_lshl_add_u64 v[202:203], v[214:215], 0, s[70:71]
	s_mov_b32 m0, s52
	s_nop 0
	global_load_lds_dwordx4 v[202:203], off
	s_waitcnt vmcnt(8)
	s_waitcnt lgkmcnt(0)
	s_barrier
	s_setprio 1
	s_waitcnt lgkmcnt(0)
	v_mfma_f32_16x16x32_bf16 v[60:63], v[64:67], v[174:177], v[60:63]
	v_mfma_f32_16x16x32_bf16 v[56:59], v[80:83], v[174:177], v[56:59]
	v_mfma_f32_16x16x32_bf16 v[44:47], v[64:67], v[182:185], v[44:47]
	v_mfma_f32_16x16x32_bf16 v[40:43], v[80:83], v[182:185], v[40:43]
	v_mfma_f32_16x16x32_bf16 v[28:31], v[64:67], v[190:193], v[28:31]
	v_mfma_f32_16x16x32_bf16 v[24:27], v[80:83], v[190:193], v[24:27]
	v_mfma_f32_16x16x32_bf16 v[12:15], v[64:67], v[198:201], v[12:15]
	v_mfma_f32_16x16x32_bf16 v[8:11], v[80:83], v[198:201], v[8:11]
	v_mfma_f32_16x16x32_bf16 v[60:63], v[68:71], v[178:181], v[60:63]
	v_mfma_f32_16x16x32_bf16 v[56:59], v[84:87], v[178:181], v[56:59]
	v_mfma_f32_16x16x32_bf16 v[44:47], v[68:71], v[186:189], v[44:47]
	v_mfma_f32_16x16x32_bf16 v[40:43], v[84:87], v[186:189], v[40:43]
	v_mfma_f32_16x16x32_bf16 v[28:31], v[68:71], v[194:197], v[28:31]
	v_mfma_f32_16x16x32_bf16 v[24:27], v[84:87], v[194:197], v[24:27]
	v_mfma_f32_16x16x32_bf16 v[12:15], v[68:71], v[206:209], v[12:15]
	v_mfma_f32_16x16x32_bf16 v[8:11], v[84:87], v[206:209], v[8:11]
	s_setprio 0
	s_setprio 1
	v_mfma_f32_16x16x32_bf16 v[52:55], v[144:147], v[174:177], v[52:55]
	v_mfma_f32_16x16x32_bf16 v[48:51], v[152:155], v[174:177], v[48:51]
	v_mfma_f32_16x16x32_bf16 v[36:39], v[144:147], v[182:185], v[36:39]
	v_mfma_f32_16x16x32_bf16 v[32:35], v[152:155], v[182:185], v[32:35]
	v_mfma_f32_16x16x32_bf16 v[20:23], v[144:147], v[190:193], v[20:23]
	v_mfma_f32_16x16x32_bf16 v[16:19], v[152:155], v[190:193], v[16:19]
	v_mfma_f32_16x16x32_bf16 v[4:7], v[144:147], v[198:201], v[4:7]
	v_mfma_f32_16x16x32_bf16 v[0:3], v[152:155], v[198:201], v[0:3]
	v_mfma_f32_16x16x32_bf16 v[52:55], v[148:151], v[178:181], v[52:55]
	v_mfma_f32_16x16x32_bf16 v[48:51], v[170:173], v[178:181], v[48:51]
	v_mfma_f32_16x16x32_bf16 v[36:39], v[148:151], v[186:189], v[36:39]
	v_mfma_f32_16x16x32_bf16 v[32:35], v[170:173], v[186:189], v[32:35]
	v_mfma_f32_16x16x32_bf16 v[20:23], v[148:151], v[194:197], v[20:23]
	v_mfma_f32_16x16x32_bf16 v[16:19], v[170:173], v[194:197], v[16:19]
	v_mfma_f32_16x16x32_bf16 v[4:7], v[148:151], v[206:209], v[4:7]
	v_mfma_f32_16x16x32_bf16 v[0:3], v[170:173], v[206:209], v[0:3]
	s_setprio 0
	s_barrier
	s_add_i32 s69, s69, 2
	s_add_u32 s36, s36, 0x100
	s_addc_u32 s37, s37, 0
	s_add_u32 s65, s65, 0x100
	s_addc_u32 s68, s68, 0

; #define PG8_STAGE(bufoff, gbase, voff) do { _Pragma("unroll") for (int _i = 0; _i < 2; ++_i) \
;         __builtin_amdgcn_global_load_lds((const unsigned*)((const char*)(gbase) + (voff)[_i]), (PG8_LAS unsigned*)(lds + (bufoff) + ldsw + _i * 8192), 16, 0, 0); } while (0)
; #define PG8_LDA(dst, b, h) do { _Pragma("unroll") for (int m = 0; m < 4; ++m) _Pragma("unroll") for (int k = 0; k < 2; ++k) dst[m][k] = *(const PG8_LAS bf16x8*)(lds + PG8_SA(b, h) + aoff + m * 2048 + k * 1024); } while (0)
; #define PG8_LDB(dst, b, h) do { _Pragma("unroll") for (int n = 0; n < 2; ++n) _Pragma("unroll") for (int k = 0; k < 2; ++k) dst[n][k] = *(const PG8_LAS bf16x8*)(lds + PG8_SB(b, h) + boff + n * 2048 + k * 1024); } while (0)
; #define PG8_WAIT_V(n) asm volatile("s_waitcnt vmcnt(" #n ")" ::: "memory")
; #define PG8_WAIT_L(n) asm volatile("s_waitcnt lgkmcnt(" #n ")" ::: "memory")
; #define PG8_BAR __builtin_amdgcn_s_barrier()
; #define PG8_SCHED __builtin_amdgcn_sched_barrier(0)
; template <class Epi, class Sched, bool ALIGN_EPI = false, bool SP2 = false>
; __device__ __forceinline__ void gemm_phase(PG8_LAS unsigned char* lds, const Gemm g, const Sched& S, const Epi& E, const int tid) {
;     ...
;         const char* nA = has_next ? (const char*)g.A + (size_t)nxt.pm * tstep : cA; const char* nB = has_next ? (const char*)g.Bt + (size_t)nxt.pn * tstep : cB;
;         for (int t = 0; t < nt; t += 2) {
;             const bool last = (t == nt - 2);
;             const char* a1 = cA + (size_t)(t + 1) * kstep;
;             const char* a2 = last ? nA : cA + (size_t)(t + 2) * kstep; const char* b2 = last ? nB : cB + (size_t)(t + 2) * kstep;
;             const char* a3 = a2 + kstep; const char* b3 = b2 + kstep;
;             if (last && has_next) S.a_ready(nxt);
;             if constexpr (SP2) {
;             PG8_LDB(B0, 0, 0); PG8_LDB(B1, 0, 1); PG8_SCHED; PG8_LDA(At, 0, 0); PG8_STAGE(PG8_SA(1, 1), a1 + hstep, voffA);
;             PG8_WAIT_V(8); PG8_WAIT_L(0); PG8_BAR; PG8_MMA(0, 0, At, B0); PG8_MMA(0, 1, At, B1); PG8_BAR; PG8_SCHED;
;             PG8_LDA(At, 0, 1); PG8_STAGE(PG8_SB(0, 0), b2, voffB); PG8_STAGE(PG8_SB(0, 1), b2 + hstep, voffB); PG8_STAGE(PG8_SA(0, 0), a2, voffA);
;             PG8_WAIT_V(8); PG8_WAIT_L(0); PG8_BAR; PG8_MMA(1, 0, At, B0); PG8_MMA(1, 1, At, B1); PG8_BAR; PG8_SCHED;
.LBB0_1548:
	s_ashr_i32 s17, s16, 31
	s_lshl_b64 s[18:19], s[16:17], 18
	s_add_u32 s18, s10, s18
	s_addc_u32 s19, s11, s19
	s_and_b64 s[20:21], s[4:5], exec
	s_cselect_b32 s17, s19, s25
	s_cselect_b32 s48, s18, s24
	s_ashr_i32 s15, s14, 31
	s_lshl_b64 s[20:21], s[14:15], 18
	s_add_u32 s20, s30, s20
	s_addc_u32 s21, s31, s21
	s_and_b64 s[28:29], s[4:5], exec
	s_cselect_b32 s15, s21, s27
	s_cselect_b32 s49, s20, s26
	s_add_u32 s24, s24, 0x20080
	s_addc_u32 s25, s25, 0
	s_add_u32 s50, s26, 0x100
	s_addc_u32 s51, s27, 0
	s_mov_b32 s52, -2
	s_add_u32 s26, s24, 0xfffe0080
	s_addc_u32 s27, s25, -1
	s_add_i32 s53, 0, 0x10000
	s_cmp_eq_u32 s52, 4
	s_cselect_b32 s29, s17, s27
	s_cselect_b32 s28, s48, s26
	s_cselect_b32 s27, s15, s51
	s_cselect_b32 s26, s49, s50
	s_add_i32 s62, 0, 0x14000
	v_add_u32_e32 v152, s53, v142
	v_add_u32_e32 v168, s62, v142
	ds_read_b128 v[138:141], v152
	ds_read_b128 v[144:147], v152 offset:1024
	ds_read_b128 v[148:151], v152 offset:2048
	ds_read_b128 v[152:155], v152 offset:3072
	ds_read_b128 v[156:159], v168
	ds_read_b128 v[160:163], v168 offset:1024
	ds_read_b128 v[164:167], v168 offset:2048
	ds_read_b128 v[168:171], v168 offset:3072
	v_lshl_add_u64 v[206:207], s[24:25], 0, v[134:135]
	s_add_i32 m0, s23, 0xc000
	ds_read_b128 v[172:175], v143
	ds_read_b128 v[176:179], v143 offset:1024
	ds_read_b128 v[180:183], v143 offset:2048
	ds_read_b128 v[184:187], v143 offset:3072
	ds_read_b128 v[188:191], v143 offset:4096
	ds_read_b128 v[192:195], v143 offset:5120
	ds_read_b128 v[196:199], v143 offset:6144
	ds_read_b128 v[200:203], v143 offset:7168
	global_load_lds_dwordx4 v[206:207], off
	v_lshl_add_u64 v[206:207], s[24:25], 0, v[136:137]
	s_add_i32 m0, s23, 0xe000
	s_nop 0
	global_load_lds_dwordx4 v[206:207], off
	s_waitcnt vmcnt(24)
	s_waitcnt lgkmcnt(0)
	s_barrier
	s_setprio 1
	s_waitcnt lgkmcnt(0)
	v_mfma_f32_16x16x32_bf16 v[124:127], v[138:141], v[172:175], 0
	v_mfma_f32_16x16x32_bf16 v[120:123], v[148:151], v[172:175], 0
	v_mfma_f32_16x16x32_bf16 v[116:119], v[138:141], v[180:183], 0
	v_mfma_f32_16x16x32_bf16 v[108:111], v[148:151], v[180:183], 0
	v_mfma_f32_16x16x32_bf16 v[100:103], v[138:141], v[188:191], 0
	v_mfma_f32_16x16x32_bf16 v[92:95], v[148:151], v[188:191], 0
	v_mfma_f32_16x16x32_bf16 v[84:87], v[138:141], v[196:199], 0
	v_mfma_f32_16x16x32_bf16 v[76:79], v[148:151], v[196:199], 0
	v_mfma_f32_16x16x32_bf16 v[124:127], v[144:147], v[176:179], v[124:127]
	v_mfma_f32_16x16x32_bf16 v[120:123], v[152:155], v[176:179], v[120:123]
	v_mfma_f32_16x16x32_bf16 v[116:119], v[144:147], v[184:187], v[116:119]
	v_mfma_f32_16x16x32_bf16 v[108:111], v[152:155], v[184:187], v[108:111]
	v_mfma_f32_16x16x32_bf16 v[100:103], v[144:147], v[192:195], v[100:103]
	v_mfma_f32_16x16x32_bf16 v[92:95], v[152:155], v[192:195], v[92:95]
	v_mfma_f32_16x16x32_bf16 v[84:87], v[144:147], v[200:203], v[84:87]
	v_mfma_f32_16x16x32_bf16 v[76:79], v[152:155], v[200:203], v[76:79]
	s_setprio 0
	s_setprio 1
	v_mfma_f32_16x16x32_bf16 v[112:115], v[156:159], v[172:175], 0
	v_mfma_f32_16x16x32_bf16 v[104:107], v[164:167], v[172:175], 0
	v_mfma_f32_16x16x32_bf16 v[96:99], v[156:159], v[180:183], 0
	v_mfma_f32_16x16x32_bf16 v[88:91], v[164:167], v[180:183], 0
	v_mfma_f32_16x16x32_bf16 v[80:83], v[156:159], v[188:191], 0
	v_mfma_f32_16x16x32_bf16 v[72:75], v[164:167], v[188:191], 0
	v_mfma_f32_16x16x32_bf16 v[68:71], v[156:159], v[196:199], 0
	v_mfma_f32_16x16x32_bf16 v[64:67], v[164:167], v[196:199], 0
	v_mfma_f32_16x16x32_bf16 v[112:115], v[160:163], v[176:179], v[112:115]
	v_mfma_f32_16x16x32_bf16 v[104:107], v[168:171], v[176:179], v[104:107]
	v_mfma_f32_16x16x32_bf16 v[96:99], v[160:163], v[184:187], v[96:99]
	v_mfma_f32_16x16x32_bf16 v[88:91], v[168:171], v[184:187], v[88:91]
	v_mfma_f32_16x16x32_bf16 v[80:83], v[160:163], v[192:195], v[80:83]
	v_mfma_f32_16x16x32_bf16 v[72:75], v[168:171], v[192:195], v[72:75]
	v_mfma_f32_16x16x32_bf16 v[68:71], v[160:163], v[200:203], v[68:71]
	v_mfma_f32_16x16x32_bf16 v[64:67], v[168:171], v[200:203], v[64:67]
	s_setprio 0
	s_barrier
	s_add_i32 s53, s53, s33
	v_lshl_add_u64 v[206:207], s[26:27], 0, v[204:205]
	s_mov_b32 m0, s53
	ds_read_b128 v[172:175], v143 offset:16384
	ds_read_b128 v[176:179], v143 offset:17408
	ds_read_b128 v[180:183], v143 offset:18432
	ds_read_b128 v[184:187], v143 offset:19456
	ds_read_b128 v[188:191], v143 offset:20480
	ds_read_b128 v[192:195], v143 offset:21504
	ds_read_b128 v[196:199], v143 offset:22528
	ds_read_b128 v[200:203], v143 offset:23552
	global_load_lds_dwordx4 v[206:207], off
	s_add_i32 m0, s53, 0x2000
	s_add_u32 s54, s26, 0x20000
	v_lshl_add_u64 v[208:209], s[26:27], 0, v[128:129]
	s_addc_u32 s55, s27, 0
	s_add_i32 s53, s62, s33
	global_load_lds_dwordx4 v[208:209], off
	v_lshl_add_u64 v[210:211], s[54:55], 0, v[204:205]
	s_mov_b32 m0, s53
	v_lshl_add_u64 v[212:213], s[28:29], 0, v[130:131]
	global_load_lds_dwordx4 v[210:211], off
	v_lshl_add_u64 v[210:211], s[54:55], 0, v[128:129]
	s_add_i32 m0, s53, 0x2000
	s_nop 0
	global_load_lds_dwordx4 v[210:211], off
	v_lshl_add_u64 v[210:211], s[28:29], 0, v[132:133]
	s_mov_b32 m0, s23
	s_nop 0
	global_load_lds_dwordx4 v[210:211], off
	s_mov_b32 m0, s35
	s_nop 0
	global_load_lds_dwordx4 v[212:213], off
	s_waitcnt vmcnt(8)
	s_waitcnt lgkmcnt(0)
	s_barrier
; #define PG8_STAGE(bufoff, gbase, voff) do { _Pragma("unroll") for (int _i = 0; _i < 2; ++_i) \
;         __builtin_amdgcn_global_load_lds((const unsigned*)((const char*)(gbase) + (voff)[_i]), (PG8_LAS unsigned*)(lds + (bufoff) + ldsw + _i * 8192), 16, 0, 0); } while (0)
; #define PG8_LDA(dst, b, h) do { _Pragma("unroll") for (int m = 0; m < 4; ++m) _Pragma("unroll") for (int k = 0; k < 2; ++k) dst[m][k] = *(const PG8_LAS bf16x8*)(lds + PG8_SA(b, h) + aoff + m * 2048 + k * 1024); } while (0)
; #define PG8_LDB(dst, b, h) do { _Pragma("unroll") for (int n = 0; n < 2; ++n) _Pragma("unroll") for (int k = 0; k < 2; ++k) dst[n][k] = *(const PG8_LAS bf16x8*)(lds + PG8_SB(b, h) + boff + n * 2048 + k * 1024); } while (0)
; #define PG8_MMA(ai, bj, At, Bt) do { __builtin_amdgcn_s_setprio(1); _Pragma("unroll") for (int m = 0; m < 4; ++m) _Pragma("unroll") for (int n = 0; n < 2; ++n) _Pragma("unroll") for (int k = 0; k < 2; ++k) \
;         acc[ai][bj][m][n] = __builtin_amdgcn_mfma_f32_16x16x32_bf16(Bt[n][k], At[m][k], acc[ai][bj][m][n], 0, 0, 0); __builtin_amdgcn_s_setprio(0); } while (0)
; #define PG8_WAIT_V(n) asm volatile("s_waitcnt vmcnt(" #n ")" ::: "memory")
; #define PG8_WAIT_L(n) asm volatile("s_waitcnt lgkmcnt(" #n ")" ::: "memory")
; #define PG8_BAR __builtin_amdgcn_s_barrier()
; #define PG8_SCHED __builtin_amdgcn_sched_barrier(0)
; template <class Epi, class Sched, bool ALIGN_EPI = false, bool SP2 = false>
; __device__ __forceinline__ void gemm_phase(PG8_LAS unsigned char* lds, const Gemm g, const Sched& S, const Epi& E, const int tid) {
;     ...
;             PG8_LDA(At, 0, 1); PG8_STAGE(PG8_SB(0, 0), b2, voffB); PG8_STAGE(PG8_SB(0, 1), b2 + hstep, voffB); PG8_STAGE(PG8_SA(0, 0), a2, voffA);
;             PG8_WAIT_V(8); PG8_WAIT_L(0); PG8_BAR; PG8_MMA(1, 0, At, B0); PG8_MMA(1, 1, At, B1); PG8_BAR; PG8_SCHED;
;             PG8_LDB(B0, 1, 0); PG8_LDB(B1, 1, 1); PG8_SCHED; PG8_LDA(At, 1, 0); PG8_STAGE(PG8_SA(0, 1), a2 + hstep, voffA);
;             PG8_WAIT_V(8); PG8_WAIT_L(0); PG8_BAR; PG8_MMA(0, 0, At, B0); PG8_MMA(0, 1, At, B1); PG8_BAR; PG8_SCHED;
	s_setprio 1
	s_waitcnt lgkmcnt(0)
	v_mfma_f32_16x16x32_bf16 v[60:63], v[138:141], v[172:175], 0
	v_mfma_f32_16x16x32_bf16 v[56:59], v[148:151], v[172:175], 0
	v_mfma_f32_16x16x32_bf16 v[52:55], v[138:141], v[180:183], 0
	v_mfma_f32_16x16x32_bf16 v[44:47], v[148:151], v[180:183], 0
	v_mfma_f32_16x16x32_bf16 v[36:39], v[138:141], v[188:191], 0
	v_mfma_f32_16x16x32_bf16 v[28:31], v[148:151], v[188:191], 0
	v_mfma_f32_16x16x32_bf16 v[20:23], v[138:141], v[196:199], 0
	v_mfma_f32_16x16x32_bf16 v[12:15], v[148:151], v[196:199], 0
	v_mfma_f32_16x16x32_bf16 v[60:63], v[144:147], v[176:179], v[60:63]
	v_mfma_f32_16x16x32_bf16 v[56:59], v[152:155], v[176:179], v[56:59]
	v_mfma_f32_16x16x32_bf16 v[52:55], v[144:147], v[184:187], v[52:55]
	v_mfma_f32_16x16x32_bf16 v[44:47], v[152:155], v[184:187], v[44:47]
	v_mfma_f32_16x16x32_bf16 v[36:39], v[144:147], v[192:195], v[36:39]
	v_mfma_f32_16x16x32_bf16 v[28:31], v[152:155], v[192:195], v[28:31]
	v_mfma_f32_16x16x32_bf16 v[20:23], v[144:147], v[200:203], v[20:23]
	v_mfma_f32_16x16x32_bf16 v[12:15], v[152:155], v[200:203], v[12:15]
	s_setprio 0
	s_setprio 1
	v_mfma_f32_16x16x32_bf16 v[48:51], v[156:159], v[172:175], 0
	v_mfma_f32_16x16x32_bf16 v[40:43], v[164:167], v[172:175], 0
	v_mfma_f32_16x16x32_bf16 v[32:35], v[156:159], v[180:183], 0
	v_mfma_f32_16x16x32_bf16 v[24:27], v[164:167], v[180:183], 0
	v_mfma_f32_16x16x32_bf16 v[16:19], v[156:159], v[188:191], 0
	v_mfma_f32_16x16x32_bf16 v[8:11], v[164:167], v[188:191], 0
	v_mfma_f32_16x16x32_bf16 v[4:7], v[156:159], v[196:199], 0
	v_mfma_f32_16x16x32_bf16 v[0:3], v[164:167], v[196:199], 0
	v_mfma_f32_16x16x32_bf16 v[48:51], v[160:163], v[176:179], v[48:51]
	v_mfma_f32_16x16x32_bf16 v[40:43], v[168:171], v[176:179], v[40:43]
	v_mfma_f32_16x16x32_bf16 v[32:35], v[160:163], v[184:187], v[32:35]
	v_mfma_f32_16x16x32_bf16 v[24:27], v[168:171], v[184:187], v[24:27]
	v_mfma_f32_16x16x32_bf16 v[16:19], v[160:163], v[192:195], v[16:19]
	v_mfma_f32_16x16x32_bf16 v[8:11], v[168:171], v[192:195], v[8:11]
	v_mfma_f32_16x16x32_bf16 v[4:7], v[160:163], v[200:203], v[4:7]
	v_mfma_f32_16x16x32_bf16 v[0:3], v[168:171], v[200:203], v[0:3]
	s_setprio 0
	s_barrier
	s_add_i32 s53, 0, 0x18000
	s_add_i32 s54, 0, 0x1c000
	v_add_u32_e32 v152, s53, v142
	v_add_u32_e32 v168, s54, v142
	ds_read_b128 v[138:141], v152
	ds_read_b128 v[144:147], v152 offset:1024
	ds_read_b128 v[148:151], v152 offset:2048
	ds_read_b128 v[152:155], v152 offset:3072
	ds_read_b128 v[156:159], v168
	ds_read_b128 v[160:163], v168 offset:1024
	ds_read_b128 v[164:167], v168 offset:2048
	ds_read_b128 v[168:171], v168 offset:3072
	s_add_u32 s28, s28, 0x20000
	s_addc_u32 s29, s29, 0
	s_mov_b32 m0, s36
	v_lshl_add_u64 v[214:215], s[28:29], 0, v[132:133]
	ds_read_b128 v[172:175], v143 offset:32768
	ds_read_b128 v[176:179], v143 offset:33792
	ds_read_b128 v[180:183], v143 offset:34816
	ds_read_b128 v[184:187], v143 offset:35840
	ds_read_b128 v[188:191], v143 offset:36864
	ds_read_b128 v[192:195], v143 offset:37888
	ds_read_b128 v[196:199], v143 offset:38912
	ds_read_b128 v[200:203], v143 offset:39936
	global_load_lds_dwordx4 v[214:215], off
	v_lshl_add_u64 v[214:215], s[28:29], 0, v[130:131]
	s_mov_b32 m0, s37
	s_nop 0
	global_load_lds_dwordx4 v[214:215], off
	s_waitcnt vmcnt(8)
	s_waitcnt lgkmcnt(0)
	s_barrier
	s_setprio 1
	s_waitcnt lgkmcnt(0)
	v_mfma_f32_16x16x32_bf16 v[124:127], v[138:141], v[172:175], v[124:127]
	v_mfma_f32_16x16x32_bf16 v[120:123], v[148:151], v[172:175], v[120:123]
	v_mfma_f32_16x16x32_bf16 v[116:119], v[138:141], v[180:183], v[116:119]
	v_mfma_f32_16x16x32_bf16 v[108:111], v[148:151], v[180:183], v[108:111]
	v_mfma_f32_16x16x32_bf16 v[100:103], v[138:141], v[188:191], v[100:103]
	v_mfma_f32_16x16x32_bf16 v[92:95], v[148:151], v[188:191], v[92:95]
	v_mfma_f32_16x16x32_bf16 v[84:87], v[138:141], v[196:199], v[84:87]
	v_mfma_f32_16x16x32_bf16 v[76:79], v[148:151], v[196:199], v[76:79]
	v_mfma_f32_16x16x32_bf16 v[124:127], v[144:147], v[176:179], v[124:127]
	v_mfma_f32_16x16x32_bf16 v[120:123], v[152:155], v[176:179], v[120:123]
	v_mfma_f32_16x16x32_bf16 v[116:119], v[144:147], v[184:187], v[116:119]
	v_mfma_f32_16x16x32_bf16 v[108:111], v[152:155], v[184:187], v[108:111]
	v_mfma_f32_16x16x32_bf16 v[100:103], v[144:147], v[192:195], v[100:103]
	v_mfma_f32_16x16x32_bf16 v[92:95], v[152:155], v[192:195], v[92:95]
	v_mfma_f32_16x16x32_bf16 v[84:87], v[144:147], v[200:203], v[84:87]
	v_mfma_f32_16x16x32_bf16 v[76:79], v[152:155], v[200:203], v[76:79]
	s_setprio 0
	s_setprio 1
	v_mfma_f32_16x16x32_bf16 v[112:115], v[156:159], v[172:175], v[112:115]
	v_mfma_f32_16x16x32_bf16 v[104:107], v[164:167], v[172:175], v[104:107]
	v_mfma_f32_16x16x32_bf16 v[96:99], v[156:159], v[180:183], v[96:99]
	v_mfma_f32_16x16x32_bf16 v[88:91], v[164:167], v[180:183], v[88:91]
	v_mfma_f32_16x16x32_bf16 v[80:83], v[156:159], v[188:191], v[80:83]
	v_mfma_f32_16x16x32_bf16 v[72:75], v[164:167], v[188:191], v[72:75]
	v_mfma_f32_16x16x32_bf16 v[68:71], v[156:159], v[196:199], v[68:71]
	v_mfma_f32_16x16x32_bf16 v[64:67], v[164:167], v[196:199], v[64:67]
	v_mfma_f32_16x16x32_bf16 v[112:115], v[160:163], v[176:179], v[112:115]
	v_mfma_f32_16x16x32_bf16 v[104:107], v[168:171], v[176:179], v[104:107]
	v_mfma_f32_16x16x32_bf16 v[96:99], v[160:163], v[184:187], v[96:99]
	v_mfma_f32_16x16x32_bf16 v[88:91], v[168:171], v[184:187], v[88:91]
	v_mfma_f32_16x16x32_bf16 v[80:83], v[160:163], v[192:195], v[80:83]
	v_mfma_f32_16x16x32_bf16 v[72:75], v[168:171], v[192:195], v[72:75]
	v_mfma_f32_16x16x32_bf16 v[68:71], v[160:163], v[200:203], v[68:71]
	v_mfma_f32_16x16x32_bf16 v[64:67], v[168:171], v[200:203], v[64:67]
	s_setprio 0
	s_barrier
; #define PG8_STAGE(bufoff, gbase, voff) do { _Pragma("unroll") for (int _i = 0; _i < 2; ++_i) \
;         __builtin_amdgcn_global_load_lds((const unsigned*)((const char*)(gbase) + (voff)[_i]), (PG8_LAS unsigned*)(lds + (bufoff) + ldsw + _i * 8192), 16, 0, 0); } while (0)
; #define PG8_LDA(dst, b, h) do { _Pragma("unroll") for (int m = 0; m < 4; ++m) _Pragma("unroll") for (int k = 0; k < 2; ++k) dst[m][k] = *(const PG8_LAS bf16x8*)(lds + PG8_SA(b, h) + aoff + m * 2048 + k * 1024); } while (0)
; #define PG8_MMA(ai, bj, At, Bt) do { __builtin_amdgcn_s_setprio(1); _Pragma("unroll") for (int m = 0; m < 4; ++m) _Pragma("unroll") for (int n = 0; n < 2; ++n) _Pragma("unroll") for (int k = 0; k < 2; ++k) \
;         acc[ai][bj][m][n] = __builtin_amdgcn_mfma_f32_16x16x32_bf16(Bt[n][k], At[m][k], acc[ai][bj][m][n], 0, 0, 0); __builtin_amdgcn_s_setprio(0); } while (0)
; #define PG8_WAIT_V(n) asm volatile("s_waitcnt vmcnt(" #n ")" ::: "memory")
; #define PG8_WAIT_L(n) asm volatile("s_waitcnt lgkmcnt(" #n ")" ::: "memory")
; #define PG8_BAR __builtin_amdgcn_s_barrier()
; #define PG8_SCHED __builtin_amdgcn_sched_barrier(0)
; template <class Epi, class Sched, bool ALIGN_EPI = false, bool SP2 = false>
; __device__ __forceinline__ void gemm_phase(PG8_LAS unsigned char* lds, const Gemm g, const Sched& S, const Epi& E, const int tid) {
;     ...
;             PG8_LDA(At, 1, 1); PG8_STAGE(PG8_SB(1, 0), b3, voffB); PG8_STAGE(PG8_SB(1, 1), b3 + hstep, voffB); PG8_STAGE(PG8_SA(1, 0), a3, voffA);
;             PG8_WAIT_V(8); PG8_WAIT_L(0); PG8_BAR; PG8_MMA(1, 0, At, B0); PG8_MMA(1, 1, At, B1); PG8_BAR; PG8_SCHED;
	s_add_i32 s28, s53, s33
	v_lshl_add_u64 v[206:207], v[206:207], 0, s[70:71]
	s_mov_b32 m0, s28
	ds_read_b128 v[172:175], v143 offset:49152
	ds_read_b128 v[176:179], v143 offset:50176
	ds_read_b128 v[180:183], v143 offset:51200
	ds_read_b128 v[184:187], v143 offset:52224
	ds_read_b128 v[188:191], v143 offset:53248
	ds_read_b128 v[192:195], v143 offset:54272
	ds_read_b128 v[196:199], v143 offset:55296
	ds_read_b128 v[200:203], v143 offset:56320
	global_load_lds_dwordx4 v[206:207], off
	s_add_i32 m0, s28, 0x2000
	s_add_u32 s26, s26, 0x20080
	v_lshl_add_u64 v[206:207], v[208:209], 0, s[70:71]
	s_addc_u32 s27, s27, 0
	s_add_i32 s28, s54, s33
	global_load_lds_dwordx4 v[206:207], off
	v_lshl_add_u64 v[206:207], s[26:27], 0, v[204:205]
	s_mov_b32 m0, s28
	s_nop 0
	global_load_lds_dwordx4 v[206:207], off
	v_lshl_add_u64 v[206:207], s[26:27], 0, v[128:129]
	s_add_i32 m0, s28, 0x2000
	s_nop 0
	global_load_lds_dwordx4 v[206:207], off
	v_lshl_add_u64 v[206:207], v[210:211], 0, s[70:71]
	s_mov_b32 m0, s43
	s_nop 0
	global_load_lds_dwordx4 v[206:207], off
	v_lshl_add_u64 v[206:207], v[212:213], 0, s[70:71]
	s_mov_b32 m0, s44
	s_nop 0
	global_load_lds_dwordx4 v[206:207], off
	s_waitcnt vmcnt(8)
	s_waitcnt lgkmcnt(0)
	s_barrier
	s_setprio 1
	s_waitcnt lgkmcnt(0)
	v_mfma_f32_16x16x32_bf16 v[60:63], v[138:141], v[172:175], v[60:63]
	v_mfma_f32_16x16x32_bf16 v[56:59], v[148:151], v[172:175], v[56:59]
	v_mfma_f32_16x16x32_bf16 v[52:55], v[138:141], v[180:183], v[52:55]
	v_mfma_f32_16x16x32_bf16 v[44:47], v[148:151], v[180:183], v[44:47]
	v_mfma_f32_16x16x32_bf16 v[36:39], v[138:141], v[188:191], v[36:39]
	v_mfma_f32_16x16x32_bf16 v[28:31], v[148:151], v[188:191], v[28:31]
	v_mfma_f32_16x16x32_bf16 v[20:23], v[138:141], v[196:199], v[20:23]
	v_mfma_f32_16x16x32_bf16 v[12:15], v[148:151], v[196:199], v[12:15]
	v_mfma_f32_16x16x32_bf16 v[60:63], v[144:147], v[176:179], v[60:63]
	v_mfma_f32_16x16x32_bf16 v[56:59], v[152:155], v[176:179], v[56:59]
	v_mfma_f32_16x16x32_bf16 v[52:55], v[144:147], v[184:187], v[52:55]
	v_mfma_f32_16x16x32_bf16 v[44:47], v[152:155], v[184:187], v[44:47]
	v_mfma_f32_16x16x32_bf16 v[36:39], v[144:147], v[192:195], v[36:39]
	v_mfma_f32_16x16x32_bf16 v[28:31], v[152:155], v[192:195], v[28:31]
	v_mfma_f32_16x16x32_bf16 v[20:23], v[144:147], v[200:203], v[20:23]
	v_mfma_f32_16x16x32_bf16 v[12:15], v[152:155], v[200:203], v[12:15]
	s_setprio 0
	s_setprio 1
	v_mfma_f32_16x16x32_bf16 v[48:51], v[156:159], v[172:175], v[48:51]
	v_mfma_f32_16x16x32_bf16 v[40:43], v[164:167], v[172:175], v[40:43]
	v_mfma_f32_16x16x32_bf16 v[32:35], v[156:159], v[180:183], v[32:35]
	v_mfma_f32_16x16x32_bf16 v[24:27], v[164:167], v[180:183], v[24:27]
	v_mfma_f32_16x16x32_bf16 v[16:19], v[156:159], v[188:191], v[16:19]
	v_mfma_f32_16x16x32_bf16 v[8:11], v[164:167], v[188:191], v[8:11]
	v_mfma_f32_16x16x32_bf16 v[4:7], v[156:159], v[196:199], v[4:7]
	v_mfma_f32_16x16x32_bf16 v[0:3], v[164:167], v[196:199], v[0:3]
	v_mfma_f32_16x16x32_bf16 v[48:51], v[160:163], v[176:179], v[48:51]
	v_mfma_f32_16x16x32_bf16 v[40:43], v[168:171], v[176:179], v[40:43]
	v_mfma_f32_16x16x32_bf16 v[32:35], v[160:163], v[184:187], v[32:35]
	v_mfma_f32_16x16x32_bf16 v[24:27], v[168:171], v[184:187], v[24:27]
	v_mfma_f32_16x16x32_bf16 v[16:19], v[160:163], v[192:195], v[16:19]
	v_mfma_f32_16x16x32_bf16 v[8:11], v[168:171], v[192:195], v[8:11]
	v_mfma_f32_16x16x32_bf16 v[4:7], v[160:163], v[200:203], v[4:7]
	v_mfma_f32_16x16x32_bf16 v[0:3], v[168:171], v[200:203], v[0:3]
	s_setprio 0
	s_barrier
	s_add_i32 s52, s52, 2
	s_add_u32 s24, s24, 0x100
	s_addc_u32 s25, s25, 0
	s_add_u32 s50, s50, 0x100
	s_addc_u32 s51, s51, 0

; #define PG8_STAGE(bufoff, gbase, voff) do { _Pragma("unroll") for (int _i = 0; _i < 2; ++_i) \
;         __builtin_amdgcn_global_load_lds((const unsigned*)((const char*)(gbase) + (voff)[_i]), (PG8_LAS unsigned*)(lds + (bufoff) + ldsw + _i * 8192), 16, 0, 0); } while (0)
; #define PG8_LDA(dst, b, h) do { _Pragma("unroll") for (int m = 0; m < 4; ++m) _Pragma("unroll") for (int k = 0; k < 2; ++k) dst[m][k] = *(const PG8_LAS bf16x8*)(lds + PG8_SA(b, h) + aoff + m * 2048 + k * 1024); } while (0)
; #define PG8_LDB(dst, b, h) do { _Pragma("unroll") for (int n = 0; n < 2; ++n) _Pragma("unroll") for (int k = 0; k < 2; ++k) dst[n][k] = *(const PG8_LAS bf16x8*)(lds + PG8_SB(b, h) + boff + n * 2048 + k * 1024); } while (0)
; #define PG8_WAIT_V(n) asm volatile("s_waitcnt vmcnt(" #n ")" ::: "memory")
; #define PG8_WAIT_L(n) asm volatile("s_waitcnt lgkmcnt(" #n ")" ::: "memory")
; #define PG8_BAR __builtin_amdgcn_s_barrier()
; #define PG8_SCHED __builtin_amdgcn_sched_barrier(0)
; template <class Epi, class Sched, bool ALIGN_EPI = false, bool SP2 = false>
; __device__ __forceinline__ void gemm_phase(PG8_LAS unsigned char* lds, const Gemm g, const Sched& S, const Epi& E, const int tid) {
;     ...
;         const char* nA = has_next ? (const char*)g.A + (size_t)nxt.pm * tstep : cA; const char* nB = has_next ? (const char*)g.Bt + (size_t)nxt.pn * tstep : cB;
;         for (int t = 0; t < nt; t += 2) {
;             const bool last = (t == nt - 2);
;             const char* a1 = cA + (size_t)(t + 1) * kstep;
;             const char* a2 = last ? nA : cA + (size_t)(t + 2) * kstep; const char* b2 = last ? nB : cB + (size_t)(t + 2) * kstep;
;             const char* a3 = a2 + kstep; const char* b3 = b2 + kstep;
;             if (last && has_next) S.a_ready(nxt);
;             if constexpr (SP2) {
;             PG8_LDB(B0, 0, 0); PG8_LDB(B1, 0, 1); PG8_SCHED; PG8_LDA(At, 0, 0); PG8_STAGE(PG8_SA(1, 1), a1 + hstep, voffA);
;             PG8_WAIT_V(8); PG8_WAIT_L(0); PG8_BAR; PG8_MMA(0, 0, At, B0); PG8_MMA(0, 1, At, B1); PG8_BAR; PG8_SCHED;
;             PG8_LDA(At, 0, 1); PG8_STAGE(PG8_SB(0, 0), b2, voffB); PG8_STAGE(PG8_SB(0, 1), b2 + hstep, voffB); PG8_STAGE(PG8_SA(0, 0), a2, voffA);
;             PG8_WAIT_V(8); PG8_WAIT_L(0); PG8_BAR; PG8_MMA(1, 0, At, B0); PG8_MMA(1, 1, At, B1); PG8_BAR; PG8_SCHED;
.LBB0_1572:
	s_ashr_i32 s17, s16, 31
	s_lshl_b64 s[18:19], s[16:17], 18
	s_add_u32 s18, s11, s18
	s_addc_u32 s19, s30, s19
	s_and_b64 s[20:21], s[4:5], exec
	s_cselect_b32 s17, s19, s25
	s_cselect_b32 s48, s18, s24
	s_ashr_i32 s15, s14, 31
	s_lshl_b64 s[20:21], s[14:15], 18
	s_add_u32 s20, s31, s20
	s_addc_u32 s21, s33, s21
	s_and_b64 s[28:29], s[4:5], exec
	s_cselect_b32 s15, s21, s27
	s_cselect_b32 s49, s20, s26
	s_add_u32 s24, s24, 0x20080
	s_addc_u32 s25, s25, 0
	s_add_u32 s50, s26, 0x100
	s_addc_u32 s51, s27, 0
	s_mov_b32 s52, -2
	s_add_u32 s26, s24, 0xfffe0080
	s_addc_u32 s27, s25, -1
	s_add_i32 s53, 0, 0x10000
	s_cmp_eq_u32 s52, 4
	s_cselect_b32 s29, s17, s27
	s_cselect_b32 s28, s48, s26
	v_add_u32_e32 v138, s53, v140
	s_cselect_b32 s27, s15, s51
	s_cselect_b32 s26, s49, s50
	s_add_i32 s62, 0, 0x14000
	ds_read_b128 v[142:145], v138
	ds_read_b128 v[146:149], v138 offset:1024
	ds_read_b128 v[150:153], v138 offset:2048
	ds_read_b128 v[154:157], v138 offset:3072
	v_add_u32_e32 v138, s62, v140
	ds_read_b128 v[158:161], v138
	ds_read_b128 v[162:165], v138 offset:1024
	ds_read_b128 v[166:169], v138 offset:2048
	ds_read_b128 v[170:173], v138 offset:3072
	v_lshl_add_u64 v[138:139], s[24:25], 0, v[134:135]
	s_add_i32 m0, s23, 0xc000
	ds_read_b128 v[174:177], v141
	ds_read_b128 v[178:181], v141 offset:1024
	ds_read_b128 v[182:185], v141 offset:2048
	ds_read_b128 v[186:189], v141 offset:3072
	ds_read_b128 v[190:193], v141 offset:4096
	ds_read_b128 v[194:197], v141 offset:5120
	ds_read_b128 v[198:201], v141 offset:6144
	ds_read_b128 v[206:209], v141 offset:7168
	global_load_lds_dwordx4 v[138:139], off
	v_lshl_add_u64 v[138:139], s[24:25], 0, v[136:137]
	s_add_i32 m0, s23, 0xe000
	s_nop 0
	global_load_lds_dwordx4 v[138:139], off
	s_waitcnt vmcnt(24)
	s_waitcnt lgkmcnt(0)
	s_barrier
	s_setprio 1
	s_waitcnt lgkmcnt(0)
	v_mfma_f32_16x16x32_bf16 v[124:127], v[142:145], v[174:177], 0
	v_mfma_f32_16x16x32_bf16 v[120:123], v[150:153], v[174:177], 0
	v_mfma_f32_16x16x32_bf16 v[116:119], v[142:145], v[182:185], 0
	v_mfma_f32_16x16x32_bf16 v[108:111], v[150:153], v[182:185], 0
	v_mfma_f32_16x16x32_bf16 v[100:103], v[142:145], v[190:193], 0
	v_mfma_f32_16x16x32_bf16 v[92:95], v[150:153], v[190:193], 0
	v_mfma_f32_16x16x32_bf16 v[84:87], v[142:145], v[198:201], 0
	v_mfma_f32_16x16x32_bf16 v[76:79], v[150:153], v[198:201], 0
	v_mfma_f32_16x16x32_bf16 v[124:127], v[146:149], v[178:181], v[124:127]
	v_mfma_f32_16x16x32_bf16 v[120:123], v[154:157], v[178:181], v[120:123]
	v_mfma_f32_16x16x32_bf16 v[116:119], v[146:149], v[186:189], v[116:119]
	v_mfma_f32_16x16x32_bf16 v[108:111], v[154:157], v[186:189], v[108:111]
	v_mfma_f32_16x16x32_bf16 v[100:103], v[146:149], v[194:197], v[100:103]
	v_mfma_f32_16x16x32_bf16 v[92:95], v[154:157], v[194:197], v[92:95]
	v_mfma_f32_16x16x32_bf16 v[84:87], v[146:149], v[206:209], v[84:87]
	v_mfma_f32_16x16x32_bf16 v[76:79], v[154:157], v[206:209], v[76:79]
	s_setprio 0
	s_setprio 1
	v_mfma_f32_16x16x32_bf16 v[112:115], v[158:161], v[174:177], 0
	v_mfma_f32_16x16x32_bf16 v[104:107], v[166:169], v[174:177], 0
	v_mfma_f32_16x16x32_bf16 v[96:99], v[158:161], v[182:185], 0
	v_mfma_f32_16x16x32_bf16 v[88:91], v[166:169], v[182:185], 0
	v_mfma_f32_16x16x32_bf16 v[80:83], v[158:161], v[190:193], 0
	v_mfma_f32_16x16x32_bf16 v[72:75], v[166:169], v[190:193], 0
	v_mfma_f32_16x16x32_bf16 v[68:71], v[158:161], v[198:201], 0
	v_mfma_f32_16x16x32_bf16 v[64:67], v[166:169], v[198:201], 0
	v_mfma_f32_16x16x32_bf16 v[112:115], v[162:165], v[178:181], v[112:115]
	v_mfma_f32_16x16x32_bf16 v[104:107], v[170:173], v[178:181], v[104:107]
	v_mfma_f32_16x16x32_bf16 v[96:99], v[162:165], v[186:189], v[96:99]
	v_mfma_f32_16x16x32_bf16 v[88:91], v[170:173], v[186:189], v[88:91]
	v_mfma_f32_16x16x32_bf16 v[80:83], v[162:165], v[194:197], v[80:83]
	v_mfma_f32_16x16x32_bf16 v[72:75], v[170:173], v[194:197], v[72:75]
	v_mfma_f32_16x16x32_bf16 v[68:71], v[162:165], v[206:209], v[68:71]
	v_mfma_f32_16x16x32_bf16 v[64:67], v[170:173], v[206:209], v[64:67]
	s_setprio 0
	s_barrier
	s_add_i32 s53, s53, s34
	v_lshl_add_u64 v[138:139], s[26:27], 0, v[204:205]
	s_mov_b32 m0, s53
	ds_read_b128 v[174:177], v141 offset:16384
	ds_read_b128 v[178:181], v141 offset:17408
	ds_read_b128 v[182:185], v141 offset:18432
	ds_read_b128 v[186:189], v141 offset:19456
	ds_read_b128 v[190:193], v141 offset:20480
	ds_read_b128 v[194:197], v141 offset:21504
	ds_read_b128 v[198:201], v141 offset:22528
	ds_read_b128 v[206:209], v141 offset:23552
	global_load_lds_dwordx4 v[138:139], off
	s_add_i32 m0, s53, 0x2000
	s_add_u32 s54, s26, 0x20000
	v_lshl_add_u64 v[202:203], s[26:27], 0, v[132:133]
	s_addc_u32 s55, s27, 0
	s_add_i32 s53, s62, s34
	global_load_lds_dwordx4 v[202:203], off
	v_lshl_add_u64 v[210:211], s[54:55], 0, v[204:205]
	s_mov_b32 m0, s53
	v_lshl_add_u64 v[212:213], s[28:29], 0, v[130:131]
	global_load_lds_dwordx4 v[210:211], off
	v_lshl_add_u64 v[210:211], s[54:55], 0, v[132:133]
	s_add_i32 m0, s53, 0x2000
	s_nop 0
	global_load_lds_dwordx4 v[210:211], off
	v_lshl_add_u64 v[210:211], s[28:29], 0, v[128:129]
	s_mov_b32 m0, s23
	s_nop 0
	global_load_lds_dwordx4 v[210:211], off
	s_mov_b32 m0, s35
	s_nop 0
	global_load_lds_dwordx4 v[212:213], off
	s_waitcnt vmcnt(8)
	s_waitcnt lgkmcnt(0)
	s_barrier
; #define PG8_STAGE(bufoff, gbase, voff) do { _Pragma("unroll") for (int _i = 0; _i < 2; ++_i) \
;         __builtin_amdgcn_global_load_lds((const unsigned*)((const char*)(gbase) + (voff)[_i]), (PG8_LAS unsigned*)(lds + (bufoff) + ldsw + _i * 8192), 16, 0, 0); } while (0)
; #define PG8_LDA(dst, b, h) do { _Pragma("unroll") for (int m = 0; m < 4; ++m) _Pragma("unroll") for (int k = 0; k < 2; ++k) dst[m][k] = *(const PG8_LAS bf16x8*)(lds + PG8_SA(b, h) + aoff + m * 2048 + k * 1024); } while (0)
; #define PG8_LDB(dst, b, h) do { _Pragma("unroll") for (int n = 0; n < 2; ++n) _Pragma("unroll") for (int k = 0; k < 2; ++k) dst[n][k] = *(const PG8_LAS bf16x8*)(lds + PG8_SB(b, h) + boff + n * 2048 + k * 1024); } while (0)
; #define PG8_MMA(ai, bj, At, Bt) do { __builtin_amdgcn_s_setprio(1); _Pragma("unroll") for (int m = 0; m < 4; ++m) _Pragma("unroll") for (int n = 0; n < 2; ++n) _Pragma("unroll") for (int k = 0; k < 2; ++k) \
;         acc[ai][bj][m][n] = __builtin_amdgcn_mfma_f32_16x16x32_bf16(Bt[n][k], At[m][k], acc[ai][bj][m][n], 0, 0, 0); __builtin_amdgcn_s_setprio(0); } while (0)
; #define PG8_WAIT_V(n) asm volatile("s_waitcnt vmcnt(" #n ")" ::: "memory")
; #define PG8_WAIT_L(n) asm volatile("s_waitcnt lgkmcnt(" #n ")" ::: "memory")
; #define PG8_BAR __builtin_amdgcn_s_barrier()
; #define PG8_SCHED __builtin_amdgcn_sched_barrier(0)
; template <class Epi, class Sched, bool ALIGN_EPI = false, bool SP2 = false>
; __device__ __forceinline__ void gemm_phase(PG8_LAS unsigned char* lds, const Gemm g, const Sched& S, const Epi& E, const int tid) {
;     ...
;             PG8_LDA(At, 0, 1); PG8_STAGE(PG8_SB(0, 0), b2, voffB); PG8_STAGE(PG8_SB(0, 1), b2 + hstep, voffB); PG8_STAGE(PG8_SA(0, 0), a2, voffA);
;             PG8_WAIT_V(8); PG8_WAIT_L(0); PG8_BAR; PG8_MMA(1, 0, At, B0); PG8_MMA(1, 1, At, B1); PG8_BAR; PG8_SCHED;
;             PG8_LDB(B0, 1, 0); PG8_LDB(B1, 1, 1); PG8_SCHED; PG8_LDA(At, 1, 0); PG8_STAGE(PG8_SA(0, 1), a2 + hstep, voffA);
;             PG8_WAIT_V(8); PG8_WAIT_L(0); PG8_BAR; PG8_MMA(0, 0, At, B0); PG8_MMA(0, 1, At, B1); PG8_BAR; PG8_SCHED;
	s_setprio 1
	s_waitcnt lgkmcnt(0)
	v_mfma_f32_16x16x32_bf16 v[60:63], v[142:145], v[174:177], 0
	v_mfma_f32_16x16x32_bf16 v[56:59], v[150:153], v[174:177], 0
	v_mfma_f32_16x16x32_bf16 v[52:55], v[142:145], v[182:185], 0
	v_mfma_f32_16x16x32_bf16 v[44:47], v[150:153], v[182:185], 0
	v_mfma_f32_16x16x32_bf16 v[36:39], v[142:145], v[190:193], 0
	v_mfma_f32_16x16x32_bf16 v[28:31], v[150:153], v[190:193], 0
	v_mfma_f32_16x16x32_bf16 v[20:23], v[142:145], v[198:201], 0
	v_mfma_f32_16x16x32_bf16 v[12:15], v[150:153], v[198:201], 0
	v_mfma_f32_16x16x32_bf16 v[60:63], v[146:149], v[178:181], v[60:63]
	v_mfma_f32_16x16x32_bf16 v[56:59], v[154:157], v[178:181], v[56:59]
	v_mfma_f32_16x16x32_bf16 v[52:55], v[146:149], v[186:189], v[52:55]
	v_mfma_f32_16x16x32_bf16 v[44:47], v[154:157], v[186:189], v[44:47]
	v_mfma_f32_16x16x32_bf16 v[36:39], v[146:149], v[194:197], v[36:39]
	v_mfma_f32_16x16x32_bf16 v[28:31], v[154:157], v[194:197], v[28:31]
	v_mfma_f32_16x16x32_bf16 v[20:23], v[146:149], v[206:209], v[20:23]
	v_mfma_f32_16x16x32_bf16 v[12:15], v[154:157], v[206:209], v[12:15]
	s_setprio 0
	s_setprio 1
	v_mfma_f32_16x16x32_bf16 v[48:51], v[158:161], v[174:177], 0
	v_mfma_f32_16x16x32_bf16 v[40:43], v[166:169], v[174:177], 0
	v_mfma_f32_16x16x32_bf16 v[32:35], v[158:161], v[182:185], 0
	v_mfma_f32_16x16x32_bf16 v[24:27], v[166:169], v[182:185], 0
	v_mfma_f32_16x16x32_bf16 v[16:19], v[158:161], v[190:193], 0
	v_mfma_f32_16x16x32_bf16 v[8:11], v[166:169], v[190:193], 0
	v_mfma_f32_16x16x32_bf16 v[4:7], v[158:161], v[198:201], 0
	v_mfma_f32_16x16x32_bf16 v[0:3], v[166:169], v[198:201], 0
	v_mfma_f32_16x16x32_bf16 v[48:51], v[162:165], v[178:181], v[48:51]
	v_mfma_f32_16x16x32_bf16 v[40:43], v[170:173], v[178:181], v[40:43]
	v_mfma_f32_16x16x32_bf16 v[32:35], v[162:165], v[186:189], v[32:35]
	v_mfma_f32_16x16x32_bf16 v[24:27], v[170:173], v[186:189], v[24:27]
	v_mfma_f32_16x16x32_bf16 v[16:19], v[162:165], v[194:197], v[16:19]
	v_mfma_f32_16x16x32_bf16 v[8:11], v[170:173], v[194:197], v[8:11]
	v_mfma_f32_16x16x32_bf16 v[4:7], v[162:165], v[206:209], v[4:7]
	v_mfma_f32_16x16x32_bf16 v[0:3], v[170:173], v[206:209], v[0:3]
	s_setprio 0
	s_barrier
	s_add_i32 s53, 0, 0x18000
	s_add_i32 s54, 0, 0x1c000
	v_add_u32_e32 v154, s53, v140
	v_add_u32_e32 v170, s54, v140
	ds_read_b128 v[142:145], v154
	ds_read_b128 v[146:149], v154 offset:1024
	ds_read_b128 v[150:153], v154 offset:2048
	ds_read_b128 v[154:157], v154 offset:3072
	ds_read_b128 v[158:161], v170
	ds_read_b128 v[162:165], v170 offset:1024
	ds_read_b128 v[166:169], v170 offset:2048
	ds_read_b128 v[170:173], v170 offset:3072
	s_add_u32 s28, s28, 0x20000
	s_addc_u32 s29, s29, 0
	s_mov_b32 m0, s36
	v_lshl_add_u64 v[214:215], s[28:29], 0, v[128:129]
	ds_read_b128 v[174:177], v141 offset:32768
	ds_read_b128 v[178:181], v141 offset:33792
	ds_read_b128 v[182:185], v141 offset:34816
	ds_read_b128 v[186:189], v141 offset:35840
	ds_read_b128 v[190:193], v141 offset:36864
	ds_read_b128 v[194:197], v141 offset:37888
	ds_read_b128 v[198:201], v141 offset:38912
	ds_read_b128 v[206:209], v141 offset:39936
	global_load_lds_dwordx4 v[214:215], off
	v_lshl_add_u64 v[214:215], s[28:29], 0, v[130:131]
	s_mov_b32 m0, s37
	s_nop 0
	global_load_lds_dwordx4 v[214:215], off
	s_waitcnt vmcnt(8)
	s_waitcnt lgkmcnt(0)
	s_barrier
	s_setprio 1
	s_waitcnt lgkmcnt(0)
	v_mfma_f32_16x16x32_bf16 v[124:127], v[142:145], v[174:177], v[124:127]
	v_mfma_f32_16x16x32_bf16 v[120:123], v[150:153], v[174:177], v[120:123]
	v_mfma_f32_16x16x32_bf16 v[116:119], v[142:145], v[182:185], v[116:119]
	v_mfma_f32_16x16x32_bf16 v[108:111], v[150:153], v[182:185], v[108:111]
	v_mfma_f32_16x16x32_bf16 v[100:103], v[142:145], v[190:193], v[100:103]
	v_mfma_f32_16x16x32_bf16 v[92:95], v[150:153], v[190:193], v[92:95]
	v_mfma_f32_16x16x32_bf16 v[84:87], v[142:145], v[198:201], v[84:87]
	v_mfma_f32_16x16x32_bf16 v[76:79], v[150:153], v[198:201], v[76:79]
	v_mfma_f32_16x16x32_bf16 v[124:127], v[146:149], v[178:181], v[124:127]
	v_mfma_f32_16x16x32_bf16 v[120:123], v[154:157], v[178:181], v[120:123]
	v_mfma_f32_16x16x32_bf16 v[116:119], v[146:149], v[186:189], v[116:119]
	v_mfma_f32_16x16x32_bf16 v[108:111], v[154:157], v[186:189], v[108:111]
	v_mfma_f32_16x16x32_bf16 v[100:103], v[146:149], v[194:197], v[100:103]
	v_mfma_f32_16x16x32_bf16 v[92:95], v[154:157], v[194:197], v[92:95]
	v_mfma_f32_16x16x32_bf16 v[84:87], v[146:149], v[206:209], v[84:87]
	v_mfma_f32_16x16x32_bf16 v[76:79], v[154:157], v[206:209], v[76:79]
	s_setprio 0
	s_setprio 1
	v_mfma_f32_16x16x32_bf16 v[112:115], v[158:161], v[174:177], v[112:115]
	v_mfma_f32_16x16x32_bf16 v[104:107], v[166:169], v[174:177], v[104:107]
	v_mfma_f32_16x16x32_bf16 v[96:99], v[158:161], v[182:185], v[96:99]
	v_mfma_f32_16x16x32_bf16 v[88:91], v[166:169], v[182:185], v[88:91]
	v_mfma_f32_16x16x32_bf16 v[80:83], v[158:161], v[190:193], v[80:83]
	v_mfma_f32_16x16x32_bf16 v[72:75], v[166:169], v[190:193], v[72:75]
	v_mfma_f32_16x16x32_bf16 v[68:71], v[158:161], v[198:201], v[68:71]
	v_mfma_f32_16x16x32_bf16 v[64:67], v[166:169], v[198:201], v[64:67]
	v_mfma_f32_16x16x32_bf16 v[112:115], v[162:165], v[178:181], v[112:115]
	v_mfma_f32_16x16x32_bf16 v[104:107], v[170:173], v[178:181], v[104:107]
	v_mfma_f32_16x16x32_bf16 v[96:99], v[162:165], v[186:189], v[96:99]
	v_mfma_f32_16x16x32_bf16 v[88:91], v[170:173], v[186:189], v[88:91]
	v_mfma_f32_16x16x32_bf16 v[80:83], v[162:165], v[194:197], v[80:83]
	v_mfma_f32_16x16x32_bf16 v[72:75], v[170:173], v[194:197], v[72:75]
	v_mfma_f32_16x16x32_bf16 v[68:71], v[162:165], v[206:209], v[68:71]
	v_mfma_f32_16x16x32_bf16 v[64:67], v[170:173], v[206:209], v[64:67]
	s_setprio 0
	s_barrier
; #define PG8_STAGE(bufoff, gbase, voff) do { _Pragma("unroll") for (int _i = 0; _i < 2; ++_i) \
;         __builtin_amdgcn_global_load_lds((const unsigned*)((const char*)(gbase) + (voff)[_i]), (PG8_LAS unsigned*)(lds + (bufoff) + ldsw + _i * 8192), 16, 0, 0); } while (0)
; #define PG8_LDA(dst, b, h) do { _Pragma("unroll") for (int m = 0; m < 4; ++m) _Pragma("unroll") for (int k = 0; k < 2; ++k) dst[m][k] = *(const PG8_LAS bf16x8*)(lds + PG8_SA(b, h) + aoff + m * 2048 + k * 1024); } while (0)
; #define PG8_MMA(ai, bj, At, Bt) do { __builtin_amdgcn_s_setprio(1); _Pragma("unroll") for (int m = 0; m < 4; ++m) _Pragma("unroll") for (int n = 0; n < 2; ++n) _Pragma("unroll") for (int k = 0; k < 2; ++k) \
;         acc[ai][bj][m][n] = __builtin_amdgcn_mfma_f32_16x16x32_bf16(Bt[n][k], At[m][k], acc[ai][bj][m][n], 0, 0, 0); __builtin_amdgcn_s_setprio(0); } while (0)
; #define PG8_WAIT_V(n) asm volatile("s_waitcnt vmcnt(" #n ")" ::: "memory")
; #define PG8_WAIT_L(n) asm volatile("s_waitcnt lgkmcnt(" #n ")" ::: "memory")
; #define PG8_BAR __builtin_amdgcn_s_barrier()
; #define PG8_SCHED __builtin_amdgcn_sched_barrier(0)
; template <class Epi, class Sched, bool ALIGN_EPI = false, bool SP2 = false>
; __device__ __forceinline__ void gemm_phase(PG8_LAS unsigned char* lds, const Gemm g, const Sched& S, const Epi& E, const int tid) {
;     ...
;             PG8_LDA(At, 1, 1); PG8_STAGE(PG8_SB(1, 0), b3, voffB); PG8_STAGE(PG8_SB(1, 1), b3 + hstep, voffB); PG8_STAGE(PG8_SA(1, 0), a3, voffA);
;             PG8_WAIT_V(8); PG8_WAIT_L(0); PG8_BAR; PG8_MMA(1, 0, At, B0); PG8_MMA(1, 1, At, B1); PG8_BAR; PG8_SCHED;
	s_add_i32 s28, s53, s34
	v_lshl_add_u64 v[138:139], v[138:139], 0, s[70:71]
	s_mov_b32 m0, s28
	ds_read_b128 v[174:177], v141 offset:49152
	ds_read_b128 v[178:181], v141 offset:50176
	ds_read_b128 v[182:185], v141 offset:51200
	ds_read_b128 v[186:189], v141 offset:52224
	ds_read_b128 v[190:193], v141 offset:53248
	ds_read_b128 v[194:197], v141 offset:54272
	ds_read_b128 v[198:201], v141 offset:55296
	ds_read_b128 v[206:209], v141 offset:56320
	global_load_lds_dwordx4 v[138:139], off
	s_add_i32 m0, s28, 0x2000
	s_add_u32 s26, s26, 0x20080
	v_lshl_add_u64 v[138:139], v[202:203], 0, s[70:71]
	s_addc_u32 s27, s27, 0
	s_add_i32 s28, s54, s34
	global_load_lds_dwordx4 v[138:139], off
	v_lshl_add_u64 v[138:139], s[26:27], 0, v[204:205]
	s_mov_b32 m0, s28
	s_nop 0
	global_load_lds_dwordx4 v[138:139], off
	v_lshl_add_u64 v[138:139], s[26:27], 0, v[132:133]
	s_add_i32 m0, s28, 0x2000
	s_nop 0
	global_load_lds_dwordx4 v[138:139], off
	v_lshl_add_u64 v[138:139], v[210:211], 0, s[70:71]
	s_mov_b32 m0, s43
	s_nop 0
	global_load_lds_dwordx4 v[138:139], off
	v_lshl_add_u64 v[138:139], v[212:213], 0, s[70:71]
	s_mov_b32 m0, s44
	s_nop 0
	global_load_lds_dwordx4 v[138:139], off
	s_waitcnt vmcnt(8)
	s_waitcnt lgkmcnt(0)
	s_barrier
	s_setprio 1
	s_waitcnt lgkmcnt(0)
	v_mfma_f32_16x16x32_bf16 v[60:63], v[142:145], v[174:177], v[60:63]
	v_mfma_f32_16x16x32_bf16 v[56:59], v[150:153], v[174:177], v[56:59]
	v_mfma_f32_16x16x32_bf16 v[52:55], v[142:145], v[182:185], v[52:55]
	v_mfma_f32_16x16x32_bf16 v[44:47], v[150:153], v[182:185], v[44:47]
	v_mfma_f32_16x16x32_bf16 v[36:39], v[142:145], v[190:193], v[36:39]
	v_mfma_f32_16x16x32_bf16 v[28:31], v[150:153], v[190:193], v[28:31]
	v_mfma_f32_16x16x32_bf16 v[20:23], v[142:145], v[198:201], v[20:23]
	v_mfma_f32_16x16x32_bf16 v[12:15], v[150:153], v[198:201], v[12:15]
	v_mfma_f32_16x16x32_bf16 v[60:63], v[146:149], v[178:181], v[60:63]
	v_mfma_f32_16x16x32_bf16 v[56:59], v[154:157], v[178:181], v[56:59]
	v_mfma_f32_16x16x32_bf16 v[52:55], v[146:149], v[186:189], v[52:55]
	v_mfma_f32_16x16x32_bf16 v[44:47], v[154:157], v[186:189], v[44:47]
	v_mfma_f32_16x16x32_bf16 v[36:39], v[146:149], v[194:197], v[36:39]
	v_mfma_f32_16x16x32_bf16 v[28:31], v[154:157], v[194:197], v[28:31]
	v_mfma_f32_16x16x32_bf16 v[20:23], v[146:149], v[206:209], v[20:23]
	v_mfma_f32_16x16x32_bf16 v[12:15], v[154:157], v[206:209], v[12:15]
	s_setprio 0
	s_setprio 1
	v_mfma_f32_16x16x32_bf16 v[48:51], v[158:161], v[174:177], v[48:51]
	v_mfma_f32_16x16x32_bf16 v[40:43], v[166:169], v[174:177], v[40:43]
	v_mfma_f32_16x16x32_bf16 v[32:35], v[158:161], v[182:185], v[32:35]
	v_mfma_f32_16x16x32_bf16 v[24:27], v[166:169], v[182:185], v[24:27]
	v_mfma_f32_16x16x32_bf16 v[16:19], v[158:161], v[190:193], v[16:19]
	v_mfma_f32_16x16x32_bf16 v[8:11], v[166:169], v[190:193], v[8:11]
	v_mfma_f32_16x16x32_bf16 v[4:7], v[158:161], v[198:201], v[4:7]
	v_mfma_f32_16x16x32_bf16 v[0:3], v[166:169], v[198:201], v[0:3]
	v_mfma_f32_16x16x32_bf16 v[48:51], v[162:165], v[178:181], v[48:51]
	v_mfma_f32_16x16x32_bf16 v[40:43], v[170:173], v[178:181], v[40:43]
	v_mfma_f32_16x16x32_bf16 v[32:35], v[162:165], v[186:189], v[32:35]
	v_mfma_f32_16x16x32_bf16 v[24:27], v[170:173], v[186:189], v[24:27]
	v_mfma_f32_16x16x32_bf16 v[16:19], v[162:165], v[194:197], v[16:19]
	v_mfma_f32_16x16x32_bf16 v[8:11], v[170:173], v[194:197], v[8:11]
	v_mfma_f32_16x16x32_bf16 v[4:7], v[162:165], v[206:209], v[4:7]
	v_mfma_f32_16x16x32_bf16 v[0:3], v[170:173], v[206:209], v[0:3]
	s_setprio 0
	s_barrier
	s_add_i32 s52, s52, 2
	s_add_u32 s24, s24, 0x100
	s_addc_u32 s25, s25, 0
	s_add_u32 s50, s50, 0x100
	s_addc_u32 s51, s51, 0

;     ...
;   const int wid = tid >> 6, lane = tid & 63, r32 = lane & 31, hi = lane >> 5;
;   char* V_lds = lds; char* K_lds = lds + 2 * SHM_V;
;   float* ws = (float*)(lds + CF::WS_OFF) + wid * 64; float* li_l = ws; float* al_l = ws + 32;
;   float m_reg = -1e30f, l_reg = 0; f32x16 o[4] = {}; bf16x8 qr[8];
;   const bf16_t* Qw = a.Q + (long)(wid * QBLK + r32) * ldq + hi * 8;
; #pragma unroll
;   for (int d0 = 0; d0 < CF::NQR; ++d0) qr[d0] = ld8(Qw + d0 * 16);
;   char* const qx = lds + CF::QX_OFF + wid * CF::QXW + lane * 16;
;   if constexpr (ND0 > 8) {
; #pragma unroll
;     for (int d0 = CF::NQR; d0 < ND0; ++d0) *(bf16x8*)(qx + (d0 - CF::NQR) * 1024) = ld8(Qw + d0 * 16);
;   }
;   const int sr = tid >> 4, sc = (tid & 15) * 8, vst0 = v_st(sr, sc), vst1 = v_st(32 + sr, sc);
;   const int kst0 = sr * CF::KPITCH + ((sc * 2) ^ ((sr & CF::KSWM) << 4)), kst1 = kst0 + 32 * CF::KPITCH;
;   const int kr2 = tid >> 3, kst2 = kr2 * CF::KPITCH + ((256 + (tid & 7) * 16) ^ ((kr2 & 7) << 4));
;   const bf16_t* const Vg = a.V; const bf16_t* const Kg = a.K;
;   const int voff0 = sr * ldv + sc, koff0 = sr * ldk + sc, koff2 = kr2 * ldk + 128 + (tid & 7) * 8;
;   const int vb0 = (int)(uintptr_t)V_lds + v_rd_base(lane);
;   struct { bf16x8 vs0, vs1, ks0, ks1, ks2; } sr_[SDEPTH];
;     ...
;   f32x16 pA0, pA1, pB0, pB1; float mnA, mnB, alA, alB; bf16x8 pa0, pa1, pa2, pa3; const int NT = a.nt;
;   const int qi = a.qoff + wid * QBLK + r32;
; __global__ void __launch_bounds__(NWAVES * 64, 2) mk_fwd(Args args) {
;     ...
;                   for (int i = 0; i < nu; ++i) { PHASE_VARS(); CHUNK_VARS(); bf16* const QB = (bf16*)(BIG + BB_QB); bf16* const KVB = (bf16*)(BIG + BB_KVB); bf16* const KF = (bf16*)(BIG + BB_KF); bf16* const OB = (bf16*)(BIG + BB_O);
;                       const int U8 = g8 ? (CT / 256) * 16 / 8 : (CT / 256) * 16; if (r8 + G8 * i >= U8) break;
;                       const int u = x8 * U8 + r8 + G8 * i, grp = u / NQB, qb = u % NQB, s = grp >> 4, h = grp & 15;
;                       const size_t t0 = (size_t)s * SEQ, tq = t0 + (size_t)qb * 256;
;                       att::Unit un; un.Q = QB + tq * 3072 + h * 192; un.K = KF + t0 * 3072 + h * 192; un.V = KVB + t0 * 4096 + h * 256 + 128; un.O = OB + tq * DM + h * 128; un.LSE = nullptr;
;                       un.ldq = 3072; un.ldk = 3072; un.ldv = 4096; un.ldo = DM; un.ldl = 0; un.nt = SEQ / 64; un.qoff = 0;
.LBB0_1721:
	s_mov_b32 s8, 0
	v_mbcnt_lo_u32_b32 v60, -1, 0
	v_mbcnt_hi_u32_b32 v60, -1, v60
	s_add_i32 s9, s8, s2
	s_ashr_i32 s5, s9, 31
	s_lshr_b32 s5, s5, 29
	s_add_i32 s0, s8, s1
	s_add_i32 s5, s9, s5
	s_and_b32 s4, s0, 7
	s_ashr_i32 s10, s5, 3
	s_ashr_i32 s11, s0, 3
	s_cmp_eq_u32 s4, 0
	s_cselect_b64 s[4:5], -1, 0
	s_and_b64 s[6:7], s[4:5], exec
	s_cselect_b32 s0, s11, s0
	s_cselect_b32 s6, s10, s9
	s_movk_i32 s7, 0x800
	s_mul_i32 s0, s0, s17
	s_cselect_b32 s7, 0x100, s7
	s_add_i32 s0, s0, s6
	s_cmp_ge_i32 s0, s7
	s_mov_b64 s[6:7], -1
	s_cbranch_scc1 .LBB0_1720
	s_lshl_b32 s6, s10, 3
	s_sub_i32 s9, s9, s6
	s_and_b64 s[6:7], s[4:5], exec
	s_cselect_b32 s6, s9, 0
	s_ashr_i32 s9, s8, 31
	s_add_u32 s18, s58, s8
	s_addc_u32 s19, s59, s9
	s_sub_i32 s7, 0, s8
	s_cmp_eq_u32 s38, s7
	s_cselect_b32 s21, s81, 0x2000
	s_cselect_b32 s10, 12, 13
	s_lshr_b32 s7, s21, 8
	s_and_b64 s[4:5], s[4:5], exec
	s_cselect_b32 s4, 8, 11
	s_lshl_b32 s4, s6, s4
	s_abs_i32 s6, s7
	v_cvt_f32_u32_e32 v0, s6
	s_sub_i32 s11, 0, s6
	s_add_i32 s0, s0, s4
	s_abs_i32 s5, s0
	v_rcp_iflag_f32_e32 v0, v0
	s_xor_b32 s4, s0, s7
	s_ashr_i32 s4, s4, 31
	v_add_u32_e32 v6, s3, v60
	v_mul_f32_e32 v0, 0x4f7ffffe, v0
	v_cvt_u32_f32_e32 v0, v0
	v_ashrrev_i32_e32 v173, 6, v6
	v_and_b32_e32 v62, 31, v60
	v_lshlrev_b32_e32 v172, 5, v173
	v_readfirstlane_b32 s12, v0
	s_mul_i32 s11, s11, s12
	s_mul_hi_u32 s11, s12, s11
	s_add_i32 s12, s12, s11
	s_mul_hi_u32 s11, s5, s12
	s_mul_i32 s12, s11, s6
	s_sub_i32 s5, s5, s12
	s_add_i32 s12, s11, 1
	s_sub_i32 s13, s5, s6
	s_cmp_ge_u32 s5, s6
	s_cselect_b32 s11, s12, s11
	s_cselect_b32 s5, s13, s5
	s_add_i32 s12, s11, 1
	s_cmp_ge_u32 s5, s6
	s_cselect_b32 s5, s12, s11
	s_xor_b32 s5, s5, s4
	s_sub_i32 s5, s5, s4
	s_mul_i32 s4, s5, s7
	s_sub_i32 s4, s0, s4
	s_ashr_i32 s6, s5, 4
	s_and_b32 s20, s5, 15
	s_ashr_i32 s7, s6, 31
	s_ashr_i32 s5, s4, 31
	s_lshl_b64 s[12:13], s[6:7], s10
	s_lshl_b64 s[4:5], s[4:5], 8
	s_add_u32 s6, s12, s4
	s_addc_u32 s7, s13, s5
	s_mul_i32 s0, s7, 0x1800
	s_mul_hi_u32 s4, s6, 0x1800
	s_add_i32 s4, s4, s0
	s_mul_i32 s0, s6, 0x1800
	s_add_u32 s5, s18, s0
	s_addc_u32 s4, s19, s4
	s_mul_i32 s0, s20, 0x180
	s_add_u32 s5, s5, s0
	s_addc_u32 s4, s4, 0
	s_add_u32 s26, s5, 0x33800000
	s_addc_u32 s27, s4, 0
	s_mul_i32 s4, s13, 0x1800
	s_mul_hi_u32 s10, s12, 0x1800
	s_add_i32 s10, s10, s4
	s_mul_i32 s11, s12, 0x1800
	s_add_u32 s4, s18, s11
	s_addc_u32 s5, s19, s10
	s_add_u32 s24, s4, s0
	s_addc_u32 s25, s5, 0
	s_add_u32 s4, s24, 0x4f800000
	s_addc_u32 s5, s25, 0
	s_lshl_b64 s[12:13], s[12:13], 13
	s_add_u32 s14, s18, s12
	s_addc_u32 s15, s19, s13
	s_lshl_b32 s23, s20, 9
	s_add_u32 s14, s14, s23
	s_addc_u32 s15, s15, 0
	v_and_b32_e32 v0, 0x3fffffc0, v6
	s_add_i32 s28, 0, 0x20400
	v_bfe_u32 v63, v60, 5, 1
	v_lshl_add_u32 v186, v0, 2, s28
	v_or_b32_e32 v2, v172, v62
	v_mov_b64_e32 v[0:1], s[26:27]
	v_mad_i64_i32 v[0:1], s[26:27], v2, s96, v[0:1]
	v_lshlrev_b32_e32 v204, 4, v63
	v_and_b32_e32 v61, 63, v60
	v_lshl_add_u64 v[4:5], v[0:1], 0, v[204:205]
	v_mul_lo_u32 v0, v173, s96
	s_add_i32 s26, 0, 0x14000
	v_add_u32_e32 v0, s26, v0
	v_lshlrev_b32_e32 v7, 4, v61
	global_load_dwordx4 v[148:151], v[4:5], off
	global_load_dwordx4 v[144:147], v[4:5], off offset:32
	global_load_dwordx4 v[140:143], v[4:5], off offset:64
	global_load_dwordx4 v[136:139], v[4:5], off offset:96
	global_load_dwordx4 v[132:135], v[4:5], off offset:128
	global_load_dwordx4 v[128:131], v[4:5], off offset:160
	v_add_u32_e32 v188, v0, v7
	global_load_dwordx4 v[0:3], v[4:5], off offset:192
	s_movk_i32 s27, 0x180
	s_movk_i32 s26, 0xc00
	v_mad_u32_u24 v200, v62, s27, 0
	s_lshr_b32 s21, s21, 6
	s_cmp_lg_u32 0, -1
	s_mov_b32 s40, s41
	s_mov_b32 s42, s41
	s_mov_b32 s43, s41
	s_mov_b32 s44, s41
	s_mov_b32 s45, s41
	s_mov_b32 s46, s41
	s_mov_b32 s47, s41
	s_mov_b32 s48, s41
	s_mov_b32 s49, s41
	s_mov_b32 s50, s41
	s_mov_b32 s51, s41
	s_mov_b32 s52, s41
	s_mov_b32 s53, s41
	s_mov_b32 s54, s41
	s_mov_b32 s55, s41
	v_lshl_add_u32 v224, v62, 2, v186
	v_mov_b32_e32 v222, 0x358637bd
	v_mov_b32_e32 v254, 0xff800000
	s_mov_b32 s22, 2
	v_add_u32_e32 v235, 0xe000, v200
	v_mov_b32_e32 v250, 0
	s_waitcnt vmcnt(0)
	ds_write_b128 v188, v[0:3]
	global_load_dwordx4 v[0:3], v[4:5], off offset:224
	s_waitcnt vmcnt(0)
	ds_write_b128 v188, v[0:3] offset:1024
	global_load_dwordx4 v[0:3], v[4:5], off offset:256
	s_waitcnt vmcnt(0)
	ds_write_b128 v188, v[0:3] offset:2048
	global_load_dwordx4 v[0:3], v[4:5], off offset:288
	s_waitcnt vmcnt(0)
	ds_write_b128 v188, v[0:3] offset:3072
	global_load_dwordx4 v[0:3], v[4:5], off offset:320
	s_waitcnt vmcnt(0)
	ds_write_b128 v188, v[0:3] offset:4096
	global_load_dwordx4 v[0:3], v[4:5], off offset:352
	s_waitcnt vmcnt(0)
; #define ATT_SYNC() __syncthreads()
; __device__ __forceinline__ int v_st(int k, int c) { const int kk = (k & ~0xC) | ((k & 4) << 1) | ((k & 8) >> 1); return ((kk >> 3) * 4 + (c >> 5)) * 512 + ((kk & 7) * 32 + (c & 31)) * 2; }
; __device__ __forceinline__ int v_rd_base(int lane) { return ((lane & 3) << 3) | (((lane >> 2) & 3) << 6) | (((lane >> 4) & 1) << 5) | (((lane >> 5) & 1) << 8); }
; template <class CF> __device__ __forceinline__ void qkt(f32x16& p0, f32x16& p1, const char* Ks, const bf16x8* qr, const char* qx, int r32, int hi) {
;   p0 = f32x16{}; p1 = f32x16{};
; #pragma unroll
;   for (int d0 = 0; d0 < CF::ND0; ++d0) { const int cb = (d0 * 16 + hi * 8) * 2;
;     bf16x8 b0 = *reinterpret_cast<const bf16x8*>(Ks + (r32) * CF::KPITCH + (cb ^ ((r32 & CF::KSWM) << 4)));
;     bf16x8 b1 = *reinterpret_cast<const bf16x8*>(Ks + (32 + r32) * CF::KPITCH + (cb ^ ((r32 & CF::KSWM) << 4)));
;     bf16x8 q; if (d0 < CF::NQR) q = qr[d0 < CF::NQR ? d0 : 0]; else q = *reinterpret_cast<const bf16x8*>(qx + (d0 - CF::NQR) * 1024);
;     p0 = __builtin_amdgcn_mfma_f32_32x32x16_bf16(b0, q, p0, 0, 0, 0);
;     p1 = __builtin_amdgcn_mfma_f32_32x32x16_bf16(b1, q, p1, 0, 0, 0); }
; }
;     ...
;   const int sr = tid >> 4, sc = (tid & 15) * 8, vst0 = v_st(sr, sc), vst1 = v_st(32 + sr, sc);
;   const int kst0 = sr * CF::KPITCH + ((sc * 2) ^ ((sr & CF::KSWM) << 4)), kst1 = kst0 + 32 * CF::KPITCH;
;   const int kr2 = tid >> 3, kst2 = kr2 * CF::KPITCH + ((256 + (tid & 7) * 16) ^ ((kr2 & 7) << 4));
;   const bf16_t* const Vg = a.V; const bf16_t* const Kg = a.K;
;   const int voff0 = sr * ldv + sc, koff0 = sr * ldk + sc, koff2 = kr2 * ldk + 128 + (tid & 7) * 8;
;   const int vb0 = (int)(uintptr_t)V_lds + v_rd_base(lane);
;   struct { bf16x8 vs0, vs1, ks0, ks1, ks2; } sr_[SDEPTH];
;     ...
;   f32x16 pA0, pA1, pB0, pB1; float mnA, mnB, alA, alB; bf16x8 pa0, pa1, pa2, pa3; const int NT = a.nt;
;   const int qi = a.qoff + wid * QBLK + r32;
;   constexpr int SE = 0, SO = SDEPTH - 1;
;   ATT_SLOAD(SE, 0); asm volatile("s_waitcnt vmcnt(0)" ::: "memory"); ATT_SWRITE(0, SE); ATT_SYNC();
;   qkt<CF>(pA0, pA1, K_lds, qr, qx, r32, hi); if constexpr (MASK) bandmask(pA0, pA1, 0, qi, hi); partialSM<CF>(pA0, pA1, m_reg, mnA, alA);
	ds_write_b128 v188, v[0:3] offset:5120
	v_ashrrev_i32_e32 v1, 4, v6
	v_and_b32_e32 v3, 0xfffff0, v1
	v_lshlrev_b32_e32 v4, 1, v1
	v_lshlrev_b32_e32 v0, 3, v60
	v_and_or_b32 v3, v4, 8, v3
	v_and_b32_e32 v2, 0x78, v0
	v_lshrrev_b32_e32 v4, 1, v1
	v_lshrrev_b32_e32 v3, 1, v3
	v_bfe_u32 v0, v0, 5, 2
	v_and_b32_e32 v5, 3, v1
	v_or_b32_e32 v3, v3, v0
	v_and_or_b32 v4, v4, 4, v5
	v_lshlrev_b32_e32 v5, 1, v2
	v_lshlrev_b32_e32 v3, 9, v3
	v_lshlrev_b32_e32 v4, 6, v4
	v_and_b32_e32 v8, 48, v5
	v_or3_b32 v20, v3, v4, v8
	v_add_u32_e32 v3, 32, v1
	v_and_b32_e32 v9, 0xfffff0, v3
	v_lshlrev_b32_e32 v3, 1, v3
	v_and_or_b32 v3, v3, 8, v9
	v_lshrrev_b32_e32 v3, 1, v3
	v_or_b32_e32 v0, v3, v0
	v_lshlrev_b32_e32 v0, 9, v0
	v_or3_b32 v21, v0, v4, v8
	v_mul_lo_u32 v0, v1, s27
	v_and_b32_e32 v3, 0x70, v6
	v_xad_u32 v22, v5, v3, v0
	v_ashrrev_i32_e32 v3, 3, v6
	v_and_b32_e32 v4, 7, v60
	v_mov_b32_e32 v5, 0x100
	v_lshlrev_b32_e32 v6, 4, v3
	v_mul_lo_u32 v0, v3, s27
	v_lshl_or_b32 v5, v4, 4, v5
	v_and_b32_e32 v6, 0x70, v6
	v_xad_u32 v23, v6, v5, v0
	v_lshl_or_b32 v0, v1, 12, v2
	v_mul_lo_u32 v1, v1, s26
	v_or_b32_e32 v8, v1, v2
	v_mul_lo_u32 v1, v3, s26
	v_lshl_or_b32 v16, v4, 3, v1
	v_lshlrev_b32_e32 v1, 3, v61
	v_and_b32_e32 v2, 0xc0, v7
	v_lshlrev_b32_e32 v3, 1, v60
	v_and_or_b32 v2, v1, 24, v2
	v_and_b32_e32 v3, 32, v3
	v_and_b32_e32 v1, 0x100, v1
	v_or3_b32 v97, v2, v3, v1
	v_ashrrev_i32_e32 v1, 31, v0
	v_lshlrev_b64 v[48:49], 1, v[0:1]
	v_lshl_add_u64 v[56:57], s[14:15], 0, v[48:49]
	v_add_co_u32_e32 v0, vcc, 1.0, v56
	s_mov_b32 s14, 0x3f840000
	s_nop 0
	v_addc_co_u32_e32 v1, vcc, 0, v57, vcc
	v_ashrrev_i32_e32 v9, 31, v8
	v_add_co_u32_e32 v4, vcc, s14, v56
	v_lshlrev_b64 v[50:51], 1, v[8:9]
	global_load_dwordx4 v[0:3], v[0:1], off offset:256
	v_addc_co_u32_e32 v5, vcc, 0, v57, vcc
	v_lshl_add_u64 v[58:59], s[4:5], 0, v[50:51]
	s_mov_b32 s14, 0x30000
	v_ashrrev_i32_e32 v17, 31, v16
	v_add_co_u32_e32 v12, vcc, s14, v58
	v_lshlrev_b64 v[52:53], 1, v[16:17]
	v_or_b32_e32 v54, 0x80, v16
	v_addc_co_u32_e32 v13, vcc, 0, v59, vcc
	v_lshl_add_u64 v[16:17], s[4:5], 0, v[52:53]
	global_load_dwordx4 v[4:7], v[4:5], off offset:256
	v_add_u32_e32 v195, 0, v20
	global_load_dwordx4 v[8:11], v[58:59], off
	v_add_u32_e32 v196, 0, v21
	global_load_dwordx4 v[12:15], v[12:13], off
	v_add_u32_e32 v197, 0, v22
	global_load_dwordx4 v[16:19], v[16:17], off offset:256
	s_waitcnt vmcnt(0)
	v_add_u32_e32 v199, 0, v23
	v_add_u32_e32 v96, 0x3000, v22
	s_movk_i32 s4, 0x60
	s_cselect_b32 s26, 0, 0
	s_mov_b32 s14, 0x3f880000
	v_ashrrev_i32_e32 v55, 31, v54
	v_add_u32_e32 v187, s26, v97
	v_add_u32_e32 v234, 0, v96
	s_waitcnt vmcnt(4)
	ds_write_b128 v195, v[0:3]
	v_lshlrev_b32_e32 v0, 4, v60
	v_and_b32_e32 v76, 0x70, v0
	v_xad_u32 v0, v204, v76, v200
	v_bitop3_b32 v216, v204, v76, 32 bitop3:0x36
	v_add_u32_e32 v238, 0x2000, v200
	v_add_u32_e32 v215, v238, v216
	v_bitop3_b32 v217, v204, v76, 64 bitop3:0x36
	v_add_u32_e32 v203, v238, v217
	v_bitop3_b32 v223, v204, v76, s4 bitop3:0x36
	v_add_u32_e32 v214, v238, v223
	v_bitop3_b32 v225, v204, v76, s97 bitop3:0x36
	v_add_u32_e32 v202, v238, v225
	s_movk_i32 s4, 0xa0
	s_waitcnt vmcnt(3)
	ds_write_b128 v196, v[4:7]
	s_waitcnt vmcnt(2)
	ds_write_b128 v197, v[8:11] offset:32768
	s_waitcnt vmcnt(1)
	ds_write_b128 v197, v[12:15] offset:45056
	v_bitop3_b32 v226, v204, v76, s4 bitop3:0x36
	v_add_u32_e32 v201, v238, v226
	s_waitcnt vmcnt(0)
	ds_write_b128 v199, v[16:19] offset:32768
	s_waitcnt lgkmcnt(0)
	s_barrier
	ds_read_b128 v[16:19], v0 offset:32768
	ds_read_b128 v[20:23], v0 offset:45056
	s_waitcnt lgkmcnt(1)
	v_mfma_f32_32x32x16_bf16 v[32:47], v[16:19], v[148:151], 0
	ds_read_b128 v[64:67], v215 offset:24576
	ds_read_b128 v[68:71], v215 offset:36864
	s_movk_i32 s4, 0xc0
	v_bitop3_b32 v227, v204, v76, s4 bitop3:0x36
	v_add_u32_e32 v198, v238, v227
	s_movk_i32 s4, 0xe0
	v_bitop3_b32 v228, v204, v76, s4 bitop3:0x36
	v_add_u32_e32 v192, v238, v228
	s_waitcnt lgkmcnt(2)
	v_mfma_f32_32x32x16_bf16 v[16:31], v[20:23], v[148:151], 0
	s_movk_i32 s4, 0x100
	v_bitop3_b32 v229, v204, v76, s4 bitop3:0x36
	v_add_u32_e32 v194, v238, v229
	s_movk_i32 s4, 0x120
	v_bitop3_b32 v230, v204, v76, s4 bitop3:0x36
	v_add_u32_e32 v190, v238, v230
	s_movk_i32 s4, 0x140
	s_waitcnt lgkmcnt(1)
	v_mfma_f32_32x32x16_bf16 v[32:47], v[64:67], v[144:147], v[32:47]
	v_bitop3_b32 v231, v204, v76, s4 bitop3:0x36
	v_add_u32_e32 v193, v238, v231
	s_movk_i32 s4, 0x160
	v_bitop3_b32 v232, v204, v76, s4 bitop3:0x36
	v_add_u32_e32 v191, v238, v232
	v_mov_b64_e32 v[0:1], s[40:41]
	v_mov_b64_e32 v[14:15], s[54:55]
	s_waitcnt lgkmcnt(0)
	v_mfma_f32_32x32x16_bf16 v[16:31], v[68:71], v[144:147], v[16:31]
	ds_read_b128 v[64:67], v203 offset:24576
	ds_read_b128 v[68:71], v203 offset:36864
	v_mov_b64_e32 v[2:3], s[42:43]
	v_mov_b64_e32 v[4:5], s[44:45]
	v_mov_b64_e32 v[6:7], s[46:47]
	v_mov_b64_e32 v[8:9], s[48:49]
	v_mov_b64_e32 v[10:11], s[50:51]
	v_mov_b64_e32 v[12:13], s[52:53]
	s_waitcnt lgkmcnt(1)
	v_mfma_f32_32x32x16_bf16 v[32:47], v[64:67], v[140:143], v[32:47]
	s_waitcnt lgkmcnt(0)
	v_mfma_f32_32x32x16_bf16 v[16:31], v[68:71], v[140:143], v[16:31]
	ds_read_b128 v[64:67], v214 offset:24576
	ds_read_b128 v[68:71], v214 offset:36864
	s_waitcnt lgkmcnt(1)
	v_mfma_f32_32x32x16_bf16 v[32:47], v[64:67], v[136:139], v[32:47]
	s_waitcnt lgkmcnt(0)
	v_mfma_f32_32x32x16_bf16 v[16:31], v[68:71], v[136:139], v[16:31]
	ds_read_b128 v[64:67], v202 offset:24576
	ds_read_b128 v[68:71], v202 offset:36864
	s_waitcnt lgkmcnt(1)
	v_mfma_f32_32x32x16_bf16 v[32:47], v[64:67], v[132:135], v[32:47]
	s_waitcnt lgkmcnt(0)
	v_mfma_f32_32x32x16_bf16 v[16:31], v[68:71], v[132:135], v[16:31]
	ds_read_b128 v[64:67], v201 offset:24576
	ds_read_b128 v[68:71], v201 offset:36864
	s_waitcnt lgkmcnt(1)
; #define ATT_SYNC() __syncthreads()
; #define ATT_SLOAD(i, k0) do { const bf16_t* vt_ = Vg + (long)(k0) * ldv; const bf16_t* kt_ = Kg + (long)(k0) * ldk; \
;     sr_[i].vs0 = ld8(vt_ + voff0); sr_[i].vs1 = ld8(vt_ + 32 * ldv + voff0); \
;     sr_[i].ks0 = ld8(kt_ + koff0); sr_[i].ks1 = ld8(kt_ + 32 * ldk + koff0); if constexpr (ND0 == 12) sr_[i].ks2 = ld8(kt_ + koff2); } while (0)
; #define ATT_SWRITE(b, i) do { *(bf16x8*)(V_lds + (b) * SHM_V + vst0) = sr_[i].vs0; *(bf16x8*)(V_lds + (b) * SHM_V + vst1) = sr_[i].vs1; \
;     *(bf16x8*)(K_lds + (b) * SHM_K + kst0) = sr_[i].ks0; *(bf16x8*)(K_lds + (b) * SHM_K + kst1) = sr_[i].ks1; if constexpr (ND0 == 12) *(bf16x8*)(K_lds + (b) * SHM_K + kst2) = sr_[i].ks2; } while (0)
; #define ATT_SWAIT() do { if constexpr (SDEPTH == 2) { if constexpr (ND0 == 12) asm volatile("s_waitcnt vmcnt(5)" ::: "memory"); else asm volatile("s_waitcnt vmcnt(4)" ::: "memory"); } else asm volatile("s_waitcnt vmcnt(0)" ::: "memory"); } while (0)
; template <class CF> __device__ __forceinline__ void partialSM(f32x16& p0, f32x16& p1, float& m_reg, float& mn, float& alpha) {
;   constexpr float C = CF::SCALE * 1.4426950408889634f;
;   float pmax = p0[0];
; #pragma unroll
;   for (int r = 1; r < 16; ++r) pmax = fmaxf(pmax, p0[r]);
; #pragma unroll
;   for (int r = 0; r < 16; ++r) pmax = fmaxf(pmax, p1[r]);
;   { auto rr = __builtin_amdgcn_permlane32_swap(__float_as_uint(pmax), __float_as_uint(pmax), false, false);
;     pmax = fmaxf(__uint_as_float(rr[0]), __uint_as_float(rr[1])); }
;   if (__builtin_expect(__all(pmax - m_reg <= THR / CF::SCALE), 1)) { mn = m_reg; alpha = 1.f; }
;   else { mn = fmaxf(m_reg, pmax); alpha = __builtin_amdgcn_exp2f((m_reg - mn) * C); m_reg = mn; }
;   float mnC = -mn * C;
; #pragma unroll
;   for (int r = 0; r < 16; ++r) p0[r] = fmaf(p0[r], C, mnC);
; #pragma unroll
;   for (int r = 0; r < 16; ++r) p1[r] = fmaf(p1[r], C, mnC);
; #pragma unroll
;   for (int r = 0; r < 16; ++r) p0[r] = __builtin_amdgcn_exp2f(p0[r]);
; }
;     ...
;   qkt<CF>(pA0, pA1, K_lds, qr, qx, r32, hi); if constexpr (MASK) bandmask(pA0, pA1, 0, qi, hi); partialSM<CF>(pA0, pA1, m_reg, mnA, alA);
;   ATT_SLOAD(SO, KVBLK); if constexpr (SDEPTH == 2) { if (2 < NT) ATT_SLOAD(SE, 2 * KVBLK); }
;   ATT_SWAIT(); ATT_SWRITE(1, SO); ATT_SYNC();
	v_mfma_f32_32x32x16_bf16 v[32:47], v[64:67], v[128:131], v[32:47]
	s_waitcnt lgkmcnt(0)
	v_mfma_f32_32x32x16_bf16 v[16:31], v[68:71], v[128:131], v[16:31]
	ds_read_b128 v[64:67], v198 offset:24576
	ds_read_b128 v[68:71], v198 offset:36864
	ds_read_b128 v[72:75], v188
	s_waitcnt lgkmcnt(0)
	v_mfma_f32_32x32x16_bf16 v[32:47], v[64:67], v[72:75], v[32:47]
	v_mfma_f32_32x32x16_bf16 v[16:31], v[68:71], v[72:75], v[16:31]
	ds_read_b128 v[64:67], v192 offset:24576
	ds_read_b128 v[68:71], v192 offset:36864
	ds_read_b128 v[72:75], v188 offset:1024
	s_waitcnt lgkmcnt(0)
	v_mfma_f32_32x32x16_bf16 v[32:47], v[64:67], v[72:75], v[32:47]
	v_mfma_f32_32x32x16_bf16 v[16:31], v[68:71], v[72:75], v[16:31]
	ds_read_b128 v[64:67], v194 offset:24576
	ds_read_b128 v[68:71], v194 offset:36864
	ds_read_b128 v[72:75], v188 offset:2048
	s_waitcnt lgkmcnt(0)
	v_mfma_f32_32x32x16_bf16 v[32:47], v[64:67], v[72:75], v[32:47]
	v_mfma_f32_32x32x16_bf16 v[16:31], v[68:71], v[72:75], v[16:31]
	ds_read_b128 v[64:67], v190 offset:24576
	ds_read_b128 v[68:71], v190 offset:36864
	ds_read_b128 v[72:75], v188 offset:3072
	s_waitcnt lgkmcnt(0)
	v_mfma_f32_32x32x16_bf16 v[32:47], v[64:67], v[72:75], v[32:47]
	v_mfma_f32_32x32x16_bf16 v[16:31], v[68:71], v[72:75], v[16:31]
	ds_read_b128 v[64:67], v193 offset:24576
	ds_read_b128 v[68:71], v193 offset:36864
	ds_read_b128 v[72:75], v188 offset:4096
	s_waitcnt lgkmcnt(0)
	v_mfma_f32_32x32x16_bf16 v[32:47], v[64:67], v[72:75], v[32:47]
	v_mfma_f32_32x32x16_bf16 v[16:31], v[68:71], v[72:75], v[16:31]
	ds_read_b128 v[64:67], v191 offset:24576
	ds_read_b128 v[68:71], v191 offset:36864
	ds_read_b128 v[72:75], v188 offset:5120
	s_waitcnt lgkmcnt(0)
	v_mfma_f32_32x32x16_bf16 v[32:47], v[64:67], v[72:75], v[32:47]
	v_mov_b32_e32 v66, 0xf149f2ca
	v_mfma_f32_32x32x16_bf16 v[16:31], v[68:71], v[72:75], v[16:31]
	s_nop 9
	v_max_f32_e32 v64, v33, v33
	v_max_f32_e32 v65, v32, v32
	v_max_f32_e32 v64, v65, v64
	v_max3_f32 v64, v64, v34, v35
	v_max3_f32 v64, v64, v36, v37
	v_max3_f32 v64, v64, v38, v39
	v_max3_f32 v64, v64, v40, v41
	v_max3_f32 v64, v64, v42, v43
	v_max3_f32 v64, v64, v44, v45
	v_max3_f32 v64, v64, v46, v47
	v_max3_f32 v64, v64, v16, v17
	v_max3_f32 v64, v64, v18, v19
	v_max3_f32 v64, v64, v20, v21
	v_max3_f32 v64, v64, v22, v23
	v_max3_f32 v64, v64, v24, v25
	v_max3_f32 v64, v64, v26, v27
	v_max3_f32 v64, v64, v28, v29
	v_max3_f32 v64, v64, v30, v31
	v_mov_b32_e32 v65, v64
	s_nop 1
	v_permlane32_swap_b32_e32 v64, v65
	v_max_f32_e32 v65, v65, v65
	v_max_f32_e32 v64, v64, v64
	v_max_f32_e32 v64, v64, v65
	v_add_f32_e32 v65, 0x7149f2ca, v64
	v_max_f32_e32 v64, 0xf149f2ca, v64
	v_cmp_ge_f32_e32 vcc, s63, v65
	v_sub_f32_e32 v65, 0xf149f2ca, v64
	v_mul_f32_e32 v65, 0x3dd53b94, v65
	s_cmp_eq_u64 vcc, exec
	v_exp_f32_e32 v65, v65
	s_cselect_b64 vcc, -1, 0
	v_cndmask_b32_e32 v233, v64, v66, vcc
	v_mul_f32_e32 v64, 0xbdd53b94, v233
	v_cndmask_b32_e64 v180, v65, 1.0, vcc
	v_pk_fma_f32 v[80:81], v[16:17], s[84:85], v[64:65] op_sel_hi:[1,0,0]
	v_add_co_u32_e32 v16, vcc, s14, v56
	s_mov_b32 s14, 0x3f8c0000
	s_nop 0
	v_addc_co_u32_e32 v17, vcc, 0, v57, vcc
	v_pk_fma_f32 v[84:85], v[20:21], s[84:85], v[64:65] op_sel_hi:[1,0,0]
	v_add_co_u32_e32 v20, vcc, s14, v56
	s_add_u32 s4, s24, 0x4f860000
	s_nop 0
	v_addc_co_u32_e32 v21, vcc, 0, v57, vcc
	s_mov_b32 s14, 0x90000
	v_pk_fma_f32 v[92:93], v[28:29], s[84:85], v[64:65] op_sel_hi:[1,0,0]
	s_addc_u32 s5, s25, 0
	v_add_co_u32_e32 v28, vcc, s14, v58
	v_fmamk_f32 v32, v32, 0x3dd53b94, v64
	v_fmamk_f32 v33, v33, 0x3dd53b94, v64
	v_pk_fma_f32 v[88:89], v[24:25], s[84:85], v[64:65] op_sel_hi:[1,0,0]
	v_pk_fma_f32 v[82:83], v[18:19], s[84:85], v[64:65] op_sel_hi:[1,0,0]
	global_load_dwordx4 v[16:19], v[16:17], off offset:256
	v_lshl_add_u64 v[24:25], s[4:5], 0, v[50:51]
	v_addc_co_u32_e32 v29, vcc, 0, v59, vcc
	v_fmamk_f32 v34, v34, 0x3dd53b94, v64
	v_fmamk_f32 v35, v35, 0x3dd53b94, v64
	v_fmamk_f32 v36, v36, 0x3dd53b94, v64
	v_fmamk_f32 v37, v37, 0x3dd53b94, v64
	v_fmamk_f32 v38, v38, 0x3dd53b94, v64
	v_fmamk_f32 v39, v39, 0x3dd53b94, v64
	v_fmamk_f32 v40, v40, 0x3dd53b94, v64
	v_fmamk_f32 v41, v41, 0x3dd53b94, v64
	v_fmamk_f32 v42, v42, 0x3dd53b94, v64
	v_fmamk_f32 v43, v43, 0x3dd53b94, v64
	v_fmamk_f32 v44, v44, 0x3dd53b94, v64
	v_fmamk_f32 v45, v45, 0x3dd53b94, v64
	v_fmamk_f32 v46, v46, 0x3dd53b94, v64
	v_mov_b32_e32 v79, v64
	v_pk_fma_f32 v[94:95], v[30:31], s[84:85], v[64:65] op_sel_hi:[1,0,0]
	v_pk_fma_f32 v[90:91], v[26:27], s[84:85], v[64:65] op_sel_hi:[1,0,0]
	v_pk_fma_f32 v[86:87], v[22:23], s[84:85], v[64:65] op_sel_hi:[1,0,0]
	v_exp_f32_e32 v64, v32
	v_exp_f32_e32 v65, v33
	global_load_dwordx4 v[20:23], v[20:21], off offset:256
	v_lshl_add_u64 v[32:33], v[54:55], 1, s[4:5]
	global_load_dwordx4 v[24:27], v[24:25], off
	v_exp_f32_e32 v66, v34
	global_load_dwordx4 v[28:31], v[28:29], off
	v_exp_f32_e32 v67, v35
	global_load_dwordx4 v[32:35], v[32:33], off
	s_addk_i32 s26, 0x4000
	s_or_b32 s0, s11, s0
	s_add_u32 s14, s58, s0
	v_fmac_f32_e32 v79, 0x3dd53b94, v47
	s_addc_u32 s15, s59, s10
	s_or_b32 s0, s12, s23
	v_exp_f32_e32 v68, v36
	v_exp_f32_e32 v69, v37
	v_exp_f32_e32 v70, v38
	v_exp_f32_e32 v71, v39
	v_exp_f32_e32 v72, v40
	v_exp_f32_e32 v73, v41
	v_exp_f32_e32 v74, v42
	v_exp_f32_e32 v75, v43
	v_exp_f32_e32 v76, v44
	v_exp_f32_e32 v77, v45
	v_exp_f32_e32 v78, v46
	v_exp_f32_e32 v79, v79
	s_add_u32 s10, s58, s0
	s_waitcnt vmcnt(0)
	s_waitcnt vmcnt(4)
	ds_write_b128 v195, v[16:19] offset:16384
	s_waitcnt vmcnt(3)
	ds_write_b128 v196, v[20:23] offset:16384
	s_waitcnt vmcnt(2)
	ds_write_b128 v197, v[24:27] offset:57344
	v_bitop3_b32 v16, v63, v60, 7 bitop3:0x78
	s_addc_u32 s11, s59, s13
	s_waitcnt vmcnt(1)
	ds_write_b128 v234, v[28:31] offset:57344
	s_waitcnt vmcnt(0)
	ds_write_b128 v199, v[32:35] offset:57344
	v_lshlrev_b32_e32 v236, 4, v16
	v_cmp_gt_u32_e64 s[4:5], 32, v61
	v_lshl_add_u64 v[174:175], s[14:15], 0, v[52:53]
	v_lshl_add_u64 v[176:177], s[14:15], 0, v[50:51]
	v_lshl_add_u64 v[178:179], s[10:11], 0, v[48:49]
	v_mov_b64_e32 v[62:63], v[14:15]
	v_mov_b64_e32 v[46:47], v[14:15]
	v_mov_b64_e32 v[30:31], v[14:15]
	v_add_u32_e32 v189, s26, v97
	v_mov_b64_e32 v[60:61], v[12:13]
	v_mov_b64_e32 v[58:59], v[10:11]
	v_mov_b64_e32 v[56:57], v[8:9]
	v_mov_b64_e32 v[54:55], v[6:7]
	v_mov_b64_e32 v[52:53], v[4:5]
	v_mov_b64_e32 v[50:51], v[2:3]
	v_mov_b64_e32 v[48:49], v[0:1]
	v_mov_b64_e32 v[44:45], v[12:13]
	v_mov_b64_e32 v[42:43], v[10:11]
	v_mov_b64_e32 v[40:41], v[8:9]
	v_mov_b64_e32 v[38:39], v[6:7]
	v_mov_b64_e32 v[36:37], v[4:5]
	v_mov_b64_e32 v[34:35], v[2:3]
	v_mov_b64_e32 v[32:33], v[0:1]
	v_mov_b64_e32 v[28:29], v[12:13]
	v_mov_b64_e32 v[26:27], v[10:11]
	v_mov_b64_e32 v[24:25], v[8:9]
	v_mov_b64_e32 v[22:23], v[6:7]
	v_mov_b64_e32 v[20:21], v[4:5]
	v_mov_b64_e32 v[18:19], v[2:3]
	v_mov_b64_e32 v[16:17], v[0:1]
	s_waitcnt lgkmcnt(0)
	s_barrier
	s_branch .LBB0_1725
; template <class CF> __device__ __forceinline__ void pv_sm(f32x16* o, int vb, bf16x8 pa0, bf16x8 pa1, bf16x8 pa2, bf16x8 pa3, f32x16& p0, f32x16& p1, float& m_reg, float& mn, float& alpha) {
;     ...
;   if (__builtin_expect(__all(pmax - m_reg <= THR / CF::SCALE), 1)) { mn = m_reg; alpha = 1.f; }
;   else { mn = fmaxf(m_reg, pmax); alpha = __builtin_amdgcn_exp2f((m_reg - mn) * C); m_reg = mn; }
.Latt_rare_b1:
	v_max_f32_e32 v72, v233, v218
	v_sub_f32_e32 v73, v233, v72
	v_mul_f32_e32 v73, 0x3dd53b94, v73
	v_exp_f32_e32 v73, v73
	v_mov_b32_e32 v233, v72
	s_nop 0
	v_mov_b32_e32 v252, v73
	s_branch .Latt_back_b1
.Latt_rare_b2:
	v_max_f32_e32 v104, v233, v180
	v_sub_f32_e32 v105, v233, v104
	v_mul_f32_e32 v105, 0x3dd53b94, v105
	v_exp_f32_e32 v105, v105
	v_mov_b32_e32 v233, v104
	s_nop 0
	v_mov_b32_e32 v180, v105
	s_branch .Latt_back_b2

; #define ATT_SBAR() __builtin_amdgcn_sched_barrier(0)
; #define ATT_QRD(dst, g) do { _Pragma("unroll") for (int t = 0; t < 2; ++t) { const int cb = ((2 * (g) + t) * 16 + hi * 8) * 2; \
;     dst[2 * t] = *reinterpret_cast<const bf16x8*>(kr + (cb ^ sw)); dst[2 * t + 1] = *reinterpret_cast<const bf16x8*>(kr + 32 * CF::KPITCH + (cb ^ sw)); } } while (0)
; #define ATT_QMM(src, g) do { _Pragma("unroll") for (int t = 0; t < 2; ++t) { n0 = __builtin_amdgcn_mfma_f32_32x32x16_bf16(src[2 * t], qr[2 * (g) + t], n0, 0, 0, 0); \
;     n1 = __builtin_amdgcn_mfma_f32_32x32x16_bf16(src[2 * t + 1], qr[2 * (g) + t], n1, 0, 0, 0); } } while (0)
; template <class CF> __device__ __forceinline__ void qk_sm1(f32x16& n0, f32x16& n1, const char* Ks, const bf16x8* qr, const char* qx, int r32, int hi, ...
;   static_assert(CF::ND0 == 12, "qk_sm1: 12 d0 steps");
;   n0 = f32x16{}; n1 = f32x16{};
;   const char* kr = Ks + r32 * CF::KPITCH; const int sw = (r32 & CF::KSWM) << 4;
;   bf16x8 kf[2][2], qf[2];
;     ...
;   ATT_QRD(0, 0); asm volatile("s_waitcnt lgkmcnt(0)" ::: "memory"); ATT_SBAR();
;   float ps = 0;
; #pragma unroll
;   for (int g = 0; g < 12; ++g) {
;     if (g + 1 < 12) ATT_QRD((g + 1) & 1, g + 1);
;     if (g < 2) {
; #pragma unroll
;       for (int r = 0; r < 8; ++r) p1[8 * g + r] = __builtin_amdgcn_exp2f(p1[8 * g + r]);
;       if (g == 1) asm volatile("" : "+v"(p1)); }
;     else if (g < 6) {
; #pragma unroll
;       for (int r = 0; r < 8; ++r) ps += (g < 4 ? p0[8 * (g - 2) + r] : p1[8 * (g - 4) + r]);
;       asm volatile("" : "+v"(ps)); }
;     else if (g == 6) {
;       { auto rr = __builtin_amdgcn_permlane32_swap(__float_as_uint(ps), __float_as_uint(ps), false, false);
;         ps = __uint_as_float(rr[0]) + __uint_as_float(rr[1]); }
;       l_reg = l_reg * alpha + ps;
;       ATT_PK4(p0, 0, pa0);
;       asm volatile("" : "+v"(l_reg), "+v"(pa0)); }
;     else if (g == 7) { ATT_PK4(p0, 8, pa1); asm volatile("" : "+v"(pa1)); }
;     else if (g == 8) { ATT_PK4(p1, 0, pa2); asm volatile("" : "+v"(pa2)); }
;     else if (g == 9) { ATT_PK4(p1, 8, pa3); asm volatile("" : "+v"(pa3)); }
;     ATT_QMM(g & 1, g);
;     if (g + 1 < 12) { asm volatile("s_waitcnt lgkmcnt(0)" ::: "memory"); ATT_SBAR(); }
;   }
.LBB0_1725:
	v_add_u32_e32 v237, v200, v236
	v_add_u32_e32 v238, v235, v236
	ds_read_b128 v[96:99], v237 offset:57344
	ds_read_b128 v[100:103], v238 offset:12288
	s_waitcnt lgkmcnt(1)
	v_mfma_f32_32x32x16_bf16 v[112:127], v[96:99], v[148:151], 0
	ds_read_b128 v[152:155], v215 offset:49152
	ds_read_b128 v[156:159], v215 offset:61440
	v_exp_f32_e32 v80, v80
	v_exp_f32_e32 v81, v81
	v_exp_f32_e32 v82, v82
	v_exp_f32_e32 v83, v83
	s_waitcnt lgkmcnt(2)
	v_mfma_f32_32x32x16_bf16 v[96:111], v[100:103], v[148:151], 0
	v_exp_f32_e32 v84, v84
	v_exp_f32_e32 v85, v85
	v_exp_f32_e32 v86, v86
	v_exp_f32_e32 v87, v87
	s_waitcnt lgkmcnt(1)
	v_mfma_f32_32x32x16_bf16 v[112:127], v[152:155], v[144:147], v[112:127]
	ds_read_b128 v[152:155], v203 offset:49152
	ds_read_b128 v[160:163], v203 offset:61440
	v_exp_f32_e32 v88, v88
	v_exp_f32_e32 v89, v89
	v_exp_f32_e32 v90, v90
	v_exp_f32_e32 v91, v91
	v_exp_f32_e32 v92, v92
	s_waitcnt lgkmcnt(2)
	v_mfma_f32_32x32x16_bf16 v[96:111], v[156:159], v[144:147], v[96:111]
	v_exp_f32_e32 v93, v93
	v_exp_f32_e32 v94, v94
	v_exp_f32_e32 v95, v95
	v_add_f32_e32 v168, v65, v64
	v_add_f32_e32 v168, v66, v168
	s_waitcnt lgkmcnt(1)
	v_mfma_f32_32x32x16_bf16 v[112:127], v[152:155], v[140:143], v[112:127]
	v_add_f32_e32 v152, v67, v168
	v_add_f32_e32 v152, v68, v152
	v_add_f32_e32 v152, v69, v152
	ds_read_b128 v[156:159], v214 offset:49152
	ds_read_b128 v[164:167], v214 offset:61440
	v_add_f32_e32 v152, v70, v152
	v_add_f32_e32 v168, v71, v152
	s_waitcnt lgkmcnt(2)
	v_mfma_f32_32x32x16_bf16 v[96:111], v[160:163], v[140:143], v[96:111]
	s_nop 0
	v_add_f32_e32 v168, v72, v168
	v_add_f32_e32 v168, v73, v168
	v_add_f32_e32 v168, v74, v168
	s_waitcnt lgkmcnt(1)
	v_mfma_f32_32x32x16_bf16 v[112:127], v[156:159], v[136:139], v[112:127]
	v_add_f32_e32 v156, v75, v168
	v_add_f32_e32 v156, v76, v156
	v_add_f32_e32 v156, v77, v156
	ds_read_b128 v[152:155], v202 offset:49152
	ds_read_b128 v[160:163], v202 offset:61440
	v_add_f32_e32 v156, v78, v156
	v_add_f32_e32 v168, v79, v156
	s_waitcnt lgkmcnt(2)
	v_mfma_f32_32x32x16_bf16 v[96:111], v[164:167], v[136:139], v[96:111]
	s_nop 0
	v_add_f32_e32 v168, v80, v168
	v_add_f32_e32 v168, v81, v168
	v_add_f32_e32 v168, v82, v168
	s_waitcnt lgkmcnt(1)
	v_mfma_f32_32x32x16_bf16 v[112:127], v[152:155], v[132:135], v[112:127]
	v_add_f32_e32 v152, v83, v168
	v_add_f32_e32 v152, v84, v152
	v_add_f32_e32 v152, v85, v152
	ds_read_b128 v[156:159], v201 offset:49152
	ds_read_b128 v[164:167], v201 offset:61440
	v_add_f32_e32 v152, v86, v152
	v_add_f32_e32 v152, v87, v152
	s_waitcnt lgkmcnt(2)
	v_mfma_f32_32x32x16_bf16 v[96:111], v[160:163], v[132:135], v[96:111]
	s_nop 0
	v_add_f32_e32 v152, v88, v152
	v_add_f32_e32 v152, v89, v152
	v_add_f32_e32 v152, v90, v152
	s_waitcnt lgkmcnt(1)
	v_mfma_f32_32x32x16_bf16 v[112:127], v[156:159], v[128:131], v[112:127]
	v_add_f32_e32 v152, v91, v152
	v_add_f32_e32 v152, v92, v152
	ds_read_b128 v[160:163], v198 offset:61440
	ds_read_b128 v[168:171], v198 offset:49152
	ds_read_b128 v[182:185], v188
	v_add_f32_e32 v152, v93, v152
	v_add_f32_e32 v152, v94, v152
	v_add_f32_e32 v152, v95, v152
	s_waitcnt lgkmcnt(3)
	v_mfma_f32_32x32x16_bf16 v[96:111], v[164:167], v[128:131], v[96:111]
	s_waitcnt lgkmcnt(0)
	v_mfma_f32_32x32x16_bf16 v[112:127], v[168:171], v[182:185], v[112:127]
	v_mov_b32_e32 v153, v152
	ds_read_b128 v[164:167], v192 offset:61440
	ds_read_b128 v[206:209], v192 offset:49152
	ds_read_b128 v[210:213], v188 offset:1024
	v_permlane32_swap_b32_e32 v152, v153
	v_add_f32_e32 v251, v152, v153
	v_cvt_pk_bf16_f32 v152, v64, v65
	v_mfma_f32_32x32x16_bf16 v[96:111], v[160:163], v[182:185], v[96:111]
	v_cvt_pk_bf16_f32 v153, v66, v67
	v_cvt_pk_bf16_f32 v154, v68, v69
	v_cvt_pk_bf16_f32 v155, v70, v71
	v_fmac_f32_e32 v251, v180, v250
	v_permlane32_swap_b32_e32 v152, v154
	v_permlane32_swap_b32_e32 v153, v155
	s_waitcnt lgkmcnt(0)
	v_mfma_f32_32x32x16_bf16 v[112:127], v[206:209], v[210:213], v[112:127]
	ds_read_b128 v[64:67], v194 offset:61440
	ds_read_b128 v[68:71], v194 offset:49152
	ds_read_b128 v[160:163], v188 offset:2048
	v_cvt_pk_bf16_f32 v156, v72, v73
	v_cvt_pk_bf16_f32 v157, v74, v75
	v_cvt_pk_bf16_f32 v158, v76, v77
	v_cvt_pk_bf16_f32 v159, v78, v79
	v_mfma_f32_32x32x16_bf16 v[96:111], v[164:167], v[210:213], v[96:111]
	v_permlane32_swap_b32_e32 v156, v158
	v_permlane32_swap_b32_e32 v157, v159
	s_waitcnt lgkmcnt(0)
	v_mfma_f32_32x32x16_bf16 v[112:127], v[68:71], v[160:163], v[112:127]
	ds_read_b128 v[72:75], v190 offset:61440
	ds_read_b128 v[76:79], v190 offset:49152
	ds_read_b128 v[164:167], v188 offset:3072
	v_cvt_pk_bf16_f32 v80, v80, v81
	v_cvt_pk_bf16_f32 v81, v82, v83
	v_cvt_pk_bf16_f32 v82, v84, v85
	v_cvt_pk_bf16_f32 v83, v86, v87
	v_mfma_f32_32x32x16_bf16 v[96:111], v[64:67], v[160:163], v[96:111]
	v_permlane32_swap_b32_e32 v80, v82
	v_permlane32_swap_b32_e32 v81, v83
	s_waitcnt lgkmcnt(0)
	v_mfma_f32_32x32x16_bf16 v[112:127], v[76:79], v[164:167], v[112:127]
	ds_read_b128 v[64:67], v193 offset:61440
	ds_read_b128 v[68:71], v193 offset:49152
	ds_read_b128 v[160:163], v188 offset:4096
	v_cvt_pk_bf16_f32 v84, v88, v89
	v_cvt_pk_bf16_f32 v85, v90, v91
	v_cvt_pk_bf16_f32 v86, v92, v93
	v_cvt_pk_bf16_f32 v87, v94, v95
	v_mfma_f32_32x32x16_bf16 v[96:111], v[72:75], v[164:167], v[96:111]
	v_permlane32_swap_b32_e32 v84, v86
	v_permlane32_swap_b32_e32 v85, v87
	s_waitcnt lgkmcnt(0)
	v_mfma_f32_32x32x16_bf16 v[112:127], v[68:71], v[160:163], v[112:127]
	ds_read_b128 v[68:71], v191 offset:61440
	ds_read_b128 v[72:75], v191 offset:49152
	ds_read_b128 v[76:79], v188 offset:5120
	v_mfma_f32_32x32x16_bf16 v[96:111], v[64:67], v[160:163], v[96:111]
	s_waitcnt lgkmcnt(0)
; #define ATT_SBAR() __builtin_amdgcn_sched_barrier(0)
; #define ATT_SLOAD(i, k0) do { const bf16_t* vt_ = Vg + (long)(k0) * ldv; const bf16_t* kt_ = Kg + (long)(k0) * ldk; \
;     sr_[i].vs0 = ld8(vt_ + voff0); sr_[i].vs1 = ld8(vt_ + 32 * ldv + voff0); \
;     sr_[i].ks0 = ld8(kt_ + koff0); sr_[i].ks1 = ld8(kt_ + 32 * ldk + koff0); if constexpr (ND0 == 12) sr_[i].ks2 = ld8(kt_ + koff2); } while (0)
; #define ATT_SLOAD(i, k0) do { const bf16_t* vt_ = Vg + (long)(k0) * ldv; const bf16_t* kt_ = Kg + (long)(k0) * ldk; \
;     sr_[i].vs0 = ld8(vt_ + voff0); sr_[i].vs1 = ld8(vt_ + 32 * ldv + voff0); \
;     sr_[i].ks0 = ld8(kt_ + koff0); sr_[i].ks1 = ld8(kt_ + 32 * ldk + koff0); if constexpr (ND0 == 12) sr_[i].ks2 = ld8(kt_ + koff2); } while (0)
; template <class CF> __device__ __forceinline__ void pv_sm(f32x16* o, int vb, bf16x8 pa0, bf16x8 pa1, bf16x8 pa2, bf16x8 pa3, f32x16& p0, f32x16& p1, float& m_reg, float& mn, float& alpha) {
;   constexpr float C = CF::SCALE * 1.4426950408889634f;
;   s16x4 f[8];
;   pv_reads<0>(vb, f);
;   float pmax = p0[0];
; #pragma unroll
;   for (int r = 1; r < 16; ++r) pmax = fmaxf(pmax, p0[r]);
;   asm volatile("" : "+v"(pmax));
;   pv_mfma4(o[0], f, pa0, pa1, pa2, pa3);
;   pv_reads<1>(vb, f);
; #pragma unroll
;   for (int r = 0; r < 16; ++r) pmax = fmaxf(pmax, p1[r]);
;   { auto rr = __builtin_amdgcn_permlane32_swap(__float_as_uint(pmax), __float_as_uint(pmax), false, false);
;     pmax = fmaxf(__uint_as_float(rr[0]), __uint_as_float(rr[1])); }
;   asm volatile("" : "+v"(pmax));
;   pv_mfma4(o[1], f, pa0, pa1, pa2, pa3);
;   pv_reads<2>(vb, f);
;   if (__builtin_expect(__all(pmax - m_reg <= THR / CF::SCALE), 1)) { mn = m_reg; alpha = 1.f; }
;   else { mn = fmaxf(m_reg, pmax); alpha = __builtin_amdgcn_exp2f((m_reg - mn) * C); m_reg = mn; }
;   const float mnC = -mn * C;
; #pragma unroll
;   for (int r = 0; r < 16; ++r) p0[r] = fmaf(p0[r], C, mnC);
; #pragma unroll
;   for (int r = 0; r < 16; ++r) p1[r] = fmaf(p1[r], C, mnC);
;     ...
;     ATT_SLOAD(SO, (j + SDEPTH) * KVBLK); ATT_SBAR();
	v_mfma_f32_32x32x16_bf16 v[112:127], v[72:75], v[76:79], v[112:127]
	v_mfma_f32_32x32x16_bf16 v[96:111], v[68:71], v[76:79], v[96:111]
	v_lshl_add_u64 v[180:181], v[178:179], 0, s[8:9]
	s_mov_b32 s0, 0x3f900000
	v_add_co_u32_e32 v64, vcc, s0, v180
	s_mov_b32 s0, 0x3f940000
	s_nop 0
	v_addc_co_u32_e32 v65, vcc, 0, v181, vcc
	v_add_co_u32_e32 v66, vcc, s0, v180
	v_lshl_add_u64 v[182:183], v[176:177], 0, s[8:9]
	s_nop 0
	v_addc_co_u32_e32 v67, vcc, 0, v181, vcc
	global_load_dwordx4 v[88:91], v[64:65], off offset:256
	global_load_dwordx4 v[92:95], v[66:67], off offset:256
	v_add_co_u32_e32 v64, vcc, s85, v182
	s_mov_b32 s0, 0x4f8f0000
	s_nop 0
	v_addc_co_u32_e32 v65, vcc, 0, v183, vcc
	v_add_co_u32_e32 v66, vcc, s0, v182
	v_lshl_add_u64 v[184:185], v[174:175], 0, s[8:9]
	s_nop 0
	v_addc_co_u32_e32 v67, vcc, 0, v183, vcc
	global_load_dwordx4 v[160:163], v[64:65], off
	global_load_dwordx4 v[164:167], v[66:67], off
	v_add_co_u32_e32 v64, vcc, s85, v184
	s_nop 1
	v_addc_co_u32_e32 v65, vcc, 0, v185, vcc
	global_load_dwordx4 v[168:171], v[64:65], off offset:256
	ds_read_b64_tr_b16 v[64:65], v187 offset:0
	ds_read_b64_tr_b16 v[66:67], v187 offset:0x800
	ds_read_b64_tr_b16 v[68:69], v187 offset:0x1000
	ds_read_b64_tr_b16 v[70:71], v187 offset:0x1800
	ds_read_b64_tr_b16 v[72:73], v187 offset:0x2000
	ds_read_b64_tr_b16 v[74:75], v187 offset:0x2800
	ds_read_b64_tr_b16 v[76:77], v187 offset:0x3000
	ds_read_b64_tr_b16 v[78:79], v187 offset:0x3800
	s_waitcnt lgkmcnt(6)
	v_mfma_f32_32x32x16_bf16 v[0:15], v[152:155], v[64:67], v[0:15]
	v_max_f32_e32 v206, v112, v113
	v_max3_f32 v206, v206, v114, v115
	v_max3_f32 v206, v206, v116, v117
	v_max3_f32 v206, v206, v118, v119
	v_max3_f32 v206, v206, v120, v121
	s_waitcnt lgkmcnt(4)
	v_mfma_f32_32x32x16_bf16 v[0:15], v[156:159], v[68:71], v[0:15]
	v_max3_f32 v206, v206, v122, v123
	v_max3_f32 v206, v206, v124, v125
	v_max3_f32 v206, v206, v126, v127
	ds_read_b64_tr_b16 v[64:65], v187 offset:0x200
	ds_read_b64_tr_b16 v[66:67], v187 offset:0xa00
	ds_read_b64_tr_b16 v[68:69], v187 offset:0x1200
	s_waitcnt lgkmcnt(3)
	v_mfma_f32_32x32x16_bf16 v[0:15], v[80:83], v[72:75], v[0:15]
	ds_read_b64_tr_b16 v[70:71], v187 offset:0x1a00
	ds_read_b64_tr_b16 v[72:73], v187 offset:0x2200
	ds_read_b64_tr_b16 v[74:75], v187 offset:0x2a00
	v_mfma_f32_32x32x16_bf16 v[0:15], v[84:87], v[76:79], v[0:15]
	ds_read_b64_tr_b16 v[76:77], v187 offset:0x3200
	ds_read_b64_tr_b16 v[78:79], v187 offset:0x3a00
	s_waitcnt lgkmcnt(5)
	v_mfma_f32_32x32x16_bf16 v[48:63], v[152:155], v[64:67], v[48:63]
	v_max3_f32 v206, v206, v96, v97
	v_max3_f32 v206, v206, v98, v99
	v_max3_f32 v206, v206, v100, v101
	v_max3_f32 v206, v206, v102, v103
	v_max3_f32 v206, v206, v104, v105
	v_max3_f32 v206, v206, v106, v107
	v_max3_f32 v206, v206, v108, v109
	s_waitcnt lgkmcnt(2)
	v_mfma_f32_32x32x16_bf16 v[48:63], v[156:159], v[68:71], v[48:63]
	v_max3_f32 v206, v206, v110, v111
	v_mov_b32_e32 v207, v206
	s_nop 1
	v_permlane32_swap_b32_e32 v206, v207
	v_max_f32_e32 v218, v206, v207
	v_mfma_f32_32x32x16_bf16 v[48:63], v[80:83], v[72:75], v[48:63]
	ds_read_b64_tr_b16 v[64:65], v187 offset:0x400
	ds_read_b64_tr_b16 v[66:67], v187 offset:0xc00
	ds_read_b64_tr_b16 v[68:69], v187 offset:0x1400
	ds_read_b64_tr_b16 v[70:71], v187 offset:0x1c00
	ds_read_b64_tr_b16 v[206:207], v187 offset:0x2400
	ds_read_b64_tr_b16 v[208:209], v187 offset:0x2c00
	s_waitcnt lgkmcnt(6)
	v_mfma_f32_32x32x16_bf16 v[48:63], v[84:87], v[76:79], v[48:63]
	ds_read_b64_tr_b16 v[210:211], v187 offset:0x3400
	ds_read_b64_tr_b16 v[212:213], v187 offset:0x3c00
	s_waitcnt lgkmcnt(6)
	v_mfma_f32_32x32x16_bf16 v[32:47], v[152:155], v[64:67], v[32:47]
	v_sub_f32_e32 v72, v218, v233
	v_cmp_ge_f32_e32 vcc, s63, v72
	s_waitcnt lgkmcnt(2)
	v_mfma_f32_32x32x16_bf16 v[32:47], v[156:159], v[68:71], v[32:47]
	s_nop 1
	s_cmp_eq_u64 vcc, exec
	s_cbranch_scc0 .Latt_rare_b1
	v_mov_b32_e32 v252, 1.0
.Latt_back_b1:
	v_mul_f32_e32 v218, 0xbdd53b94, v233
	v_pk_fma_f32 v[78:79], v[126:127], s[84:85], v[218:219] op_sel_hi:[1,0,0]
	v_mfma_f32_32x32x16_bf16 v[32:47], v[80:83], v[206:209], v[32:47]
	ds_read_b64_tr_b16 v[206:207], v187 offset:0x1600
	ds_read_b64_tr_b16 v[208:209], v187 offset:0x1e00
	v_fma_f32 v76, v124, s84, v218
	v_fma_f32 v77, v125, s84, v218
	v_fma_f32 v74, v122, s84, v218
	v_fma_f32 v75, v123, s84, v218
	v_fma_f32 v72, v120, s84, v218
	v_fma_f32 v73, v121, s84, v218
	v_pk_fma_f32 v[70:71], v[118:119], s[84:85], v[218:219] op_sel_hi:[1,0,0]
	v_pk_fma_f32 v[68:69], v[116:117], s[84:85], v[218:219] op_sel_hi:[1,0,0]
	v_pk_fma_f32 v[66:67], v[114:115], s[84:85], v[218:219] op_sel_hi:[1,0,0]
	v_pk_fma_f32 v[64:65], v[112:113], s[84:85], v[218:219] op_sel_hi:[1,0,0]
	v_pk_fma_f32 v[126:127], v[110:111], s[84:85], v[218:219] op_sel_hi:[1,0,0]
	v_pk_fma_f32 v[124:125], v[108:109], s[84:85], v[218:219] op_sel_hi:[1,0,0]
	v_pk_fma_f32 v[122:123], v[106:107], s[84:85], v[218:219] op_sel_hi:[1,0,0]
	v_pk_fma_f32 v[120:121], v[104:105], s[84:85], v[218:219] op_sel_hi:[1,0,0]
	v_pk_fma_f32 v[118:119], v[102:103], s[84:85], v[218:219] op_sel_hi:[1,0,0]
	v_pk_fma_f32 v[116:117], v[100:101], s[84:85], v[218:219] op_sel_hi:[1,0,0]
	v_pk_fma_f32 v[114:115], v[98:99], s[84:85], v[218:219] op_sel_hi:[1,0,0]
	v_pk_fma_f32 v[112:113], v[96:97], s[84:85], v[218:219] op_sel_hi:[1,0,0]
	ds_read_b64_tr_b16 v[104:105], v187 offset:0x600
	ds_read_b64_tr_b16 v[106:107], v187 offset:0xe00
	ds_read_b64_tr_b16 v[218:219], v187 offset:0x3600
	ds_read_b64_tr_b16 v[220:221], v187 offset:0x3e00
	s_waitcnt lgkmcnt(6)
	v_mfma_f32_32x32x16_bf16 v[32:47], v[84:87], v[210:213], v[32:47]
	s_waitcnt vmcnt(0)
	ds_write_b128 v197, v[160:163] offset:32768
	ds_write_b128 v197, v[164:167] offset:45056
	ds_write_b128 v199, v[168:171] offset:32768
	ds_read_b64_tr_b16 v[210:211], v187 offset:0x2600
	ds_read_b64_tr_b16 v[212:213], v187 offset:0x2e00
	s_waitcnt lgkmcnt(7)
	v_mfma_f32_32x32x16_bf16 v[16:31], v[152:155], v[104:107], v[16:31]
	s_waitcnt lgkmcnt(0)
	s_barrier
; #define ATT_SBAR() __builtin_amdgcn_sched_barrier(0)
; #define ATT_SYNC() __syncthreads()
; #define ATT_QRD(dst, g) do { _Pragma("unroll") for (int t = 0; t < 2; ++t) { const int cb = ((2 * (g) + t) * 16 + hi * 8) * 2; \
;     dst[2 * t] = *reinterpret_cast<const bf16x8*>(kr + (cb ^ sw)); dst[2 * t + 1] = *reinterpret_cast<const bf16x8*>(kr + 32 * CF::KPITCH + (cb ^ sw)); } } while (0)
; template <class CF> __device__ __forceinline__ void qk_sm1(f32x16& n0, f32x16& n1, const char* Ks, const bf16x8* qr, const char* qx, int r32, int hi, ...
;   static_assert(CF::ND0 == 12, "qk_sm1: 12 d0 steps");
;   n0 = f32x16{}; n1 = f32x16{};
;   const char* kr = Ks + r32 * CF::KPITCH; const int sw = (r32 & CF::KSWM) << 4;
;   bf16x8 kf[2][2], qf[2];
;     ...
;   ATT_QRD(0, 0); asm volatile("s_waitcnt lgkmcnt(0)" ::: "memory"); ATT_SBAR();
;   float ps = 0;
; #pragma unroll
;   for (int g = 0; g < 12; ++g) {
;     if (g + 1 < 12) ATT_QRD((g + 1) & 1, g + 1);
;     if (g < 2) {
; #pragma unroll
;       for (int r = 0; r < 8; ++r) p1[8 * g + r] = __builtin_amdgcn_exp2f(p1[8 * g + r]);
;       if (g == 1) asm volatile("" : "+v"(p1)); }
;     else if (g < 6) {
; #pragma unroll
;       for (int r = 0; r < 8; ++r) ps += (g < 4 ? p0[8 * (g - 2) + r] : p1[8 * (g - 4) + r]);
;       asm volatile("" : "+v"(ps)); }
;     else if (g == 6) {
;       { auto rr = __builtin_amdgcn_permlane32_swap(__float_as_uint(ps), __float_as_uint(ps), false, false);
;         ps = __uint_as_float(rr[0]) + __uint_as_float(rr[1]); }
;       l_reg = l_reg * alpha + ps;
;       ATT_PK4(p0, 0, pa0);
;       asm volatile("" : "+v"(l_reg), "+v"(pa0)); }
;     else if (g == 7) { ATT_PK4(p0, 8, pa1); asm volatile("" : "+v"(pa1)); }
;     else if (g == 8) { ATT_PK4(p1, 0, pa2); asm volatile("" : "+v"(pa2)); }
;     else if (g == 9) { ATT_PK4(p1, 8, pa3); asm volatile("" : "+v"(pa3)); }
;     ATT_QMM(g & 1, g);
;     if (g + 1 < 12) { asm volatile("s_waitcnt lgkmcnt(0)" ::: "memory"); ATT_SBAR(); }
;   }
;     ...
;     ATT_SYNC(); ATT_SWAIT(); ATT_SWRITE(0, SE);
;     ATT_RESC(alB); ATT_SYNC();
;     ATT_SBAR(); if constexpr (QKSPLIT) qk_sm<CF>(pA0, pA1, K_lds, qr, r32, hi, pB0, pB1, alB, l_reg, pa0, pa1, pa2, pa3);
;     else if constexpr (QK1) qk_sm1<CF>(pA0, pA1, K_lds, qr, qx, r32, hi, pB0, pB1, alB, l_reg, pa0, pa1, pa2, pa3);
	ds_write_b128 v195, v[88:91]
	v_exp_f32_e32 v96, v64
	v_exp_f32_e32 v97, v65
	v_exp_f32_e32 v98, v66
	v_exp_f32_e32 v99, v67
	v_exp_f32_e32 v100, v68
	v_exp_f32_e32 v101, v69
	v_exp_f32_e32 v102, v70
	v_mfma_f32_32x32x16_bf16 v[16:31], v[156:159], v[206:209], v[16:31]
	ds_write_b128 v196, v[92:95]
	v_exp_f32_e32 v103, v71
	v_exp_f32_e32 v104, v72
	v_exp_f32_e32 v105, v73
	v_exp_f32_e32 v106, v74
	v_exp_f32_e32 v107, v75
	v_exp_f32_e32 v108, v76
	v_exp_f32_e32 v109, v77
	v_mfma_f32_32x32x16_bf16 v[16:31], v[80:83], v[210:213], v[16:31]
	v_exp_f32_e32 v110, v78
	v_exp_f32_e32 v111, v79
	v_mfma_f32_32x32x16_bf16 v[16:31], v[84:87], v[218:221], v[16:31]
	v_cmp_gt_f32_e32 vcc, 1.0, v252
	s_cbranch_vccz .LBB0_1729
	s_and_saveexec_b64 s[12:13], s[4:5]
	ds_write_b32 v224, v252 offset:128
	s_or_b64 exec, exec, s[12:13]
	s_waitcnt lgkmcnt(0)
	v_add_u32_e32 v76, v186, v204
	ds_read_b128 v[64:67], v76 offset:224
	ds_read_b128 v[68:71], v76 offset:192
	ds_read_b128 v[72:75], v76 offset:160
	ds_read_b128 v[76:79], v76 offset:128
	s_waitcnt lgkmcnt(3)
	v_pk_mul_f32 v[12:13], v[12:13], v[64:65]
	s_waitcnt lgkmcnt(2)
	v_pk_mul_f32 v[8:9], v[8:9], v[68:69]
	s_waitcnt lgkmcnt(1)
	v_pk_mul_f32 v[4:5], v[4:5], v[72:73]
	v_pk_mul_f32 v[14:15], v[14:15], v[66:67]
	v_pk_mul_f32 v[10:11], v[10:11], v[70:71]
	v_pk_mul_f32 v[6:7], v[6:7], v[74:75]
	s_waitcnt lgkmcnt(0)
	v_pk_mul_f32 v[2:3], v[2:3], v[78:79]
	v_pk_mul_f32 v[0:1], v[0:1], v[76:77]
	v_pk_mul_f32 v[60:61], v[60:61], v[64:65]
	v_pk_mul_f32 v[56:57], v[56:57], v[68:69]
	v_pk_mul_f32 v[52:53], v[52:53], v[72:73]
	v_pk_mul_f32 v[62:63], v[62:63], v[66:67]
	v_pk_mul_f32 v[58:59], v[58:59], v[70:71]
	v_pk_mul_f32 v[54:55], v[54:55], v[74:75]
	v_pk_mul_f32 v[50:51], v[50:51], v[78:79]
	v_pk_mul_f32 v[48:49], v[48:49], v[76:77]
	v_pk_mul_f32 v[44:45], v[44:45], v[64:65]
	v_pk_mul_f32 v[40:41], v[40:41], v[68:69]
	v_pk_mul_f32 v[36:37], v[36:37], v[72:73]
	v_pk_mul_f32 v[46:47], v[46:47], v[66:67]
	v_pk_mul_f32 v[42:43], v[42:43], v[70:71]
	v_pk_mul_f32 v[38:39], v[38:39], v[74:75]
	v_pk_mul_f32 v[34:35], v[34:35], v[78:79]
	v_pk_mul_f32 v[32:33], v[32:33], v[76:77]
	v_pk_mul_f32 v[28:29], v[28:29], v[64:65]
	v_pk_mul_f32 v[24:25], v[24:25], v[68:69]
	v_pk_mul_f32 v[20:21], v[20:21], v[72:73]
	v_pk_mul_f32 v[30:31], v[30:31], v[66:67]
	v_pk_mul_f32 v[26:27], v[26:27], v[70:71]
	v_pk_mul_f32 v[22:23], v[22:23], v[74:75]
	v_pk_mul_f32 v[18:19], v[18:19], v[78:79]
	v_pk_mul_f32 v[16:17], v[16:17], v[76:77]
.LBB0_1729:
	ds_read_b128 v[64:67], v237 offset:32768
	ds_read_b128 v[68:71], v237 offset:45056
	s_waitcnt lgkmcnt(1)
	v_mfma_f32_32x32x16_bf16 v[80:95], v[64:67], v[148:151], 0
	ds_read_b128 v[152:155], v215 offset:24576
	ds_read_b128 v[156:159], v215 offset:36864
	v_exp_f32_e32 v112, v112
	v_exp_f32_e32 v113, v113
	v_exp_f32_e32 v114, v114
	v_exp_f32_e32 v115, v115
	v_exp_f32_e32 v116, v116
	s_waitcnt lgkmcnt(2)
	v_mfma_f32_32x32x16_bf16 v[64:79], v[68:71], v[148:151], 0
	v_exp_f32_e32 v117, v117
	v_exp_f32_e32 v118, v118
	v_exp_f32_e32 v119, v119
	s_waitcnt lgkmcnt(1)
	v_mfma_f32_32x32x16_bf16 v[80:95], v[152:155], v[144:147], v[80:95]
	ds_read_b128 v[152:155], v203 offset:24576
	ds_read_b128 v[160:163], v203 offset:36864
	v_exp_f32_e32 v120, v120
	v_exp_f32_e32 v121, v121
	v_exp_f32_e32 v122, v122
	v_exp_f32_e32 v123, v123
	v_exp_f32_e32 v124, v124
	v_exp_f32_e32 v125, v125
	s_waitcnt lgkmcnt(2)
	v_mfma_f32_32x32x16_bf16 v[64:79], v[156:159], v[144:147], v[64:79]
	v_exp_f32_e32 v126, v126
	v_exp_f32_e32 v127, v127
	v_add_f32_e32 v168, v97, v96
	v_add_f32_e32 v168, v98, v168
	s_waitcnt lgkmcnt(1)
	v_mfma_f32_32x32x16_bf16 v[80:95], v[152:155], v[140:143], v[80:95]
	v_add_f32_e32 v152, v99, v168
	v_add_f32_e32 v152, v100, v152
	v_add_f32_e32 v152, v101, v152
	ds_read_b128 v[156:159], v214 offset:24576
	ds_read_b128 v[164:167], v214 offset:36864
	v_add_f32_e32 v152, v102, v152
	v_add_f32_e32 v168, v103, v152
	s_waitcnt lgkmcnt(2)
	v_mfma_f32_32x32x16_bf16 v[64:79], v[160:163], v[140:143], v[64:79]
	v_add_f32_e32 v168, v104, v168
	v_add_f32_e32 v168, v105, v168
	v_add_f32_e32 v168, v106, v168
	s_waitcnt lgkmcnt(1)
	v_mfma_f32_32x32x16_bf16 v[80:95], v[156:159], v[136:139], v[80:95]
	v_add_f32_e32 v156, v107, v168
	v_add_f32_e32 v156, v108, v156
	v_add_f32_e32 v156, v109, v156
	ds_read_b128 v[152:155], v202 offset:24576
	ds_read_b128 v[160:163], v202 offset:36864
	v_add_f32_e32 v156, v110, v156
	v_add_f32_e32 v168, v111, v156
	s_waitcnt lgkmcnt(2)
	v_mfma_f32_32x32x16_bf16 v[64:79], v[164:167], v[136:139], v[64:79]
	v_add_f32_e32 v168, v112, v168
	v_add_f32_e32 v168, v113, v168
	v_add_f32_e32 v168, v114, v168
	s_waitcnt lgkmcnt(1)
	v_mfma_f32_32x32x16_bf16 v[80:95], v[152:155], v[132:135], v[80:95]
	v_add_f32_e32 v152, v115, v168
	v_add_f32_e32 v152, v116, v152
	v_add_f32_e32 v152, v117, v152
	ds_read_b128 v[156:159], v201 offset:24576
	ds_read_b128 v[164:167], v201 offset:36864
	v_add_f32_e32 v152, v118, v152
	v_add_f32_e32 v152, v119, v152
	s_waitcnt lgkmcnt(2)
	v_mfma_f32_32x32x16_bf16 v[64:79], v[160:163], v[132:135], v[64:79]
	v_add_f32_e32 v152, v120, v152
	v_add_f32_e32 v152, v121, v152
	v_add_f32_e32 v152, v122, v152
	s_waitcnt lgkmcnt(1)
	v_mfma_f32_32x32x16_bf16 v[80:95], v[156:159], v[128:131], v[80:95]
	v_add_f32_e32 v152, v123, v152
	v_add_f32_e32 v152, v124, v152
	ds_read_b128 v[160:163], v198 offset:36864
	ds_read_b128 v[168:171], v198 offset:24576
	ds_read_b128 v[206:209], v188
	v_add_f32_e32 v152, v125, v152
	v_add_f32_e32 v152, v126, v152
	v_add_f32_e32 v152, v127, v152
	s_waitcnt lgkmcnt(3)
	v_mfma_f32_32x32x16_bf16 v[64:79], v[164:167], v[128:131], v[64:79]
	s_waitcnt lgkmcnt(0)
; #define ATT_SBAR() __builtin_amdgcn_sched_barrier(0)
; #define ATT_SLOAD(i, k0) do { const bf16_t* vt_ = Vg + (long)(k0) * ldv; const bf16_t* kt_ = Kg + (long)(k0) * ldk; \
;     sr_[i].vs0 = ld8(vt_ + voff0); sr_[i].vs1 = ld8(vt_ + 32 * ldv + voff0); \
;     sr_[i].ks0 = ld8(kt_ + koff0); sr_[i].ks1 = ld8(kt_ + 32 * ldk + koff0); if constexpr (ND0 == 12) sr_[i].ks2 = ld8(kt_ + koff2); } while (0)
; #define ATT_SLOAD(i, k0) do { const bf16_t* vt_ = Vg + (long)(k0) * ldv; const bf16_t* kt_ = Kg + (long)(k0) * ldk; \
;     sr_[i].vs0 = ld8(vt_ + voff0); sr_[i].vs1 = ld8(vt_ + 32 * ldv + voff0); \
;     sr_[i].ks0 = ld8(kt_ + koff0); sr_[i].ks1 = ld8(kt_ + 32 * ldk + koff0); if constexpr (ND0 == 12) sr_[i].ks2 = ld8(kt_ + koff2); } while (0)
; template <class CF> __device__ __forceinline__ void pv_sm(f32x16* o, int vb, bf16x8 pa0, bf16x8 pa1, bf16x8 pa2, bf16x8 pa3, f32x16& p0, f32x16& p1, float& m_reg, float& mn, float& alpha) {
;   constexpr float C = CF::SCALE * 1.4426950408889634f;
;   s16x4 f[8];
;   pv_reads<0>(vb, f);
;   float pmax = p0[0];
; #pragma unroll
;   for (int r = 1; r < 16; ++r) pmax = fmaxf(pmax, p0[r]);
;   asm volatile("" : "+v"(pmax));
;   pv_mfma4(o[0], f, pa0, pa1, pa2, pa3);
;   pv_reads<1>(vb, f);
; #pragma unroll
;   for (int r = 0; r < 16; ++r) pmax = fmaxf(pmax, p1[r]);
;   { auto rr = __builtin_amdgcn_permlane32_swap(__float_as_uint(pmax), __float_as_uint(pmax), false, false);
;     pmax = fmaxf(__uint_as_float(rr[0]), __uint_as_float(rr[1])); }
;   asm volatile("" : "+v"(pmax));
;   pv_mfma4(o[1], f, pa0, pa1, pa2, pa3);
;   pv_reads<2>(vb, f);
;   if (__builtin_expect(__all(pmax - m_reg <= THR / CF::SCALE), 1)) { mn = m_reg; alpha = 1.f; }
;   else { mn = fmaxf(m_reg, pmax); alpha = __builtin_amdgcn_exp2f((m_reg - mn) * C); m_reg = mn; }
;   const float mnC = -mn * C;
; #pragma unroll
;   for (int r = 0; r < 16; ++r) p0[r] = fmaf(p0[r], C, mnC);
; #pragma unroll
;   for (int r = 0; r < 16; ++r) p1[r] = fmaf(p1[r], C, mnC);
;     ...
;     if (SDEPTH == 1 || j + 3 < NT) ATT_SLOAD(SE, (j + 1 + SDEPTH) * KVBLK); ATT_SBAR();
	v_mfma_f32_32x32x16_bf16 v[80:95], v[168:171], v[206:209], v[80:95]
	v_mov_b32_e32 v153, v152
	ds_read_b128 v[164:167], v192 offset:36864
	ds_read_b128 v[210:213], v192 offset:24576
	ds_read_b128 v[218:221], v188 offset:1024
	v_permlane32_swap_b32_e32 v152, v153
	v_add_f32_e32 v250, v152, v153
	v_cvt_pk_bf16_f32 v152, v96, v97
	v_cvt_pk_bf16_f32 v153, v98, v99
	v_mfma_f32_32x32x16_bf16 v[64:79], v[160:163], v[206:209], v[64:79]
	v_cvt_pk_bf16_f32 v154, v100, v101
	v_cvt_pk_bf16_f32 v155, v102, v103
	v_fmac_f32_e32 v250, v251, v252
	v_permlane32_swap_b32_e32 v152, v154
	v_permlane32_swap_b32_e32 v153, v155
	s_waitcnt lgkmcnt(0)
	v_mfma_f32_32x32x16_bf16 v[80:95], v[210:213], v[218:221], v[80:95]
	ds_read_b128 v[96:99], v194 offset:36864
	ds_read_b128 v[100:103], v194 offset:24576
	ds_read_b128 v[160:163], v188 offset:2048
	v_cvt_pk_bf16_f32 v156, v104, v105
	v_cvt_pk_bf16_f32 v157, v106, v107
	v_cvt_pk_bf16_f32 v158, v108, v109
	v_cvt_pk_bf16_f32 v159, v110, v111
	s_nop 0
	v_permlane32_swap_b32_e32 v156, v158
	v_mfma_f32_32x32x16_bf16 v[64:79], v[164:167], v[218:221], v[64:79]
	v_permlane32_swap_b32_e32 v157, v159
	s_waitcnt lgkmcnt(0)
	v_mfma_f32_32x32x16_bf16 v[80:95], v[100:103], v[160:163], v[80:95]
	ds_read_b128 v[104:107], v190 offset:36864
	ds_read_b128 v[108:111], v190 offset:24576
	ds_read_b128 v[164:167], v188 offset:3072
	v_cvt_pk_bf16_f32 v112, v112, v113
	v_cvt_pk_bf16_f32 v113, v114, v115
	v_cvt_pk_bf16_f32 v114, v116, v117
	v_cvt_pk_bf16_f32 v115, v118, v119
	s_nop 0
	v_permlane32_swap_b32_e32 v112, v114
	v_mfma_f32_32x32x16_bf16 v[64:79], v[96:99], v[160:163], v[64:79]
	v_permlane32_swap_b32_e32 v113, v115
	s_waitcnt lgkmcnt(0)
	v_mfma_f32_32x32x16_bf16 v[80:95], v[108:111], v[164:167], v[80:95]
	ds_read_b128 v[96:99], v193 offset:36864
	ds_read_b128 v[100:103], v193 offset:24576
	ds_read_b128 v[160:163], v188 offset:4096
	v_cvt_pk_bf16_f32 v116, v120, v121
	v_cvt_pk_bf16_f32 v117, v122, v123
	v_cvt_pk_bf16_f32 v118, v124, v125
	v_cvt_pk_bf16_f32 v119, v126, v127
	s_nop 0
	v_permlane32_swap_b32_e32 v116, v118
	v_mfma_f32_32x32x16_bf16 v[64:79], v[104:107], v[164:167], v[64:79]
	v_permlane32_swap_b32_e32 v117, v119
	s_waitcnt lgkmcnt(0)
	v_mfma_f32_32x32x16_bf16 v[80:95], v[100:103], v[160:163], v[80:95]
	ds_read_b128 v[100:103], v191 offset:36864
	ds_read_b128 v[104:107], v191 offset:24576
	ds_read_b128 v[108:111], v188 offset:5120
	v_mfma_f32_32x32x16_bf16 v[64:79], v[96:99], v[160:163], v[64:79]
	s_waitcnt lgkmcnt(0)
	v_mfma_f32_32x32x16_bf16 v[80:95], v[104:107], v[108:111], v[80:95]
	v_mfma_f32_32x32x16_bf16 v[64:79], v[100:103], v[108:111], v[64:79]
	s_mov_b32 s0, 0x3f980000
	v_add_co_u32_e32 v96, vcc, s0, v180
	s_mov_b32 s0, 0x3f9c0000
	s_nop 0
	v_addc_co_u32_e32 v97, vcc, 0, v181, vcc
	v_add_co_u32_e32 v98, vcc, s0, v180
	s_mov_b32 s0, 0x4f950000
	s_nop 0
	v_addc_co_u32_e32 v99, vcc, 0, v181, vcc
	global_load_dwordx4 v[120:123], v[96:97], off offset:256
	global_load_dwordx4 v[124:127], v[98:99], off offset:256
	v_add_co_u32_e32 v96, vcc, s61, v182
	s_nop 1
	v_addc_co_u32_e32 v97, vcc, 0, v183, vcc
	v_add_co_u32_e32 v98, vcc, s0, v182
	s_nop 1
	v_addc_co_u32_e32 v99, vcc, 0, v183, vcc
	global_load_dwordx4 v[160:163], v[96:97], off
	global_load_dwordx4 v[164:167], v[98:99], off
	v_add_co_u32_e32 v96, vcc, s61, v184
	s_nop 1
	v_addc_co_u32_e32 v97, vcc, 0, v185, vcc
	global_load_dwordx4 v[168:171], v[96:97], off offset:256
	ds_read_b64_tr_b16 v[96:97], v189 offset:0
	ds_read_b64_tr_b16 v[98:99], v189 offset:0x800
	ds_read_b64_tr_b16 v[100:101], v189 offset:0x1000
	ds_read_b64_tr_b16 v[102:103], v189 offset:0x1800
	ds_read_b64_tr_b16 v[104:105], v189 offset:0x2000
	ds_read_b64_tr_b16 v[106:107], v189 offset:0x2800
	ds_read_b64_tr_b16 v[108:109], v189 offset:0x3000
	ds_read_b64_tr_b16 v[110:111], v189 offset:0x3800
	s_waitcnt lgkmcnt(6)
	v_mfma_f32_32x32x16_bf16 v[0:15], v[152:155], v[96:99], v[0:15]
	v_max_f32_e32 v180, v80, v81
	v_max3_f32 v180, v180, v82, v83
	v_max3_f32 v180, v180, v84, v85
	v_max3_f32 v180, v180, v86, v87
	v_max3_f32 v180, v180, v88, v89
	s_waitcnt lgkmcnt(4)
	v_mfma_f32_32x32x16_bf16 v[0:15], v[156:159], v[100:103], v[0:15]
	v_max3_f32 v180, v180, v90, v91
	v_max3_f32 v180, v180, v92, v93
	v_max3_f32 v180, v180, v94, v95
	ds_read_b64_tr_b16 v[96:97], v189 offset:0x200
	ds_read_b64_tr_b16 v[98:99], v189 offset:0xa00
	ds_read_b64_tr_b16 v[100:101], v189 offset:0x1200
	s_waitcnt lgkmcnt(3)
	v_mfma_f32_32x32x16_bf16 v[0:15], v[112:115], v[104:107], v[0:15]
	ds_read_b64_tr_b16 v[102:103], v189 offset:0x1a00
	ds_read_b64_tr_b16 v[104:105], v189 offset:0x2200
	ds_read_b64_tr_b16 v[106:107], v189 offset:0x2a00
	v_mfma_f32_32x32x16_bf16 v[0:15], v[116:119], v[108:111], v[0:15]
	ds_read_b64_tr_b16 v[108:109], v189 offset:0x3200
	ds_read_b64_tr_b16 v[110:111], v189 offset:0x3a00
	s_waitcnt lgkmcnt(5)
	v_mfma_f32_32x32x16_bf16 v[48:63], v[152:155], v[96:99], v[48:63]
	v_max3_f32 v180, v180, v64, v65
	v_max3_f32 v180, v180, v66, v67
	v_max3_f32 v180, v180, v68, v69
	v_max3_f32 v180, v180, v70, v71
	v_max3_f32 v180, v180, v72, v73
	v_max3_f32 v180, v180, v74, v75
	v_max3_f32 v180, v180, v76, v77
	s_waitcnt lgkmcnt(2)
	v_mfma_f32_32x32x16_bf16 v[48:63], v[156:159], v[100:103], v[48:63]
	v_max3_f32 v180, v180, v78, v79
	v_mov_b32_e32 v181, v180
	s_nop 1
	v_permlane32_swap_b32_e32 v180, v181
	v_max_f32_e32 v180, v180, v181
	v_mfma_f32_32x32x16_bf16 v[48:63], v[112:115], v[104:107], v[48:63]
	ds_read_b64_tr_b16 v[96:97], v189 offset:0x400
	ds_read_b64_tr_b16 v[98:99], v189 offset:0xc00
	ds_read_b64_tr_b16 v[100:101], v189 offset:0x1400
	ds_read_b64_tr_b16 v[102:103], v189 offset:0x1c00
	ds_read_b64_tr_b16 v[182:183], v189 offset:0x2400
	ds_read_b64_tr_b16 v[184:185], v189 offset:0x2c00
	s_waitcnt lgkmcnt(6)
	v_mfma_f32_32x32x16_bf16 v[48:63], v[116:119], v[108:111], v[48:63]
	ds_read_b64_tr_b16 v[206:207], v189 offset:0x3400
	ds_read_b64_tr_b16 v[208:209], v189 offset:0x3c00
	s_waitcnt lgkmcnt(6)
	v_mfma_f32_32x32x16_bf16 v[32:47], v[152:155], v[96:99], v[32:47]
	v_sub_f32_e32 v104, v180, v233
	v_cmp_ge_f32_e32 vcc, s63, v104
	s_waitcnt lgkmcnt(2)
	v_mfma_f32_32x32x16_bf16 v[32:47], v[156:159], v[100:103], v[32:47]
	s_nop 1
	s_cmp_eq_u64 vcc, exec
	s_cbranch_scc0 .Latt_rare_b2
	v_mov_b32_e32 v180, 1.0
; #define ATT_SBAR() __builtin_amdgcn_sched_barrier(0)
; #define ATT_SYNC() __syncthreads()
; #define ATT_SWRITE(b, i) do { *(bf16x8*)(V_lds + (b) * SHM_V + vst0) = sr_[i].vs0; *(bf16x8*)(V_lds + (b) * SHM_V + vst1) = sr_[i].vs1; \
;     *(bf16x8*)(K_lds + (b) * SHM_K + kst0) = sr_[i].ks0; *(bf16x8*)(K_lds + (b) * SHM_K + kst1) = sr_[i].ks1; if constexpr (ND0 == 12) *(bf16x8*)(K_lds + (b) * SHM_K + kst2) = sr_[i].ks2; } while (0)
; #define ATT_SWAIT() do { if constexpr (SDEPTH == 2) { if constexpr (ND0 == 12) asm volatile("s_waitcnt vmcnt(5)" ::: "memory"); else asm volatile("s_waitcnt vmcnt(4)" ::: "memory"); } else asm volatile("s_waitcnt vmcnt(0)" ::: "memory"); } while (0)
; #define ATT_RESC(al) do { if (__any((al) < 1.f)) { if (hi == 0) al_l[r32] = (al); asm volatile("s_waitcnt lgkmcnt(0)" ::: "memory"); \
;     _Pragma("unroll") for (int d = 0; d < 4; ++d) _Pragma("unroll") for (int r = 0; r < 16; ++r) o[d][r] *= al_l[crow(r, hi)]; } } while (0)
; #define ATT_SWRITE(b, i) do { *(bf16x8*)(V_lds + (b) * SHM_V + vst0) = sr_[i].vs0; *(bf16x8*)(V_lds + (b) * SHM_V + vst1) = sr_[i].vs1; \
;     *(bf16x8*)(K_lds + (b) * SHM_K + kst0) = sr_[i].ks0; *(bf16x8*)(K_lds + (b) * SHM_K + kst1) = sr_[i].ks1; if constexpr (ND0 == 12) *(bf16x8*)(K_lds + (b) * SHM_K + kst2) = sr_[i].ks2; } while (0)
; template <class CF> __device__ __forceinline__ void pv_sm(f32x16* o, int vb, bf16x8 pa0, bf16x8 pa1, bf16x8 pa2, bf16x8 pa3, f32x16& p0, f32x16& p1, float& m_reg, float& mn, float& alpha) {
;     ...
;   for (int r = 0; r < 16; ++r) p0[r] = fmaf(p0[r], C, mnC);
; #pragma unroll
;   for (int r = 0; r < 16; ++r) p1[r] = fmaf(p1[r], C, mnC);
;   asm volatile("" : "+v"(p0), "+v"(p1));
;   pv_mfma4(o[2], f, pa0, pa1, pa2, pa3);
;   pv_reads<3>(vb, f);
; #pragma unroll
;   for (int r = 0; r < 16; ++r) p0[r] = __builtin_amdgcn_exp2f(p0[r]);
;   asm volatile("" : "+v"(p0));
;   pv_mfma4(o[3], f, pa0, pa1, pa2, pa3);
; }
;     ...
;     ATT_SYNC(); ATT_SWAIT(); ATT_SWRITE(1, SO);
;     ATT_RESC(alA); ATT_SYNC();
;   }
;   ATT_SBAR(); if constexpr (QKSPLIT) qk_sm<CF>(pB0, pB1, K_lds + SHM_K, qr, r32, hi, pA0, pA1, alA, l_reg, pa0, pa1, pa2, pa3);
;   else if constexpr (QK1) qk_sm1<CF>(pB0, pB1, K_lds + SHM_K, qr, qx, r32, hi, pA0, pA1, alA, l_reg, pa0, pa1, pa2, pa3);
.Latt_back_b2:
	v_mul_f32_e32 v210, 0xbdd53b94, v233
	v_pk_fma_f32 v[110:111], v[94:95], s[84:85], v[210:211] op_sel_hi:[1,0,0]
	v_mfma_f32_32x32x16_bf16 v[32:47], v[112:115], v[182:185], v[32:47]
	ds_read_b64_tr_b16 v[182:183], v189 offset:0x1600
	ds_read_b64_tr_b16 v[184:185], v189 offset:0x1e00
	v_fma_f32 v108, v92, s84, v210
	v_fma_f32 v109, v93, s84, v210
	v_fma_f32 v106, v90, s84, v210
	v_fma_f32 v107, v91, s84, v210
	v_fma_f32 v104, v88, s84, v210
	v_fma_f32 v105, v89, s84, v210
	v_pk_fma_f32 v[102:103], v[86:87], s[84:85], v[210:211] op_sel_hi:[1,0,0]
	v_pk_fma_f32 v[100:101], v[84:85], s[84:85], v[210:211] op_sel_hi:[1,0,0]
	v_pk_fma_f32 v[98:99], v[82:83], s[84:85], v[210:211] op_sel_hi:[1,0,0]
	v_pk_fma_f32 v[96:97], v[80:81], s[84:85], v[210:211] op_sel_hi:[1,0,0]
	v_pk_fma_f32 v[94:95], v[78:79], s[84:85], v[210:211] op_sel_hi:[1,0,0]
	v_pk_fma_f32 v[92:93], v[76:77], s[84:85], v[210:211] op_sel_hi:[1,0,0]
	v_pk_fma_f32 v[90:91], v[74:75], s[84:85], v[210:211] op_sel_hi:[1,0,0]
	v_pk_fma_f32 v[88:89], v[72:73], s[84:85], v[210:211] op_sel_hi:[1,0,0]
	v_pk_fma_f32 v[86:87], v[70:71], s[84:85], v[210:211] op_sel_hi:[1,0,0]
	v_pk_fma_f32 v[84:85], v[68:69], s[84:85], v[210:211] op_sel_hi:[1,0,0]
	v_pk_fma_f32 v[82:83], v[66:67], s[84:85], v[210:211] op_sel_hi:[1,0,0]
	v_pk_fma_f32 v[80:81], v[64:65], s[84:85], v[210:211] op_sel_hi:[1,0,0]
	ds_read_b64_tr_b16 v[72:73], v189 offset:0x600
	ds_read_b64_tr_b16 v[74:75], v189 offset:0xe00
	ds_read_b64_tr_b16 v[210:211], v189 offset:0x3600
	ds_read_b64_tr_b16 v[212:213], v189 offset:0x3e00
	s_waitcnt lgkmcnt(6)
	v_mfma_f32_32x32x16_bf16 v[32:47], v[116:119], v[206:209], v[32:47]
	s_waitcnt vmcnt(0)
	ds_write_b128 v197, v[160:163] offset:57344
	ds_write_b128 v234, v[164:167] offset:57344
	ds_write_b128 v199, v[168:171] offset:57344
	ds_read_b64_tr_b16 v[206:207], v189 offset:0x2600
	ds_read_b64_tr_b16 v[208:209], v189 offset:0x2e00
	s_waitcnt lgkmcnt(7)
	v_mfma_f32_32x32x16_bf16 v[16:31], v[152:155], v[72:75], v[16:31]
	s_waitcnt lgkmcnt(0)
	s_barrier
	ds_write_b128 v195, v[120:123] offset:16384
	v_exp_f32_e32 v64, v96
	v_exp_f32_e32 v65, v97
	v_exp_f32_e32 v66, v98
	v_exp_f32_e32 v67, v99
	v_exp_f32_e32 v68, v100
	v_exp_f32_e32 v69, v101
	v_exp_f32_e32 v70, v102
	v_mfma_f32_32x32x16_bf16 v[16:31], v[156:159], v[182:185], v[16:31]
	ds_write_b128 v196, v[124:127] offset:16384
	v_exp_f32_e32 v71, v103
	v_exp_f32_e32 v72, v104
	v_exp_f32_e32 v73, v105
	v_exp_f32_e32 v74, v106
	v_exp_f32_e32 v75, v107
	v_exp_f32_e32 v76, v108
	v_exp_f32_e32 v77, v109
	v_mfma_f32_32x32x16_bf16 v[16:31], v[112:115], v[206:209], v[16:31]
	v_exp_f32_e32 v78, v110
	v_exp_f32_e32 v79, v111
	v_mfma_f32_32x32x16_bf16 v[16:31], v[116:119], v[210:213], v[16:31]
	v_cmp_gt_f32_e32 vcc, 1.0, v180
	s_cbranch_vccz .LBB0_1724
	s_and_saveexec_b64 s[12:13], s[4:5]
	s_cbranch_execz .LBB0_1723
	ds_write_b32 v224, v180 offset:128
	s_branch .LBB0_1723
.LBB0_1732:
	ds_read_b128 v[96:99], v237 offset:57344
	ds_read_b128 v[100:103], v238 offset:12288
	s_waitcnt lgkmcnt(0)
	ds_read_b128 v[152:155], v215 offset:49152
	ds_read_b128 v[156:159], v215 offset:61440
	v_exp_f32_e32 v80, v80
	v_exp_f32_e32 v81, v81
	v_exp_f32_e32 v82, v82
	v_exp_f32_e32 v83, v83
	v_exp_f32_e32 v84, v84
	v_exp_f32_e32 v85, v85
	v_exp_f32_e32 v86, v86
	v_exp_f32_e32 v87, v87
	s_waitcnt lgkmcnt(0)
	s_waitcnt lgkmcnt(3)
	v_mfma_f32_32x32x16_bf16 v[112:127], v[96:99], v[148:151], 0
	s_waitcnt lgkmcnt(2)
	v_mfma_f32_32x32x16_bf16 v[96:111], v[100:103], v[148:151], 0
	s_waitcnt lgkmcnt(1)
	v_mfma_f32_32x32x16_bf16 v[112:127], v[152:155], v[144:147], v[112:127]
	ds_read_b128 v[148:151], v203 offset:49152
	ds_read_b128 v[152:155], v203 offset:61440
	v_exp_f32_e32 v88, v88
	v_exp_f32_e32 v89, v89
	v_exp_f32_e32 v90, v90
	v_exp_f32_e32 v91, v91
	v_exp_f32_e32 v92, v92
	v_exp_f32_e32 v93, v93
	v_exp_f32_e32 v94, v94
	v_exp_f32_e32 v95, v95
	s_waitcnt lgkmcnt(0)
	s_waitcnt lgkmcnt(2)
	v_mfma_f32_32x32x16_bf16 v[96:111], v[156:159], v[144:147], v[96:111]
	v_add_f32_e32 v160, 0, v64
	v_add_f32_e32 v160, v65, v160
	v_add_f32_e32 v160, v66, v160
	s_waitcnt lgkmcnt(1)
	v_mfma_f32_32x32x16_bf16 v[112:127], v[148:151], v[140:143], v[112:127]
	v_add_f32_e32 v148, v67, v160
	v_add_f32_e32 v148, v68, v148
	v_add_f32_e32 v148, v69, v148
	ds_read_b128 v[144:147], v214 offset:49152
	ds_read_b128 v[156:159], v214 offset:61440
	v_add_f32_e32 v148, v70, v148
	v_add_f32_e32 v160, v71, v148
	s_waitcnt lgkmcnt(0)
	s_waitcnt lgkmcnt(2)
	v_mfma_f32_32x32x16_bf16 v[96:111], v[152:155], v[140:143], v[96:111]
	v_add_f32_e32 v152, v72, v160
	v_add_f32_e32 v152, v73, v152
	v_add_f32_e32 v152, v74, v152
	s_waitcnt lgkmcnt(1)
	v_mfma_f32_32x32x16_bf16 v[112:127], v[144:147], v[136:139], v[112:127]
	v_add_f32_e32 v144, v75, v152
	v_add_f32_e32 v144, v76, v144
	v_add_f32_e32 v144, v77, v144
	ds_read_b128 v[140:143], v202 offset:49152
	ds_read_b128 v[148:151], v202 offset:61440
	v_add_f32_e32 v144, v78, v144
	v_add_f32_e32 v152, v79, v144
	s_waitcnt lgkmcnt(0)
	s_waitcnt lgkmcnt(2)
	v_mfma_f32_32x32x16_bf16 v[96:111], v[156:159], v[136:139], v[96:111]
	v_add_f32_e32 v152, v80, v152
	v_add_f32_e32 v152, v81, v152
	v_add_f32_e32 v152, v82, v152
	s_waitcnt lgkmcnt(1)
	v_mfma_f32_32x32x16_bf16 v[112:127], v[140:143], v[132:135], v[112:127]
	v_add_f32_e32 v140, v83, v152
	v_add_f32_e32 v140, v84, v140
	v_add_f32_e32 v140, v85, v140
	ds_read_b128 v[136:139], v201 offset:49152
	ds_read_b128 v[144:147], v201 offset:61440
	v_add_f32_e32 v140, v86, v140
	v_add_f32_e32 v152, v87, v140
	s_waitcnt lgkmcnt(0)
	s_waitcnt lgkmcnt(2)
; template <class CF> __device__ __forceinline__ void qk_sm1(f32x16& n0, f32x16& n1, const char* Ks, const bf16x8* qr, const char* qx, int r32, int hi, ...
;   static_assert(CF::ND0 == 12, "qk_sm1: 12 d0 steps");
;   n0 = f32x16{}; n1 = f32x16{};
;   const char* kr = Ks + r32 * CF::KPITCH; const int sw = (r32 & CF::KSWM) << 4;
;   bf16x8 kf[2][2], qf[2];
;     ...
;   ATT_QRD(0, 0); asm volatile("s_waitcnt lgkmcnt(0)" ::: "memory"); ATT_SBAR();
;   float ps = 0;
; #pragma unroll
;   for (int g = 0; g < 12; ++g) {
;     if (g + 1 < 12) ATT_QRD((g + 1) & 1, g + 1);
;     if (g < 2) {
; #pragma unroll
;       for (int r = 0; r < 8; ++r) p1[8 * g + r] = __builtin_amdgcn_exp2f(p1[8 * g + r]);
;       if (g == 1) asm volatile("" : "+v"(p1)); }
;     else if (g < 6) {
; #pragma unroll
;       for (int r = 0; r < 8; ++r) ps += (g < 4 ? p0[8 * (g - 2) + r] : p1[8 * (g - 4) + r]);
;       asm volatile("" : "+v"(ps)); }
;     else if (g == 6) {
;       { auto rr = __builtin_amdgcn_permlane32_swap(__float_as_uint(ps), __float_as_uint(ps), false, false);
;         ps = __uint_as_float(rr[0]) + __uint_as_float(rr[1]); }
;       l_reg = l_reg * alpha + ps;
;       ATT_PK4(p0, 0, pa0);
;       asm volatile("" : "+v"(l_reg), "+v"(pa0)); }
;     else if (g == 7) { ATT_PK4(p0, 8, pa1); asm volatile("" : "+v"(pa1)); }
;     else if (g == 8) { ATT_PK4(p1, 0, pa2); asm volatile("" : "+v"(pa2)); }
;     else if (g == 9) { ATT_PK4(p1, 8, pa3); asm volatile("" : "+v"(pa3)); }
;     ATT_QMM(g & 1, g);
;     if (g + 1 < 12) { asm volatile("s_waitcnt lgkmcnt(0)" ::: "memory"); ATT_SBAR(); }
;   }
; template <class CF> __device__ __forceinline__ void pv_sm(f32x16* o, int vb, bf16x8 pa0, bf16x8 pa1, bf16x8 pa2, bf16x8 pa3, f32x16& p0, f32x16& p1, float& m_reg, float& mn, float& alpha) {
;   constexpr float C = CF::SCALE * 1.4426950408889634f;
;   s16x4 f[8];
;   pv_reads<0>(vb, f);
;   float pmax = p0[0];
; #pragma unroll
;   for (int r = 1; r < 16; ++r) pmax = fmaxf(pmax, p0[r]);
;   asm volatile("" : "+v"(pmax));
;   pv_mfma4(o[0], f, pa0, pa1, pa2, pa3);
;   pv_reads<1>(vb, f);
; #pragma unroll
;   for (int r = 0; r < 16; ++r) pmax = fmaxf(pmax, p1[r]);
;   { auto rr = __builtin_amdgcn_permlane32_swap(__float_as_uint(pmax), __float_as_uint(pmax), false, false);
;     pmax = fmaxf(__uint_as_float(rr[0]), __uint_as_float(rr[1])); }
;   asm volatile("" : "+v"(pmax));
	v_mfma_f32_32x32x16_bf16 v[96:111], v[148:151], v[132:135], v[96:111]
	v_add_f32_e32 v152, v88, v152
	v_add_f32_e32 v152, v89, v152
	v_add_f32_e32 v152, v90, v152
	s_waitcnt lgkmcnt(1)
	v_mfma_f32_32x32x16_bf16 v[112:127], v[136:139], v[128:131], v[112:127]
	v_add_f32_e32 v136, v91, v152
	v_add_f32_e32 v136, v92, v136
	ds_read_b128 v[132:135], v198 offset:61440
	ds_read_b128 v[140:143], v198 offset:49152
	ds_read_b128 v[148:151], v188
	v_add_f32_e32 v136, v93, v136
	v_add_f32_e32 v136, v94, v136
	v_add_f32_e32 v160, v95, v136
	s_waitcnt lgkmcnt(0)
	s_waitcnt lgkmcnt(3)
	v_mfma_f32_32x32x16_bf16 v[96:111], v[144:147], v[128:131], v[96:111]
	v_mov_b32_e32 v128, v160
	ds_read_b128 v[136:139], v192 offset:61440
	ds_read_b128 v[152:155], v192 offset:49152
	ds_read_b128 v[156:159], v188 offset:1024
	v_permlane32_swap_b32_e32 v160, v128
	v_add_f32_e32 v144, v160, v128
	v_cvt_pk_bf16_f32 v128, v64, v65
	v_cvt_pk_bf16_f32 v129, v66, v67
	v_cvt_pk_bf16_f32 v130, v68, v69
	v_cvt_pk_bf16_f32 v131, v70, v71
	v_fmac_f32_e32 v144, v250, v180
	v_permlane32_swap_b32_e32 v128, v130
	v_permlane32_swap_b32_e32 v129, v131
	s_waitcnt lgkmcnt(0)
	s_waitcnt lgkmcnt(3)
	v_mfma_f32_32x32x16_bf16 v[112:127], v[140:143], v[148:151], v[112:127]
	v_mfma_f32_32x32x16_bf16 v[96:111], v[132:135], v[148:151], v[96:111]
	ds_read_b128 v[64:67], v194 offset:61440
	ds_read_b128 v[68:71], v194 offset:49152
	ds_read_b128 v[140:143], v188 offset:2048
	v_cvt_pk_bf16_f32 v132, v72, v73
	v_cvt_pk_bf16_f32 v133, v74, v75
	v_cvt_pk_bf16_f32 v134, v76, v77
	v_cvt_pk_bf16_f32 v135, v78, v79
	s_waitcnt lgkmcnt(3)
	v_mfma_f32_32x32x16_bf16 v[112:127], v[152:155], v[156:159], v[112:127]
	v_permlane32_swap_b32_e32 v132, v134
	v_permlane32_swap_b32_e32 v133, v135
	s_waitcnt lgkmcnt(0)
	v_mfma_f32_32x32x16_bf16 v[96:111], v[136:139], v[156:159], v[96:111]
	ds_read_b128 v[72:75], v190 offset:61440
	ds_read_b128 v[76:79], v190 offset:49152
	ds_read_b128 v[146:149], v188 offset:3072
	v_cvt_pk_bf16_f32 v136, v80, v81
	v_cvt_pk_bf16_f32 v137, v82, v83
	v_cvt_pk_bf16_f32 v138, v84, v85
	v_cvt_pk_bf16_f32 v139, v86, v87
	s_waitcnt lgkmcnt(3)
	v_mfma_f32_32x32x16_bf16 v[112:127], v[68:71], v[140:143], v[112:127]
	v_permlane32_swap_b32_e32 v136, v138
	v_permlane32_swap_b32_e32 v137, v139
	s_waitcnt lgkmcnt(0)
	v_mfma_f32_32x32x16_bf16 v[96:111], v[64:67], v[140:143], v[96:111]
	ds_read_b128 v[64:67], v193 offset:61440
	ds_read_b128 v[68:71], v193 offset:49152
	ds_read_b128 v[80:83], v188 offset:4096
	v_cvt_pk_bf16_f32 v140, v88, v89
	v_cvt_pk_bf16_f32 v141, v90, v91
	v_cvt_pk_bf16_f32 v142, v92, v93
	v_cvt_pk_bf16_f32 v143, v94, v95
	s_waitcnt lgkmcnt(3)
	v_mfma_f32_32x32x16_bf16 v[112:127], v[76:79], v[146:149], v[112:127]
	v_permlane32_swap_b32_e32 v140, v142
	v_permlane32_swap_b32_e32 v141, v143
	s_waitcnt lgkmcnt(0)
	v_mfma_f32_32x32x16_bf16 v[96:111], v[72:75], v[146:149], v[96:111]
	s_waitcnt lgkmcnt(0)
	v_mfma_f32_32x32x16_bf16 v[112:127], v[68:71], v[80:83], v[112:127]
	ds_read_b128 v[68:71], v191 offset:61440
	ds_read_b128 v[72:75], v191 offset:49152
	ds_read_b128 v[76:79], v188 offset:5120
	s_waitcnt lgkmcnt(0)
	v_mfma_f32_32x32x16_bf16 v[96:111], v[64:67], v[80:83], v[96:111]
	s_waitcnt lgkmcnt(0)
	v_mfma_f32_32x32x16_bf16 v[112:127], v[72:75], v[76:79], v[112:127]
	v_mfma_f32_32x32x16_bf16 v[96:111], v[68:71], v[76:79], v[96:111]
	ds_read_b64_tr_b16 v[64:65], v187 offset:0
	ds_read_b64_tr_b16 v[66:67], v187 offset:0x800
	ds_read_b64_tr_b16 v[68:69], v187 offset:0x1000
	ds_read_b64_tr_b16 v[70:71], v187 offset:0x1800
	ds_read_b64_tr_b16 v[72:73], v187 offset:0x2000
	ds_read_b64_tr_b16 v[74:75], v187 offset:0x2800
	ds_read_b64_tr_b16 v[76:77], v187 offset:0x3000
	ds_read_b64_tr_b16 v[78:79], v187 offset:0x3800
	s_waitcnt lgkmcnt(0)
	s_nop 0
	v_mfma_f32_32x32x16_bf16 v[0:15], v[128:131], v[64:67], v[0:15]
	s_nop 8
	v_max_f32_e32 v80, v113, v113
	v_max_f32_e32 v81, v112, v112
	v_max_f32_e32 v80, v81, v80
	v_max3_f32 v80, v80, v114, v115
	v_max3_f32 v80, v80, v116, v117
	v_max3_f32 v80, v80, v118, v119
	v_max3_f32 v80, v80, v120, v121
	v_mfma_f32_32x32x16_bf16 v[0:15], v[132:135], v[68:71], v[0:15]
	v_max3_f32 v80, v80, v122, v123
	v_max3_f32 v80, v80, v124, v125
	v_max3_f32 v80, v80, v126, v127
	ds_read_b64_tr_b16 v[64:65], v187 offset:0x200
	ds_read_b64_tr_b16 v[66:67], v187 offset:0xa00
	ds_read_b64_tr_b16 v[68:69], v187 offset:0x1200
	v_mfma_f32_32x32x16_bf16 v[0:15], v[136:139], v[72:75], v[0:15]
	ds_read_b64_tr_b16 v[70:71], v187 offset:0x1a00
	ds_read_b64_tr_b16 v[72:73], v187 offset:0x2200
	ds_read_b64_tr_b16 v[74:75], v187 offset:0x2a00
	v_mfma_f32_32x32x16_bf16 v[0:15], v[140:143], v[76:79], v[0:15]
	ds_read_b64_tr_b16 v[76:77], v187 offset:0x3200
	ds_read_b64_tr_b16 v[78:79], v187 offset:0x3a00
	s_waitcnt lgkmcnt(0)
	v_mfma_f32_32x32x16_bf16 v[48:63], v[128:131], v[64:67], v[48:63]
	v_max3_f32 v80, v80, v96, v97
	v_max3_f32 v80, v80, v98, v99
	v_max3_f32 v80, v80, v100, v101
	v_max3_f32 v80, v80, v102, v103
	v_max3_f32 v80, v80, v104, v105
	v_max3_f32 v80, v80, v106, v107
	v_max3_f32 v80, v80, v108, v109
	v_mfma_f32_32x32x16_bf16 v[48:63], v[132:135], v[68:71], v[48:63]
	v_max3_f32 v80, v80, v110, v111
	v_mov_b32_e32 v81, v80
	s_nop 1
	v_permlane32_swap_b32_e32 v80, v81
	v_max_f32_e32 v81, v81, v81
	v_max_f32_e32 v80, v80, v80
	v_max_f32_e32 v84, v80, v81
	v_mfma_f32_32x32x16_bf16 v[48:63], v[136:139], v[72:75], v[48:63]
	ds_read_b64_tr_b16 v[64:65], v187 offset:0x400
	ds_read_b64_tr_b16 v[66:67], v187 offset:0xc00
	ds_read_b64_tr_b16 v[68:69], v187 offset:0x1400
	ds_read_b64_tr_b16 v[70:71], v187 offset:0x1c00
	ds_read_b64_tr_b16 v[80:81], v187 offset:0x2400
	ds_read_b64_tr_b16 v[82:83], v187 offset:0x2c00
	v_mfma_f32_32x32x16_bf16 v[48:63], v[140:143], v[76:79], v[48:63]
	ds_read_b64_tr_b16 v[146:147], v187 offset:0x3400
	ds_read_b64_tr_b16 v[148:149], v187 offset:0x3c00
	s_waitcnt lgkmcnt(0)
; template <class CF> __device__ __forceinline__ void pv_sm(f32x16* o, int vb, bf16x8 pa0, bf16x8 pa1, bf16x8 pa2, bf16x8 pa3, f32x16& p0, f32x16& p1, float& m_reg, float& mn, float& alpha) {
;     ...
;   if (__builtin_expect(__all(pmax - m_reg <= THR / CF::SCALE), 1)) { mn = m_reg; alpha = 1.f; }
;   else { mn = fmaxf(m_reg, pmax); alpha = __builtin_amdgcn_exp2f((m_reg - mn) * C); m_reg = mn; }
;   const float mnC = -mn * C;
; #pragma unroll
;   for (int r = 0; r < 16; ++r) p0[r] = fmaf(p0[r], C, mnC);
; #pragma unroll
;   for (int r = 0; r < 16; ++r) p1[r] = fmaf(p1[r], C, mnC);
;   asm volatile("" : "+v"(p0), "+v"(p1));
;   pv_mfma4(o[2], f, pa0, pa1, pa2, pa3);
;   pv_reads<3>(vb, f);
; #pragma unroll
;   for (int r = 0; r < 16; ++r) p0[r] = __builtin_amdgcn_exp2f(p0[r]);
;   asm volatile("" : "+v"(p0));
;   pv_mfma4(o[3], f, pa0, pa1, pa2, pa3);
	v_mfma_f32_32x32x16_bf16 v[32:47], v[128:131], v[64:67], v[32:47]
	v_sub_f32_e32 v72, v84, v233
	v_cmp_ge_f32_e32 vcc, s63, v72
	v_max_f32_e32 v72, v84, v84
	v_max_f32_e32 v73, v233, v233
	v_max_f32_e32 v72, v73, v72
	v_sub_f32_e32 v73, v233, v72
	v_mul_f32_e32 v73, 0x3dd53b94, v73
	v_mfma_f32_32x32x16_bf16 v[32:47], v[132:135], v[68:71], v[32:47]
	v_exp_f32_e32 v73, v73
	s_cmp_eq_u64 vcc, exec
	s_cselect_b64 vcc, -1, 0
	v_cndmask_b32_e32 v64, v72, v233, vcc
	v_mul_f32_e32 v150, 0xbdd53b94, v64
	v_cndmask_b32_e64 v145, v73, 1.0, vcc
	v_pk_fma_f32 v[78:79], v[126:127], s[84:85], v[150:151] op_sel_hi:[1,0,0]
	v_mfma_f32_32x32x16_bf16 v[32:47], v[136:139], v[80:83], v[32:47]
	v_fma_f32 v76, v124, s84, v150
	v_fma_f32 v77, v125, s84, v150
	v_fma_f32 v74, v122, s84, v150
	v_fma_f32 v75, v123, s84, v150
	v_fma_f32 v72, v120, s84, v150
	v_fma_f32 v73, v121, s84, v150
	v_pk_fma_f32 v[70:71], v[118:119], s[84:85], v[150:151] op_sel_hi:[1,0,0]
	v_pk_fma_f32 v[68:69], v[116:117], s[84:85], v[150:151] op_sel_hi:[1,0,0]
	v_pk_fma_f32 v[66:67], v[114:115], s[84:85], v[150:151] op_sel_hi:[1,0,0]
	v_pk_fma_f32 v[64:65], v[112:113], s[84:85], v[150:151] op_sel_hi:[1,0,0]
	v_pk_fma_f32 v[94:95], v[110:111], s[84:85], v[150:151] op_sel_hi:[1,0,0]
	v_pk_fma_f32 v[92:93], v[108:109], s[84:85], v[150:151] op_sel_hi:[1,0,0]
	v_pk_fma_f32 v[90:91], v[106:107], s[84:85], v[150:151] op_sel_hi:[1,0,0]
	v_pk_fma_f32 v[88:89], v[104:105], s[84:85], v[150:151] op_sel_hi:[1,0,0]
	v_pk_fma_f32 v[86:87], v[102:103], s[84:85], v[150:151] op_sel_hi:[1,0,0]
	v_pk_fma_f32 v[84:85], v[100:101], s[84:85], v[150:151] op_sel_hi:[1,0,0]
	v_pk_fma_f32 v[82:83], v[98:99], s[84:85], v[150:151] op_sel_hi:[1,0,0]
	v_pk_fma_f32 v[80:81], v[96:97], s[84:85], v[150:151] op_sel_hi:[1,0,0]
	v_mfma_f32_32x32x16_bf16 v[32:47], v[140:143], v[146:149], v[32:47]
	ds_read_b64_tr_b16 v[96:97], v187 offset:0x600
	ds_read_b64_tr_b16 v[98:99], v187 offset:0xe00
	ds_read_b64_tr_b16 v[100:101], v187 offset:0x1600
	ds_read_b64_tr_b16 v[102:103], v187 offset:0x1e00
	ds_read_b64_tr_b16 v[104:105], v187 offset:0x2600
	ds_read_b64_tr_b16 v[106:107], v187 offset:0x2e00
	ds_read_b64_tr_b16 v[108:109], v187 offset:0x3600
	ds_read_b64_tr_b16 v[110:111], v187 offset:0x3e00
	s_waitcnt lgkmcnt(0)
	s_nop 0
	v_mfma_f32_32x32x16_bf16 v[16:31], v[128:131], v[96:99], v[16:31]
	v_exp_f32_e32 v64, v64
	v_exp_f32_e32 v65, v65
	v_exp_f32_e32 v66, v66
	v_exp_f32_e32 v67, v67
	v_exp_f32_e32 v68, v68
	v_exp_f32_e32 v69, v69
	v_exp_f32_e32 v70, v70
	v_mfma_f32_32x32x16_bf16 v[16:31], v[132:135], v[100:103], v[16:31]
	v_exp_f32_e32 v71, v71
	v_exp_f32_e32 v72, v72
	v_exp_f32_e32 v73, v73
	v_exp_f32_e32 v74, v74
	v_exp_f32_e32 v75, v75
	v_exp_f32_e32 v76, v76
	v_exp_f32_e32 v77, v77
	v_mfma_f32_32x32x16_bf16 v[16:31], v[136:139], v[104:107], v[16:31]
	v_exp_f32_e32 v78, v78
	v_exp_f32_e32 v79, v79
	v_cmp_gt_f32_e32 vcc, 1.0, v145
	s_barrier
	v_mfma_f32_32x32x16_bf16 v[16:31], v[140:143], v[108:111], v[16:31]
	s_cbranch_vccz .LBB0_1736
	s_mov_b64 s[8:9], exec
	s_and_b64 s[4:5], s[8:9], s[4:5]
	v_mov_b32_e32 v248, v254
	v_mov_b64_e32 v[250:251], 0x400
	v_mov_b64_e32 v[238:239], 0x3ff
	v_mov_b32_e32 v254, 1
	s_mov_b64 exec, s[4:5]
	ds_write_b32 v224, v145 offset:128
	s_or_b64 exec, exec, s[8:9]
	s_waitcnt lgkmcnt(0)
	v_add_u32_e32 v108, v186, v204
	ds_read_b128 v[96:99], v108 offset:224
	ds_read_b128 v[100:103], v108 offset:192
	ds_read_b128 v[104:107], v108 offset:160
	ds_read_b128 v[108:111], v108 offset:128
	s_waitcnt lgkmcnt(3)
	v_pk_mul_f32 v[12:13], v[12:13], v[96:97]
	s_waitcnt lgkmcnt(2)
	v_pk_mul_f32 v[8:9], v[8:9], v[100:101]
	s_waitcnt lgkmcnt(1)
	v_pk_mul_f32 v[4:5], v[4:5], v[104:105]
	v_pk_mul_f32 v[14:15], v[14:15], v[98:99]
	v_pk_mul_f32 v[10:11], v[10:11], v[102:103]
	v_pk_mul_f32 v[6:7], v[6:7], v[106:107]
	s_waitcnt lgkmcnt(0)
	v_pk_mul_f32 v[2:3], v[2:3], v[110:111]
	v_pk_mul_f32 v[0:1], v[0:1], v[108:109]
	v_pk_mul_f32 v[60:61], v[60:61], v[96:97]
	v_pk_mul_f32 v[56:57], v[56:57], v[100:101]
	v_pk_mul_f32 v[52:53], v[52:53], v[104:105]
	v_pk_mul_f32 v[62:63], v[62:63], v[98:99]
	v_pk_mul_f32 v[58:59], v[58:59], v[102:103]
	v_pk_mul_f32 v[54:55], v[54:55], v[106:107]
	v_pk_mul_f32 v[50:51], v[50:51], v[110:111]
	v_pk_mul_f32 v[48:49], v[48:49], v[108:109]
	v_pk_mul_f32 v[44:45], v[44:45], v[96:97]
	v_pk_mul_f32 v[40:41], v[40:41], v[100:101]
	v_pk_mul_f32 v[36:37], v[36:37], v[104:105]
	v_pk_mul_f32 v[46:47], v[46:47], v[98:99]
	v_pk_mul_f32 v[42:43], v[42:43], v[102:103]
	v_pk_mul_f32 v[38:39], v[38:39], v[106:107]
	v_pk_mul_f32 v[34:35], v[34:35], v[110:111]
	v_pk_mul_f32 v[32:33], v[32:33], v[108:109]
	v_pk_mul_f32 v[28:29], v[28:29], v[96:97]
	v_pk_mul_f32 v[24:25], v[24:25], v[100:101]
	v_pk_mul_f32 v[20:21], v[20:21], v[104:105]
	v_pk_mul_f32 v[30:31], v[30:31], v[98:99]
	v_pk_mul_f32 v[26:27], v[26:27], v[102:103]
	v_pk_mul_f32 v[22:23], v[22:23], v[106:107]
	v_pk_mul_f32 v[18:19], v[18:19], v[110:111]
	v_pk_mul_f32 v[16:17], v[16:17], v[108:109]
	s_branch .LBB0_1737
